# swizzle + decoupled load/write pipeline (tile base via readfirstlane into vcc/s100:101, advancing voffsets) in all 7 big GEMM instances
# speedup vs baseline: 1.0369x; 1.0217x over previous
.LBB0_463:
	s_or_b64 exec, exec, s[14:15]
	s_mov_b64 s[6:7], s[60:61]
	s_waitcnt lgkmcnt(0)
	s_barrier
	s_load_dwordx2 s[16:17], s[6:7], 0x130
	v_mov_b32_e32 v2, v172
	s_mov_b32 s11, s42
	s_mov_b32 s20, s94
	s_waitcnt lgkmcnt(0)
	s_add_u32 s14, s16, 0x6035800
	s_addc_u32 s15, s17, 0
	s_add_u32 s18, s16, 0x3200000
	s_addc_u32 s19, s17, 0
	s_cmpk_lt_i32 s20, 0x600
	s_cbranch_scc0 .LBB0_468
	v_ashrrev_i32_e32 v204, 3, v2
	v_bfe_u32 v3, v2, 4, 2
	v_and_b32_e32 v4, 15, v2
	v_lshlrev_b32_e32 v0, 4, v2
	v_ashrrev_i32_e32 v5, 1, v2
	s_movk_i32 s2, 0xffc0
	v_lshlrev_b32_e32 v2, 1, v2
	v_and_b32_e32 v0, 0x70, v0
	v_and_or_b32 v205, v5, s2, v4
	v_and_b32_e32 v207, 0x80, v2
	s_movk_i32 s2, 0x90
	v_or_b32_e32 v2, v207, v4
	v_and_b32_e32 v100, 7, v204
	v_lshlrev_b32_e32 v100, 4, v100
	v_xor_b32_e32 v100, v100, v0
	v_lshl_add_u32 v166, v204, 7, v100
	v_lshl_add_u64 v[162:163], s[18:19], 0, v[0:1]
	v_lshl_add_u64 v[164:165], s[16:17], 0, v[0:1]
	v_and_b32_e32 v100, 7, v4
	v_xor_b32_e32 v100, v100, v3
	v_lshlrev_b32_e32 v206, 4, v100
	v_lshlrev_b32_e32 v208, 2, v3
	v_lshlrev_b32_e32 v0, 7, v205
	v_lshlrev_b32_e32 v167, 7, v2
.LBB0_465:
	s_mul_hi_i32 s4, s20, 0x38e38e39
	s_lshr_b32 s6, s4, 31
	s_ashr_i32 s4, s4, 4
	s_add_i32 s4, s4, s6
	s_mul_i32 s6, s4, 0x48
	s_sub_i32 s6, s20, s6
	s_lshl_b32 s6, s6, 8
	v_add_u32_e32 v2, s6, v204
	v_ashrrev_i32_e32 v3, 31, v2
	v_lshlrev_b64 v[2:3], 11, v[2:3]
	v_lshl_add_u64 v[168:169], v[162:163], 0, v[2:3]
	v_add_co_u32_e32 v56, vcc, s34, v168
	s_lshl_b32 s7, s4, 8
	s_nop 0
	v_addc_co_u32_e32 v57, vcc, 0, v169, vcc
	v_add_u32_e32 v2, s7, v204
	s_waitcnt vmcnt(9)
	v_add_co_u32_e32 v58, vcc, s35, v168
	v_ashrrev_i32_e32 v3, 31, v2
	s_nop 0
	v_addc_co_u32_e32 v59, vcc, 0, v169, vcc
	v_lshlrev_b64 v[2:3], 11, v[2:3]
	v_add_co_u32_e32 v60, vcc, s36, v168
	v_lshl_add_u64 v[170:171], v[164:165], 0, v[2:3]
	s_nop 0
	v_addc_co_u32_e32 v61, vcc, 0, v169, vcc
	s_waitcnt vmcnt(8)
	v_add_co_u32_e32 v62, vcc, s35, v170
	global_load_dwordx4 v[24:27], v[56:57], off
	global_load_dwordx4 v[28:31], v[58:59], off
	v_addc_co_u32_e32 v63, vcc, 0, v171, vcc
	v_add_co_u32_e32 v64, vcc, s36, v170
	global_load_dwordx4 v[32:35], v[168:169], off
	global_load_dwordx4 v[36:39], v[170:171], off
	v_addc_co_u32_e32 v65, vcc, 0, v171, vcc
	v_add_co_u32_e32 v66, vcc, s34, v170
	global_load_dwordx4 v[40:43], v[62:63], off
	global_load_dwordx4 v[44:47], v[64:65], off
	v_addc_co_u32_e32 v67, vcc, 0, v171, vcc
	global_load_dwordx4 v[48:51], v[60:61], off
	global_load_dwordx4 v[52:55], v[66:67], off
	s_barrier
	global_load_dwordx4 v[114:117], v[168:169], off offset:128
	global_load_dwordx4 v[106:109], v[56:57], off offset:128
	global_load_dwordx4 v[110:113], v[58:59], off offset:128
	global_load_dwordx4 v[126:129], v[60:61], off offset:128
	global_load_dwordx4 v[122:125], v[170:171], off offset:128
	global_load_dwordx4 v[118:121], v[66:67], off offset:128
	global_load_dwordx4 v[134:137], v[62:63], off offset:128
	global_load_dwordx4 v[130:133], v[64:65], off offset:128
	v_readfirstlane_b32 vcc_lo, v168
	v_readfirstlane_b32 vcc_hi, v169
	v_readfirstlane_b32 s100, v170
	v_readfirstlane_b32 s101, v171
	s_nop 1
	v_subrev_u32_e32 v168, vcc_lo, v168
	v_subrev_u32_e32 v170, s100, v170
	v_mov_b32_e32 v2, 0
	s_mov_b32 s4, 0
	v_mov_b32_e32 v3, v2
	v_mov_b32_e32 v4, v2
	v_mov_b32_e32 v5, v2
	v_mov_b32_e32 v6, v2
	v_mov_b32_e32 v7, v2
	v_mov_b32_e32 v8, v2
	v_mov_b32_e32 v9, v2
	v_mov_b32_e32 v10, v2
	v_mov_b32_e32 v11, v2
	v_mov_b32_e32 v12, v2
	v_mov_b32_e32 v13, v2
	v_mov_b32_e32 v14, v2
	v_mov_b32_e32 v15, v2
	v_mov_b32_e32 v16, v2
	v_mov_b32_e32 v17, v2
	v_mov_b32_e32 v18, v2
	v_mov_b32_e32 v19, v2
	v_mov_b32_e32 v20, v2
	v_mov_b32_e32 v21, v2
	v_mov_b32_e32 v22, v2
	v_mov_b32_e32 v23, v2
	v_mov_b32_e32 v56, v2
	v_mov_b32_e32 v57, v2
	v_mov_b32_e32 v58, v2
	v_mov_b32_e32 v59, v2
	v_mov_b32_e32 v60, v2
	v_mov_b32_e32 v61, v2
	v_mov_b32_e32 v62, v2
	v_mov_b32_e32 v63, v2
	v_mov_b32_e32 v64, v2
	v_mov_b32_e32 v65, v2
	v_mov_b32_e32 v66, v2
	v_mov_b32_e32 v67, v2
	v_mov_b32_e32 v68, v2
	v_mov_b32_e32 v69, v2
	v_mov_b32_e32 v70, v2
	v_mov_b32_e32 v71, v2
	v_mov_b32_e32 v72, v2
	v_mov_b32_e32 v73, v2
	v_mov_b32_e32 v74, v2
	v_mov_b32_e32 v75, v2
	v_mov_b32_e32 v76, v2
	v_mov_b32_e32 v77, v2
	v_mov_b32_e32 v78, v2
	v_mov_b32_e32 v79, v2
	v_mov_b32_e32 v80, v2
	v_mov_b32_e32 v81, v2
	v_mov_b32_e32 v82, v2
	v_mov_b32_e32 v83, v2
	v_mov_b32_e32 v84, v2
	v_mov_b32_e32 v85, v2
	s_waitcnt vmcnt(11)
	ds_write_b128 v166, v[40:43] offset:49152
	s_waitcnt vmcnt(10)
	ds_write_b128 v166, v[44:47] offset:57344
	ds_write_b128 v166, v[32:35]
	ds_write_b128 v166, v[36:39] offset:32768
	ds_write_b128 v166, v[24:27] offset:8192
	ds_write_b128 v166, v[28:31] offset:16384
	s_waitcnt vmcnt(9)
	ds_write_b128 v166, v[48:51] offset:24576
	s_waitcnt vmcnt(8)
	ds_write_b128 v166, v[52:55] offset:40960
	v_mov_b32_e32 v24, v2
	v_mov_b32_e32 v25, v2
	v_mov_b32_e32 v26, v2
	v_mov_b32_e32 v27, v2
	v_mov_b32_e32 v28, v2
	v_mov_b32_e32 v29, v2
	v_mov_b32_e32 v30, v2
	v_mov_b32_e32 v31, v2
	v_mov_b32_e32 v32, v2
	v_mov_b32_e32 v33, v2
	v_mov_b32_e32 v34, v2
	v_mov_b32_e32 v35, v2
	v_mov_b32_e32 v36, v2
	v_mov_b32_e32 v37, v2
	v_mov_b32_e32 v38, v2
	v_mov_b32_e32 v39, v2
	v_mov_b32_e32 v40, v2
	v_mov_b32_e32 v41, v2
	v_mov_b32_e32 v42, v2
	v_mov_b32_e32 v43, v2
	v_mov_b32_e32 v44, v2
	v_mov_b32_e32 v45, v2
	v_mov_b32_e32 v46, v2
	v_mov_b32_e32 v47, v2
	v_mov_b32_e32 v48, v2
	v_mov_b32_e32 v49, v2
	v_mov_b32_e32 v50, v2
	v_mov_b32_e32 v51, v2
	v_mov_b32_e32 v52, v2
	v_mov_b32_e32 v53, v2
	v_mov_b32_e32 v54, v2
	v_mov_b32_e32 v55, v2
	v_mov_b32_e32 v86, v2
	v_mov_b32_e32 v87, v2
	v_mov_b32_e32 v88, v2
	v_mov_b32_e32 v89, v2
	v_mov_b32_e32 v90, v2
	v_mov_b32_e32 v91, v2
	v_mov_b32_e32 v92, v2
	v_mov_b32_e32 v93, v2
	v_mov_b32_e32 v94, v2
	v_mov_b32_e32 v95, v2
	v_mov_b32_e32 v96, v2
	v_mov_b32_e32 v97, v2
	v_mov_b32_e32 v98, v2
	v_mov_b32_e32 v99, v2
	v_mov_b32_e32 v100, v2
	v_mov_b32_e32 v101, v2
	v_mov_b32_e32 v102, v2
	v_mov_b32_e32 v103, v2
	v_mov_b32_e32 v104, v2
	v_mov_b32_e32 v105, v2
	v_mov_b32_e32 v138, v2
	v_mov_b32_e32 v139, v2
	v_mov_b32_e32 v140, v2
	v_mov_b32_e32 v141, v2
	v_mov_b32_e32 v142, v2
	v_mov_b32_e32 v143, v2
	v_mov_b32_e32 v144, v2
	v_mov_b32_e32 v145, v2
	v_mov_b32_e32 v146, v2
	v_mov_b32_e32 v147, v2
	v_mov_b32_e32 v148, v2
	v_mov_b32_e32 v149, v2
	v_mov_b32_e32 v150, v2
	v_mov_b32_e32 v151, v2
	v_mov_b32_e32 v152, v2
	v_mov_b32_e32 v153, v2
	v_mov_b32_e32 v154, v2
	v_mov_b32_e32 v155, v2
	v_mov_b32_e32 v156, v2
	v_mov_b32_e32 v157, v2
	v_mov_b32_e32 v158, v2
	v_mov_b32_e32 v159, v2
	v_mov_b32_e32 v160, v2
	v_mov_b32_e32 v161, v2
	s_waitcnt lgkmcnt(0)
	s_barrier
.LBB0_466:
	s_bitcmp1_b32 s4, 0
	s_cselect_b32 s21, 0x12000, 0
	v_or_b32_e32 v184, s21, v206
	v_add_u32_e32 v185, v184, v0
	v_add_u32_e32 v184, v184, v167
	ds_read_b128 v[210:213], v185
	ds_read_b128 v[214:217], v185 offset:2048
	ds_read_b128 v[218:221], v185 offset:4096
	ds_read_b128 v[222:225], v185 offset:6144
	ds_read_b128 v[226:229], v184 offset:32768
	ds_read_b128 v[230:233], v184 offset:34816
	ds_read_b128 v[234:237], v184 offset:36864
	ds_read_b128 v[238:241], v184 offset:38912
	ds_read_b128 v[242:245], v184 offset:40960
	ds_read_b128 v[246:249], v184 offset:43008
	ds_read_b128 v[198:201], v184 offset:45056
	ds_read_b128 v[184:187], v184 offset:47104
	s_add_i32 s10, s4, 1
	s_bitcmp1_b32 s10, 0
	s_cselect_b32 s23, 0x12000, 0
	s_waitcnt lgkmcnt(7)
	v_mfma_f32_16x16x32_bf16 v[158:161], v[226:229], v[210:213], v[158:161]
	v_mfma_f32_16x16x32_bf16 v[94:97], v[226:229], v[214:217], v[94:97]
	v_mfma_f32_16x16x32_bf16 v[62:65], v[226:229], v[218:221], v[62:65]
	v_mfma_f32_16x16x32_bf16 v[30:33], v[226:229], v[222:225], v[30:33]
	v_add_u32_e32 v226, s23, v166
	s_waitcnt vmcnt(7)
	ds_write_b128 v226, v[114:117]
	s_waitcnt lgkmcnt(7)
	v_mfma_f32_16x16x32_bf16 v[154:157], v[230:233], v[210:213], v[154:157]
	v_mfma_f32_16x16x32_bf16 v[90:93], v[230:233], v[214:217], v[90:93]
	global_load_dwordx4 v[114:117], v168, vcc offset:256
	v_mfma_f32_16x16x32_bf16 v[58:61], v[230:233], v[218:221], v[58:61]
	v_mfma_f32_16x16x32_bf16 v[26:29], v[230:233], v[222:225], v[26:29]
	s_waitcnt vmcnt(7)
	ds_write_b128 v226, v[106:109] offset:8192
	s_waitcnt lgkmcnt(7)
	v_mfma_f32_16x16x32_bf16 v[150:153], v[234:237], v[210:213], v[150:153]
	v_mfma_f32_16x16x32_bf16 v[86:89], v[234:237], v[214:217], v[86:89]
	v_add_u32_e32 v106, s34, v168
	global_load_dwordx4 v[106:109], v106, vcc offset:256
	v_mfma_f32_16x16x32_bf16 v[54:57], v[234:237], v[218:221], v[54:57]
	v_mfma_f32_16x16x32_bf16 v[22:25], v[234:237], v[222:225], v[22:25]
	s_waitcnt vmcnt(7)
	ds_write_b128 v226, v[110:113] offset:16384
	s_waitcnt lgkmcnt(7)
	v_mfma_f32_16x16x32_bf16 v[146:149], v[238:241], v[210:213], v[146:149]
	v_mfma_f32_16x16x32_bf16 v[82:85], v[238:241], v[214:217], v[82:85]
	v_add_u32_e32 v110, s35, v168
	global_load_dwordx4 v[110:113], v110, vcc offset:256
	v_mfma_f32_16x16x32_bf16 v[50:53], v[238:241], v[218:221], v[50:53]
	v_mfma_f32_16x16x32_bf16 v[18:21], v[238:241], v[222:225], v[18:21]
	s_waitcnt vmcnt(7)
	ds_write_b128 v226, v[126:129] offset:24576
	s_waitcnt lgkmcnt(7)
	v_mfma_f32_16x16x32_bf16 v[142:145], v[242:245], v[210:213], v[142:145]
	v_mfma_f32_16x16x32_bf16 v[78:81], v[242:245], v[214:217], v[78:81]
	v_add_u32_e32 v126, s36, v168
	global_load_dwordx4 v[126:129], v126, vcc offset:256
	v_mfma_f32_16x16x32_bf16 v[46:49], v[242:245], v[218:221], v[46:49]
	v_mfma_f32_16x16x32_bf16 v[14:17], v[242:245], v[222:225], v[14:17]
	s_waitcnt vmcnt(7)
	ds_write_b128 v226, v[122:125] offset:32768
	s_waitcnt lgkmcnt(7)
	v_mfma_f32_16x16x32_bf16 v[138:141], v[246:249], v[210:213], v[138:141]
	v_mfma_f32_16x16x32_bf16 v[74:77], v[246:249], v[214:217], v[74:77]
	global_load_dwordx4 v[122:125], v170, s[100:101] offset:256
	v_mfma_f32_16x16x32_bf16 v[42:45], v[246:249], v[218:221], v[42:45]
	v_mfma_f32_16x16x32_bf16 v[10:13], v[246:249], v[222:225], v[10:13]
	s_waitcnt vmcnt(7)
	ds_write_b128 v226, v[118:121] offset:40960
	s_waitcnt lgkmcnt(7)
	v_mfma_f32_16x16x32_bf16 v[102:105], v[198:201], v[210:213], v[102:105]
	v_mfma_f32_16x16x32_bf16 v[70:73], v[198:201], v[214:217], v[70:73]
	v_add_u32_e32 v118, s34, v170
	global_load_dwordx4 v[118:121], v118, s[100:101] offset:256
	v_mfma_f32_16x16x32_bf16 v[38:41], v[198:201], v[218:221], v[38:41]
	v_mfma_f32_16x16x32_bf16 v[6:9], v[198:201], v[222:225], v[6:9]
	s_waitcnt vmcnt(7)
	ds_write_b128 v226, v[134:137] offset:49152
	s_waitcnt lgkmcnt(7)
	v_mfma_f32_16x16x32_bf16 v[98:101], v[184:187], v[210:213], v[98:101]
	v_mfma_f32_16x16x32_bf16 v[66:69], v[184:187], v[214:217], v[66:69]
	v_add_u32_e32 v134, s35, v170
	global_load_dwordx4 v[134:137], v134, s[100:101] offset:256
	v_mfma_f32_16x16x32_bf16 v[34:37], v[184:187], v[218:221], v[34:37]
	v_mfma_f32_16x16x32_bf16 v[2:5], v[184:187], v[222:225], v[2:5]
	s_waitcnt vmcnt(7)
	ds_write_b128 v226, v[130:133] offset:57344
	v_add3_u32 v214, s21, v0, v206
	v_xor_b32_e32 v214, 64, v214
	v_add3_u32 v246, s21, v167, v206
	v_xor_b32_e32 v246, 64, v246
	v_add_u32_e32 v130, s36, v170
	global_load_dwordx4 v[130:133], v130, s[100:101] offset:256
	v_add_u32_e32 v168, 0x80, v168
	v_add_u32_e32 v170, 0x80, v170
	ds_read_b128 v[184:187], v214
	ds_read_b128 v[198:201], v214 offset:2048
	ds_read_b128 v[210:213], v214 offset:4096
	ds_read_b128 v[218:221], v246 offset:32768
	ds_read_b128 v[214:217], v214 offset:6144
	ds_read_b128 v[222:225], v246 offset:34816
	ds_read_b128 v[226:229], v246 offset:36864
	ds_read_b128 v[230:233], v246 offset:38912
	ds_read_b128 v[234:237], v246 offset:40960
	ds_read_b128 v[238:241], v246 offset:43008
	ds_read_b128 v[242:245], v246 offset:45056
	ds_read_b128 v[246:249], v246 offset:47104
	s_waitcnt lgkmcnt(8)
	v_mfma_f32_16x16x32_bf16 v[158:161], v[218:221], v[184:187], v[158:161]
	v_mfma_f32_16x16x32_bf16 v[94:97], v[218:221], v[198:201], v[94:97]
	v_mfma_f32_16x16x32_bf16 v[62:65], v[218:221], v[210:213], v[62:65]
	s_waitcnt lgkmcnt(7)
	v_mfma_f32_16x16x32_bf16 v[30:33], v[218:221], v[214:217], v[30:33]
	s_waitcnt lgkmcnt(6)
	v_mfma_f32_16x16x32_bf16 v[154:157], v[222:225], v[184:187], v[154:157]
	v_mfma_f32_16x16x32_bf16 v[90:93], v[222:225], v[198:201], v[90:93]
	v_mfma_f32_16x16x32_bf16 v[58:61], v[222:225], v[210:213], v[58:61]
	v_mfma_f32_16x16x32_bf16 v[26:29], v[222:225], v[214:217], v[26:29]
	s_waitcnt lgkmcnt(5)
	v_mfma_f32_16x16x32_bf16 v[150:153], v[226:229], v[184:187], v[150:153]
	v_mfma_f32_16x16x32_bf16 v[86:89], v[226:229], v[198:201], v[86:89]
	v_mfma_f32_16x16x32_bf16 v[54:57], v[226:229], v[210:213], v[54:57]
	v_mfma_f32_16x16x32_bf16 v[22:25], v[226:229], v[214:217], v[22:25]
	s_waitcnt lgkmcnt(4)
	v_mfma_f32_16x16x32_bf16 v[146:149], v[230:233], v[184:187], v[146:149]
	v_mfma_f32_16x16x32_bf16 v[82:85], v[230:233], v[198:201], v[82:85]
	v_mfma_f32_16x16x32_bf16 v[50:53], v[230:233], v[210:213], v[50:53]
	v_mfma_f32_16x16x32_bf16 v[18:21], v[230:233], v[214:217], v[18:21]
	s_waitcnt lgkmcnt(3)
	v_mfma_f32_16x16x32_bf16 v[142:145], v[234:237], v[184:187], v[142:145]
	v_mfma_f32_16x16x32_bf16 v[78:81], v[234:237], v[198:201], v[78:81]
	v_mfma_f32_16x16x32_bf16 v[46:49], v[234:237], v[210:213], v[46:49]
	v_mfma_f32_16x16x32_bf16 v[14:17], v[234:237], v[214:217], v[14:17]
	s_waitcnt lgkmcnt(2)
	v_mfma_f32_16x16x32_bf16 v[138:141], v[238:241], v[184:187], v[138:141]
	v_mfma_f32_16x16x32_bf16 v[74:77], v[238:241], v[198:201], v[74:77]
	v_mfma_f32_16x16x32_bf16 v[42:45], v[238:241], v[210:213], v[42:45]
	v_mfma_f32_16x16x32_bf16 v[10:13], v[238:241], v[214:217], v[10:13]
	s_waitcnt lgkmcnt(1)
	v_mfma_f32_16x16x32_bf16 v[102:105], v[242:245], v[184:187], v[102:105]
	v_mfma_f32_16x16x32_bf16 v[70:73], v[242:245], v[198:201], v[70:73]
	v_mfma_f32_16x16x32_bf16 v[38:41], v[242:245], v[210:213], v[38:41]
	v_mfma_f32_16x16x32_bf16 v[6:9], v[242:245], v[214:217], v[6:9]
	s_waitcnt lgkmcnt(0)
	v_mfma_f32_16x16x32_bf16 v[98:101], v[246:249], v[184:187], v[98:101]
	v_mfma_f32_16x16x32_bf16 v[66:69], v[246:249], v[198:201], v[66:69]
	v_mfma_f32_16x16x32_bf16 v[34:37], v[246:249], v[210:213], v[34:37]
	v_mfma_f32_16x16x32_bf16 v[2:5], v[246:249], v[214:217], v[2:5]
	s_waitcnt lgkmcnt(0)
	s_barrier
	s_cmp_eq_u32 s10, 16
	s_mov_b32 s4, s10
	s_cbranch_scc0 .LBB0_466
	s_waitcnt vmcnt(6)
	v_mul_f32_e32 v109, 0xbfb8aa3b, v158
	v_exp_f32_e32 v109, v109
	s_waitcnt vmcnt(5)
	v_mul_f32_e32 v111, 0xbfb8aa3b, v159
	v_exp_f32_e32 v111, v111
	v_mul_f32_e32 v115, 0xbfb8aa3b, v161
	v_add_f32_e32 v109, 1.0, v109
	v_rcp_f32_e32 v114, v109
	v_add_f32_e32 v109, 1.0, v111
	v_mul_f32_e32 v111, 0xbfb8aa3b, v160
	v_exp_f32_e32 v111, v111
	v_exp_f32_e32 v117, v115
	v_rcp_f32_e32 v116, v109
	s_waitcnt vmcnt(2)
	v_mov_b32_e32 v118, v158
	v_add_f32_e32 v109, 1.0, v111
	v_rcp_f32_e32 v115, v109
	v_add_f32_e32 v109, 1.0, v117
	v_rcp_f32_e32 v117, v109
	v_mov_b32_e32 v119, v160
	v_pk_mul_f32 v[114:115], v[118:119], v[114:115]
	v_mov_b32_e32 v118, v154
	v_mov_b32_e32 v119, v156
	v_mov_b32_e32 v160, v159
	v_pk_mul_f32 v[114:115], v[118:119], v[114:115]
	v_pk_mul_f32 v[116:117], v[160:161], v[116:117]
	v_mov_b32_e32 v156, v155
	v_pk_mul_f32 v[116:117], v[156:157], v[116:117]
	v_and_b32_sdwa v111, v115, v177 dst_sel:DWORD dst_unused:UNUSED_PAD src0_sel:WORD_1 src1_sel:DWORD
	v_and_b32_sdwa v118, v114, v177 dst_sel:DWORD dst_unused:UNUSED_PAD src0_sel:WORD_1 src1_sel:DWORD
	v_add3_u32 v111, v115, v111, s28
	v_and_b32_sdwa v115, v117, v177 dst_sel:DWORD dst_unused:UNUSED_PAD src0_sel:WORD_1 src1_sel:DWORD
	v_add3_u32 v114, v114, v118, s28
	v_and_b32_sdwa v118, v116, v177 dst_sel:DWORD dst_unused:UNUSED_PAD src0_sel:WORD_1 src1_sel:DWORD
	v_add3_u32 v115, v117, v115, s28
	v_or_b32_e32 v106, s7, v207
	v_add3_u32 v116, v116, v118, s28
	v_and_b32_e32 v115, 0xffff0000, v115
	v_ashrrev_i32_e32 v106, 1, v106
	v_and_b32_e32 v116, 0xffff0000, v116
	v_or_b32_sdwa v115, v115, v111 dst_sel:DWORD dst_unused:UNUSED_PAD src0_sel:DWORD src1_sel:WORD_1
	v_mul_f32_e32 v111, 0xbfb8aa3b, v150
	v_or_b32_e32 v108, v106, v208
	v_or_b32_sdwa v114, v116, v114 dst_sel:DWORD dst_unused:UNUSED_PAD src0_sel:DWORD src1_sel:WORD_1
	v_exp_f32_e32 v111, v111
	v_mul_f32_e32 v116, 0xbfb8aa3b, v151
	v_add_u32_e32 v110, s6, v205
	v_mov_b64_e32 v[106:107], s[14:15]
	v_ashrrev_i32_e32 v109, 31, v108
	v_exp_f32_e32 v116, v116
	v_mad_i64_i32 v[112:113], s[6:7], v110, s52, v[106:107]
	v_lshlrev_b64 v[108:109], 1, v[108:109]
	v_lshl_add_u64 v[112:113], v[112:113], 0, v[108:109]
	s_waitcnt vmcnt(0)
	global_store_dwordx2 v[112:113], v[114:115], off
	v_add_f32_e32 v111, 1.0, v111
	v_mul_f32_e32 v115, 0xbfb8aa3b, v152
	v_rcp_f32_e32 v114, v111
	v_add_f32_e32 v111, 1.0, v116
	v_exp_f32_e32 v115, v115
	v_mul_f32_e32 v116, 0xbfb8aa3b, v153
	v_exp_f32_e32 v117, v116
	v_rcp_f32_e32 v116, v111
	v_add_f32_e32 v111, 1.0, v115
	v_rcp_f32_e32 v115, v111
	v_add_f32_e32 v111, 1.0, v117
	v_rcp_f32_e32 v117, v111
	v_mov_b32_e32 v118, v150
	v_mov_b32_e32 v119, v152
	v_pk_mul_f32 v[114:115], v[118:119], v[114:115]
	v_mov_b32_e32 v118, v146
	v_mov_b32_e32 v119, v148
	v_mov_b32_e32 v152, v151
	v_pk_mul_f32 v[114:115], v[118:119], v[114:115]
	v_pk_mul_f32 v[116:117], v[152:153], v[116:117]
	v_mov_b32_e32 v148, v147
	v_pk_mul_f32 v[116:117], v[148:149], v[116:117]
	v_and_b32_sdwa v111, v115, v177 dst_sel:DWORD dst_unused:UNUSED_PAD src0_sel:WORD_1 src1_sel:DWORD
	v_and_b32_sdwa v118, v114, v177 dst_sel:DWORD dst_unused:UNUSED_PAD src0_sel:WORD_1 src1_sel:DWORD
	v_add3_u32 v111, v115, v111, s28
	v_and_b32_sdwa v115, v117, v177 dst_sel:DWORD dst_unused:UNUSED_PAD src0_sel:WORD_1 src1_sel:DWORD
	v_add3_u32 v114, v114, v118, s28
	v_and_b32_sdwa v118, v116, v177 dst_sel:DWORD dst_unused:UNUSED_PAD src0_sel:WORD_1 src1_sel:DWORD
	v_add3_u32 v115, v117, v115, s28
	v_add3_u32 v116, v116, v118, s28
	v_and_b32_e32 v115, 0xffff0000, v115
	v_and_b32_e32 v116, 0xffff0000, v116
	v_or_b32_sdwa v115, v115, v111 dst_sel:DWORD dst_unused:UNUSED_PAD src0_sel:DWORD src1_sel:WORD_1
	v_mul_f32_e32 v111, 0xbfb8aa3b, v142
	v_or_b32_sdwa v114, v116, v114 dst_sel:DWORD dst_unused:UNUSED_PAD src0_sel:DWORD src1_sel:WORD_1
	v_exp_f32_e32 v111, v111
	v_mul_f32_e32 v116, 0xbfb8aa3b, v143
	v_exp_f32_e32 v116, v116
	global_store_dwordx2 v[112:113], v[114:115], off offset:32
	v_add_f32_e32 v111, 1.0, v111
	v_mul_f32_e32 v115, 0xbfb8aa3b, v144
	v_rcp_f32_e32 v114, v111
	v_add_f32_e32 v111, 1.0, v116
	v_exp_f32_e32 v115, v115
	v_mul_f32_e32 v116, 0xbfb8aa3b, v145
	v_exp_f32_e32 v117, v116
	v_rcp_f32_e32 v116, v111
	v_add_f32_e32 v111, 1.0, v115
	v_rcp_f32_e32 v115, v111
	v_add_f32_e32 v111, 1.0, v117
	v_rcp_f32_e32 v117, v111
	v_mov_b32_e32 v118, v142
	v_mov_b32_e32 v119, v144
	v_pk_mul_f32 v[114:115], v[118:119], v[114:115]
	v_mov_b32_e32 v118, v138
	v_mov_b32_e32 v119, v140
	v_mov_b32_e32 v144, v143
	v_pk_mul_f32 v[114:115], v[118:119], v[114:115]
	v_pk_mul_f32 v[116:117], v[144:145], v[116:117]
	v_mov_b32_e32 v140, v139
	v_pk_mul_f32 v[116:117], v[140:141], v[116:117]
	v_and_b32_sdwa v111, v115, v177 dst_sel:DWORD dst_unused:UNUSED_PAD src0_sel:WORD_1 src1_sel:DWORD
	v_and_b32_sdwa v118, v114, v177 dst_sel:DWORD dst_unused:UNUSED_PAD src0_sel:WORD_1 src1_sel:DWORD
	v_add3_u32 v111, v115, v111, s28
	v_and_b32_sdwa v115, v117, v177 dst_sel:DWORD dst_unused:UNUSED_PAD src0_sel:WORD_1 src1_sel:DWORD
	v_add3_u32 v114, v114, v118, s28
	v_and_b32_sdwa v118, v116, v177 dst_sel:DWORD dst_unused:UNUSED_PAD src0_sel:WORD_1 src1_sel:DWORD
	v_add3_u32 v115, v117, v115, s28
	v_add3_u32 v116, v116, v118, s28
	v_and_b32_e32 v115, 0xffff0000, v115
	v_and_b32_e32 v116, 0xffff0000, v116
	v_or_b32_sdwa v115, v115, v111 dst_sel:DWORD dst_unused:UNUSED_PAD src0_sel:DWORD src1_sel:WORD_1
	v_mul_f32_e32 v111, 0xbfb8aa3b, v102
	v_or_b32_sdwa v114, v116, v114 dst_sel:DWORD dst_unused:UNUSED_PAD src0_sel:DWORD src1_sel:WORD_1
	v_exp_f32_e32 v111, v111
	v_mul_f32_e32 v116, 0xbfb8aa3b, v103
	v_exp_f32_e32 v116, v116
	global_store_dwordx2 v[112:113], v[114:115], off offset:64
	v_add_f32_e32 v111, 1.0, v111
	v_mul_f32_e32 v115, 0xbfb8aa3b, v104
	v_rcp_f32_e32 v114, v111
	v_add_f32_e32 v111, 1.0, v116
	v_exp_f32_e32 v115, v115
	v_mul_f32_e32 v116, 0xbfb8aa3b, v105
	v_exp_f32_e32 v117, v116
	v_rcp_f32_e32 v116, v111
	v_add_f32_e32 v111, 1.0, v115
	v_rcp_f32_e32 v115, v111
	v_add_f32_e32 v111, 1.0, v117
	v_rcp_f32_e32 v117, v111
	v_mov_b32_e32 v118, v102
	v_mov_b32_e32 v119, v104
	v_mov_b32_e32 v104, v103
	v_pk_mul_f32 v[114:115], v[118:119], v[114:115]
	v_mov_b32_e32 v119, v100
	v_pk_mul_f32 v[102:103], v[104:105], v[116:117]
	v_mov_b32_e32 v100, v99
	v_mov_b32_e32 v118, v98
	v_pk_mul_f32 v[98:99], v[100:101], v[102:103]
	v_pk_mul_f32 v[114:115], v[118:119], v[114:115]
	v_and_b32_sdwa v102, v99, v177 dst_sel:DWORD dst_unused:UNUSED_PAD src0_sel:WORD_1 src1_sel:DWORD
	v_and_b32_sdwa v103, v98, v177 dst_sel:DWORD dst_unused:UNUSED_PAD src0_sel:WORD_1 src1_sel:DWORD
	v_and_b32_sdwa v100, v115, v177 dst_sel:DWORD dst_unused:UNUSED_PAD src0_sel:WORD_1 src1_sel:DWORD
	v_and_b32_sdwa v101, v114, v177 dst_sel:DWORD dst_unused:UNUSED_PAD src0_sel:WORD_1 src1_sel:DWORD
	v_add3_u32 v99, v99, v102, s28
	v_add3_u32 v98, v98, v103, s28
	v_add3_u32 v101, v114, v101, s28
	v_add3_u32 v100, v115, v100, s28
	v_and_b32_e32 v99, 0xffff0000, v99
	v_and_b32_e32 v98, 0xffff0000, v98
	v_or_b32_sdwa v99, v99, v100 dst_sel:DWORD dst_unused:UNUSED_PAD src0_sel:DWORD src1_sel:WORD_1
	v_or_b32_sdwa v98, v98, v101 dst_sel:DWORD dst_unused:UNUSED_PAD src0_sel:DWORD src1_sel:WORD_1
	global_store_dwordx2 v[112:113], v[98:99], off offset:96
	v_mul_f32_e32 v99, 0xbfb8aa3b, v94
	v_exp_f32_e32 v100, v99
	v_mul_f32_e32 v99, 0xbfb8aa3b, v95
	v_mul_f32_e32 v102, 0xbfb8aa3b, v96
	v_exp_f32_e32 v101, v99
	v_exp_f32_e32 v103, v102
	v_mul_f32_e32 v102, 0xbfb8aa3b, v97
	v_exp_f32_e32 v104, v102
	v_add_f32_e32 v101, 1.0, v101
	v_add_f32_e32 v100, 1.0, v100
	v_rcp_f32_e32 v102, v101
	v_add_f32_e32 v101, 1.0, v103
	v_add_f32_e32 v103, 1.0, v104
	v_rcp_f32_e32 v100, v100
	v_rcp_f32_e32 v101, v101
	v_rcp_f32_e32 v103, v103
	v_mov_b32_e32 v104, v94
	v_mov_b32_e32 v105, v96
	v_mov_b32_e32 v96, v95
	v_pk_mul_f32 v[100:101], v[104:105], v[100:101]
	v_mov_b32_e32 v105, v92
	v_pk_mul_f32 v[94:95], v[96:97], v[102:103]
	v_mov_b32_e32 v92, v91
	v_mov_b32_e32 v104, v90
	v_pk_mul_f32 v[90:91], v[92:93], v[94:95]
	v_pk_mul_f32 v[100:101], v[104:105], v[100:101]
	v_and_b32_sdwa v94, v91, v177 dst_sel:DWORD dst_unused:UNUSED_PAD src0_sel:WORD_1 src1_sel:DWORD
	v_and_b32_sdwa v92, v101, v177 dst_sel:DWORD dst_unused:UNUSED_PAD src0_sel:WORD_1 src1_sel:DWORD
	v_and_b32_sdwa v95, v90, v177 dst_sel:DWORD dst_unused:UNUSED_PAD src0_sel:WORD_1 src1_sel:DWORD
	v_add3_u32 v91, v91, v94, s28
	v_and_b32_sdwa v93, v100, v177 dst_sel:DWORD dst_unused:UNUSED_PAD src0_sel:WORD_1 src1_sel:DWORD
	v_add3_u32 v92, v101, v92, s28
	v_add3_u32 v90, v90, v95, s28
	v_and_b32_e32 v91, 0xffff0000, v91
	v_add3_u32 v93, v100, v93, s28
	v_and_b32_e32 v90, 0xffff0000, v90
	v_or_b32_sdwa v91, v91, v92 dst_sel:DWORD dst_unused:UNUSED_PAD src0_sel:DWORD src1_sel:WORD_1
	v_mul_f32_e32 v92, 0xbfb8aa3b, v86
	v_or_b32_sdwa v90, v90, v93 dst_sel:DWORD dst_unused:UNUSED_PAD src0_sel:DWORD src1_sel:WORD_1
	v_exp_f32_e32 v92, v92
	v_mul_f32_e32 v93, 0xbfb8aa3b, v87
	v_or_b32_e32 v98, 16, v110
	v_exp_f32_e32 v93, v93
	v_mad_i64_i32 v[98:99], s[6:7], v98, s52, v[106:107]
	v_lshl_add_u64 v[98:99], v[98:99], 0, v[108:109]
	global_store_dwordx2 v[98:99], v[90:91], off
	v_add_f32_e32 v90, 1.0, v92
	v_mul_f32_e32 v92, 0xbfb8aa3b, v88
	v_add_f32_e32 v91, 1.0, v93
	v_exp_f32_e32 v93, v92
	v_mul_f32_e32 v92, 0xbfb8aa3b, v89
	v_exp_f32_e32 v94, v92
	v_rcp_f32_e32 v92, v91
	v_add_f32_e32 v91, 1.0, v93
	v_rcp_f32_e32 v90, v90
	v_add_f32_e32 v93, 1.0, v94
	v_rcp_f32_e32 v91, v91
	v_rcp_f32_e32 v93, v93
	v_mov_b32_e32 v94, v86
	v_mov_b32_e32 v95, v88
	v_mov_b32_e32 v88, v87
	v_pk_mul_f32 v[90:91], v[94:95], v[90:91]
	v_mov_b32_e32 v95, v84
	v_pk_mul_f32 v[86:87], v[88:89], v[92:93]
	v_mov_b32_e32 v84, v83
	v_mov_b32_e32 v94, v82
	v_pk_mul_f32 v[82:83], v[84:85], v[86:87]
	v_pk_mul_f32 v[90:91], v[94:95], v[90:91]
	v_and_b32_sdwa v86, v83, v177 dst_sel:DWORD dst_unused:UNUSED_PAD src0_sel:WORD_1 src1_sel:DWORD
	v_and_b32_sdwa v84, v91, v177 dst_sel:DWORD dst_unused:UNUSED_PAD src0_sel:WORD_1 src1_sel:DWORD
	v_and_b32_sdwa v87, v82, v177 dst_sel:DWORD dst_unused:UNUSED_PAD src0_sel:WORD_1 src1_sel:DWORD
	v_add3_u32 v83, v83, v86, s28
	v_and_b32_sdwa v85, v90, v177 dst_sel:DWORD dst_unused:UNUSED_PAD src0_sel:WORD_1 src1_sel:DWORD
	v_add3_u32 v84, v91, v84, s28
	v_add3_u32 v82, v82, v87, s28
	v_and_b32_e32 v83, 0xffff0000, v83
	v_add3_u32 v85, v90, v85, s28
	v_and_b32_e32 v82, 0xffff0000, v82
	v_or_b32_sdwa v83, v83, v84 dst_sel:DWORD dst_unused:UNUSED_PAD src0_sel:DWORD src1_sel:WORD_1
	v_mul_f32_e32 v84, 0xbfb8aa3b, v78
	v_or_b32_sdwa v82, v82, v85 dst_sel:DWORD dst_unused:UNUSED_PAD src0_sel:DWORD src1_sel:WORD_1
	v_exp_f32_e32 v84, v84
	v_mul_f32_e32 v85, 0xbfb8aa3b, v79
	v_exp_f32_e32 v85, v85
	global_store_dwordx2 v[98:99], v[82:83], off offset:32
	v_add_f32_e32 v82, 1.0, v84
	v_mul_f32_e32 v84, 0xbfb8aa3b, v80
	v_add_f32_e32 v83, 1.0, v85
	v_exp_f32_e32 v85, v84
	v_mul_f32_e32 v84, 0xbfb8aa3b, v81
	v_exp_f32_e32 v86, v84
	v_rcp_f32_e32 v84, v83
	v_add_f32_e32 v83, 1.0, v85
	v_rcp_f32_e32 v82, v82
	v_add_f32_e32 v85, 1.0, v86
	v_rcp_f32_e32 v83, v83
	v_rcp_f32_e32 v85, v85
	v_mov_b32_e32 v86, v78
	v_mov_b32_e32 v87, v80
	v_mov_b32_e32 v80, v79
	v_pk_mul_f32 v[82:83], v[86:87], v[82:83]
	v_mov_b32_e32 v87, v76
	v_pk_mul_f32 v[78:79], v[80:81], v[84:85]
	v_mov_b32_e32 v76, v75
	v_mov_b32_e32 v86, v74
	v_pk_mul_f32 v[74:75], v[76:77], v[78:79]
	v_pk_mul_f32 v[82:83], v[86:87], v[82:83]
	v_and_b32_sdwa v78, v75, v177 dst_sel:DWORD dst_unused:UNUSED_PAD src0_sel:WORD_1 src1_sel:DWORD
	v_and_b32_sdwa v76, v83, v177 dst_sel:DWORD dst_unused:UNUSED_PAD src0_sel:WORD_1 src1_sel:DWORD
	v_and_b32_sdwa v79, v74, v177 dst_sel:DWORD dst_unused:UNUSED_PAD src0_sel:WORD_1 src1_sel:DWORD
	v_add3_u32 v75, v75, v78, s28
	v_and_b32_sdwa v77, v82, v177 dst_sel:DWORD dst_unused:UNUSED_PAD src0_sel:WORD_1 src1_sel:DWORD
	v_add3_u32 v76, v83, v76, s28
	v_add3_u32 v74, v74, v79, s28
	v_and_b32_e32 v75, 0xffff0000, v75
	v_add3_u32 v77, v82, v77, s28
	v_and_b32_e32 v74, 0xffff0000, v74
	v_or_b32_sdwa v75, v75, v76 dst_sel:DWORD dst_unused:UNUSED_PAD src0_sel:DWORD src1_sel:WORD_1
	v_mul_f32_e32 v76, 0xbfb8aa3b, v70
	v_or_b32_sdwa v74, v74, v77 dst_sel:DWORD dst_unused:UNUSED_PAD src0_sel:DWORD src1_sel:WORD_1
	v_exp_f32_e32 v76, v76
	v_mul_f32_e32 v77, 0xbfb8aa3b, v71
	v_exp_f32_e32 v77, v77
	global_store_dwordx2 v[98:99], v[74:75], off offset:64
	v_add_f32_e32 v74, 1.0, v76
	v_mul_f32_e32 v76, 0xbfb8aa3b, v72
	v_add_f32_e32 v75, 1.0, v77
	v_exp_f32_e32 v77, v76
	v_mul_f32_e32 v76, 0xbfb8aa3b, v73
	v_exp_f32_e32 v78, v76
	v_rcp_f32_e32 v76, v75
	v_add_f32_e32 v75, 1.0, v77
	v_rcp_f32_e32 v74, v74
	v_add_f32_e32 v77, 1.0, v78
	v_rcp_f32_e32 v75, v75
	v_rcp_f32_e32 v77, v77
	v_mov_b32_e32 v78, v70
	v_mov_b32_e32 v79, v72
	v_mov_b32_e32 v72, v71
	v_pk_mul_f32 v[74:75], v[78:79], v[74:75]
	v_mov_b32_e32 v79, v68
	v_pk_mul_f32 v[70:71], v[72:73], v[76:77]
	v_mov_b32_e32 v68, v67
	v_mov_b32_e32 v78, v66
	v_pk_mul_f32 v[66:67], v[68:69], v[70:71]
	v_pk_mul_f32 v[74:75], v[78:79], v[74:75]
	v_and_b32_sdwa v70, v67, v177 dst_sel:DWORD dst_unused:UNUSED_PAD src0_sel:WORD_1 src1_sel:DWORD
	v_and_b32_sdwa v71, v66, v177 dst_sel:DWORD dst_unused:UNUSED_PAD src0_sel:WORD_1 src1_sel:DWORD
	v_and_b32_sdwa v68, v75, v177 dst_sel:DWORD dst_unused:UNUSED_PAD src0_sel:WORD_1 src1_sel:DWORD
	v_and_b32_sdwa v69, v74, v177 dst_sel:DWORD dst_unused:UNUSED_PAD src0_sel:WORD_1 src1_sel:DWORD
	v_add3_u32 v67, v67, v70, s28
	v_add3_u32 v66, v66, v71, s28
	v_add3_u32 v69, v74, v69, s28
	v_add3_u32 v68, v75, v68, s28
	v_and_b32_e32 v67, 0xffff0000, v67
	v_and_b32_e32 v66, 0xffff0000, v66
	v_or_b32_sdwa v67, v67, v68 dst_sel:DWORD dst_unused:UNUSED_PAD src0_sel:DWORD src1_sel:WORD_1
	v_or_b32_sdwa v66, v66, v69 dst_sel:DWORD dst_unused:UNUSED_PAD src0_sel:DWORD src1_sel:WORD_1
	global_store_dwordx2 v[98:99], v[66:67], off offset:96
	v_mul_f32_e32 v67, 0xbfb8aa3b, v62
	v_exp_f32_e32 v68, v67
	v_mul_f32_e32 v67, 0xbfb8aa3b, v63
	v_mul_f32_e32 v70, 0xbfb8aa3b, v64
	v_exp_f32_e32 v69, v67
	v_exp_f32_e32 v71, v70
	v_mul_f32_e32 v70, 0xbfb8aa3b, v65
	v_exp_f32_e32 v72, v70
	v_add_f32_e32 v69, 1.0, v69
	v_add_f32_e32 v68, 1.0, v68
	v_rcp_f32_e32 v70, v69
	v_add_f32_e32 v69, 1.0, v71
	v_add_f32_e32 v71, 1.0, v72
	v_rcp_f32_e32 v68, v68
	v_rcp_f32_e32 v69, v69
	v_rcp_f32_e32 v71, v71
	v_mov_b32_e32 v72, v62
	v_mov_b32_e32 v73, v64
	v_mov_b32_e32 v64, v63
	v_pk_mul_f32 v[68:69], v[72:73], v[68:69]
	v_mov_b32_e32 v73, v60
	v_pk_mul_f32 v[62:63], v[64:65], v[70:71]
	v_mov_b32_e32 v60, v59
	v_mov_b32_e32 v72, v58
	v_pk_mul_f32 v[58:59], v[60:61], v[62:63]
	v_pk_mul_f32 v[68:69], v[72:73], v[68:69]
	v_and_b32_sdwa v62, v59, v177 dst_sel:DWORD dst_unused:UNUSED_PAD src0_sel:WORD_1 src1_sel:DWORD
	v_and_b32_sdwa v60, v69, v177 dst_sel:DWORD dst_unused:UNUSED_PAD src0_sel:WORD_1 src1_sel:DWORD
	v_and_b32_sdwa v63, v58, v177 dst_sel:DWORD dst_unused:UNUSED_PAD src0_sel:WORD_1 src1_sel:DWORD
	v_add3_u32 v59, v59, v62, s28
	v_and_b32_sdwa v61, v68, v177 dst_sel:DWORD dst_unused:UNUSED_PAD src0_sel:WORD_1 src1_sel:DWORD
	v_add3_u32 v60, v69, v60, s28
	v_add3_u32 v58, v58, v63, s28
	v_and_b32_e32 v59, 0xffff0000, v59
	v_add3_u32 v61, v68, v61, s28
	v_and_b32_e32 v58, 0xffff0000, v58
	v_or_b32_sdwa v59, v59, v60 dst_sel:DWORD dst_unused:UNUSED_PAD src0_sel:DWORD src1_sel:WORD_1
	v_mul_f32_e32 v60, 0xbfb8aa3b, v54
	v_or_b32_sdwa v58, v58, v61 dst_sel:DWORD dst_unused:UNUSED_PAD src0_sel:DWORD src1_sel:WORD_1
	v_exp_f32_e32 v60, v60
	v_mul_f32_e32 v61, 0xbfb8aa3b, v55
	v_or_b32_e32 v66, 32, v110
	v_exp_f32_e32 v61, v61
	v_mad_i64_i32 v[66:67], s[6:7], v66, s52, v[106:107]
	v_lshl_add_u64 v[66:67], v[66:67], 0, v[108:109]
	global_store_dwordx2 v[66:67], v[58:59], off
	v_add_f32_e32 v58, 1.0, v60
	v_mul_f32_e32 v60, 0xbfb8aa3b, v56
	v_add_f32_e32 v59, 1.0, v61
	v_exp_f32_e32 v61, v60
	v_mul_f32_e32 v60, 0xbfb8aa3b, v57
	v_exp_f32_e32 v62, v60
	v_rcp_f32_e32 v60, v59
	v_add_f32_e32 v59, 1.0, v61
	v_rcp_f32_e32 v58, v58
	v_add_f32_e32 v61, 1.0, v62
	v_rcp_f32_e32 v59, v59
	v_rcp_f32_e32 v61, v61
	v_mov_b32_e32 v62, v54
	v_mov_b32_e32 v63, v56
	v_mov_b32_e32 v56, v55
	v_pk_mul_f32 v[58:59], v[62:63], v[58:59]
	v_mov_b32_e32 v63, v52
	v_pk_mul_f32 v[54:55], v[56:57], v[60:61]
	v_mov_b32_e32 v52, v51
	v_mov_b32_e32 v62, v50
	v_pk_mul_f32 v[50:51], v[52:53], v[54:55]
	v_pk_mul_f32 v[58:59], v[62:63], v[58:59]
	v_and_b32_sdwa v54, v51, v177 dst_sel:DWORD dst_unused:UNUSED_PAD src0_sel:WORD_1 src1_sel:DWORD
	v_and_b32_sdwa v52, v59, v177 dst_sel:DWORD dst_unused:UNUSED_PAD src0_sel:WORD_1 src1_sel:DWORD
	v_and_b32_sdwa v55, v50, v177 dst_sel:DWORD dst_unused:UNUSED_PAD src0_sel:WORD_1 src1_sel:DWORD
	v_add3_u32 v51, v51, v54, s28
	v_and_b32_sdwa v53, v58, v177 dst_sel:DWORD dst_unused:UNUSED_PAD src0_sel:WORD_1 src1_sel:DWORD
	v_add3_u32 v52, v59, v52, s28
	v_add3_u32 v50, v50, v55, s28
	v_and_b32_e32 v51, 0xffff0000, v51
	v_add3_u32 v53, v58, v53, s28
	v_and_b32_e32 v50, 0xffff0000, v50
	v_or_b32_sdwa v51, v51, v52 dst_sel:DWORD dst_unused:UNUSED_PAD src0_sel:DWORD src1_sel:WORD_1
	v_mul_f32_e32 v52, 0xbfb8aa3b, v46
	v_or_b32_sdwa v50, v50, v53 dst_sel:DWORD dst_unused:UNUSED_PAD src0_sel:DWORD src1_sel:WORD_1
	v_exp_f32_e32 v52, v52
	v_mul_f32_e32 v53, 0xbfb8aa3b, v47
	v_exp_f32_e32 v53, v53
	global_store_dwordx2 v[66:67], v[50:51], off offset:32
	v_add_f32_e32 v50, 1.0, v52
	v_mul_f32_e32 v52, 0xbfb8aa3b, v48
	v_add_f32_e32 v51, 1.0, v53
	v_exp_f32_e32 v53, v52
	v_mul_f32_e32 v52, 0xbfb8aa3b, v49
	v_exp_f32_e32 v54, v52
	v_rcp_f32_e32 v52, v51
	v_add_f32_e32 v51, 1.0, v53
	v_rcp_f32_e32 v50, v50
	v_add_f32_e32 v53, 1.0, v54
	v_rcp_f32_e32 v51, v51
	v_rcp_f32_e32 v53, v53
	v_mov_b32_e32 v54, v46
	v_mov_b32_e32 v55, v48
	v_mov_b32_e32 v48, v47
	v_pk_mul_f32 v[50:51], v[54:55], v[50:51]
	v_mov_b32_e32 v55, v44
	v_pk_mul_f32 v[46:47], v[48:49], v[52:53]
	v_mov_b32_e32 v44, v43
	v_mov_b32_e32 v54, v42
	v_pk_mul_f32 v[42:43], v[44:45], v[46:47]
	v_pk_mul_f32 v[50:51], v[54:55], v[50:51]
	v_and_b32_sdwa v46, v43, v177 dst_sel:DWORD dst_unused:UNUSED_PAD src0_sel:WORD_1 src1_sel:DWORD
	v_and_b32_sdwa v44, v51, v177 dst_sel:DWORD dst_unused:UNUSED_PAD src0_sel:WORD_1 src1_sel:DWORD
	v_and_b32_sdwa v47, v42, v177 dst_sel:DWORD dst_unused:UNUSED_PAD src0_sel:WORD_1 src1_sel:DWORD
	v_add3_u32 v43, v43, v46, s28
	v_and_b32_sdwa v45, v50, v177 dst_sel:DWORD dst_unused:UNUSED_PAD src0_sel:WORD_1 src1_sel:DWORD
	v_add3_u32 v44, v51, v44, s28
	v_add3_u32 v42, v42, v47, s28
	v_and_b32_e32 v43, 0xffff0000, v43
	v_add3_u32 v45, v50, v45, s28
	v_and_b32_e32 v42, 0xffff0000, v42
	v_or_b32_sdwa v43, v43, v44 dst_sel:DWORD dst_unused:UNUSED_PAD src0_sel:DWORD src1_sel:WORD_1
	v_mul_f32_e32 v44, 0xbfb8aa3b, v38
	v_or_b32_sdwa v42, v42, v45 dst_sel:DWORD dst_unused:UNUSED_PAD src0_sel:DWORD src1_sel:WORD_1
	v_exp_f32_e32 v44, v44
	v_mul_f32_e32 v45, 0xbfb8aa3b, v39
	v_exp_f32_e32 v45, v45
	global_store_dwordx2 v[66:67], v[42:43], off offset:64
	v_add_f32_e32 v42, 1.0, v44
	v_mul_f32_e32 v44, 0xbfb8aa3b, v40
	v_add_f32_e32 v43, 1.0, v45
	v_exp_f32_e32 v45, v44
	v_mul_f32_e32 v44, 0xbfb8aa3b, v41
	v_exp_f32_e32 v46, v44
	v_rcp_f32_e32 v44, v43
	v_add_f32_e32 v43, 1.0, v45
	v_rcp_f32_e32 v42, v42
	v_add_f32_e32 v45, 1.0, v46
	v_rcp_f32_e32 v43, v43
	v_rcp_f32_e32 v45, v45
	v_mov_b32_e32 v46, v38
	v_mov_b32_e32 v47, v40
	v_mov_b32_e32 v40, v39
	v_pk_mul_f32 v[42:43], v[46:47], v[42:43]
	v_mov_b32_e32 v47, v36
	v_pk_mul_f32 v[38:39], v[40:41], v[44:45]
	v_mov_b32_e32 v36, v35
	v_mov_b32_e32 v46, v34
	v_pk_mul_f32 v[34:35], v[36:37], v[38:39]
	v_pk_mul_f32 v[42:43], v[46:47], v[42:43]
	v_and_b32_sdwa v38, v35, v177 dst_sel:DWORD dst_unused:UNUSED_PAD src0_sel:WORD_1 src1_sel:DWORD
	v_and_b32_sdwa v39, v34, v177 dst_sel:DWORD dst_unused:UNUSED_PAD src0_sel:WORD_1 src1_sel:DWORD
	v_and_b32_sdwa v36, v43, v177 dst_sel:DWORD dst_unused:UNUSED_PAD src0_sel:WORD_1 src1_sel:DWORD
	v_and_b32_sdwa v37, v42, v177 dst_sel:DWORD dst_unused:UNUSED_PAD src0_sel:WORD_1 src1_sel:DWORD
	v_add3_u32 v35, v35, v38, s28
	v_add3_u32 v34, v34, v39, s28
	v_add3_u32 v37, v42, v37, s28
	v_add3_u32 v36, v43, v36, s28
	v_and_b32_e32 v35, 0xffff0000, v35
	v_and_b32_e32 v34, 0xffff0000, v34
	v_or_b32_sdwa v35, v35, v36 dst_sel:DWORD dst_unused:UNUSED_PAD src0_sel:DWORD src1_sel:WORD_1
	v_or_b32_sdwa v34, v34, v37 dst_sel:DWORD dst_unused:UNUSED_PAD src0_sel:DWORD src1_sel:WORD_1
	global_store_dwordx2 v[66:67], v[34:35], off offset:96
	v_mul_f32_e32 v35, 0xbfb8aa3b, v30
	v_exp_f32_e32 v36, v35
	v_mul_f32_e32 v35, 0xbfb8aa3b, v31
	v_mul_f32_e32 v38, 0xbfb8aa3b, v32
	v_exp_f32_e32 v37, v35
	v_exp_f32_e32 v39, v38
	v_mul_f32_e32 v38, 0xbfb8aa3b, v33
	v_exp_f32_e32 v40, v38
	v_add_f32_e32 v37, 1.0, v37
	v_add_f32_e32 v36, 1.0, v36
	v_rcp_f32_e32 v38, v37
	v_add_f32_e32 v37, 1.0, v39
	v_add_f32_e32 v39, 1.0, v40
	v_rcp_f32_e32 v36, v36
	v_rcp_f32_e32 v37, v37
	v_rcp_f32_e32 v39, v39
	v_mov_b32_e32 v40, v30
	v_mov_b32_e32 v41, v32
	v_mov_b32_e32 v32, v31
	v_pk_mul_f32 v[36:37], v[40:41], v[36:37]
	v_mov_b32_e32 v41, v28
	v_pk_mul_f32 v[30:31], v[32:33], v[38:39]
	v_mov_b32_e32 v28, v27
	v_mov_b32_e32 v40, v26
	v_pk_mul_f32 v[26:27], v[28:29], v[30:31]
	v_pk_mul_f32 v[36:37], v[40:41], v[36:37]
	v_and_b32_sdwa v30, v27, v177 dst_sel:DWORD dst_unused:UNUSED_PAD src0_sel:WORD_1 src1_sel:DWORD
	v_and_b32_sdwa v28, v37, v177 dst_sel:DWORD dst_unused:UNUSED_PAD src0_sel:WORD_1 src1_sel:DWORD
	v_and_b32_sdwa v31, v26, v177 dst_sel:DWORD dst_unused:UNUSED_PAD src0_sel:WORD_1 src1_sel:DWORD
	v_add3_u32 v27, v27, v30, s28
	v_and_b32_sdwa v29, v36, v177 dst_sel:DWORD dst_unused:UNUSED_PAD src0_sel:WORD_1 src1_sel:DWORD
	v_add3_u32 v28, v37, v28, s28
	v_add3_u32 v26, v26, v31, s28
	v_and_b32_e32 v27, 0xffff0000, v27
	v_add3_u32 v29, v36, v29, s28
	v_and_b32_e32 v26, 0xffff0000, v26
	v_or_b32_sdwa v27, v27, v28 dst_sel:DWORD dst_unused:UNUSED_PAD src0_sel:DWORD src1_sel:WORD_1
	v_mul_f32_e32 v28, 0xbfb8aa3b, v22
	v_or_b32_sdwa v26, v26, v29 dst_sel:DWORD dst_unused:UNUSED_PAD src0_sel:DWORD src1_sel:WORD_1
	v_exp_f32_e32 v28, v28
	v_mul_f32_e32 v29, 0xbfb8aa3b, v23
	v_or_b32_e32 v34, 48, v110
	v_exp_f32_e32 v29, v29
	v_mad_i64_i32 v[34:35], s[6:7], v34, s52, v[106:107]
	v_lshl_add_u64 v[34:35], v[34:35], 0, v[108:109]
	global_store_dwordx2 v[34:35], v[26:27], off
	v_add_f32_e32 v26, 1.0, v28
	v_mul_f32_e32 v28, 0xbfb8aa3b, v24
	v_add_f32_e32 v27, 1.0, v29
	v_exp_f32_e32 v29, v28
	v_mul_f32_e32 v28, 0xbfb8aa3b, v25
	v_exp_f32_e32 v30, v28
	v_rcp_f32_e32 v28, v27
	v_add_f32_e32 v27, 1.0, v29
	v_rcp_f32_e32 v26, v26
	v_add_f32_e32 v29, 1.0, v30
	v_rcp_f32_e32 v27, v27
	v_rcp_f32_e32 v29, v29
	v_mov_b32_e32 v30, v22
	v_mov_b32_e32 v31, v24
	v_mov_b32_e32 v24, v23
	v_pk_mul_f32 v[26:27], v[30:31], v[26:27]
	v_mov_b32_e32 v31, v20
	v_pk_mul_f32 v[22:23], v[24:25], v[28:29]
	v_mov_b32_e32 v20, v19
	v_mov_b32_e32 v30, v18
	v_pk_mul_f32 v[18:19], v[20:21], v[22:23]
	v_pk_mul_f32 v[26:27], v[30:31], v[26:27]
	v_and_b32_sdwa v22, v19, v177 dst_sel:DWORD dst_unused:UNUSED_PAD src0_sel:WORD_1 src1_sel:DWORD
	v_and_b32_sdwa v20, v27, v177 dst_sel:DWORD dst_unused:UNUSED_PAD src0_sel:WORD_1 src1_sel:DWORD
	v_and_b32_sdwa v23, v18, v177 dst_sel:DWORD dst_unused:UNUSED_PAD src0_sel:WORD_1 src1_sel:DWORD
	v_add3_u32 v19, v19, v22, s28
	v_and_b32_sdwa v21, v26, v177 dst_sel:DWORD dst_unused:UNUSED_PAD src0_sel:WORD_1 src1_sel:DWORD
	v_add3_u32 v20, v27, v20, s28
	v_add3_u32 v18, v18, v23, s28
	v_and_b32_e32 v19, 0xffff0000, v19
	v_add3_u32 v21, v26, v21, s28
	v_and_b32_e32 v18, 0xffff0000, v18
	v_or_b32_sdwa v19, v19, v20 dst_sel:DWORD dst_unused:UNUSED_PAD src0_sel:DWORD src1_sel:WORD_1
	v_mul_f32_e32 v20, 0xbfb8aa3b, v14
	v_or_b32_sdwa v18, v18, v21 dst_sel:DWORD dst_unused:UNUSED_PAD src0_sel:DWORD src1_sel:WORD_1
	v_exp_f32_e32 v20, v20
	v_mul_f32_e32 v21, 0xbfb8aa3b, v15
	v_exp_f32_e32 v21, v21
	global_store_dwordx2 v[34:35], v[18:19], off offset:32
	v_add_f32_e32 v18, 1.0, v20
	v_mul_f32_e32 v20, 0xbfb8aa3b, v16
	v_add_f32_e32 v19, 1.0, v21
	v_exp_f32_e32 v21, v20
	v_mul_f32_e32 v20, 0xbfb8aa3b, v17
	v_exp_f32_e32 v22, v20
	v_rcp_f32_e32 v20, v19
	v_add_f32_e32 v19, 1.0, v21
	v_rcp_f32_e32 v18, v18
	v_add_f32_e32 v21, 1.0, v22
	v_rcp_f32_e32 v19, v19
	v_rcp_f32_e32 v21, v21
	v_mov_b32_e32 v22, v14
	v_mov_b32_e32 v23, v16
	v_mov_b32_e32 v16, v15
	v_pk_mul_f32 v[18:19], v[22:23], v[18:19]
	v_mov_b32_e32 v23, v12
	v_pk_mul_f32 v[14:15], v[16:17], v[20:21]
	v_mov_b32_e32 v12, v11
	v_mov_b32_e32 v22, v10
	v_pk_mul_f32 v[10:11], v[12:13], v[14:15]
	v_pk_mul_f32 v[18:19], v[22:23], v[18:19]
	v_and_b32_sdwa v14, v11, v177 dst_sel:DWORD dst_unused:UNUSED_PAD src0_sel:WORD_1 src1_sel:DWORD
	v_and_b32_sdwa v12, v19, v177 dst_sel:DWORD dst_unused:UNUSED_PAD src0_sel:WORD_1 src1_sel:DWORD
	v_and_b32_sdwa v15, v10, v177 dst_sel:DWORD dst_unused:UNUSED_PAD src0_sel:WORD_1 src1_sel:DWORD
	v_add3_u32 v11, v11, v14, s28
	v_and_b32_sdwa v13, v18, v177 dst_sel:DWORD dst_unused:UNUSED_PAD src0_sel:WORD_1 src1_sel:DWORD
	v_add3_u32 v12, v19, v12, s28
	v_add3_u32 v10, v10, v15, s28
	v_and_b32_e32 v11, 0xffff0000, v11
	v_add3_u32 v13, v18, v13, s28
	v_and_b32_e32 v10, 0xffff0000, v10
	v_or_b32_sdwa v11, v11, v12 dst_sel:DWORD dst_unused:UNUSED_PAD src0_sel:DWORD src1_sel:WORD_1
	v_mul_f32_e32 v12, 0xbfb8aa3b, v6
	v_or_b32_sdwa v10, v10, v13 dst_sel:DWORD dst_unused:UNUSED_PAD src0_sel:DWORD src1_sel:WORD_1
	v_exp_f32_e32 v12, v12
	v_mul_f32_e32 v13, 0xbfb8aa3b, v7
	v_exp_f32_e32 v13, v13
	global_store_dwordx2 v[34:35], v[10:11], off offset:64
	v_add_f32_e32 v10, 1.0, v12
	v_mul_f32_e32 v12, 0xbfb8aa3b, v8
	v_add_f32_e32 v11, 1.0, v13
	v_exp_f32_e32 v13, v12
	v_mul_f32_e32 v12, 0xbfb8aa3b, v9
	v_exp_f32_e32 v14, v12
	v_rcp_f32_e32 v12, v11
	v_add_f32_e32 v11, 1.0, v13
	v_rcp_f32_e32 v10, v10
	v_add_f32_e32 v13, 1.0, v14
	v_rcp_f32_e32 v11, v11
	v_rcp_f32_e32 v13, v13
	v_mov_b32_e32 v14, v6
	v_mov_b32_e32 v15, v8
	v_mov_b32_e32 v8, v7
	v_pk_mul_f32 v[10:11], v[14:15], v[10:11]
	v_mov_b32_e32 v15, v4
	v_pk_mul_f32 v[6:7], v[8:9], v[12:13]
	v_mov_b32_e32 v4, v3
	v_mov_b32_e32 v14, v2
	v_pk_mul_f32 v[2:3], v[4:5], v[6:7]
	v_pk_mul_f32 v[10:11], v[14:15], v[10:11]
	v_and_b32_sdwa v6, v3, v177 dst_sel:DWORD dst_unused:UNUSED_PAD src0_sel:WORD_1 src1_sel:DWORD
	v_and_b32_sdwa v7, v2, v177 dst_sel:DWORD dst_unused:UNUSED_PAD src0_sel:WORD_1 src1_sel:DWORD
	v_and_b32_sdwa v4, v11, v177 dst_sel:DWORD dst_unused:UNUSED_PAD src0_sel:WORD_1 src1_sel:DWORD
	v_and_b32_sdwa v5, v10, v177 dst_sel:DWORD dst_unused:UNUSED_PAD src0_sel:WORD_1 src1_sel:DWORD
	v_add3_u32 v3, v3, v6, s28
	v_add3_u32 v2, v2, v7, s28
	v_add3_u32 v5, v10, v5, s28
	v_add3_u32 v4, v11, v4, s28
	v_and_b32_e32 v3, 0xffff0000, v3
	v_and_b32_e32 v2, 0xffff0000, v2
	s_add_i32 s20, s20, s11
	v_or_b32_sdwa v3, v3, v4 dst_sel:DWORD dst_unused:UNUSED_PAD src0_sel:DWORD src1_sel:WORD_1
	v_or_b32_sdwa v2, v2, v5 dst_sel:DWORD dst_unused:UNUSED_PAD src0_sel:DWORD src1_sel:WORD_1
	s_cmpk_gt_i32 s20, 0x5ff
	global_store_dwordx2 v[34:35], v[2:3], off offset:96
	s_cbranch_scc0 .LBB0_465

.LBB0_531:
	s_lshl_b64 s[2:3], s[12:13], 2
	s_add_u32 s4, s14, s2
	v_writelane_b32 v255, s2, 48
	s_addc_u32 s6, s15, s3
	s_add_u32 s12, s4, 0x5602000
	s_addc_u32 s13, s6, 0
	s_load_dwordx2 s[48:49], s[18:19], 0x128
	s_add_u32 s18, s14, 0x6035800
	s_addc_u32 s19, s15, 0
	s_add_u32 s50, s14, 0x1600000
	s_addc_u32 s51, s15, 0
	v_mov_b32_e32 v2, v172
	s_mov_b32 s10, s42
	s_mov_b32 s11, s94
	v_writelane_b32 v255, s3, 49
	s_cmpk_gt_i32 s11, 0xff
	s_cbranch_scc1 .LBB0_536
	v_ashrrev_i32_e32 v204, 3, v2
	v_and_b32_e32 v205, 15, v2
	v_bfe_u32 v3, v2, 4, 2
	v_lshlrev_b32_e32 v0, 4, v2
	v_ashrrev_i32_e32 v4, 1, v2
	v_lshlrev_b32_e32 v2, 1, v2
	v_and_b32_e32 v0, 0x70, v0
	v_and_b32_e32 v206, 0xffffffc0, v4
	v_and_b32_e32 v2, 0x80, v2
	s_movk_i32 s2, 0x90
	v_or_b32_e32 v4, v206, v205
	v_or_b32_e32 v5, v2, v205
	v_and_b32_e32 v100, 7, v204
	v_lshlrev_b32_e32 v100, 4, v100
	v_xor_b32_e32 v100, v100, v0
	v_lshl_add_u32 v166, v204, 7, v100
	v_lshl_add_u64 v[162:163], s[18:19], 0, v[0:1]
	v_lshl_add_u64 v[164:165], s[50:51], 0, v[0:1]
	v_and_b32_e32 v100, 7, v205
	v_xor_b32_e32 v100, v100, v3
	v_lshlrev_b32_e32 v207, 4, v100
	v_lshl_or_b32 v208, v3, 2, v2
	v_lshlrev_b32_e32 v0, 7, v4
	v_lshlrev_b32_e32 v167, 7, v5
.LBB0_533:
	s_ashr_i32 s4, s11, 31
	s_lshr_b32 s4, s4, 26
	s_add_i32 s4, s11, s4
	s_and_b32 s6, s4, 0xffffc0
	s_sub_i32 s6, s11, s6
	s_lshl_b32 s7, s6, 8
	v_add_u32_e32 v2, s7, v204
	v_mad_i64_i32 v[168:169], s[20:21], v2, s52, v[162:163]
	v_add_co_u32_e32 v56, vcc, 0x58000, v168
	s_lshl_b32 s4, s4, 2
	s_nop 0
	v_addc_co_u32_e32 v57, vcc, 0, v169, vcc
	v_add_co_u32_e32 v58, vcc, 0xb0000, v168
	s_and_b32 s6, s4, 0xffffff00
	s_nop 0
	v_addc_co_u32_e32 v59, vcc, 0, v169, vcc
	v_add_u32_e32 v2, s6, v204
	v_add_co_u32_e32 v60, vcc, 0x108000, v168
	v_mad_i64_i32 v[170:171], s[20:21], v2, s52, v[164:165]
	s_nop 0
	v_addc_co_u32_e32 v61, vcc, 0, v169, vcc
	v_add_co_u32_e32 v62, vcc, s92, v170
	global_load_dwordx4 v[24:27], v[56:57], off
	global_load_dwordx4 v[28:31], v[58:59], off
	v_addc_co_u32_e32 v63, vcc, 0, v171, vcc
	v_add_co_u32_e32 v64, vcc, s53, v170
	global_load_dwordx4 v[32:35], v[168:169], off
	global_load_dwordx4 v[36:39], v[170:171], off
	v_addc_co_u32_e32 v65, vcc, 0, v171, vcc
	v_add_co_u32_e32 v66, vcc, s8, v170
	global_load_dwordx4 v[40:43], v[60:61], off
	global_load_dwordx4 v[44:47], v[62:63], off
	v_addc_co_u32_e32 v67, vcc, 0, v171, vcc
	global_load_dwordx4 v[48:51], v[64:65], off
	global_load_dwordx4 v[52:55], v[66:67], off
	s_waitcnt lgkmcnt(0)
	s_barrier
	global_load_dwordx4 v[110:113], v[168:169], off offset:128
	global_load_dwordx4 v[102:105], v[56:57], off offset:128
	global_load_dwordx4 v[106:109], v[58:59], off offset:128
	global_load_dwordx4 v[122:125], v[60:61], off offset:128
	global_load_dwordx4 v[118:121], v[170:171], off offset:128
	global_load_dwordx4 v[114:117], v[62:63], off offset:128
	global_load_dwordx4 v[130:133], v[64:65], off offset:128
	global_load_dwordx4 v[126:129], v[66:67], off offset:128
	v_readfirstlane_b32 vcc_lo, v168
	v_readfirstlane_b32 vcc_hi, v169
	v_readfirstlane_b32 s100, v170
	v_readfirstlane_b32 s101, v171
	s_nop 1
	v_subrev_u32_e32 v168, vcc_lo, v168
	v_subrev_u32_e32 v170, s100, v170
	v_mov_b32_e32 v2, 0
	s_mov_b32 s4, 0
	v_mov_b32_e32 v3, v2
	v_mov_b32_e32 v4, v2
	v_mov_b32_e32 v5, v2
	v_mov_b32_e32 v6, v2
	v_mov_b32_e32 v7, v2
	v_mov_b32_e32 v8, v2
	v_mov_b32_e32 v9, v2
	v_mov_b32_e32 v10, v2
	v_mov_b32_e32 v11, v2
	v_mov_b32_e32 v12, v2
	v_mov_b32_e32 v13, v2
	v_mov_b32_e32 v14, v2
	v_mov_b32_e32 v15, v2
	v_mov_b32_e32 v16, v2
	v_mov_b32_e32 v17, v2
	v_mov_b32_e32 v18, v2
	v_mov_b32_e32 v19, v2
	v_mov_b32_e32 v20, v2
	v_mov_b32_e32 v21, v2
	v_mov_b32_e32 v22, v2
	v_mov_b32_e32 v23, v2
	v_mov_b32_e32 v56, v2
	v_mov_b32_e32 v57, v2
	v_mov_b32_e32 v58, v2
	v_mov_b32_e32 v59, v2
	v_mov_b32_e32 v60, v2
	v_mov_b32_e32 v61, v2
	v_mov_b32_e32 v62, v2
	v_mov_b32_e32 v63, v2
	v_mov_b32_e32 v64, v2
	v_mov_b32_e32 v65, v2
	v_mov_b32_e32 v66, v2
	v_mov_b32_e32 v67, v2
	v_mov_b32_e32 v68, v2
	v_mov_b32_e32 v69, v2
	v_mov_b32_e32 v70, v2
	v_mov_b32_e32 v71, v2
	v_mov_b32_e32 v72, v2
	v_mov_b32_e32 v73, v2
	v_mov_b32_e32 v74, v2
	v_mov_b32_e32 v75, v2
	v_mov_b32_e32 v76, v2
	v_mov_b32_e32 v77, v2
	v_mov_b32_e32 v78, v2
	v_mov_b32_e32 v79, v2
	v_mov_b32_e32 v80, v2
	v_mov_b32_e32 v81, v2
	v_mov_b32_e32 v82, v2
	v_mov_b32_e32 v83, v2
	v_mov_b32_e32 v84, v2
	v_mov_b32_e32 v85, v2
	s_waitcnt vmcnt(13)
	ds_write_b128 v166, v[32:35]
	s_waitcnt vmcnt(12)
	ds_write_b128 v166, v[36:39] offset:32768
	ds_write_b128 v166, v[24:27] offset:8192
	ds_write_b128 v166, v[28:31] offset:16384
	s_waitcnt vmcnt(11)
	ds_write_b128 v166, v[40:43] offset:24576
	s_waitcnt vmcnt(10)
	ds_write_b128 v166, v[44:47] offset:40960
	s_waitcnt vmcnt(9)
	ds_write_b128 v166, v[48:51] offset:49152
	s_waitcnt vmcnt(8)
	ds_write_b128 v166, v[52:55] offset:57344
	v_mov_b32_e32 v24, v2
	v_mov_b32_e32 v25, v2
	v_mov_b32_e32 v26, v2
	v_mov_b32_e32 v27, v2
	v_mov_b32_e32 v28, v2
	v_mov_b32_e32 v29, v2
	v_mov_b32_e32 v30, v2
	v_mov_b32_e32 v31, v2
	v_mov_b32_e32 v32, v2
	v_mov_b32_e32 v33, v2
	v_mov_b32_e32 v34, v2
	v_mov_b32_e32 v35, v2
	v_mov_b32_e32 v36, v2
	v_mov_b32_e32 v37, v2
	v_mov_b32_e32 v38, v2
	v_mov_b32_e32 v39, v2
	v_mov_b32_e32 v40, v2
	v_mov_b32_e32 v41, v2
	v_mov_b32_e32 v42, v2
	v_mov_b32_e32 v43, v2
	v_mov_b32_e32 v44, v2
	v_mov_b32_e32 v45, v2
	v_mov_b32_e32 v46, v2
	v_mov_b32_e32 v47, v2
	v_mov_b32_e32 v48, v2
	v_mov_b32_e32 v49, v2
	v_mov_b32_e32 v50, v2
	v_mov_b32_e32 v51, v2
	v_mov_b32_e32 v52, v2
	v_mov_b32_e32 v53, v2
	v_mov_b32_e32 v54, v2
	v_mov_b32_e32 v55, v2
	v_mov_b32_e32 v86, v2
	v_mov_b32_e32 v87, v2
	v_mov_b32_e32 v88, v2
	v_mov_b32_e32 v89, v2
	v_mov_b32_e32 v90, v2
	v_mov_b32_e32 v91, v2
	v_mov_b32_e32 v92, v2
	v_mov_b32_e32 v93, v2
	v_mov_b32_e32 v94, v2
	v_mov_b32_e32 v95, v2
	v_mov_b32_e32 v96, v2
	v_mov_b32_e32 v97, v2
	v_mov_b32_e32 v98, v2
	v_mov_b32_e32 v99, v2
	v_mov_b32_e32 v100, v2
	v_mov_b32_e32 v101, v2
	v_mov_b32_e32 v134, v2
	v_mov_b32_e32 v135, v2
	v_mov_b32_e32 v136, v2
	v_mov_b32_e32 v137, v2
	v_mov_b32_e32 v138, v2
	v_mov_b32_e32 v139, v2
	v_mov_b32_e32 v140, v2
	v_mov_b32_e32 v141, v2
	v_mov_b32_e32 v142, v2
	v_mov_b32_e32 v143, v2
	v_mov_b32_e32 v144, v2
	v_mov_b32_e32 v145, v2
	v_mov_b32_e32 v146, v2
	v_mov_b32_e32 v147, v2
	v_mov_b32_e32 v148, v2
	v_mov_b32_e32 v149, v2
	v_mov_b32_e32 v150, v2
	v_mov_b32_e32 v151, v2
	v_mov_b32_e32 v152, v2
	v_mov_b32_e32 v153, v2
	v_mov_b32_e32 v154, v2
	v_mov_b32_e32 v155, v2
	v_mov_b32_e32 v156, v2
	v_mov_b32_e32 v157, v2
	v_mov_b32_e32 v158, v2
	v_mov_b32_e32 v159, v2
	v_mov_b32_e32 v160, v2
	v_mov_b32_e32 v161, v2
	s_waitcnt lgkmcnt(0)
	s_barrier
.LBB0_534:
	s_bitcmp1_b32 s4, 0
	s_cselect_b32 s21, 0x12000, 0
	v_or_b32_e32 v218, s21, v207
	v_add_u32_e32 v214, v218, v0
	v_add_u32_e32 v246, v218, v167
	ds_read_b128 v[184:187], v214
	ds_read_b128 v[198:201], v214 offset:2048
	ds_read_b128 v[210:213], v214 offset:4096
	ds_read_b128 v[214:217], v214 offset:6144
	ds_read_b128 v[218:221], v246 offset:32768
	ds_read_b128 v[222:225], v246 offset:34816
	ds_read_b128 v[226:229], v246 offset:36864
	ds_read_b128 v[230:233], v246 offset:38912
	ds_read_b128 v[234:237], v246 offset:40960
	ds_read_b128 v[238:241], v246 offset:43008
	ds_read_b128 v[242:245], v246 offset:45056
	ds_read_b128 v[246:249], v246 offset:47104
	s_add_i32 s20, s4, 1
	s_bitcmp1_b32 s20, 0
	s_cselect_b32 s23, 0x12000, 0
	s_waitcnt lgkmcnt(7)
	v_mfma_f32_16x16x32_bf16 v[158:161], v[218:221], v[184:187], v[158:161]
	v_mfma_f32_16x16x32_bf16 v[94:97], v[218:221], v[198:201], v[94:97]
	v_mfma_f32_16x16x32_bf16 v[62:65], v[218:221], v[210:213], v[62:65]
	v_mfma_f32_16x16x32_bf16 v[30:33], v[218:221], v[214:217], v[30:33]
	v_add_u32_e32 v218, s23, v166
	s_waitcnt vmcnt(7)
	ds_write_b128 v218, v[110:113]
	s_waitcnt lgkmcnt(7)
	v_mfma_f32_16x16x32_bf16 v[154:157], v[222:225], v[184:187], v[154:157]
	v_mfma_f32_16x16x32_bf16 v[90:93], v[222:225], v[198:201], v[90:93]
	global_load_dwordx4 v[110:113], v168, vcc offset:256
	v_mfma_f32_16x16x32_bf16 v[58:61], v[222:225], v[210:213], v[58:61]
	v_mfma_f32_16x16x32_bf16 v[26:29], v[222:225], v[214:217], v[26:29]
	s_waitcnt vmcnt(7)
	ds_write_b128 v218, v[102:105] offset:8192
	s_waitcnt lgkmcnt(7)
	v_mfma_f32_16x16x32_bf16 v[150:153], v[226:229], v[184:187], v[150:153]
	v_mfma_f32_16x16x32_bf16 v[86:89], v[226:229], v[198:201], v[86:89]
	v_add_u32_e32 v102, 0x58000, v168
	global_load_dwordx4 v[102:105], v102, vcc offset:256
	v_mfma_f32_16x16x32_bf16 v[54:57], v[226:229], v[210:213], v[54:57]
	v_mfma_f32_16x16x32_bf16 v[22:25], v[226:229], v[214:217], v[22:25]
	s_waitcnt vmcnt(7)
	ds_write_b128 v218, v[106:109] offset:16384
	s_waitcnt lgkmcnt(7)
	v_mfma_f32_16x16x32_bf16 v[146:149], v[230:233], v[184:187], v[146:149]
	v_mfma_f32_16x16x32_bf16 v[82:85], v[230:233], v[198:201], v[82:85]
	v_add_u32_e32 v106, 0xb0000, v168
	global_load_dwordx4 v[106:109], v106, vcc offset:256
	v_mfma_f32_16x16x32_bf16 v[50:53], v[230:233], v[210:213], v[50:53]
	v_mfma_f32_16x16x32_bf16 v[18:21], v[230:233], v[214:217], v[18:21]
	s_waitcnt vmcnt(7)
	ds_write_b128 v218, v[122:125] offset:24576
	s_waitcnt lgkmcnt(7)
	v_mfma_f32_16x16x32_bf16 v[142:145], v[234:237], v[184:187], v[142:145]
	v_mfma_f32_16x16x32_bf16 v[78:81], v[234:237], v[198:201], v[78:81]
	v_add_u32_e32 v122, 0x108000, v168
	global_load_dwordx4 v[122:125], v122, vcc offset:256
	v_mfma_f32_16x16x32_bf16 v[46:49], v[234:237], v[210:213], v[46:49]
	v_mfma_f32_16x16x32_bf16 v[14:17], v[234:237], v[214:217], v[14:17]
	s_waitcnt vmcnt(7)
	ds_write_b128 v218, v[118:121] offset:32768
	s_waitcnt lgkmcnt(7)
	v_mfma_f32_16x16x32_bf16 v[138:141], v[238:241], v[184:187], v[138:141]
	v_mfma_f32_16x16x32_bf16 v[74:77], v[238:241], v[198:201], v[74:77]
	global_load_dwordx4 v[118:121], v170, s[100:101] offset:256
	v_mfma_f32_16x16x32_bf16 v[42:45], v[238:241], v[210:213], v[42:45]
	v_mfma_f32_16x16x32_bf16 v[10:13], v[238:241], v[214:217], v[10:13]
	s_waitcnt vmcnt(7)
	ds_write_b128 v218, v[114:117] offset:40960
	s_waitcnt lgkmcnt(7)
	v_mfma_f32_16x16x32_bf16 v[134:137], v[242:245], v[184:187], v[134:137]
	v_mfma_f32_16x16x32_bf16 v[70:73], v[242:245], v[198:201], v[70:73]
	v_add_u32_e32 v114, 0x58000, v170
	global_load_dwordx4 v[114:117], v114, s[100:101] offset:256
	v_mfma_f32_16x16x32_bf16 v[38:41], v[242:245], v[210:213], v[38:41]
	v_mfma_f32_16x16x32_bf16 v[6:9], v[242:245], v[214:217], v[6:9]
	s_waitcnt vmcnt(7)
	ds_write_b128 v218, v[130:133] offset:49152
	s_waitcnt lgkmcnt(7)
	v_mfma_f32_16x16x32_bf16 v[98:101], v[246:249], v[184:187], v[98:101]
	v_mfma_f32_16x16x32_bf16 v[66:69], v[246:249], v[198:201], v[66:69]
	v_add_u32_e32 v130, 0xb0000, v170
	global_load_dwordx4 v[130:133], v130, s[100:101] offset:256
	v_mfma_f32_16x16x32_bf16 v[34:37], v[246:249], v[210:213], v[34:37]
	v_mfma_f32_16x16x32_bf16 v[2:5], v[246:249], v[214:217], v[2:5]
	s_waitcnt vmcnt(7)
	ds_write_b128 v218, v[126:129] offset:57344
	v_add3_u32 v214, s21, v0, v207
	v_xor_b32_e32 v214, 64, v214
	v_add3_u32 v246, s21, v167, v207
	v_xor_b32_e32 v246, 64, v246
	v_add_u32_e32 v126, 0x108000, v170
	global_load_dwordx4 v[126:129], v126, s[100:101] offset:256
	v_add_u32_e32 v168, 0x80, v168
	v_add_u32_e32 v170, 0x80, v170
	ds_read_b128 v[184:187], v214
	ds_read_b128 v[198:201], v214 offset:2048
	ds_read_b128 v[210:213], v214 offset:4096
	ds_read_b128 v[214:217], v214 offset:6144
	ds_read_b128 v[218:221], v246 offset:32768
	ds_read_b128 v[222:225], v246 offset:34816
	ds_read_b128 v[226:229], v246 offset:36864
	ds_read_b128 v[230:233], v246 offset:38912
	ds_read_b128 v[234:237], v246 offset:40960
	ds_read_b128 v[238:241], v246 offset:43008
	ds_read_b128 v[242:245], v246 offset:45056
	ds_read_b128 v[246:249], v246 offset:47104
	s_waitcnt lgkmcnt(7)
	v_mfma_f32_16x16x32_bf16 v[158:161], v[218:221], v[184:187], v[158:161]
	v_mfma_f32_16x16x32_bf16 v[94:97], v[218:221], v[198:201], v[94:97]
	v_mfma_f32_16x16x32_bf16 v[62:65], v[218:221], v[210:213], v[62:65]
	v_mfma_f32_16x16x32_bf16 v[30:33], v[218:221], v[214:217], v[30:33]
	s_waitcnt lgkmcnt(6)
	v_mfma_f32_16x16x32_bf16 v[154:157], v[222:225], v[184:187], v[154:157]
	v_mfma_f32_16x16x32_bf16 v[90:93], v[222:225], v[198:201], v[90:93]
	v_mfma_f32_16x16x32_bf16 v[58:61], v[222:225], v[210:213], v[58:61]
	v_mfma_f32_16x16x32_bf16 v[26:29], v[222:225], v[214:217], v[26:29]
	s_waitcnt lgkmcnt(5)
	v_mfma_f32_16x16x32_bf16 v[150:153], v[226:229], v[184:187], v[150:153]
	v_mfma_f32_16x16x32_bf16 v[86:89], v[226:229], v[198:201], v[86:89]
	v_mfma_f32_16x16x32_bf16 v[54:57], v[226:229], v[210:213], v[54:57]
	v_mfma_f32_16x16x32_bf16 v[22:25], v[226:229], v[214:217], v[22:25]
	s_waitcnt lgkmcnt(4)
	v_mfma_f32_16x16x32_bf16 v[146:149], v[230:233], v[184:187], v[146:149]
	v_mfma_f32_16x16x32_bf16 v[82:85], v[230:233], v[198:201], v[82:85]
	v_mfma_f32_16x16x32_bf16 v[50:53], v[230:233], v[210:213], v[50:53]
	v_mfma_f32_16x16x32_bf16 v[18:21], v[230:233], v[214:217], v[18:21]
	s_waitcnt lgkmcnt(3)
	v_mfma_f32_16x16x32_bf16 v[142:145], v[234:237], v[184:187], v[142:145]
	v_mfma_f32_16x16x32_bf16 v[78:81], v[234:237], v[198:201], v[78:81]
	v_mfma_f32_16x16x32_bf16 v[46:49], v[234:237], v[210:213], v[46:49]
	v_mfma_f32_16x16x32_bf16 v[14:17], v[234:237], v[214:217], v[14:17]
	s_waitcnt lgkmcnt(2)
	v_mfma_f32_16x16x32_bf16 v[138:141], v[238:241], v[184:187], v[138:141]
	v_mfma_f32_16x16x32_bf16 v[74:77], v[238:241], v[198:201], v[74:77]
	v_mfma_f32_16x16x32_bf16 v[42:45], v[238:241], v[210:213], v[42:45]
	v_mfma_f32_16x16x32_bf16 v[10:13], v[238:241], v[214:217], v[10:13]
	s_waitcnt lgkmcnt(1)
	v_mfma_f32_16x16x32_bf16 v[134:137], v[242:245], v[184:187], v[134:137]
	v_mfma_f32_16x16x32_bf16 v[70:73], v[242:245], v[198:201], v[70:73]
	v_mfma_f32_16x16x32_bf16 v[38:41], v[242:245], v[210:213], v[38:41]
	v_mfma_f32_16x16x32_bf16 v[6:9], v[242:245], v[214:217], v[6:9]
	s_waitcnt lgkmcnt(0)
	v_mfma_f32_16x16x32_bf16 v[98:101], v[246:249], v[184:187], v[98:101]
	v_mfma_f32_16x16x32_bf16 v[66:69], v[246:249], v[198:201], v[66:69]
	v_mfma_f32_16x16x32_bf16 v[34:37], v[246:249], v[210:213], v[34:37]
	v_mfma_f32_16x16x32_bf16 v[2:5], v[246:249], v[214:217], v[2:5]
	s_waitcnt lgkmcnt(0)
	s_barrier
	s_cmp_eq_u32 s20, 44
	s_mov_b32 s4, s20
	s_cbranch_scc0 .LBB0_534
	s_waitcnt vmcnt(4)
	v_add_u32_e32 v102, s7, v206
	v_or_b32_e32 v104, v102, v205
	v_cmp_lt_i32_e32 vcc, s97, v104
	s_waitcnt vmcnt(3)
	v_ashrrev_i32_e32 v106, 31, v104
	v_add_u32_e32 v107, 0xffffc000, v104
	v_ashrrev_i32_e32 v105, 11, v102
	v_cndmask_b32_e64 v111, v106, 0, vcc
	v_cndmask_b32_e32 v110, v104, v107, vcc
	v_mov_b32_e32 v106, s45
	v_mov_b32_e32 v107, s47
	v_mov_b32_e32 v108, s44
	v_mov_b32_e32 v109, s46
	v_or_b32_e32 v102, s6, v208
	s_waitcnt vmcnt(2)
	v_cndmask_b32_e64 v114, v105, 8, vcc
	v_cndmask_b32_e32 v113, v106, v107, vcc
	v_cndmask_b32_e32 v112, v108, v109, vcc
	v_lshlrev_b64 v[122:123], 12, v[110:111]
	v_ashrrev_i32_e32 v103, 31, v102
	v_lshl_add_u64 v[110:111], v[112:113], 0, v[122:123]
	v_mul_hi_i32_i24_e32 v113, 0x9000, v114
	v_mul_i32_i24_e32 v112, 0x9000, v114
	v_lshl_add_u64 v[112:113], s[12:13], 0, v[112:113]
	v_lshlrev_b64 v[102:103], 2, v[102:103]
	s_waitcnt vmcnt(0)
	v_lshl_add_u64 v[124:125], v[112:113], 0, v[102:103]
	global_load_dwordx4 v[114:117], v[124:125], off
	s_waitcnt vmcnt(1)
	v_lshl_add_u64 v[126:127], v[110:111], 0, v[102:103]
	global_load_dwordx4 v[118:121], v[126:127], off
	v_mov_b32_e32 v110, s49
	v_mov_b32_e32 v111, s17
	v_mov_b32_e32 v112, s48
	v_mov_b32_e32 v113, s16
	v_cndmask_b32_e32 v129, v110, v111, vcc
	v_cndmask_b32_e32 v128, v112, v113, vcc
	v_lshl_add_u64 v[122:123], v[128:129], 0, v[122:123]
	v_lshl_add_u64 v[122:123], v[122:123], 0, v[102:103]
	s_waitcnt vmcnt(1)
	v_pk_mul_f32 v[114:115], v[114:115], 0.5 op_sel_hi:[1,0]
	v_pk_mul_f32 v[116:117], v[116:117], 0.5 op_sel_hi:[1,0]
	s_waitcnt vmcnt(0)
	v_pk_fma_f32 v[114:115], v[158:159], v[114:115], v[118:119]
	v_pk_fma_f32 v[116:117], v[160:161], v[116:117], v[120:121]
	global_store_dwordx4 v[122:123], v[114:117], off
	global_load_dwordx4 v[114:117], v[124:125], off offset:64
	s_nop 0
	global_load_dwordx4 v[118:121], v[126:127], off offset:64
	s_waitcnt vmcnt(1)
	v_pk_mul_f32 v[114:115], v[114:115], 0.5 op_sel_hi:[1,0]
	v_pk_mul_f32 v[116:117], v[116:117], 0.5 op_sel_hi:[1,0]
	s_waitcnt vmcnt(0)
	v_pk_fma_f32 v[114:115], v[154:155], v[114:115], v[118:119]
	v_pk_fma_f32 v[116:117], v[156:157], v[116:117], v[120:121]
	global_store_dwordx4 v[122:123], v[114:117], off offset:64
	global_load_dwordx4 v[114:117], v[124:125], off offset:128
	s_nop 0
	global_load_dwordx4 v[118:121], v[126:127], off offset:128
	s_waitcnt vmcnt(1)
	v_pk_mul_f32 v[114:115], v[114:115], 0.5 op_sel_hi:[1,0]
	v_pk_mul_f32 v[116:117], v[116:117], 0.5 op_sel_hi:[1,0]
	s_waitcnt vmcnt(0)
	v_pk_fma_f32 v[114:115], v[150:151], v[114:115], v[118:119]
	v_pk_fma_f32 v[116:117], v[152:153], v[116:117], v[120:121]
	global_store_dwordx4 v[122:123], v[114:117], off offset:128
	global_load_dwordx4 v[114:117], v[124:125], off offset:192
	s_nop 0
	global_load_dwordx4 v[118:121], v[126:127], off offset:192
	s_waitcnt vmcnt(1)
	v_pk_mul_f32 v[114:115], v[114:115], 0.5 op_sel_hi:[1,0]
	v_pk_mul_f32 v[116:117], v[116:117], 0.5 op_sel_hi:[1,0]
	s_waitcnt vmcnt(0)
	v_pk_fma_f32 v[114:115], v[146:147], v[114:115], v[118:119]
	v_pk_fma_f32 v[116:117], v[148:149], v[116:117], v[120:121]
	global_store_dwordx4 v[122:123], v[114:117], off offset:192
	global_load_dwordx4 v[114:117], v[124:125], off offset:256
	s_nop 0
	global_load_dwordx4 v[118:121], v[126:127], off offset:256
	s_waitcnt vmcnt(1)
	v_pk_mul_f32 v[114:115], v[114:115], 0.5 op_sel_hi:[1,0]
	v_pk_mul_f32 v[116:117], v[116:117], 0.5 op_sel_hi:[1,0]
	s_waitcnt vmcnt(0)
	v_pk_fma_f32 v[114:115], v[142:143], v[114:115], v[118:119]
	v_pk_fma_f32 v[116:117], v[144:145], v[116:117], v[120:121]
	global_store_dwordx4 v[122:123], v[114:117], off offset:256
	global_load_dwordx4 v[114:117], v[124:125], off offset:320
	s_nop 0
	global_load_dwordx4 v[118:121], v[126:127], off offset:320
	s_waitcnt vmcnt(1)
	v_pk_mul_f32 v[114:115], v[114:115], 0.5 op_sel_hi:[1,0]
	v_pk_mul_f32 v[116:117], v[116:117], 0.5 op_sel_hi:[1,0]
	s_waitcnt vmcnt(0)
	v_pk_fma_f32 v[114:115], v[138:139], v[114:115], v[118:119]
	v_pk_fma_f32 v[116:117], v[140:141], v[116:117], v[120:121]
	global_store_dwordx4 v[122:123], v[114:117], off offset:320
	global_load_dwordx4 v[114:117], v[124:125], off offset:384
	s_nop 0
	global_load_dwordx4 v[118:121], v[126:127], off offset:384
	s_waitcnt vmcnt(1)
	v_pk_mul_f32 v[114:115], v[114:115], 0.5 op_sel_hi:[1,0]
	v_pk_mul_f32 v[116:117], v[116:117], 0.5 op_sel_hi:[1,0]
	s_waitcnt vmcnt(0)
	v_pk_fma_f32 v[114:115], v[134:135], v[114:115], v[118:119]
	v_pk_fma_f32 v[116:117], v[136:137], v[116:117], v[120:121]
	global_store_dwordx4 v[122:123], v[114:117], off offset:384
	global_load_dwordx4 v[114:117], v[124:125], off offset:448
	s_nop 0
	global_load_dwordx4 v[118:121], v[126:127], off offset:448
	s_waitcnt vmcnt(1)
	v_pk_mul_f32 v[114:115], v[114:115], 0.5 op_sel_hi:[1,0]
	v_pk_mul_f32 v[116:117], v[116:117], 0.5 op_sel_hi:[1,0]
	s_waitcnt vmcnt(0)
	v_pk_fma_f32 v[98:99], v[98:99], v[114:115], v[118:119]
	v_pk_fma_f32 v[100:101], v[100:101], v[116:117], v[120:121]
	global_store_dwordx4 v[122:123], v[98:101], off offset:448
	s_nop 1
	v_or_b32_e32 v98, 16, v104
	v_cmp_lt_i32_e32 vcc, s97, v98
	v_add_u32_e32 v100, 0xffffc010, v104
	v_ashrrev_i32_e32 v99, 31, v98
	v_cndmask_b32_e64 v116, v105, 8, vcc
	v_cndmask_b32_e64 v99, v99, 0, vcc
	v_cndmask_b32_e32 v98, v98, v100, vcc
	v_lshlrev_b64 v[118:119], 12, v[98:99]
	v_mul_hi_i32_i24_e32 v99, 0x9000, v116
	v_mul_i32_i24_e32 v98, 0x9000, v116
	v_cndmask_b32_e32 v101, v106, v107, vcc
	v_cndmask_b32_e32 v100, v108, v109, vcc
	v_lshl_add_u64 v[98:99], s[12:13], 0, v[98:99]
	v_lshl_add_u64 v[114:115], v[100:101], 0, v[118:119]
	v_lshl_add_u64 v[120:121], v[98:99], 0, v[102:103]
	global_load_dwordx4 v[98:101], v[120:121], off
	v_lshl_add_u64 v[122:123], v[114:115], 0, v[102:103]
	global_load_dwordx4 v[114:117], v[122:123], off
	v_cndmask_b32_e32 v125, v110, v111, vcc
	v_cndmask_b32_e32 v124, v112, v113, vcc
	v_lshl_add_u64 v[118:119], v[124:125], 0, v[118:119]
	v_lshl_add_u64 v[118:119], v[118:119], 0, v[102:103]
	s_waitcnt vmcnt(1)
	v_pk_mul_f32 v[98:99], v[98:99], 0.5 op_sel_hi:[1,0]
	v_pk_mul_f32 v[100:101], v[100:101], 0.5 op_sel_hi:[1,0]
	s_waitcnt vmcnt(0)
	v_pk_fma_f32 v[94:95], v[94:95], v[98:99], v[114:115]
	v_pk_fma_f32 v[96:97], v[96:97], v[100:101], v[116:117]
	global_store_dwordx4 v[118:119], v[94:97], off
	global_load_dwordx4 v[94:97], v[120:121], off offset:64
	s_nop 0
	global_load_dwordx4 v[98:101], v[122:123], off offset:64
	s_waitcnt vmcnt(1)
	v_pk_mul_f32 v[94:95], v[94:95], 0.5 op_sel_hi:[1,0]
	v_pk_mul_f32 v[96:97], v[96:97], 0.5 op_sel_hi:[1,0]
	s_waitcnt vmcnt(0)
	v_pk_fma_f32 v[90:91], v[90:91], v[94:95], v[98:99]
	v_pk_fma_f32 v[92:93], v[92:93], v[96:97], v[100:101]
	global_store_dwordx4 v[118:119], v[90:93], off offset:64
	global_load_dwordx4 v[90:93], v[120:121], off offset:128
	s_nop 0
	global_load_dwordx4 v[94:97], v[122:123], off offset:128
	s_waitcnt vmcnt(1)
	v_pk_mul_f32 v[90:91], v[90:91], 0.5 op_sel_hi:[1,0]
	v_pk_mul_f32 v[92:93], v[92:93], 0.5 op_sel_hi:[1,0]
	s_waitcnt vmcnt(0)
	v_pk_fma_f32 v[86:87], v[86:87], v[90:91], v[94:95]
	v_pk_fma_f32 v[88:89], v[88:89], v[92:93], v[96:97]
	global_store_dwordx4 v[118:119], v[86:89], off offset:128
	global_load_dwordx4 v[86:89], v[120:121], off offset:192
	s_nop 0
	global_load_dwordx4 v[90:93], v[122:123], off offset:192
	s_waitcnt vmcnt(1)
	v_pk_mul_f32 v[86:87], v[86:87], 0.5 op_sel_hi:[1,0]
	v_pk_mul_f32 v[88:89], v[88:89], 0.5 op_sel_hi:[1,0]
	s_waitcnt vmcnt(0)
	v_pk_fma_f32 v[82:83], v[82:83], v[86:87], v[90:91]
	v_pk_fma_f32 v[84:85], v[84:85], v[88:89], v[92:93]
	global_store_dwordx4 v[118:119], v[82:85], off offset:192
	global_load_dwordx4 v[82:85], v[120:121], off offset:256
	s_nop 0
	global_load_dwordx4 v[86:89], v[122:123], off offset:256
	s_waitcnt vmcnt(1)
	v_pk_mul_f32 v[82:83], v[82:83], 0.5 op_sel_hi:[1,0]
	v_pk_mul_f32 v[84:85], v[84:85], 0.5 op_sel_hi:[1,0]
	s_waitcnt vmcnt(0)
	v_pk_fma_f32 v[78:79], v[78:79], v[82:83], v[86:87]
	v_pk_fma_f32 v[80:81], v[80:81], v[84:85], v[88:89]
	global_store_dwordx4 v[118:119], v[78:81], off offset:256
	global_load_dwordx4 v[78:81], v[120:121], off offset:320
	s_nop 0
	global_load_dwordx4 v[82:85], v[122:123], off offset:320
	s_waitcnt vmcnt(1)
	v_pk_mul_f32 v[78:79], v[78:79], 0.5 op_sel_hi:[1,0]
	v_pk_mul_f32 v[80:81], v[80:81], 0.5 op_sel_hi:[1,0]
	s_waitcnt vmcnt(0)
	v_pk_fma_f32 v[74:75], v[74:75], v[78:79], v[82:83]
	v_pk_fma_f32 v[76:77], v[76:77], v[80:81], v[84:85]
	global_store_dwordx4 v[118:119], v[74:77], off offset:320
	global_load_dwordx4 v[74:77], v[120:121], off offset:384
	s_nop 0
	global_load_dwordx4 v[78:81], v[122:123], off offset:384
	s_waitcnt vmcnt(1)
	v_pk_mul_f32 v[74:75], v[74:75], 0.5 op_sel_hi:[1,0]
	v_pk_mul_f32 v[76:77], v[76:77], 0.5 op_sel_hi:[1,0]
	s_waitcnt vmcnt(0)
	v_pk_fma_f32 v[70:71], v[70:71], v[74:75], v[78:79]
	v_pk_fma_f32 v[72:73], v[72:73], v[76:77], v[80:81]
	global_store_dwordx4 v[118:119], v[70:73], off offset:384
	global_load_dwordx4 v[70:73], v[120:121], off offset:448
	s_nop 0
	global_load_dwordx4 v[74:77], v[122:123], off offset:448
	s_waitcnt vmcnt(1)
	v_pk_mul_f32 v[70:71], v[70:71], 0.5 op_sel_hi:[1,0]
	v_pk_mul_f32 v[72:73], v[72:73], 0.5 op_sel_hi:[1,0]
	s_waitcnt vmcnt(0)
	v_pk_fma_f32 v[66:67], v[66:67], v[70:71], v[74:75]
	v_pk_fma_f32 v[68:69], v[68:69], v[72:73], v[76:77]
	global_store_dwordx4 v[118:119], v[66:69], off offset:448
	s_nop 1
	v_or_b32_e32 v66, 32, v104
	v_cmp_lt_i32_e32 vcc, s97, v66
	v_add_u32_e32 v68, 0xffffc020, v104
	v_ashrrev_i32_e32 v67, 31, v66
	v_cndmask_b32_e64 v72, v105, 8, vcc
	v_cndmask_b32_e64 v67, v67, 0, vcc
	v_cndmask_b32_e32 v66, v66, v68, vcc
	v_lshlrev_b64 v[74:75], 12, v[66:67]
	v_mul_hi_i32_i24_e32 v67, 0x9000, v72
	v_mul_i32_i24_e32 v66, 0x9000, v72
	v_cndmask_b32_e32 v69, v106, v107, vcc
	v_cndmask_b32_e32 v68, v108, v109, vcc
	v_lshl_add_u64 v[66:67], s[12:13], 0, v[66:67]
	v_lshl_add_u64 v[70:71], v[68:69], 0, v[74:75]
	v_lshl_add_u64 v[76:77], v[66:67], 0, v[102:103]
	global_load_dwordx4 v[66:69], v[76:77], off
	v_lshl_add_u64 v[78:79], v[70:71], 0, v[102:103]
	global_load_dwordx4 v[70:73], v[78:79], off
	v_cndmask_b32_e32 v81, v110, v111, vcc
	v_cndmask_b32_e32 v80, v112, v113, vcc
	v_lshl_add_u64 v[74:75], v[80:81], 0, v[74:75]
	v_lshl_add_u64 v[74:75], v[74:75], 0, v[102:103]
	s_waitcnt vmcnt(1)
	v_pk_mul_f32 v[66:67], v[66:67], 0.5 op_sel_hi:[1,0]
	v_pk_mul_f32 v[68:69], v[68:69], 0.5 op_sel_hi:[1,0]
	s_waitcnt vmcnt(0)
	v_pk_fma_f32 v[62:63], v[62:63], v[66:67], v[70:71]
	v_pk_fma_f32 v[64:65], v[64:65], v[68:69], v[72:73]
	global_store_dwordx4 v[74:75], v[62:65], off
	global_load_dwordx4 v[62:65], v[76:77], off offset:64
	s_nop 0
	global_load_dwordx4 v[66:69], v[78:79], off offset:64
	s_waitcnt vmcnt(1)
	v_pk_mul_f32 v[62:63], v[62:63], 0.5 op_sel_hi:[1,0]
	v_pk_mul_f32 v[64:65], v[64:65], 0.5 op_sel_hi:[1,0]
	s_waitcnt vmcnt(0)
	v_pk_fma_f32 v[58:59], v[58:59], v[62:63], v[66:67]
	v_pk_fma_f32 v[60:61], v[60:61], v[64:65], v[68:69]
	global_store_dwordx4 v[74:75], v[58:61], off offset:64
	global_load_dwordx4 v[58:61], v[76:77], off offset:128
	s_nop 0
	global_load_dwordx4 v[62:65], v[78:79], off offset:128
	s_waitcnt vmcnt(1)
	v_pk_mul_f32 v[58:59], v[58:59], 0.5 op_sel_hi:[1,0]
	v_pk_mul_f32 v[60:61], v[60:61], 0.5 op_sel_hi:[1,0]
	s_waitcnt vmcnt(0)
	v_pk_fma_f32 v[54:55], v[54:55], v[58:59], v[62:63]
	v_pk_fma_f32 v[56:57], v[56:57], v[60:61], v[64:65]
	global_store_dwordx4 v[74:75], v[54:57], off offset:128
	global_load_dwordx4 v[54:57], v[76:77], off offset:192
	s_nop 0
	global_load_dwordx4 v[58:61], v[78:79], off offset:192
	s_waitcnt vmcnt(1)
	v_pk_mul_f32 v[54:55], v[54:55], 0.5 op_sel_hi:[1,0]
	v_pk_mul_f32 v[56:57], v[56:57], 0.5 op_sel_hi:[1,0]
	s_waitcnt vmcnt(0)
	v_pk_fma_f32 v[50:51], v[50:51], v[54:55], v[58:59]
	v_pk_fma_f32 v[52:53], v[52:53], v[56:57], v[60:61]
	global_store_dwordx4 v[74:75], v[50:53], off offset:192
	global_load_dwordx4 v[50:53], v[76:77], off offset:256
	s_nop 0
	global_load_dwordx4 v[54:57], v[78:79], off offset:256
	s_waitcnt vmcnt(1)
	v_pk_mul_f32 v[50:51], v[50:51], 0.5 op_sel_hi:[1,0]
	v_pk_mul_f32 v[52:53], v[52:53], 0.5 op_sel_hi:[1,0]
	s_waitcnt vmcnt(0)
	v_pk_fma_f32 v[46:47], v[46:47], v[50:51], v[54:55]
	v_pk_fma_f32 v[48:49], v[48:49], v[52:53], v[56:57]
	global_store_dwordx4 v[74:75], v[46:49], off offset:256
	global_load_dwordx4 v[46:49], v[76:77], off offset:320
	s_nop 0
	global_load_dwordx4 v[50:53], v[78:79], off offset:320
	s_waitcnt vmcnt(1)
	v_pk_mul_f32 v[46:47], v[46:47], 0.5 op_sel_hi:[1,0]
	v_pk_mul_f32 v[48:49], v[48:49], 0.5 op_sel_hi:[1,0]
	s_waitcnt vmcnt(0)
	v_pk_fma_f32 v[42:43], v[42:43], v[46:47], v[50:51]
	v_pk_fma_f32 v[44:45], v[44:45], v[48:49], v[52:53]
	global_store_dwordx4 v[74:75], v[42:45], off offset:320
	global_load_dwordx4 v[42:45], v[76:77], off offset:384
	s_nop 0
	global_load_dwordx4 v[46:49], v[78:79], off offset:384
	s_waitcnt vmcnt(1)
	v_pk_mul_f32 v[42:43], v[42:43], 0.5 op_sel_hi:[1,0]
	v_pk_mul_f32 v[44:45], v[44:45], 0.5 op_sel_hi:[1,0]
	s_waitcnt vmcnt(0)
	v_pk_fma_f32 v[38:39], v[38:39], v[42:43], v[46:47]
	v_pk_fma_f32 v[40:41], v[40:41], v[44:45], v[48:49]
	global_store_dwordx4 v[74:75], v[38:41], off offset:384
	global_load_dwordx4 v[38:41], v[76:77], off offset:448
	s_nop 0
	global_load_dwordx4 v[42:45], v[78:79], off offset:448
	s_waitcnt vmcnt(1)
	v_pk_mul_f32 v[38:39], v[38:39], 0.5 op_sel_hi:[1,0]
	v_pk_mul_f32 v[40:41], v[40:41], 0.5 op_sel_hi:[1,0]
	s_waitcnt vmcnt(0)
	v_pk_fma_f32 v[34:35], v[34:35], v[38:39], v[42:43]
	v_pk_fma_f32 v[36:37], v[36:37], v[40:41], v[44:45]
	global_store_dwordx4 v[74:75], v[34:37], off offset:448
	s_nop 1
	v_or_b32_e32 v34, 48, v104
	v_cmp_lt_i32_e32 vcc, s97, v34
	v_add_u32_e32 v36, 0xffffc030, v104
	v_ashrrev_i32_e32 v35, 31, v34
	v_cndmask_b32_e64 v35, v35, 0, vcc
	v_cndmask_b32_e32 v34, v34, v36, vcc
	v_cndmask_b32_e64 v40, v105, 8, vcc
	v_cndmask_b32_e32 v37, v106, v107, vcc
	v_cndmask_b32_e32 v36, v108, v109, vcc
	v_lshlrev_b64 v[34:35], 12, v[34:35]
	v_cndmask_b32_e32 v39, v110, v111, vcc
	v_cndmask_b32_e32 v38, v112, v113, vcc
	v_lshl_add_u64 v[36:37], v[36:37], 0, v[34:35]
	v_lshl_add_u64 v[34:35], v[38:39], 0, v[34:35]
	v_mul_hi_i32_i24_e32 v39, 0x9000, v40
	v_mul_i32_i24_e32 v38, 0x9000, v40
	v_lshl_add_u64 v[38:39], s[12:13], 0, v[38:39]
	v_lshl_add_u64 v[42:43], v[38:39], 0, v[102:103]
	v_lshl_add_u64 v[44:45], v[36:37], 0, v[102:103]
	v_lshl_add_u64 v[46:47], v[34:35], 0, v[102:103]
	global_load_dwordx4 v[34:37], v[42:43], off
	global_load_dwordx4 v[38:41], v[44:45], off
	s_waitcnt vmcnt(1)
	v_pk_mul_f32 v[34:35], v[34:35], 0.5 op_sel_hi:[1,0]
	s_waitcnt vmcnt(0)
	v_pk_fma_f32 v[30:31], v[30:31], v[34:35], v[38:39]
	v_pk_mul_f32 v[34:35], v[36:37], 0.5 op_sel_hi:[1,0]
	s_nop 0
	v_pk_fma_f32 v[32:33], v[32:33], v[34:35], v[40:41]
	global_store_dwordx4 v[46:47], v[30:33], off
	global_load_dwordx4 v[30:33], v[42:43], off offset:64
	s_nop 0
	global_load_dwordx4 v[34:37], v[44:45], off offset:64
	s_waitcnt vmcnt(1)
	v_pk_mul_f32 v[30:31], v[30:31], 0.5 op_sel_hi:[1,0]
	s_waitcnt vmcnt(0)
	v_pk_fma_f32 v[26:27], v[26:27], v[30:31], v[34:35]
	v_pk_mul_f32 v[30:31], v[32:33], 0.5 op_sel_hi:[1,0]
	s_nop 0
	v_pk_fma_f32 v[28:29], v[28:29], v[30:31], v[36:37]
	global_store_dwordx4 v[46:47], v[26:29], off offset:64
	global_load_dwordx4 v[26:29], v[42:43], off offset:128
	s_nop 0
	global_load_dwordx4 v[30:33], v[44:45], off offset:128
	s_waitcnt vmcnt(1)
	v_pk_mul_f32 v[26:27], v[26:27], 0.5 op_sel_hi:[1,0]
	s_waitcnt vmcnt(0)
	v_pk_fma_f32 v[22:23], v[22:23], v[26:27], v[30:31]
	v_pk_mul_f32 v[26:27], v[28:29], 0.5 op_sel_hi:[1,0]
	s_nop 0
	v_pk_fma_f32 v[24:25], v[24:25], v[26:27], v[32:33]
	global_store_dwordx4 v[46:47], v[22:25], off offset:128
	global_load_dwordx4 v[22:25], v[42:43], off offset:192
	s_nop 0
	global_load_dwordx4 v[26:29], v[44:45], off offset:192
	s_waitcnt vmcnt(1)
	v_pk_mul_f32 v[22:23], v[22:23], 0.5 op_sel_hi:[1,0]
	s_waitcnt vmcnt(0)
	v_pk_fma_f32 v[18:19], v[18:19], v[22:23], v[26:27]
	v_pk_mul_f32 v[22:23], v[24:25], 0.5 op_sel_hi:[1,0]
	s_nop 0
	v_pk_fma_f32 v[20:21], v[20:21], v[22:23], v[28:29]
	global_store_dwordx4 v[46:47], v[18:21], off offset:192
	global_load_dwordx4 v[18:21], v[42:43], off offset:256
	s_nop 0
	global_load_dwordx4 v[22:25], v[44:45], off offset:256
	s_waitcnt vmcnt(1)
	v_pk_mul_f32 v[18:19], v[18:19], 0.5 op_sel_hi:[1,0]
	s_waitcnt vmcnt(0)
	v_pk_fma_f32 v[14:15], v[14:15], v[18:19], v[22:23]
	v_pk_mul_f32 v[18:19], v[20:21], 0.5 op_sel_hi:[1,0]
	s_nop 0
	v_pk_fma_f32 v[16:17], v[16:17], v[18:19], v[24:25]
	global_store_dwordx4 v[46:47], v[14:17], off offset:256
	global_load_dwordx4 v[14:17], v[42:43], off offset:320
	s_nop 0
	global_load_dwordx4 v[18:21], v[44:45], off offset:320
	s_waitcnt vmcnt(1)
	v_pk_mul_f32 v[14:15], v[14:15], 0.5 op_sel_hi:[1,0]
	s_waitcnt vmcnt(0)
	v_pk_fma_f32 v[10:11], v[10:11], v[14:15], v[18:19]
	v_pk_mul_f32 v[14:15], v[16:17], 0.5 op_sel_hi:[1,0]
	s_nop 0
	v_pk_fma_f32 v[12:13], v[12:13], v[14:15], v[20:21]
	global_store_dwordx4 v[46:47], v[10:13], off offset:320
	global_load_dwordx4 v[10:13], v[42:43], off offset:384
	s_nop 0
	global_load_dwordx4 v[14:17], v[44:45], off offset:384
	s_waitcnt vmcnt(1)
	v_pk_mul_f32 v[10:11], v[10:11], 0.5 op_sel_hi:[1,0]
	s_waitcnt vmcnt(0)
	v_pk_fma_f32 v[6:7], v[6:7], v[10:11], v[14:15]
	v_pk_mul_f32 v[10:11], v[12:13], 0.5 op_sel_hi:[1,0]
	s_nop 0
	v_pk_fma_f32 v[8:9], v[8:9], v[10:11], v[16:17]
	global_store_dwordx4 v[46:47], v[6:9], off offset:384
	global_load_dwordx4 v[6:9], v[42:43], off offset:448
	s_nop 0
	global_load_dwordx4 v[10:13], v[44:45], off offset:448
	s_waitcnt vmcnt(1)
	v_pk_mul_f32 v[6:7], v[6:7], 0.5 op_sel_hi:[1,0]
	s_waitcnt vmcnt(0)
	v_pk_fma_f32 v[2:3], v[2:3], v[6:7], v[10:11]
	v_pk_mul_f32 v[6:7], v[8:9], 0.5 op_sel_hi:[1,0]
	s_nop 0
	v_pk_fma_f32 v[4:5], v[4:5], v[6:7], v[12:13]
	global_store_dwordx4 v[46:47], v[2:5], off offset:448
	s_add_i32 s11, s11, s10
	s_cmpk_gt_i32 s11, 0xff
	s_cbranch_scc0 .LBB0_533

.LBB0_662:
	s_or_b64 exec, exec, s[12:13]
	s_mov_b64 s[12:13], s[60:61]
	s_waitcnt lgkmcnt(0)
	v_mov_b32_e32 v2, v172
	s_mov_b32 s10, s42
	s_mov_b32 s11, s94
	s_barrier
	s_cmpk_lt_i32 s11, 0x3f0
	s_mov_b32 s42, 0xffff0000
	s_mov_b32 s94, 0x3f200000
	s_cbranch_scc0 .LBB0_667
	s_load_dwordx2 s[6:7], s[12:13], 0x130
	v_lshlrev_b32_e32 v0, 4, v2
	v_and_b32_e32 v0, 0x70, v0
	s_mov_b64 s[2:3], 0x3200000
	v_ashrrev_i32_e32 v204, 3, v2
	s_waitcnt lgkmcnt(0)
	s_add_u32 s12, s6, 0x6035800
	s_addc_u32 s13, s7, 0
	v_lshl_add_u64 v[4:5], s[6:7], 0, v[0:1]
	s_mov_b64 s[6:7], 0x2100000
	v_bfe_u32 v3, v2, 4, 2
	v_and_b32_e32 v6, 15, v2
	v_lshl_add_u64 v[162:163], v[4:5], 0, s[2:3]
	v_lshl_add_u64 v[164:165], v[4:5], 0, s[6:7]
	v_ashrrev_i32_e32 v4, 1, v2
	s_movk_i32 s2, 0xffc0
	v_lshlrev_b32_e32 v2, 1, v2
	v_and_or_b32 v205, v4, s2, v6
	v_and_b32_e32 v2, 0x80, v2
	s_movk_i32 s2, 0x90
	v_or_b32_e32 v4, v2, v6
	v_and_b32_e32 v100, 7, v204
	v_lshlrev_b32_e32 v100, 4, v100
	v_xor_b32_e32 v100, v100, v0
	v_lshl_add_u32 v166, v204, 7, v100
	v_and_b32_e32 v100, 7, v6
	v_xor_b32_e32 v100, v100, v3
	v_lshlrev_b32_e32 v206, 4, v100
	v_lshl_or_b32 v207, v3, 2, v2
	v_lshlrev_b32_e32 v0, 7, v205
	v_lshlrev_b32_e32 v167, 7, v4
.LBB0_664:
	s_mul_hi_i32 s4, s11, 0x38e38e39
	s_lshr_b32 s6, s4, 31
	s_ashr_i32 s4, s4, 4
	s_add_i32 s4, s4, s6
	s_mul_i32 s6, s4, 0x48
	s_sub_i32 s6, s11, s6
	s_lshl_b32 s6, s6, 8
	v_add_u32_e32 v2, s6, v204
	v_ashrrev_i32_e32 v3, 31, v2
	v_lshlrev_b64 v[2:3], 11, v[2:3]
	v_lshl_add_u64 v[168:169], v[162:163], 0, v[2:3]
	v_add_co_u32_e32 v56, vcc, s34, v168
	s_lshl_b32 s7, s4, 8
	s_nop 0
	v_addc_co_u32_e32 v57, vcc, 0, v169, vcc
	v_add_u32_e32 v2, s7, v204
	v_add_co_u32_e32 v58, vcc, s35, v168
	v_ashrrev_i32_e32 v3, 31, v2
	s_nop 0
	v_addc_co_u32_e32 v59, vcc, 0, v169, vcc
	v_lshlrev_b64 v[2:3], 11, v[2:3]
	v_add_co_u32_e32 v60, vcc, s36, v168
	v_lshl_add_u64 v[170:171], v[164:165], 0, v[2:3]
	s_nop 0
	v_addc_co_u32_e32 v61, vcc, 0, v169, vcc
	v_add_co_u32_e32 v62, vcc, s35, v170
	global_load_dwordx4 v[24:27], v[56:57], off
	global_load_dwordx4 v[28:31], v[58:59], off
	v_addc_co_u32_e32 v63, vcc, 0, v171, vcc
	v_add_co_u32_e32 v64, vcc, s36, v170
	global_load_dwordx4 v[32:35], v[168:169], off
	global_load_dwordx4 v[36:39], v[170:171], off
	v_addc_co_u32_e32 v65, vcc, 0, v171, vcc
	v_add_co_u32_e32 v66, vcc, s34, v170
	global_load_dwordx4 v[40:43], v[62:63], off
	global_load_dwordx4 v[44:47], v[64:65], off
	v_addc_co_u32_e32 v67, vcc, 0, v171, vcc
	global_load_dwordx4 v[48:51], v[60:61], off
	global_load_dwordx4 v[52:55], v[66:67], off
	s_barrier
	global_load_dwordx4 v[94:97], v[168:169], off offset:128
	global_load_dwordx4 v[86:89], v[56:57], off offset:128
	global_load_dwordx4 v[90:93], v[58:59], off offset:128
	global_load_dwordx4 v[106:109], v[60:61], off offset:128
	global_load_dwordx4 v[102:105], v[170:171], off offset:128
	global_load_dwordx4 v[98:101], v[66:67], off offset:128
	global_load_dwordx4 v[118:121], v[62:63], off offset:128
	global_load_dwordx4 v[110:113], v[64:65], off offset:128
	v_readfirstlane_b32 vcc_lo, v168
	v_readfirstlane_b32 vcc_hi, v169
	v_readfirstlane_b32 s100, v170
	v_readfirstlane_b32 s101, v171
	s_nop 1
	v_subrev_u32_e32 v168, vcc_lo, v168
	v_subrev_u32_e32 v170, s100, v170
	v_mov_b32_e32 v2, 0
	s_mov_b32 s4, 0
	v_mov_b32_e32 v3, v2
	v_mov_b32_e32 v4, v2
	v_mov_b32_e32 v5, v2
	v_mov_b32_e32 v6, v2
	v_mov_b32_e32 v7, v2
	v_mov_b32_e32 v8, v2
	v_mov_b32_e32 v9, v2
	v_mov_b32_e32 v10, v2
	v_mov_b32_e32 v11, v2
	v_mov_b32_e32 v12, v2
	v_mov_b32_e32 v13, v2
	v_mov_b32_e32 v14, v2
	v_mov_b32_e32 v15, v2
	v_mov_b32_e32 v16, v2
	v_mov_b32_e32 v17, v2
	v_mov_b32_e32 v18, v2
	v_mov_b32_e32 v19, v2
	v_mov_b32_e32 v20, v2
	v_mov_b32_e32 v21, v2
	v_mov_b32_e32 v22, v2
	v_mov_b32_e32 v23, v2
	v_mov_b32_e32 v56, v2
	v_mov_b32_e32 v57, v2
	v_mov_b32_e32 v58, v2
	v_mov_b32_e32 v59, v2
	v_mov_b32_e32 v60, v2
	v_mov_b32_e32 v61, v2
	v_mov_b32_e32 v66, v2
	v_mov_b32_e32 v67, v2
	v_mov_b32_e32 v68, v2
	v_mov_b32_e32 v69, v2
	v_mov_b32_e32 v62, v2
	v_mov_b32_e32 v63, v2
	v_mov_b32_e32 v64, v2
	v_mov_b32_e32 v65, v2
	v_mov_b32_e32 v70, v2
	v_mov_b32_e32 v71, v2
	v_mov_b32_e32 v72, v2
	v_mov_b32_e32 v73, v2
	v_mov_b32_e32 v74, v2
	v_mov_b32_e32 v75, v2
	v_mov_b32_e32 v76, v2
	v_mov_b32_e32 v77, v2
	v_mov_b32_e32 v78, v2
	v_mov_b32_e32 v79, v2
	v_mov_b32_e32 v80, v2
	v_mov_b32_e32 v81, v2
	v_mov_b32_e32 v82, v2
	v_mov_b32_e32 v83, v2
	v_mov_b32_e32 v84, v2
	v_mov_b32_e32 v85, v2
	s_waitcnt vmcnt(11)
	ds_write_b128 v166, v[40:43] offset:49152
	s_waitcnt vmcnt(10)
	ds_write_b128 v166, v[44:47] offset:57344
	ds_write_b128 v166, v[32:35]
	ds_write_b128 v166, v[36:39] offset:32768
	ds_write_b128 v166, v[24:27] offset:8192
	ds_write_b128 v166, v[28:31] offset:16384
	s_waitcnt vmcnt(9)
	ds_write_b128 v166, v[48:51] offset:24576
	s_waitcnt vmcnt(8)
	ds_write_b128 v166, v[52:55] offset:40960
	v_mov_b32_e32 v24, v2
	v_mov_b32_e32 v25, v2
	v_mov_b32_e32 v26, v2
	v_mov_b32_e32 v27, v2
	v_mov_b32_e32 v28, v2
	v_mov_b32_e32 v29, v2
	v_mov_b32_e32 v34, v2
	v_mov_b32_e32 v35, v2
	v_mov_b32_e32 v36, v2
	v_mov_b32_e32 v37, v2
	v_mov_b32_e32 v30, v2
	v_mov_b32_e32 v31, v2
	v_mov_b32_e32 v32, v2
	v_mov_b32_e32 v33, v2
	v_mov_b32_e32 v38, v2
	v_mov_b32_e32 v39, v2
	v_mov_b32_e32 v40, v2
	v_mov_b32_e32 v41, v2
	v_mov_b32_e32 v42, v2
	v_mov_b32_e32 v43, v2
	v_mov_b32_e32 v44, v2
	v_mov_b32_e32 v45, v2
	v_mov_b32_e32 v46, v2
	v_mov_b32_e32 v47, v2
	v_mov_b32_e32 v48, v2
	v_mov_b32_e32 v49, v2
	v_mov_b32_e32 v50, v2
	v_mov_b32_e32 v51, v2
	v_mov_b32_e32 v52, v2
	v_mov_b32_e32 v53, v2
	v_mov_b32_e32 v54, v2
	v_mov_b32_e32 v55, v2
	v_mov_b32_e32 v114, v2
	v_mov_b32_e32 v115, v2
	v_mov_b32_e32 v116, v2
	v_mov_b32_e32 v117, v2
	v_mov_b32_e32 v122, v2
	v_mov_b32_e32 v123, v2
	v_mov_b32_e32 v124, v2
	v_mov_b32_e32 v125, v2
	v_mov_b32_e32 v130, v2
	v_mov_b32_e32 v131, v2
	v_mov_b32_e32 v132, v2
	v_mov_b32_e32 v133, v2
	v_mov_b32_e32 v126, v2
	v_mov_b32_e32 v127, v2
	v_mov_b32_e32 v128, v2
	v_mov_b32_e32 v129, v2
	v_mov_b32_e32 v134, v2
	v_mov_b32_e32 v135, v2
	v_mov_b32_e32 v136, v2
	v_mov_b32_e32 v137, v2
	v_mov_b32_e32 v138, v2
	v_mov_b32_e32 v139, v2
	v_mov_b32_e32 v140, v2
	v_mov_b32_e32 v141, v2
	v_mov_b32_e32 v142, v2
	v_mov_b32_e32 v143, v2
	v_mov_b32_e32 v144, v2
	v_mov_b32_e32 v145, v2
	v_mov_b32_e32 v146, v2
	v_mov_b32_e32 v147, v2
	v_mov_b32_e32 v148, v2
	v_mov_b32_e32 v149, v2
	v_mov_b32_e32 v150, v2
	v_mov_b32_e32 v151, v2
	v_mov_b32_e32 v152, v2
	v_mov_b32_e32 v153, v2
	v_mov_b32_e32 v154, v2
	v_mov_b32_e32 v155, v2
	v_mov_b32_e32 v156, v2
	v_mov_b32_e32 v157, v2
	v_mov_b32_e32 v158, v2
	v_mov_b32_e32 v159, v2
	v_mov_b32_e32 v160, v2
	v_mov_b32_e32 v161, v2
	s_waitcnt lgkmcnt(0)
	s_barrier
.LBB0_665:
	s_bitcmp1_b32 s4, 0
	s_cselect_b32 s15, 0x12000, 0
	v_or_b32_e32 v208, s15, v206
	v_add_u32_e32 v214, v208, v0
	v_add_u32_e32 v208, v208, v167
	ds_read_b128 v[184:187], v214
	ds_read_b128 v[198:201], v214 offset:2048
	ds_read_b128 v[210:213], v214 offset:4096
	ds_read_b128 v[214:217], v214 offset:6144
	ds_read_b128 v[218:221], v208 offset:32768
	ds_read_b128 v[222:225], v208 offset:34816
	ds_read_b128 v[226:229], v208 offset:36864
	ds_read_b128 v[230:233], v208 offset:38912
	ds_read_b128 v[234:237], v208 offset:40960
	ds_read_b128 v[238:241], v208 offset:43008
	ds_read_b128 v[242:245], v208 offset:45056
	ds_read_b128 v[246:249], v208 offset:47104
	s_add_i32 s14, s4, 1
	s_bitcmp1_b32 s14, 0
	s_cselect_b32 s16, 0x12000, 0
	v_add_u32_e32 v208, s16, v166
	s_waitcnt lgkmcnt(7)
	v_mfma_f32_16x16x32_bf16 v[158:161], v[218:221], v[184:187], v[158:161]
	v_mfma_f32_16x16x32_bf16 v[130:133], v[218:221], v[198:201], v[130:133]
	v_mfma_f32_16x16x32_bf16 v[66:69], v[218:221], v[210:213], v[66:69]
	v_mfma_f32_16x16x32_bf16 v[34:37], v[218:221], v[214:217], v[34:37]
	s_waitcnt vmcnt(7)
	ds_write_b128 v208, v[94:97]
	s_waitcnt lgkmcnt(7)
	v_mfma_f32_16x16x32_bf16 v[154:157], v[222:225], v[184:187], v[154:157]
	v_mfma_f32_16x16x32_bf16 v[122:125], v[222:225], v[198:201], v[122:125]
	global_load_dwordx4 v[94:97], v168, vcc offset:256
	v_mfma_f32_16x16x32_bf16 v[58:61], v[222:225], v[210:213], v[58:61]
	v_mfma_f32_16x16x32_bf16 v[26:29], v[222:225], v[214:217], v[26:29]
	s_waitcnt vmcnt(7)
	ds_write_b128 v208, v[86:89] offset:8192
	s_waitcnt lgkmcnt(7)
	v_mfma_f32_16x16x32_bf16 v[150:153], v[226:229], v[184:187], v[150:153]
	v_mfma_f32_16x16x32_bf16 v[114:117], v[226:229], v[198:201], v[114:117]
	v_add_u32_e32 v86, s34, v168
	global_load_dwordx4 v[86:89], v86, vcc offset:256
	v_mfma_f32_16x16x32_bf16 v[54:57], v[226:229], v[210:213], v[54:57]
	v_mfma_f32_16x16x32_bf16 v[22:25], v[226:229], v[214:217], v[22:25]
	s_waitcnt vmcnt(7)
	ds_write_b128 v208, v[90:93] offset:16384
	s_waitcnt lgkmcnt(7)
	v_mfma_f32_16x16x32_bf16 v[146:149], v[230:233], v[184:187], v[146:149]
	v_mfma_f32_16x16x32_bf16 v[82:85], v[230:233], v[198:201], v[82:85]
	v_add_u32_e32 v90, s35, v168
	global_load_dwordx4 v[90:93], v90, vcc offset:256
	v_mfma_f32_16x16x32_bf16 v[50:53], v[230:233], v[210:213], v[50:53]
	v_mfma_f32_16x16x32_bf16 v[18:21], v[230:233], v[214:217], v[18:21]
	s_waitcnt vmcnt(7)
	ds_write_b128 v208, v[106:109] offset:24576
	s_waitcnt lgkmcnt(7)
	v_mfma_f32_16x16x32_bf16 v[142:145], v[234:237], v[184:187], v[142:145]
	v_mfma_f32_16x16x32_bf16 v[78:81], v[234:237], v[198:201], v[78:81]
	v_add_u32_e32 v106, s36, v168
	global_load_dwordx4 v[106:109], v106, vcc offset:256
	v_mfma_f32_16x16x32_bf16 v[46:49], v[234:237], v[210:213], v[46:49]
	v_mfma_f32_16x16x32_bf16 v[14:17], v[234:237], v[214:217], v[14:17]
	s_waitcnt vmcnt(7)
	ds_write_b128 v208, v[102:105] offset:32768
	s_waitcnt lgkmcnt(7)
	v_mfma_f32_16x16x32_bf16 v[138:141], v[238:241], v[184:187], v[138:141]
	v_mfma_f32_16x16x32_bf16 v[74:77], v[238:241], v[198:201], v[74:77]
	global_load_dwordx4 v[102:105], v170, s[100:101] offset:256
	v_mfma_f32_16x16x32_bf16 v[42:45], v[238:241], v[210:213], v[42:45]
	v_mfma_f32_16x16x32_bf16 v[10:13], v[238:241], v[214:217], v[10:13]
	s_waitcnt vmcnt(7)
	ds_write_b128 v208, v[98:101] offset:40960
	s_waitcnt lgkmcnt(7)
	v_mfma_f32_16x16x32_bf16 v[134:137], v[242:245], v[184:187], v[134:137]
	v_mfma_f32_16x16x32_bf16 v[70:73], v[242:245], v[198:201], v[70:73]
	v_add_u32_e32 v98, s34, v170
	global_load_dwordx4 v[98:101], v98, s[100:101] offset:256
	v_mfma_f32_16x16x32_bf16 v[38:41], v[242:245], v[210:213], v[38:41]
	v_mfma_f32_16x16x32_bf16 v[6:9], v[242:245], v[214:217], v[6:9]
	s_waitcnt vmcnt(7)
	ds_write_b128 v208, v[118:121] offset:49152
	s_waitcnt lgkmcnt(7)
	v_mfma_f32_16x16x32_bf16 v[126:129], v[246:249], v[184:187], v[126:129]
	v_mfma_f32_16x16x32_bf16 v[62:65], v[246:249], v[198:201], v[62:65]
	v_add_u32_e32 v118, s35, v170
	global_load_dwordx4 v[118:121], v118, s[100:101] offset:256
	v_mfma_f32_16x16x32_bf16 v[30:33], v[246:249], v[210:213], v[30:33]
	v_mfma_f32_16x16x32_bf16 v[2:5], v[246:249], v[214:217], v[2:5]
	s_waitcnt vmcnt(7)
	ds_write_b128 v208, v[110:113] offset:57344
	v_add3_u32 v208, s15, v0, v206
	v_xor_b32_e32 v208, 64, v208
	v_add_u32_e32 v110, s36, v170
	global_load_dwordx4 v[110:113], v110, s[100:101] offset:256
	v_add_u32_e32 v168, 0x80, v168
	v_add_u32_e32 v170, 0x80, v170
	ds_read_b128 v[184:187], v208
	ds_read_b128 v[198:201], v208 offset:2048
	ds_read_b128 v[210:213], v208 offset:4096
	ds_read_b128 v[214:217], v208 offset:6144
	v_add3_u32 v208, s15, v167, v206
	v_xor_b32_e32 v208, 64, v208
	ds_read_b128 v[218:221], v208 offset:32768
	ds_read_b128 v[222:225], v208 offset:34816
	ds_read_b128 v[226:229], v208 offset:36864
	ds_read_b128 v[230:233], v208 offset:38912
	ds_read_b128 v[234:237], v208 offset:40960
	ds_read_b128 v[238:241], v208 offset:43008
	ds_read_b128 v[242:245], v208 offset:45056
	ds_read_b128 v[246:249], v208 offset:47104
	s_waitcnt lgkmcnt(7)
	v_mfma_f32_16x16x32_bf16 v[158:161], v[218:221], v[184:187], v[158:161]
	v_mfma_f32_16x16x32_bf16 v[130:133], v[218:221], v[198:201], v[130:133]
	v_mfma_f32_16x16x32_bf16 v[66:69], v[218:221], v[210:213], v[66:69]
	v_mfma_f32_16x16x32_bf16 v[34:37], v[218:221], v[214:217], v[34:37]
	s_waitcnt lgkmcnt(6)
	v_mfma_f32_16x16x32_bf16 v[154:157], v[222:225], v[184:187], v[154:157]
	v_mfma_f32_16x16x32_bf16 v[122:125], v[222:225], v[198:201], v[122:125]
	v_mfma_f32_16x16x32_bf16 v[58:61], v[222:225], v[210:213], v[58:61]
	v_mfma_f32_16x16x32_bf16 v[26:29], v[222:225], v[214:217], v[26:29]
	s_waitcnt lgkmcnt(5)
	v_mfma_f32_16x16x32_bf16 v[150:153], v[226:229], v[184:187], v[150:153]
	v_mfma_f32_16x16x32_bf16 v[114:117], v[226:229], v[198:201], v[114:117]
	v_mfma_f32_16x16x32_bf16 v[54:57], v[226:229], v[210:213], v[54:57]
	v_mfma_f32_16x16x32_bf16 v[22:25], v[226:229], v[214:217], v[22:25]
	s_waitcnt lgkmcnt(4)
	v_mfma_f32_16x16x32_bf16 v[146:149], v[230:233], v[184:187], v[146:149]
	v_mfma_f32_16x16x32_bf16 v[82:85], v[230:233], v[198:201], v[82:85]
	v_mfma_f32_16x16x32_bf16 v[50:53], v[230:233], v[210:213], v[50:53]
	v_mfma_f32_16x16x32_bf16 v[18:21], v[230:233], v[214:217], v[18:21]
	s_waitcnt lgkmcnt(3)
	v_mfma_f32_16x16x32_bf16 v[142:145], v[234:237], v[184:187], v[142:145]
	v_mfma_f32_16x16x32_bf16 v[78:81], v[234:237], v[198:201], v[78:81]
	v_mfma_f32_16x16x32_bf16 v[46:49], v[234:237], v[210:213], v[46:49]
	v_mfma_f32_16x16x32_bf16 v[14:17], v[234:237], v[214:217], v[14:17]
	s_waitcnt lgkmcnt(2)
	v_mfma_f32_16x16x32_bf16 v[138:141], v[238:241], v[184:187], v[138:141]
	v_mfma_f32_16x16x32_bf16 v[74:77], v[238:241], v[198:201], v[74:77]
	v_mfma_f32_16x16x32_bf16 v[42:45], v[238:241], v[210:213], v[42:45]
	v_mfma_f32_16x16x32_bf16 v[10:13], v[238:241], v[214:217], v[10:13]
	s_waitcnt lgkmcnt(1)
	v_mfma_f32_16x16x32_bf16 v[134:137], v[242:245], v[184:187], v[134:137]
	v_mfma_f32_16x16x32_bf16 v[70:73], v[242:245], v[198:201], v[70:73]
	v_mfma_f32_16x16x32_bf16 v[38:41], v[242:245], v[210:213], v[38:41]
	v_mfma_f32_16x16x32_bf16 v[6:9], v[242:245], v[214:217], v[6:9]
	s_waitcnt lgkmcnt(0)
	v_mfma_f32_16x16x32_bf16 v[126:129], v[246:249], v[184:187], v[126:129]
	v_mfma_f32_16x16x32_bf16 v[62:65], v[246:249], v[198:201], v[62:65]
	v_mfma_f32_16x16x32_bf16 v[30:33], v[246:249], v[210:213], v[30:33]
	v_mfma_f32_16x16x32_bf16 v[2:5], v[246:249], v[214:217], v[2:5]
	s_waitcnt lgkmcnt(0)
	s_barrier
	s_cmp_eq_u32 s14, 16
	s_mov_b32 s4, s14
	s_cbranch_scc0 .LBB0_665
	s_waitcnt vmcnt(3)
	v_and_b32_sdwa v93, v158, v177 dst_sel:DWORD dst_unused:UNUSED_PAD src0_sel:WORD_1 src1_sel:DWORD
	v_or_b32_e32 v88, s7, v207
	v_add3_u32 v95, v158, v93, s28
	v_and_b32_sdwa v93, v161, v177 dst_sel:DWORD dst_unused:UNUSED_PAD src0_sel:WORD_1 src1_sel:DWORD
	v_and_b32_sdwa v96, v159, v177 dst_sel:DWORD dst_unused:UNUSED_PAD src0_sel:WORD_1 src1_sel:DWORD
	v_add_u32_e32 v94, s6, v205
	v_mov_b64_e32 v[86:87], s[12:13]
	v_ashrrev_i32_e32 v89, 31, v88
	v_and_b32_sdwa v92, v160, v177 dst_sel:DWORD dst_unused:UNUSED_PAD src0_sel:WORD_1 src1_sel:DWORD
	v_add3_u32 v93, v161, v93, s28
	v_add3_u32 v96, v159, v96, s28
	v_mad_i64_i32 v[90:91], s[6:7], v94, s8, v[86:87]
	v_lshlrev_b64 v[88:89], 1, v[88:89]
	v_add3_u32 v92, v160, v92, s28
	v_and_b32_e32 v93, 0xffff0000, v93
	v_and_b32_e32 v96, 0xffff0000, v96
	v_lshl_add_u64 v[90:91], v[90:91], 0, v[88:89]
	v_or_b32_sdwa v93, v93, v92 dst_sel:DWORD dst_unused:UNUSED_PAD src0_sel:DWORD src1_sel:WORD_1
	v_or_b32_sdwa v92, v96, v95 dst_sel:DWORD dst_unused:UNUSED_PAD src0_sel:DWORD src1_sel:WORD_1
	s_waitcnt vmcnt(0)
	global_store_dwordx2 v[90:91], v[92:93], off
	v_and_b32_sdwa v93, v154, v177 dst_sel:DWORD dst_unused:UNUSED_PAD src0_sel:WORD_1 src1_sel:DWORD
	v_add3_u32 v95, v154, v93, s28
	v_and_b32_sdwa v93, v157, v177 dst_sel:DWORD dst_unused:UNUSED_PAD src0_sel:WORD_1 src1_sel:DWORD
	v_and_b32_sdwa v96, v155, v177 dst_sel:DWORD dst_unused:UNUSED_PAD src0_sel:WORD_1 src1_sel:DWORD
	v_and_b32_sdwa v92, v156, v177 dst_sel:DWORD dst_unused:UNUSED_PAD src0_sel:WORD_1 src1_sel:DWORD
	v_add3_u32 v93, v157, v93, s28
	v_add3_u32 v96, v155, v96, s28
	v_add3_u32 v92, v156, v92, s28
	v_and_b32_e32 v93, 0xffff0000, v93
	v_and_b32_e32 v96, 0xffff0000, v96
	v_or_b32_sdwa v93, v93, v92 dst_sel:DWORD dst_unused:UNUSED_PAD src0_sel:DWORD src1_sel:WORD_1
	v_or_b32_sdwa v92, v96, v95 dst_sel:DWORD dst_unused:UNUSED_PAD src0_sel:DWORD src1_sel:WORD_1
	global_store_dwordx2 v[90:91], v[92:93], off offset:32
	v_and_b32_sdwa v93, v150, v177 dst_sel:DWORD dst_unused:UNUSED_PAD src0_sel:WORD_1 src1_sel:DWORD
	v_add3_u32 v95, v150, v93, s28
	v_and_b32_sdwa v93, v153, v177 dst_sel:DWORD dst_unused:UNUSED_PAD src0_sel:WORD_1 src1_sel:DWORD
	v_and_b32_sdwa v96, v151, v177 dst_sel:DWORD dst_unused:UNUSED_PAD src0_sel:WORD_1 src1_sel:DWORD
	v_and_b32_sdwa v92, v152, v177 dst_sel:DWORD dst_unused:UNUSED_PAD src0_sel:WORD_1 src1_sel:DWORD
	v_add3_u32 v93, v153, v93, s28
	v_add3_u32 v96, v151, v96, s28
	v_add3_u32 v92, v152, v92, s28
	v_and_b32_e32 v93, 0xffff0000, v93
	v_and_b32_e32 v96, 0xffff0000, v96
	v_or_b32_sdwa v93, v93, v92 dst_sel:DWORD dst_unused:UNUSED_PAD src0_sel:DWORD src1_sel:WORD_1
	v_or_b32_sdwa v92, v96, v95 dst_sel:DWORD dst_unused:UNUSED_PAD src0_sel:DWORD src1_sel:WORD_1
	global_store_dwordx2 v[90:91], v[92:93], off offset:64
	v_and_b32_sdwa v93, v146, v177 dst_sel:DWORD dst_unused:UNUSED_PAD src0_sel:WORD_1 src1_sel:DWORD
	v_add3_u32 v95, v146, v93, s28
	v_and_b32_sdwa v93, v149, v177 dst_sel:DWORD dst_unused:UNUSED_PAD src0_sel:WORD_1 src1_sel:DWORD
	v_and_b32_sdwa v96, v147, v177 dst_sel:DWORD dst_unused:UNUSED_PAD src0_sel:WORD_1 src1_sel:DWORD
	v_and_b32_sdwa v92, v148, v177 dst_sel:DWORD dst_unused:UNUSED_PAD src0_sel:WORD_1 src1_sel:DWORD
	v_add3_u32 v93, v149, v93, s28
	v_add3_u32 v96, v147, v96, s28
	v_add3_u32 v92, v148, v92, s28
	v_and_b32_e32 v93, 0xffff0000, v93
	v_and_b32_e32 v96, 0xffff0000, v96
	v_or_b32_sdwa v93, v93, v92 dst_sel:DWORD dst_unused:UNUSED_PAD src0_sel:DWORD src1_sel:WORD_1
	v_or_b32_sdwa v92, v96, v95 dst_sel:DWORD dst_unused:UNUSED_PAD src0_sel:DWORD src1_sel:WORD_1
	global_store_dwordx2 v[90:91], v[92:93], off offset:96
	v_and_b32_sdwa v93, v142, v177 dst_sel:DWORD dst_unused:UNUSED_PAD src0_sel:WORD_1 src1_sel:DWORD
	v_add3_u32 v95, v142, v93, s28
	v_and_b32_sdwa v93, v145, v177 dst_sel:DWORD dst_unused:UNUSED_PAD src0_sel:WORD_1 src1_sel:DWORD
	v_and_b32_sdwa v96, v143, v177 dst_sel:DWORD dst_unused:UNUSED_PAD src0_sel:WORD_1 src1_sel:DWORD
	v_and_b32_sdwa v92, v144, v177 dst_sel:DWORD dst_unused:UNUSED_PAD src0_sel:WORD_1 src1_sel:DWORD
	v_add3_u32 v93, v145, v93, s28
	v_add3_u32 v96, v143, v96, s28
	v_add3_u32 v92, v144, v92, s28
	v_and_b32_e32 v93, 0xffff0000, v93
	v_and_b32_e32 v96, 0xffff0000, v96
	v_or_b32_sdwa v93, v93, v92 dst_sel:DWORD dst_unused:UNUSED_PAD src0_sel:DWORD src1_sel:WORD_1
	v_or_b32_sdwa v92, v96, v95 dst_sel:DWORD dst_unused:UNUSED_PAD src0_sel:DWORD src1_sel:WORD_1
	global_store_dwordx2 v[90:91], v[92:93], off offset:128
	v_and_b32_sdwa v93, v138, v177 dst_sel:DWORD dst_unused:UNUSED_PAD src0_sel:WORD_1 src1_sel:DWORD
	v_add3_u32 v95, v138, v93, s28
	v_and_b32_sdwa v93, v141, v177 dst_sel:DWORD dst_unused:UNUSED_PAD src0_sel:WORD_1 src1_sel:DWORD
	v_and_b32_sdwa v96, v139, v177 dst_sel:DWORD dst_unused:UNUSED_PAD src0_sel:WORD_1 src1_sel:DWORD
	v_and_b32_sdwa v92, v140, v177 dst_sel:DWORD dst_unused:UNUSED_PAD src0_sel:WORD_1 src1_sel:DWORD
	v_add3_u32 v93, v141, v93, s28
	v_add3_u32 v96, v139, v96, s28
	v_add3_u32 v92, v140, v92, s28
	v_and_b32_e32 v93, 0xffff0000, v93
	v_and_b32_e32 v96, 0xffff0000, v96
	v_or_b32_sdwa v93, v93, v92 dst_sel:DWORD dst_unused:UNUSED_PAD src0_sel:DWORD src1_sel:WORD_1
	v_or_b32_sdwa v92, v96, v95 dst_sel:DWORD dst_unused:UNUSED_PAD src0_sel:DWORD src1_sel:WORD_1
	global_store_dwordx2 v[90:91], v[92:93], off offset:160
	v_and_b32_sdwa v93, v134, v177 dst_sel:DWORD dst_unused:UNUSED_PAD src0_sel:WORD_1 src1_sel:DWORD
	v_add3_u32 v95, v134, v93, s28
	v_and_b32_sdwa v93, v137, v177 dst_sel:DWORD dst_unused:UNUSED_PAD src0_sel:WORD_1 src1_sel:DWORD
	v_and_b32_sdwa v96, v135, v177 dst_sel:DWORD dst_unused:UNUSED_PAD src0_sel:WORD_1 src1_sel:DWORD
	v_and_b32_sdwa v92, v136, v177 dst_sel:DWORD dst_unused:UNUSED_PAD src0_sel:WORD_1 src1_sel:DWORD
	v_add3_u32 v93, v137, v93, s28
	v_add3_u32 v96, v135, v96, s28
	v_add3_u32 v92, v136, v92, s28
	v_and_b32_e32 v93, 0xffff0000, v93
	v_and_b32_e32 v96, 0xffff0000, v96
	v_or_b32_sdwa v93, v93, v92 dst_sel:DWORD dst_unused:UNUSED_PAD src0_sel:DWORD src1_sel:WORD_1
	v_or_b32_sdwa v92, v96, v95 dst_sel:DWORD dst_unused:UNUSED_PAD src0_sel:DWORD src1_sel:WORD_1
	global_store_dwordx2 v[90:91], v[92:93], off offset:192
	v_and_b32_sdwa v93, v126, v177 dst_sel:DWORD dst_unused:UNUSED_PAD src0_sel:WORD_1 src1_sel:DWORD
	v_add3_u32 v95, v126, v93, s28
	v_and_b32_sdwa v93, v129, v177 dst_sel:DWORD dst_unused:UNUSED_PAD src0_sel:WORD_1 src1_sel:DWORD
	v_and_b32_sdwa v96, v127, v177 dst_sel:DWORD dst_unused:UNUSED_PAD src0_sel:WORD_1 src1_sel:DWORD
	v_and_b32_sdwa v92, v128, v177 dst_sel:DWORD dst_unused:UNUSED_PAD src0_sel:WORD_1 src1_sel:DWORD
	v_add3_u32 v93, v129, v93, s28
	v_add3_u32 v96, v127, v96, s28
	v_add3_u32 v92, v128, v92, s28
	v_and_b32_e32 v93, 0xffff0000, v93
	v_and_b32_e32 v96, 0xffff0000, v96
	v_or_b32_sdwa v93, v93, v92 dst_sel:DWORD dst_unused:UNUSED_PAD src0_sel:DWORD src1_sel:WORD_1
	v_or_b32_sdwa v92, v96, v95 dst_sel:DWORD dst_unused:UNUSED_PAD src0_sel:DWORD src1_sel:WORD_1
	global_store_dwordx2 v[90:91], v[92:93], off offset:224
	v_and_b32_sdwa v93, v130, v177 dst_sel:DWORD dst_unused:UNUSED_PAD src0_sel:WORD_1 src1_sel:DWORD
	v_add3_u32 v95, v130, v93, s28
	v_and_b32_sdwa v93, v133, v177 dst_sel:DWORD dst_unused:UNUSED_PAD src0_sel:WORD_1 src1_sel:DWORD
	v_and_b32_sdwa v96, v131, v177 dst_sel:DWORD dst_unused:UNUSED_PAD src0_sel:WORD_1 src1_sel:DWORD
	v_or_b32_e32 v90, 16, v94
	v_and_b32_sdwa v92, v132, v177 dst_sel:DWORD dst_unused:UNUSED_PAD src0_sel:WORD_1 src1_sel:DWORD
	v_add3_u32 v93, v133, v93, s28
	v_add3_u32 v96, v131, v96, s28
	v_mad_i64_i32 v[90:91], s[6:7], v90, s8, v[86:87]
	v_add3_u32 v92, v132, v92, s28
	v_and_b32_e32 v93, 0xffff0000, v93
	v_and_b32_e32 v96, 0xffff0000, v96
	v_lshl_add_u64 v[90:91], v[90:91], 0, v[88:89]
	v_or_b32_sdwa v93, v93, v92 dst_sel:DWORD dst_unused:UNUSED_PAD src0_sel:DWORD src1_sel:WORD_1
	v_or_b32_sdwa v92, v96, v95 dst_sel:DWORD dst_unused:UNUSED_PAD src0_sel:DWORD src1_sel:WORD_1
	global_store_dwordx2 v[90:91], v[92:93], off
	v_and_b32_sdwa v93, v122, v177 dst_sel:DWORD dst_unused:UNUSED_PAD src0_sel:WORD_1 src1_sel:DWORD
	v_add3_u32 v95, v122, v93, s28
	v_and_b32_sdwa v93, v125, v177 dst_sel:DWORD dst_unused:UNUSED_PAD src0_sel:WORD_1 src1_sel:DWORD
	v_and_b32_sdwa v96, v123, v177 dst_sel:DWORD dst_unused:UNUSED_PAD src0_sel:WORD_1 src1_sel:DWORD
	v_and_b32_sdwa v92, v124, v177 dst_sel:DWORD dst_unused:UNUSED_PAD src0_sel:WORD_1 src1_sel:DWORD
	v_add3_u32 v93, v125, v93, s28
	v_add3_u32 v96, v123, v96, s28
	v_add3_u32 v92, v124, v92, s28
	v_and_b32_e32 v93, 0xffff0000, v93
	v_and_b32_e32 v96, 0xffff0000, v96
	v_or_b32_sdwa v93, v93, v92 dst_sel:DWORD dst_unused:UNUSED_PAD src0_sel:DWORD src1_sel:WORD_1
	v_or_b32_sdwa v92, v96, v95 dst_sel:DWORD dst_unused:UNUSED_PAD src0_sel:DWORD src1_sel:WORD_1
	global_store_dwordx2 v[90:91], v[92:93], off offset:32
	v_and_b32_sdwa v93, v114, v177 dst_sel:DWORD dst_unused:UNUSED_PAD src0_sel:WORD_1 src1_sel:DWORD
	v_add3_u32 v95, v114, v93, s28
	v_and_b32_sdwa v93, v117, v177 dst_sel:DWORD dst_unused:UNUSED_PAD src0_sel:WORD_1 src1_sel:DWORD
	v_and_b32_sdwa v96, v115, v177 dst_sel:DWORD dst_unused:UNUSED_PAD src0_sel:WORD_1 src1_sel:DWORD
	v_and_b32_sdwa v92, v116, v177 dst_sel:DWORD dst_unused:UNUSED_PAD src0_sel:WORD_1 src1_sel:DWORD
	v_add3_u32 v93, v117, v93, s28
	v_add3_u32 v96, v115, v96, s28
	v_add3_u32 v92, v116, v92, s28
	v_and_b32_e32 v93, 0xffff0000, v93
	v_and_b32_e32 v96, 0xffff0000, v96
	v_or_b32_sdwa v93, v93, v92 dst_sel:DWORD dst_unused:UNUSED_PAD src0_sel:DWORD src1_sel:WORD_1
	v_or_b32_sdwa v92, v96, v95 dst_sel:DWORD dst_unused:UNUSED_PAD src0_sel:DWORD src1_sel:WORD_1
	global_store_dwordx2 v[90:91], v[92:93], off offset:64
	v_and_b32_sdwa v92, v84, v177 dst_sel:DWORD dst_unused:UNUSED_PAD src0_sel:WORD_1 src1_sel:DWORD
	v_and_b32_sdwa v93, v82, v177 dst_sel:DWORD dst_unused:UNUSED_PAD src0_sel:WORD_1 src1_sel:DWORD
	v_add3_u32 v82, v82, v93, s28
	v_add3_u32 v84, v84, v92, s28
	v_and_b32_sdwa v92, v85, v177 dst_sel:DWORD dst_unused:UNUSED_PAD src0_sel:WORD_1 src1_sel:DWORD
	v_and_b32_sdwa v93, v83, v177 dst_sel:DWORD dst_unused:UNUSED_PAD src0_sel:WORD_1 src1_sel:DWORD
	v_add3_u32 v85, v85, v92, s28
	v_add3_u32 v83, v83, v93, s28
	v_and_b32_e32 v85, 0xffff0000, v85
	v_and_b32_e32 v92, 0xffff0000, v83
	v_or_b32_sdwa v83, v85, v84 dst_sel:DWORD dst_unused:UNUSED_PAD src0_sel:DWORD src1_sel:WORD_1
	v_or_b32_sdwa v82, v92, v82 dst_sel:DWORD dst_unused:UNUSED_PAD src0_sel:DWORD src1_sel:WORD_1
	global_store_dwordx2 v[90:91], v[82:83], off offset:96
	v_and_b32_sdwa v82, v80, v177 dst_sel:DWORD dst_unused:UNUSED_PAD src0_sel:WORD_1 src1_sel:DWORD
	v_and_b32_sdwa v83, v78, v177 dst_sel:DWORD dst_unused:UNUSED_PAD src0_sel:WORD_1 src1_sel:DWORD
	v_add3_u32 v78, v78, v83, s28
	v_add3_u32 v80, v80, v82, s28
	v_and_b32_sdwa v82, v81, v177 dst_sel:DWORD dst_unused:UNUSED_PAD src0_sel:WORD_1 src1_sel:DWORD
	v_and_b32_sdwa v83, v79, v177 dst_sel:DWORD dst_unused:UNUSED_PAD src0_sel:WORD_1 src1_sel:DWORD
	v_add3_u32 v81, v81, v82, s28
	v_add3_u32 v79, v79, v83, s28
	v_and_b32_e32 v81, 0xffff0000, v81
	v_and_b32_e32 v82, 0xffff0000, v79
	v_or_b32_sdwa v79, v81, v80 dst_sel:DWORD dst_unused:UNUSED_PAD src0_sel:DWORD src1_sel:WORD_1
	v_or_b32_sdwa v78, v82, v78 dst_sel:DWORD dst_unused:UNUSED_PAD src0_sel:DWORD src1_sel:WORD_1
	global_store_dwordx2 v[90:91], v[78:79], off offset:128
	v_and_b32_sdwa v78, v76, v177 dst_sel:DWORD dst_unused:UNUSED_PAD src0_sel:WORD_1 src1_sel:DWORD
	v_and_b32_sdwa v79, v74, v177 dst_sel:DWORD dst_unused:UNUSED_PAD src0_sel:WORD_1 src1_sel:DWORD
	v_add3_u32 v74, v74, v79, s28
	v_add3_u32 v76, v76, v78, s28
	v_and_b32_sdwa v78, v77, v177 dst_sel:DWORD dst_unused:UNUSED_PAD src0_sel:WORD_1 src1_sel:DWORD
	v_and_b32_sdwa v79, v75, v177 dst_sel:DWORD dst_unused:UNUSED_PAD src0_sel:WORD_1 src1_sel:DWORD
	v_add3_u32 v77, v77, v78, s28
	v_add3_u32 v75, v75, v79, s28
	v_and_b32_e32 v77, 0xffff0000, v77
	v_and_b32_e32 v78, 0xffff0000, v75
	v_or_b32_sdwa v75, v77, v76 dst_sel:DWORD dst_unused:UNUSED_PAD src0_sel:DWORD src1_sel:WORD_1
	v_or_b32_sdwa v74, v78, v74 dst_sel:DWORD dst_unused:UNUSED_PAD src0_sel:DWORD src1_sel:WORD_1
	global_store_dwordx2 v[90:91], v[74:75], off offset:160
	v_and_b32_sdwa v74, v72, v177 dst_sel:DWORD dst_unused:UNUSED_PAD src0_sel:WORD_1 src1_sel:DWORD
	v_and_b32_sdwa v75, v70, v177 dst_sel:DWORD dst_unused:UNUSED_PAD src0_sel:WORD_1 src1_sel:DWORD
	v_add3_u32 v70, v70, v75, s28
	v_add3_u32 v72, v72, v74, s28
	v_and_b32_sdwa v74, v73, v177 dst_sel:DWORD dst_unused:UNUSED_PAD src0_sel:WORD_1 src1_sel:DWORD
	v_and_b32_sdwa v75, v71, v177 dst_sel:DWORD dst_unused:UNUSED_PAD src0_sel:WORD_1 src1_sel:DWORD
	v_add3_u32 v73, v73, v74, s28
	v_add3_u32 v71, v71, v75, s28
	v_and_b32_e32 v73, 0xffff0000, v73
	v_and_b32_e32 v74, 0xffff0000, v71
	v_or_b32_sdwa v71, v73, v72 dst_sel:DWORD dst_unused:UNUSED_PAD src0_sel:DWORD src1_sel:WORD_1
	v_or_b32_sdwa v70, v74, v70 dst_sel:DWORD dst_unused:UNUSED_PAD src0_sel:DWORD src1_sel:WORD_1
	global_store_dwordx2 v[90:91], v[70:71], off offset:192
	v_and_b32_sdwa v70, v64, v177 dst_sel:DWORD dst_unused:UNUSED_PAD src0_sel:WORD_1 src1_sel:DWORD
	v_and_b32_sdwa v71, v62, v177 dst_sel:DWORD dst_unused:UNUSED_PAD src0_sel:WORD_1 src1_sel:DWORD
	v_add3_u32 v64, v64, v70, s28
	v_and_b32_sdwa v70, v65, v177 dst_sel:DWORD dst_unused:UNUSED_PAD src0_sel:WORD_1 src1_sel:DWORD
	v_add3_u32 v62, v62, v71, s28
	v_and_b32_sdwa v71, v63, v177 dst_sel:DWORD dst_unused:UNUSED_PAD src0_sel:WORD_1 src1_sel:DWORD
	v_add3_u32 v65, v65, v70, s28
	v_add3_u32 v63, v63, v71, s28
	v_and_b32_e32 v65, 0xffff0000, v65
	v_and_b32_e32 v70, 0xffff0000, v63
	v_or_b32_sdwa v63, v65, v64 dst_sel:DWORD dst_unused:UNUSED_PAD src0_sel:DWORD src1_sel:WORD_1
	v_and_b32_sdwa v64, v68, v177 dst_sel:DWORD dst_unused:UNUSED_PAD src0_sel:WORD_1 src1_sel:DWORD
	v_and_b32_sdwa v65, v66, v177 dst_sel:DWORD dst_unused:UNUSED_PAD src0_sel:WORD_1 src1_sel:DWORD
	v_or_b32_sdwa v62, v70, v62 dst_sel:DWORD dst_unused:UNUSED_PAD src0_sel:DWORD src1_sel:WORD_1
	v_add3_u32 v66, v66, v65, s28
	v_add3_u32 v64, v68, v64, s28
	v_and_b32_sdwa v65, v69, v177 dst_sel:DWORD dst_unused:UNUSED_PAD src0_sel:WORD_1 src1_sel:DWORD
	v_and_b32_sdwa v68, v67, v177 dst_sel:DWORD dst_unused:UNUSED_PAD src0_sel:WORD_1 src1_sel:DWORD
	global_store_dwordx2 v[90:91], v[62:63], off offset:224
	v_or_b32_e32 v62, 32, v94
	v_add3_u32 v65, v69, v65, s28
	v_add3_u32 v67, v67, v68, s28
	v_mad_i64_i32 v[62:63], s[6:7], v62, s8, v[86:87]
	v_and_b32_e32 v65, 0xffff0000, v65
	v_and_b32_e32 v67, 0xffff0000, v67
	v_lshl_add_u64 v[62:63], v[62:63], 0, v[88:89]
	v_or_b32_sdwa v65, v65, v64 dst_sel:DWORD dst_unused:UNUSED_PAD src0_sel:DWORD src1_sel:WORD_1
	v_or_b32_sdwa v64, v67, v66 dst_sel:DWORD dst_unused:UNUSED_PAD src0_sel:DWORD src1_sel:WORD_1
	global_store_dwordx2 v[62:63], v[64:65], off
	v_and_b32_sdwa v64, v60, v177 dst_sel:DWORD dst_unused:UNUSED_PAD src0_sel:WORD_1 src1_sel:DWORD
	v_and_b32_sdwa v65, v58, v177 dst_sel:DWORD dst_unused:UNUSED_PAD src0_sel:WORD_1 src1_sel:DWORD
	v_add3_u32 v58, v58, v65, s28
	v_add3_u32 v60, v60, v64, s28
	v_and_b32_sdwa v64, v61, v177 dst_sel:DWORD dst_unused:UNUSED_PAD src0_sel:WORD_1 src1_sel:DWORD
	v_and_b32_sdwa v65, v59, v177 dst_sel:DWORD dst_unused:UNUSED_PAD src0_sel:WORD_1 src1_sel:DWORD
	v_add3_u32 v61, v61, v64, s28
	v_add3_u32 v59, v59, v65, s28
	v_and_b32_e32 v61, 0xffff0000, v61
	v_and_b32_e32 v64, 0xffff0000, v59
	v_or_b32_sdwa v59, v61, v60 dst_sel:DWORD dst_unused:UNUSED_PAD src0_sel:DWORD src1_sel:WORD_1
	v_or_b32_sdwa v58, v64, v58 dst_sel:DWORD dst_unused:UNUSED_PAD src0_sel:DWORD src1_sel:WORD_1
	global_store_dwordx2 v[62:63], v[58:59], off offset:32
	v_and_b32_sdwa v58, v56, v177 dst_sel:DWORD dst_unused:UNUSED_PAD src0_sel:WORD_1 src1_sel:DWORD
	v_and_b32_sdwa v59, v54, v177 dst_sel:DWORD dst_unused:UNUSED_PAD src0_sel:WORD_1 src1_sel:DWORD
	v_add3_u32 v54, v54, v59, s28
	v_add3_u32 v56, v56, v58, s28
	v_and_b32_sdwa v58, v57, v177 dst_sel:DWORD dst_unused:UNUSED_PAD src0_sel:WORD_1 src1_sel:DWORD
	v_and_b32_sdwa v59, v55, v177 dst_sel:DWORD dst_unused:UNUSED_PAD src0_sel:WORD_1 src1_sel:DWORD
	v_add3_u32 v57, v57, v58, s28
	v_add3_u32 v55, v55, v59, s28
	v_and_b32_e32 v57, 0xffff0000, v57
	v_and_b32_e32 v58, 0xffff0000, v55
	v_or_b32_sdwa v55, v57, v56 dst_sel:DWORD dst_unused:UNUSED_PAD src0_sel:DWORD src1_sel:WORD_1
	v_or_b32_sdwa v54, v58, v54 dst_sel:DWORD dst_unused:UNUSED_PAD src0_sel:DWORD src1_sel:WORD_1
	global_store_dwordx2 v[62:63], v[54:55], off offset:64
	v_and_b32_sdwa v54, v52, v177 dst_sel:DWORD dst_unused:UNUSED_PAD src0_sel:WORD_1 src1_sel:DWORD
	v_and_b32_sdwa v55, v50, v177 dst_sel:DWORD dst_unused:UNUSED_PAD src0_sel:WORD_1 src1_sel:DWORD
	v_add3_u32 v50, v50, v55, s28
	v_add3_u32 v52, v52, v54, s28
	v_and_b32_sdwa v54, v53, v177 dst_sel:DWORD dst_unused:UNUSED_PAD src0_sel:WORD_1 src1_sel:DWORD
	v_and_b32_sdwa v55, v51, v177 dst_sel:DWORD dst_unused:UNUSED_PAD src0_sel:WORD_1 src1_sel:DWORD
	v_add3_u32 v53, v53, v54, s28
	v_add3_u32 v51, v51, v55, s28
	v_and_b32_e32 v53, 0xffff0000, v53
	v_and_b32_e32 v54, 0xffff0000, v51
	v_or_b32_sdwa v51, v53, v52 dst_sel:DWORD dst_unused:UNUSED_PAD src0_sel:DWORD src1_sel:WORD_1
	v_or_b32_sdwa v50, v54, v50 dst_sel:DWORD dst_unused:UNUSED_PAD src0_sel:DWORD src1_sel:WORD_1
	global_store_dwordx2 v[62:63], v[50:51], off offset:96
	v_and_b32_sdwa v50, v48, v177 dst_sel:DWORD dst_unused:UNUSED_PAD src0_sel:WORD_1 src1_sel:DWORD
	v_and_b32_sdwa v51, v46, v177 dst_sel:DWORD dst_unused:UNUSED_PAD src0_sel:WORD_1 src1_sel:DWORD
	v_add3_u32 v46, v46, v51, s28
	v_add3_u32 v48, v48, v50, s28
	v_and_b32_sdwa v50, v49, v177 dst_sel:DWORD dst_unused:UNUSED_PAD src0_sel:WORD_1 src1_sel:DWORD
	v_and_b32_sdwa v51, v47, v177 dst_sel:DWORD dst_unused:UNUSED_PAD src0_sel:WORD_1 src1_sel:DWORD
	v_add3_u32 v49, v49, v50, s28
	v_add3_u32 v47, v47, v51, s28
	v_and_b32_e32 v49, 0xffff0000, v49
	v_and_b32_e32 v50, 0xffff0000, v47
	v_or_b32_sdwa v47, v49, v48 dst_sel:DWORD dst_unused:UNUSED_PAD src0_sel:DWORD src1_sel:WORD_1
	v_or_b32_sdwa v46, v50, v46 dst_sel:DWORD dst_unused:UNUSED_PAD src0_sel:DWORD src1_sel:WORD_1
	global_store_dwordx2 v[62:63], v[46:47], off offset:128
	v_and_b32_sdwa v46, v44, v177 dst_sel:DWORD dst_unused:UNUSED_PAD src0_sel:WORD_1 src1_sel:DWORD
	v_and_b32_sdwa v47, v42, v177 dst_sel:DWORD dst_unused:UNUSED_PAD src0_sel:WORD_1 src1_sel:DWORD
	v_add3_u32 v42, v42, v47, s28
	v_add3_u32 v44, v44, v46, s28
	v_and_b32_sdwa v46, v45, v177 dst_sel:DWORD dst_unused:UNUSED_PAD src0_sel:WORD_1 src1_sel:DWORD
	v_and_b32_sdwa v47, v43, v177 dst_sel:DWORD dst_unused:UNUSED_PAD src0_sel:WORD_1 src1_sel:DWORD
	v_add3_u32 v45, v45, v46, s28
	v_add3_u32 v43, v43, v47, s28
	v_and_b32_e32 v45, 0xffff0000, v45
	v_and_b32_e32 v46, 0xffff0000, v43
	v_or_b32_sdwa v43, v45, v44 dst_sel:DWORD dst_unused:UNUSED_PAD src0_sel:DWORD src1_sel:WORD_1
	v_or_b32_sdwa v42, v46, v42 dst_sel:DWORD dst_unused:UNUSED_PAD src0_sel:DWORD src1_sel:WORD_1
	global_store_dwordx2 v[62:63], v[42:43], off offset:160
	v_and_b32_sdwa v42, v40, v177 dst_sel:DWORD dst_unused:UNUSED_PAD src0_sel:WORD_1 src1_sel:DWORD
	v_and_b32_sdwa v43, v38, v177 dst_sel:DWORD dst_unused:UNUSED_PAD src0_sel:WORD_1 src1_sel:DWORD
	v_add3_u32 v38, v38, v43, s28
	v_add3_u32 v40, v40, v42, s28
	v_and_b32_sdwa v42, v41, v177 dst_sel:DWORD dst_unused:UNUSED_PAD src0_sel:WORD_1 src1_sel:DWORD
	v_and_b32_sdwa v43, v39, v177 dst_sel:DWORD dst_unused:UNUSED_PAD src0_sel:WORD_1 src1_sel:DWORD
	v_add3_u32 v41, v41, v42, s28
	v_add3_u32 v39, v39, v43, s28
	v_and_b32_e32 v41, 0xffff0000, v41
	v_and_b32_e32 v42, 0xffff0000, v39
	v_or_b32_sdwa v39, v41, v40 dst_sel:DWORD dst_unused:UNUSED_PAD src0_sel:DWORD src1_sel:WORD_1
	v_or_b32_sdwa v38, v42, v38 dst_sel:DWORD dst_unused:UNUSED_PAD src0_sel:DWORD src1_sel:WORD_1
	global_store_dwordx2 v[62:63], v[38:39], off offset:192
	v_and_b32_sdwa v38, v32, v177 dst_sel:DWORD dst_unused:UNUSED_PAD src0_sel:WORD_1 src1_sel:DWORD
	v_and_b32_sdwa v39, v30, v177 dst_sel:DWORD dst_unused:UNUSED_PAD src0_sel:WORD_1 src1_sel:DWORD
	v_add3_u32 v32, v32, v38, s28
	v_and_b32_sdwa v38, v33, v177 dst_sel:DWORD dst_unused:UNUSED_PAD src0_sel:WORD_1 src1_sel:DWORD
	v_add3_u32 v30, v30, v39, s28
	v_and_b32_sdwa v39, v31, v177 dst_sel:DWORD dst_unused:UNUSED_PAD src0_sel:WORD_1 src1_sel:DWORD
	v_add3_u32 v33, v33, v38, s28
	v_add3_u32 v31, v31, v39, s28
	v_and_b32_e32 v33, 0xffff0000, v33
	v_and_b32_e32 v38, 0xffff0000, v31
	v_or_b32_sdwa v31, v33, v32 dst_sel:DWORD dst_unused:UNUSED_PAD src0_sel:DWORD src1_sel:WORD_1
	v_and_b32_sdwa v32, v36, v177 dst_sel:DWORD dst_unused:UNUSED_PAD src0_sel:WORD_1 src1_sel:DWORD
	v_and_b32_sdwa v33, v34, v177 dst_sel:DWORD dst_unused:UNUSED_PAD src0_sel:WORD_1 src1_sel:DWORD
	v_or_b32_sdwa v30, v38, v30 dst_sel:DWORD dst_unused:UNUSED_PAD src0_sel:DWORD src1_sel:WORD_1
	v_add3_u32 v34, v34, v33, s28
	v_add3_u32 v32, v36, v32, s28
	v_and_b32_sdwa v33, v37, v177 dst_sel:DWORD dst_unused:UNUSED_PAD src0_sel:WORD_1 src1_sel:DWORD
	v_and_b32_sdwa v36, v35, v177 dst_sel:DWORD dst_unused:UNUSED_PAD src0_sel:WORD_1 src1_sel:DWORD
	global_store_dwordx2 v[62:63], v[30:31], off offset:224
	v_or_b32_e32 v30, 48, v94
	v_add3_u32 v33, v37, v33, s28
	v_add3_u32 v35, v35, v36, s28
	v_mad_i64_i32 v[30:31], s[6:7], v30, s8, v[86:87]
	v_and_b32_e32 v33, 0xffff0000, v33
	v_and_b32_e32 v35, 0xffff0000, v35
	v_lshl_add_u64 v[30:31], v[30:31], 0, v[88:89]
	v_or_b32_sdwa v33, v33, v32 dst_sel:DWORD dst_unused:UNUSED_PAD src0_sel:DWORD src1_sel:WORD_1
	v_or_b32_sdwa v32, v35, v34 dst_sel:DWORD dst_unused:UNUSED_PAD src0_sel:DWORD src1_sel:WORD_1
	global_store_dwordx2 v[30:31], v[32:33], off
	v_and_b32_sdwa v32, v28, v177 dst_sel:DWORD dst_unused:UNUSED_PAD src0_sel:WORD_1 src1_sel:DWORD
	v_and_b32_sdwa v33, v26, v177 dst_sel:DWORD dst_unused:UNUSED_PAD src0_sel:WORD_1 src1_sel:DWORD
	v_add3_u32 v26, v26, v33, s28
	v_add3_u32 v28, v28, v32, s28
	v_and_b32_sdwa v32, v29, v177 dst_sel:DWORD dst_unused:UNUSED_PAD src0_sel:WORD_1 src1_sel:DWORD
	v_and_b32_sdwa v33, v27, v177 dst_sel:DWORD dst_unused:UNUSED_PAD src0_sel:WORD_1 src1_sel:DWORD
	v_add3_u32 v29, v29, v32, s28
	v_add3_u32 v27, v27, v33, s28
	v_and_b32_e32 v29, 0xffff0000, v29
	v_and_b32_e32 v32, 0xffff0000, v27
	v_or_b32_sdwa v27, v29, v28 dst_sel:DWORD dst_unused:UNUSED_PAD src0_sel:DWORD src1_sel:WORD_1
	v_or_b32_sdwa v26, v32, v26 dst_sel:DWORD dst_unused:UNUSED_PAD src0_sel:DWORD src1_sel:WORD_1
	global_store_dwordx2 v[30:31], v[26:27], off offset:32
	v_and_b32_sdwa v26, v24, v177 dst_sel:DWORD dst_unused:UNUSED_PAD src0_sel:WORD_1 src1_sel:DWORD
	v_and_b32_sdwa v27, v22, v177 dst_sel:DWORD dst_unused:UNUSED_PAD src0_sel:WORD_1 src1_sel:DWORD
	v_add3_u32 v22, v22, v27, s28
	v_add3_u32 v24, v24, v26, s28
	v_and_b32_sdwa v26, v25, v177 dst_sel:DWORD dst_unused:UNUSED_PAD src0_sel:WORD_1 src1_sel:DWORD
	v_and_b32_sdwa v27, v23, v177 dst_sel:DWORD dst_unused:UNUSED_PAD src0_sel:WORD_1 src1_sel:DWORD
	v_add3_u32 v25, v25, v26, s28
	v_add3_u32 v23, v23, v27, s28
	v_and_b32_e32 v25, 0xffff0000, v25
	v_and_b32_e32 v26, 0xffff0000, v23
	v_or_b32_sdwa v23, v25, v24 dst_sel:DWORD dst_unused:UNUSED_PAD src0_sel:DWORD src1_sel:WORD_1
	v_or_b32_sdwa v22, v26, v22 dst_sel:DWORD dst_unused:UNUSED_PAD src0_sel:DWORD src1_sel:WORD_1
	global_store_dwordx2 v[30:31], v[22:23], off offset:64
	v_and_b32_sdwa v22, v20, v177 dst_sel:DWORD dst_unused:UNUSED_PAD src0_sel:WORD_1 src1_sel:DWORD
	v_and_b32_sdwa v23, v18, v177 dst_sel:DWORD dst_unused:UNUSED_PAD src0_sel:WORD_1 src1_sel:DWORD
	v_add3_u32 v18, v18, v23, s28
	v_add3_u32 v20, v20, v22, s28
	v_and_b32_sdwa v22, v21, v177 dst_sel:DWORD dst_unused:UNUSED_PAD src0_sel:WORD_1 src1_sel:DWORD
	v_and_b32_sdwa v23, v19, v177 dst_sel:DWORD dst_unused:UNUSED_PAD src0_sel:WORD_1 src1_sel:DWORD
	v_add3_u32 v21, v21, v22, s28
	v_add3_u32 v19, v19, v23, s28
	v_and_b32_e32 v21, 0xffff0000, v21
	v_and_b32_e32 v22, 0xffff0000, v19
	v_or_b32_sdwa v19, v21, v20 dst_sel:DWORD dst_unused:UNUSED_PAD src0_sel:DWORD src1_sel:WORD_1
	v_or_b32_sdwa v18, v22, v18 dst_sel:DWORD dst_unused:UNUSED_PAD src0_sel:DWORD src1_sel:WORD_1
	global_store_dwordx2 v[30:31], v[18:19], off offset:96
	v_and_b32_sdwa v18, v16, v177 dst_sel:DWORD dst_unused:UNUSED_PAD src0_sel:WORD_1 src1_sel:DWORD
	v_and_b32_sdwa v19, v14, v177 dst_sel:DWORD dst_unused:UNUSED_PAD src0_sel:WORD_1 src1_sel:DWORD
	v_add3_u32 v14, v14, v19, s28
	v_add3_u32 v16, v16, v18, s28
	v_and_b32_sdwa v18, v17, v177 dst_sel:DWORD dst_unused:UNUSED_PAD src0_sel:WORD_1 src1_sel:DWORD
	v_and_b32_sdwa v19, v15, v177 dst_sel:DWORD dst_unused:UNUSED_PAD src0_sel:WORD_1 src1_sel:DWORD
	v_add3_u32 v17, v17, v18, s28
	v_add3_u32 v15, v15, v19, s28
	v_and_b32_e32 v17, 0xffff0000, v17
	v_and_b32_e32 v18, 0xffff0000, v15
	v_or_b32_sdwa v15, v17, v16 dst_sel:DWORD dst_unused:UNUSED_PAD src0_sel:DWORD src1_sel:WORD_1
	v_or_b32_sdwa v14, v18, v14 dst_sel:DWORD dst_unused:UNUSED_PAD src0_sel:DWORD src1_sel:WORD_1
	global_store_dwordx2 v[30:31], v[14:15], off offset:128
	v_and_b32_sdwa v14, v12, v177 dst_sel:DWORD dst_unused:UNUSED_PAD src0_sel:WORD_1 src1_sel:DWORD
	v_and_b32_sdwa v15, v10, v177 dst_sel:DWORD dst_unused:UNUSED_PAD src0_sel:WORD_1 src1_sel:DWORD
	v_add3_u32 v10, v10, v15, s28
	v_add3_u32 v12, v12, v14, s28
	v_and_b32_sdwa v14, v13, v177 dst_sel:DWORD dst_unused:UNUSED_PAD src0_sel:WORD_1 src1_sel:DWORD
	v_and_b32_sdwa v15, v11, v177 dst_sel:DWORD dst_unused:UNUSED_PAD src0_sel:WORD_1 src1_sel:DWORD
	v_add3_u32 v13, v13, v14, s28
	v_add3_u32 v11, v11, v15, s28
	v_and_b32_e32 v13, 0xffff0000, v13
	v_and_b32_e32 v14, 0xffff0000, v11
	v_or_b32_sdwa v11, v13, v12 dst_sel:DWORD dst_unused:UNUSED_PAD src0_sel:DWORD src1_sel:WORD_1
	v_or_b32_sdwa v10, v14, v10 dst_sel:DWORD dst_unused:UNUSED_PAD src0_sel:DWORD src1_sel:WORD_1
	global_store_dwordx2 v[30:31], v[10:11], off offset:160
	v_and_b32_sdwa v10, v8, v177 dst_sel:DWORD dst_unused:UNUSED_PAD src0_sel:WORD_1 src1_sel:DWORD
	v_and_b32_sdwa v11, v6, v177 dst_sel:DWORD dst_unused:UNUSED_PAD src0_sel:WORD_1 src1_sel:DWORD
	v_add3_u32 v6, v6, v11, s28
	v_add3_u32 v8, v8, v10, s28
	v_and_b32_sdwa v10, v9, v177 dst_sel:DWORD dst_unused:UNUSED_PAD src0_sel:WORD_1 src1_sel:DWORD
	v_and_b32_sdwa v11, v7, v177 dst_sel:DWORD dst_unused:UNUSED_PAD src0_sel:WORD_1 src1_sel:DWORD
	v_add3_u32 v9, v9, v10, s28
	v_add3_u32 v7, v7, v11, s28
	v_and_b32_e32 v9, 0xffff0000, v9
	v_and_b32_e32 v10, 0xffff0000, v7
	v_or_b32_sdwa v7, v9, v8 dst_sel:DWORD dst_unused:UNUSED_PAD src0_sel:DWORD src1_sel:WORD_1
	v_or_b32_sdwa v6, v10, v6 dst_sel:DWORD dst_unused:UNUSED_PAD src0_sel:DWORD src1_sel:WORD_1
	global_store_dwordx2 v[30:31], v[6:7], off offset:192
	v_and_b32_sdwa v6, v4, v177 dst_sel:DWORD dst_unused:UNUSED_PAD src0_sel:WORD_1 src1_sel:DWORD
	v_and_b32_sdwa v7, v2, v177 dst_sel:DWORD dst_unused:UNUSED_PAD src0_sel:WORD_1 src1_sel:DWORD
	v_add3_u32 v2, v2, v7, s28
	v_add3_u32 v4, v4, v6, s28
	v_and_b32_sdwa v6, v5, v177 dst_sel:DWORD dst_unused:UNUSED_PAD src0_sel:WORD_1 src1_sel:DWORD
	v_and_b32_sdwa v7, v3, v177 dst_sel:DWORD dst_unused:UNUSED_PAD src0_sel:WORD_1 src1_sel:DWORD
	v_add3_u32 v5, v5, v6, s28
	v_add3_u32 v3, v3, v7, s28
	v_and_b32_e32 v5, 0xffff0000, v5
	v_and_b32_e32 v6, 0xffff0000, v3
	s_add_i32 s11, s11, s10
	v_or_b32_sdwa v3, v5, v4 dst_sel:DWORD dst_unused:UNUSED_PAD src0_sel:DWORD src1_sel:WORD_1
	v_or_b32_sdwa v2, v6, v2 dst_sel:DWORD dst_unused:UNUSED_PAD src0_sel:DWORD src1_sel:WORD_1
	s_cmpk_gt_i32 s11, 0x3ef
	global_store_dwordx2 v[30:31], v[2:3], off offset:224
	s_cbranch_scc0 .LBB0_664

.LBB0_1305:
	s_or_b64 exec, exec, s[12:13]
	s_mov_b64 s[6:7], s[60:61]
	s_waitcnt lgkmcnt(0)
	s_barrier
	s_load_dwordx4 s[44:47], s[6:7], 0x128
	v_readlane_b32 s2, v255, 48
	v_readlane_b32 s3, v255, 49
	v_mov_b32_e32 v2, v172
	s_mov_b32 s18, s42
	s_waitcnt lgkmcnt(0)
	s_add_u32 s12, s46, 0x2a00000
	s_addc_u32 s13, s47, 0
	s_add_u32 s2, s46, s2
	s_addc_u32 s3, s47, s3
	s_add_u32 s14, s2, 0x5605000
	s_addc_u32 s15, s3, 0
	s_add_u32 s16, s46, 0x3200000
	s_addc_u32 s17, s47, 0
	s_add_u32 s48, s46, 0x2800000
	s_addc_u32 s49, s47, 0
	s_mov_b32 s19, s94
	s_cmpk_gt_i32 s19, 0xff
	s_cbranch_scc1 .LBB0_1310
	v_ashrrev_i32_e32 v204, 3, v2
	v_and_b32_e32 v205, 15, v2
	v_bfe_u32 v3, v2, 4, 2
	v_lshlrev_b32_e32 v0, 4, v2
	v_ashrrev_i32_e32 v4, 1, v2
	v_lshlrev_b32_e32 v2, 1, v2
	v_and_b32_e32 v0, 0x70, v0
	v_and_b32_e32 v206, 0xffffffc0, v4
	v_and_b32_e32 v2, 0x80, v2
	s_movk_i32 s2, 0x90
	v_or_b32_e32 v4, v206, v205
	v_or_b32_e32 v5, v2, v205
	v_and_b32_e32 v100, 7, v204
	v_lshlrev_b32_e32 v100, 4, v100
	v_xor_b32_e32 v100, v100, v0
	v_lshl_add_u32 v166, v204, 7, v100
	v_lshl_add_u64 v[162:163], s[16:17], 0, v[0:1]
	v_lshl_add_u64 v[164:165], s[48:49], 0, v[0:1]
	v_and_b32_e32 v100, 7, v205
	v_xor_b32_e32 v100, v100, v3
	v_lshlrev_b32_e32 v207, 4, v100
	v_lshl_or_b32 v208, v3, 2, v2
	v_lshlrev_b32_e32 v0, 7, v4
	v_lshlrev_b32_e32 v167, 7, v5
.LBB0_1307:
	s_ashr_i32 s2, s19, 31
	s_lshr_b32 s2, s2, 26
	s_add_i32 s2, s19, s2
	s_and_b32 s3, s2, 0xffffc0
	s_sub_i32 s3, s19, s3
	s_lshl_b32 s7, s3, 8
	v_add_u32_e32 v2, s7, v204
	v_ashrrev_i32_e32 v3, 31, v2
	v_lshlrev_b64 v[2:3], 11, v[2:3]
	v_lshl_add_u64 v[168:169], v[162:163], 0, v[2:3]
	s_lshl_b32 s2, s2, 2
	v_add_co_u32_e32 v56, vcc, s34, v168
	s_and_b32 s6, s2, 0xffffff00
	s_nop 0
	v_addc_co_u32_e32 v57, vcc, 0, v169, vcc
	v_add_u32_e32 v2, s6, v204
	v_add_co_u32_e32 v58, vcc, s35, v168
	v_ashrrev_i32_e32 v3, 31, v2
	s_nop 0
	v_addc_co_u32_e32 v59, vcc, 0, v169, vcc
	v_add_co_u32_e32 v60, vcc, s36, v168
	v_lshlrev_b64 v[2:3], 11, v[2:3]
	s_nop 0
	v_addc_co_u32_e32 v61, vcc, 0, v169, vcc
	v_lshl_add_u64 v[170:171], v[164:165], 0, v[2:3]
	v_add_co_u32_e32 v62, vcc, s35, v170
	global_load_dwordx4 v[24:27], v[56:57], off
	global_load_dwordx4 v[28:31], v[58:59], off
	v_addc_co_u32_e32 v63, vcc, 0, v171, vcc
	v_add_co_u32_e32 v64, vcc, s36, v170
	global_load_dwordx4 v[32:35], v[168:169], off
	global_load_dwordx4 v[36:39], v[170:171], off
	v_addc_co_u32_e32 v65, vcc, 0, v171, vcc
	v_add_co_u32_e32 v66, vcc, s34, v170
	global_load_dwordx4 v[40:43], v[62:63], off
	global_load_dwordx4 v[44:47], v[64:65], off
	v_addc_co_u32_e32 v67, vcc, 0, v171, vcc
	global_load_dwordx4 v[48:51], v[60:61], off
	global_load_dwordx4 v[52:55], v[66:67], off
	s_barrier
	global_load_dwordx4 v[118:121], v[168:169], off offset:128
	global_load_dwordx4 v[110:113], v[56:57], off offset:128
	global_load_dwordx4 v[114:117], v[58:59], off offset:128
	global_load_dwordx4 v[130:133], v[60:61], off offset:128
	global_load_dwordx4 v[126:129], v[170:171], off offset:128
	global_load_dwordx4 v[122:125], v[66:67], off offset:128
	global_load_dwordx4 v[138:141], v[62:63], off offset:128
	global_load_dwordx4 v[134:137], v[64:65], off offset:128
	v_readfirstlane_b32 vcc_lo, v168
	v_readfirstlane_b32 vcc_hi, v169
	v_readfirstlane_b32 s100, v170
	v_readfirstlane_b32 s101, v171
	s_nop 1
	v_subrev_u32_e32 v168, vcc_lo, v168
	v_subrev_u32_e32 v170, s100, v170
	v_mov_b32_e32 v2, 0
	s_mov_b32 s4, 0
	v_mov_b32_e32 v3, v2
	v_mov_b32_e32 v4, v2
	v_mov_b32_e32 v5, v2
	v_mov_b32_e32 v6, v2
	v_mov_b32_e32 v7, v2
	v_mov_b32_e32 v8, v2
	v_mov_b32_e32 v9, v2
	v_mov_b32_e32 v10, v2
	v_mov_b32_e32 v11, v2
	v_mov_b32_e32 v12, v2
	v_mov_b32_e32 v13, v2
	v_mov_b32_e32 v14, v2
	v_mov_b32_e32 v15, v2
	v_mov_b32_e32 v16, v2
	v_mov_b32_e32 v17, v2
	v_mov_b32_e32 v18, v2
	v_mov_b32_e32 v19, v2
	v_mov_b32_e32 v20, v2
	v_mov_b32_e32 v21, v2
	v_mov_b32_e32 v22, v2
	v_mov_b32_e32 v23, v2
	v_mov_b32_e32 v56, v2
	v_mov_b32_e32 v57, v2
	v_mov_b32_e32 v58, v2
	v_mov_b32_e32 v59, v2
	v_mov_b32_e32 v60, v2
	v_mov_b32_e32 v61, v2
	v_mov_b32_e32 v66, v2
	v_mov_b32_e32 v67, v2
	v_mov_b32_e32 v68, v2
	v_mov_b32_e32 v69, v2
	v_mov_b32_e32 v62, v2
	v_mov_b32_e32 v63, v2
	v_mov_b32_e32 v64, v2
	v_mov_b32_e32 v65, v2
	v_mov_b32_e32 v70, v2
	v_mov_b32_e32 v71, v2
	v_mov_b32_e32 v72, v2
	v_mov_b32_e32 v73, v2
	v_mov_b32_e32 v74, v2
	v_mov_b32_e32 v75, v2
	v_mov_b32_e32 v76, v2
	v_mov_b32_e32 v77, v2
	v_mov_b32_e32 v78, v2
	v_mov_b32_e32 v79, v2
	v_mov_b32_e32 v80, v2
	v_mov_b32_e32 v81, v2
	v_mov_b32_e32 v82, v2
	v_mov_b32_e32 v83, v2
	v_mov_b32_e32 v84, v2
	v_mov_b32_e32 v85, v2
	s_waitcnt vmcnt(13)
	ds_write_b128 v166, v[32:35]
	s_waitcnt vmcnt(12)
	ds_write_b128 v166, v[36:39] offset:32768
	s_waitcnt vmcnt(11)
	ds_write_b128 v166, v[40:43] offset:49152
	s_waitcnt vmcnt(10)
	ds_write_b128 v166, v[44:47] offset:57344
	ds_write_b128 v166, v[24:27] offset:8192
	ds_write_b128 v166, v[28:31] offset:16384
	s_waitcnt vmcnt(9)
	ds_write_b128 v166, v[48:51] offset:24576
	s_waitcnt vmcnt(8)
	ds_write_b128 v166, v[52:55] offset:40960
	v_mov_b32_e32 v24, v2
	v_mov_b32_e32 v25, v2
	v_mov_b32_e32 v26, v2
	v_mov_b32_e32 v27, v2
	v_mov_b32_e32 v28, v2
	v_mov_b32_e32 v29, v2
	v_mov_b32_e32 v34, v2
	v_mov_b32_e32 v35, v2
	v_mov_b32_e32 v36, v2
	v_mov_b32_e32 v37, v2
	v_mov_b32_e32 v30, v2
	v_mov_b32_e32 v31, v2
	v_mov_b32_e32 v32, v2
	v_mov_b32_e32 v33, v2
	v_mov_b32_e32 v38, v2
	v_mov_b32_e32 v39, v2
	v_mov_b32_e32 v40, v2
	v_mov_b32_e32 v41, v2
	v_mov_b32_e32 v42, v2
	v_mov_b32_e32 v43, v2
	v_mov_b32_e32 v44, v2
	v_mov_b32_e32 v45, v2
	v_mov_b32_e32 v46, v2
	v_mov_b32_e32 v47, v2
	v_mov_b32_e32 v48, v2
	v_mov_b32_e32 v49, v2
	v_mov_b32_e32 v50, v2
	v_mov_b32_e32 v51, v2
	v_mov_b32_e32 v52, v2
	v_mov_b32_e32 v53, v2
	v_mov_b32_e32 v54, v2
	v_mov_b32_e32 v55, v2
	v_mov_b32_e32 v86, v2
	v_mov_b32_e32 v87, v2
	v_mov_b32_e32 v88, v2
	v_mov_b32_e32 v89, v2
	v_mov_b32_e32 v90, v2
	v_mov_b32_e32 v91, v2
	v_mov_b32_e32 v92, v2
	v_mov_b32_e32 v93, v2
	v_mov_b32_e32 v98, v2
	v_mov_b32_e32 v99, v2
	v_mov_b32_e32 v100, v2
	v_mov_b32_e32 v101, v2
	v_mov_b32_e32 v94, v2
	v_mov_b32_e32 v95, v2
	v_mov_b32_e32 v96, v2
	v_mov_b32_e32 v97, v2
	v_mov_b32_e32 v102, v2
	v_mov_b32_e32 v103, v2
	v_mov_b32_e32 v104, v2
	v_mov_b32_e32 v105, v2
	v_mov_b32_e32 v106, v2
	v_mov_b32_e32 v107, v2
	v_mov_b32_e32 v108, v2
	v_mov_b32_e32 v109, v2
	v_mov_b32_e32 v142, v2
	v_mov_b32_e32 v143, v2
	v_mov_b32_e32 v144, v2
	v_mov_b32_e32 v145, v2
	v_mov_b32_e32 v146, v2
	v_mov_b32_e32 v147, v2
	v_mov_b32_e32 v148, v2
	v_mov_b32_e32 v149, v2
	v_mov_b32_e32 v150, v2
	v_mov_b32_e32 v151, v2
	v_mov_b32_e32 v152, v2
	v_mov_b32_e32 v153, v2
	v_mov_b32_e32 v154, v2
	v_mov_b32_e32 v155, v2
	v_mov_b32_e32 v156, v2
	v_mov_b32_e32 v157, v2
	v_mov_b32_e32 v158, v2
	v_mov_b32_e32 v159, v2
	v_mov_b32_e32 v160, v2
	v_mov_b32_e32 v161, v2
	s_waitcnt lgkmcnt(0)
	s_barrier
.LBB0_1308:
	s_bitcmp1_b32 s4, 0
	s_cselect_b32 s2, 0x12000, 0
	v_or_b32_e32 v218, s2, v207
	v_add_u32_e32 v214, v218, v0
	v_add_u32_e32 v246, v218, v167
	ds_read_b128 v[184:187], v214
	ds_read_b128 v[198:201], v214 offset:2048
	ds_read_b128 v[210:213], v214 offset:4096
	ds_read_b128 v[214:217], v214 offset:6144
	ds_read_b128 v[218:221], v246 offset:32768
	ds_read_b128 v[222:225], v246 offset:34816
	ds_read_b128 v[226:229], v246 offset:36864
	ds_read_b128 v[230:233], v246 offset:38912
	ds_read_b128 v[234:237], v246 offset:40960
	ds_read_b128 v[238:241], v246 offset:43008
	ds_read_b128 v[242:245], v246 offset:45056
	ds_read_b128 v[246:249], v246 offset:47104
	s_add_i32 s10, s4, 1
	s_bitcmp1_b32 s10, 0
	s_cselect_b32 s3, 0x12000, 0
	s_waitcnt lgkmcnt(7)
	v_mfma_f32_16x16x32_bf16 v[158:161], v[218:221], v[184:187], v[158:161]
	v_mfma_f32_16x16x32_bf16 v[98:101], v[218:221], v[198:201], v[98:101]
	v_mfma_f32_16x16x32_bf16 v[66:69], v[218:221], v[210:213], v[66:69]
	v_mfma_f32_16x16x32_bf16 v[34:37], v[218:221], v[214:217], v[34:37]
	v_add_u32_e32 v218, s3, v166
	s_waitcnt vmcnt(7)
	ds_write_b128 v218, v[118:121]
	s_waitcnt lgkmcnt(7)
	v_mfma_f32_16x16x32_bf16 v[154:157], v[222:225], v[184:187], v[154:157]
	v_mfma_f32_16x16x32_bf16 v[90:93], v[222:225], v[198:201], v[90:93]
	global_load_dwordx4 v[118:121], v168, vcc offset:256
	v_mfma_f32_16x16x32_bf16 v[58:61], v[222:225], v[210:213], v[58:61]
	v_mfma_f32_16x16x32_bf16 v[26:29], v[222:225], v[214:217], v[26:29]
	s_waitcnt vmcnt(7)
	ds_write_b128 v218, v[110:113] offset:8192
	s_waitcnt lgkmcnt(7)
	v_mfma_f32_16x16x32_bf16 v[150:153], v[226:229], v[184:187], v[150:153]
	v_mfma_f32_16x16x32_bf16 v[86:89], v[226:229], v[198:201], v[86:89]
	v_add_u32_e32 v110, s34, v168
	global_load_dwordx4 v[110:113], v110, vcc offset:256
	v_mfma_f32_16x16x32_bf16 v[54:57], v[226:229], v[210:213], v[54:57]
	v_mfma_f32_16x16x32_bf16 v[22:25], v[226:229], v[214:217], v[22:25]
	s_waitcnt vmcnt(7)
	ds_write_b128 v218, v[114:117] offset:16384
	s_waitcnt lgkmcnt(7)
	v_mfma_f32_16x16x32_bf16 v[146:149], v[230:233], v[184:187], v[146:149]
	v_mfma_f32_16x16x32_bf16 v[82:85], v[230:233], v[198:201], v[82:85]
	v_add_u32_e32 v114, s35, v168
	global_load_dwordx4 v[114:117], v114, vcc offset:256
	v_mfma_f32_16x16x32_bf16 v[50:53], v[230:233], v[210:213], v[50:53]
	v_mfma_f32_16x16x32_bf16 v[18:21], v[230:233], v[214:217], v[18:21]
	s_waitcnt vmcnt(7)
	ds_write_b128 v218, v[130:133] offset:24576
	s_waitcnt lgkmcnt(7)
	v_mfma_f32_16x16x32_bf16 v[142:145], v[234:237], v[184:187], v[142:145]
	v_mfma_f32_16x16x32_bf16 v[78:81], v[234:237], v[198:201], v[78:81]
	v_add_u32_e32 v130, s36, v168
	global_load_dwordx4 v[130:133], v130, vcc offset:256
	v_mfma_f32_16x16x32_bf16 v[46:49], v[234:237], v[210:213], v[46:49]
	v_mfma_f32_16x16x32_bf16 v[14:17], v[234:237], v[214:217], v[14:17]
	s_waitcnt vmcnt(7)
	ds_write_b128 v218, v[126:129] offset:32768
	s_waitcnt lgkmcnt(7)
	v_mfma_f32_16x16x32_bf16 v[106:109], v[238:241], v[184:187], v[106:109]
	v_mfma_f32_16x16x32_bf16 v[74:77], v[238:241], v[198:201], v[74:77]
	global_load_dwordx4 v[126:129], v170, s[100:101] offset:256
	v_mfma_f32_16x16x32_bf16 v[42:45], v[238:241], v[210:213], v[42:45]
	v_mfma_f32_16x16x32_bf16 v[10:13], v[238:241], v[214:217], v[10:13]
	s_waitcnt vmcnt(7)
	ds_write_b128 v218, v[122:125] offset:40960
	s_waitcnt lgkmcnt(7)
	v_mfma_f32_16x16x32_bf16 v[102:105], v[242:245], v[184:187], v[102:105]
	v_mfma_f32_16x16x32_bf16 v[70:73], v[242:245], v[198:201], v[70:73]
	v_add_u32_e32 v122, s34, v170
	global_load_dwordx4 v[122:125], v122, s[100:101] offset:256
	v_mfma_f32_16x16x32_bf16 v[38:41], v[242:245], v[210:213], v[38:41]
	v_mfma_f32_16x16x32_bf16 v[6:9], v[242:245], v[214:217], v[6:9]
	s_waitcnt vmcnt(7)
	ds_write_b128 v218, v[138:141] offset:49152
	s_waitcnt lgkmcnt(7)
	v_mfma_f32_16x16x32_bf16 v[94:97], v[246:249], v[184:187], v[94:97]
	v_mfma_f32_16x16x32_bf16 v[62:65], v[246:249], v[198:201], v[62:65]
	v_add_u32_e32 v138, s35, v170
	global_load_dwordx4 v[138:141], v138, s[100:101] offset:256
	v_mfma_f32_16x16x32_bf16 v[30:33], v[246:249], v[210:213], v[30:33]
	v_mfma_f32_16x16x32_bf16 v[2:5], v[246:249], v[214:217], v[2:5]
	s_waitcnt vmcnt(7)
	ds_write_b128 v218, v[134:137] offset:57344
	v_add3_u32 v214, s2, v0, v207
	v_xor_b32_e32 v214, 64, v214
	v_add3_u32 v246, s2, v167, v207
	v_xor_b32_e32 v246, 64, v246
	v_add_u32_e32 v134, s36, v170
	global_load_dwordx4 v[134:137], v134, s[100:101] offset:256
	v_add_u32_e32 v168, 0x80, v168
	v_add_u32_e32 v170, 0x80, v170
	ds_read_b128 v[184:187], v214
	ds_read_b128 v[198:201], v214 offset:2048
	ds_read_b128 v[210:213], v214 offset:4096
	ds_read_b128 v[214:217], v214 offset:6144
	ds_read_b128 v[218:221], v246 offset:32768
	ds_read_b128 v[222:225], v246 offset:34816
	ds_read_b128 v[226:229], v246 offset:36864
	ds_read_b128 v[230:233], v246 offset:38912
	ds_read_b128 v[234:237], v246 offset:40960
	ds_read_b128 v[238:241], v246 offset:43008
	ds_read_b128 v[242:245], v246 offset:45056
	ds_read_b128 v[246:249], v246 offset:47104
	s_waitcnt lgkmcnt(7)
	v_mfma_f32_16x16x32_bf16 v[158:161], v[218:221], v[184:187], v[158:161]
	v_mfma_f32_16x16x32_bf16 v[98:101], v[218:221], v[198:201], v[98:101]
	v_mfma_f32_16x16x32_bf16 v[66:69], v[218:221], v[210:213], v[66:69]
	v_mfma_f32_16x16x32_bf16 v[34:37], v[218:221], v[214:217], v[34:37]
	s_waitcnt lgkmcnt(6)
	v_mfma_f32_16x16x32_bf16 v[154:157], v[222:225], v[184:187], v[154:157]
	v_mfma_f32_16x16x32_bf16 v[90:93], v[222:225], v[198:201], v[90:93]
	v_mfma_f32_16x16x32_bf16 v[58:61], v[222:225], v[210:213], v[58:61]
	v_mfma_f32_16x16x32_bf16 v[26:29], v[222:225], v[214:217], v[26:29]
	s_waitcnt lgkmcnt(5)
	v_mfma_f32_16x16x32_bf16 v[150:153], v[226:229], v[184:187], v[150:153]
	v_mfma_f32_16x16x32_bf16 v[86:89], v[226:229], v[198:201], v[86:89]
	v_mfma_f32_16x16x32_bf16 v[54:57], v[226:229], v[210:213], v[54:57]
	v_mfma_f32_16x16x32_bf16 v[22:25], v[226:229], v[214:217], v[22:25]
	s_waitcnt lgkmcnt(4)
	v_mfma_f32_16x16x32_bf16 v[146:149], v[230:233], v[184:187], v[146:149]
	v_mfma_f32_16x16x32_bf16 v[82:85], v[230:233], v[198:201], v[82:85]
	v_mfma_f32_16x16x32_bf16 v[50:53], v[230:233], v[210:213], v[50:53]
	v_mfma_f32_16x16x32_bf16 v[18:21], v[230:233], v[214:217], v[18:21]
	s_waitcnt lgkmcnt(3)
	v_mfma_f32_16x16x32_bf16 v[142:145], v[234:237], v[184:187], v[142:145]
	v_mfma_f32_16x16x32_bf16 v[78:81], v[234:237], v[198:201], v[78:81]
	v_mfma_f32_16x16x32_bf16 v[46:49], v[234:237], v[210:213], v[46:49]
	v_mfma_f32_16x16x32_bf16 v[14:17], v[234:237], v[214:217], v[14:17]
	s_waitcnt lgkmcnt(2)
	v_mfma_f32_16x16x32_bf16 v[106:109], v[238:241], v[184:187], v[106:109]
	v_mfma_f32_16x16x32_bf16 v[74:77], v[238:241], v[198:201], v[74:77]
	v_mfma_f32_16x16x32_bf16 v[42:45], v[238:241], v[210:213], v[42:45]
	v_mfma_f32_16x16x32_bf16 v[10:13], v[238:241], v[214:217], v[10:13]
	s_waitcnt lgkmcnt(1)
	v_mfma_f32_16x16x32_bf16 v[102:105], v[242:245], v[184:187], v[102:105]
	v_mfma_f32_16x16x32_bf16 v[70:73], v[242:245], v[198:201], v[70:73]
	v_mfma_f32_16x16x32_bf16 v[38:41], v[242:245], v[210:213], v[38:41]
	v_mfma_f32_16x16x32_bf16 v[6:9], v[242:245], v[214:217], v[6:9]
	s_waitcnt lgkmcnt(0)
	v_mfma_f32_16x16x32_bf16 v[94:97], v[246:249], v[184:187], v[94:97]
	v_mfma_f32_16x16x32_bf16 v[62:65], v[246:249], v[198:201], v[62:65]
	v_mfma_f32_16x16x32_bf16 v[30:33], v[246:249], v[210:213], v[30:33]
	v_mfma_f32_16x16x32_bf16 v[2:5], v[246:249], v[214:217], v[2:5]
	s_waitcnt lgkmcnt(0)
	s_barrier
	s_cmp_eq_u32 s10, 16
	s_mov_b32 s4, s10
	s_cbranch_scc0 .LBB0_1308
	s_waitcnt vmcnt(4)
	v_add_u32_e32 v110, s7, v206
	s_waitcnt vmcnt(3)
	v_or_b32_e32 v114, v110, v205
	v_cmp_lt_i32_e32 vcc, s97, v114
	v_ashrrev_i32_e32 v112, 31, v114
	v_add_u32_e32 v116, 0xffffc000, v114
	v_ashrrev_i32_e32 v115, 11, v110
	v_cndmask_b32_e64 v113, v112, 0, vcc
	v_cndmask_b32_e32 v112, v114, v116, vcc
	v_mov_b32_e32 v116, s45
	v_mov_b32_e32 v117, s13
	v_mov_b32_e32 v118, s44
	v_mov_b32_e32 v119, s12
	v_or_b32_e32 v110, s6, v208
	s_waitcnt vmcnt(2)
	v_cndmask_b32_e64 v122, v115, 8, vcc
	v_cndmask_b32_e32 v121, v116, v117, vcc
	v_cndmask_b32_e32 v120, v118, v119, vcc
	v_lshlrev_b64 v[112:113], 12, v[112:113]
	v_ashrrev_i32_e32 v111, 31, v110
	v_lshl_add_u64 v[112:113], v[120:121], 0, v[112:113]
	v_mul_hi_i32_i24_e32 v121, 0x9000, v122
	v_mul_i32_i24_e32 v120, 0x9000, v122
	v_lshl_add_u64 v[120:121], s[14:15], 0, v[120:121]
	v_lshlrev_b64 v[110:111], 2, v[110:111]
	s_waitcnt vmcnt(0)
	v_lshl_add_u64 v[128:129], v[120:121], 0, v[110:111]
	v_lshl_add_u64 v[112:113], v[112:113], 0, v[110:111]
	global_load_dwordx4 v[120:123], v[128:129], off
	global_load_dwordx4 v[124:127], v[112:113], off
	s_waitcnt vmcnt(0)
	v_pk_fma_f32 v[120:121], v[158:159], v[120:121], v[124:125]
	v_pk_fma_f32 v[122:123], v[160:161], v[122:123], v[126:127]
	global_store_dwordx4 v[112:113], v[120:123], off
	global_load_dwordx4 v[120:123], v[128:129], off offset:64
	s_nop 0
	global_load_dwordx4 v[124:127], v[112:113], off offset:64
	s_waitcnt vmcnt(0)
	v_pk_fma_f32 v[120:121], v[154:155], v[120:121], v[124:125]
	v_pk_fma_f32 v[122:123], v[156:157], v[122:123], v[126:127]
	global_store_dwordx4 v[112:113], v[120:123], off offset:64
	global_load_dwordx4 v[120:123], v[128:129], off offset:128
	s_nop 0
	global_load_dwordx4 v[124:127], v[112:113], off offset:128
	s_waitcnt vmcnt(0)
	v_pk_fma_f32 v[120:121], v[150:151], v[120:121], v[124:125]
	v_pk_fma_f32 v[122:123], v[152:153], v[122:123], v[126:127]
	global_store_dwordx4 v[112:113], v[120:123], off offset:128
	global_load_dwordx4 v[120:123], v[128:129], off offset:192
	s_nop 0
	global_load_dwordx4 v[124:127], v[112:113], off offset:192
	s_waitcnt vmcnt(0)
	v_pk_fma_f32 v[120:121], v[146:147], v[120:121], v[124:125]
	v_pk_fma_f32 v[122:123], v[148:149], v[122:123], v[126:127]
	global_store_dwordx4 v[112:113], v[120:123], off offset:192
	global_load_dwordx4 v[120:123], v[128:129], off offset:256
	s_nop 0
	global_load_dwordx4 v[124:127], v[112:113], off offset:256
	s_waitcnt vmcnt(0)
	v_pk_fma_f32 v[120:121], v[142:143], v[120:121], v[124:125]
	v_pk_fma_f32 v[122:123], v[144:145], v[122:123], v[126:127]
	global_store_dwordx4 v[112:113], v[120:123], off offset:256
	global_load_dwordx4 v[120:123], v[128:129], off offset:320
	s_nop 0
	global_load_dwordx4 v[124:127], v[112:113], off offset:320
	s_waitcnt vmcnt(0)
	v_pk_fma_f32 v[106:107], v[106:107], v[120:121], v[124:125]
	v_pk_fma_f32 v[108:109], v[108:109], v[122:123], v[126:127]
	global_store_dwordx4 v[112:113], v[106:109], off offset:320
	global_load_dwordx4 v[106:109], v[128:129], off offset:384
	s_nop 0
	global_load_dwordx4 v[120:123], v[112:113], off offset:384
	s_waitcnt vmcnt(0)
	v_pk_fma_f32 v[102:103], v[102:103], v[106:107], v[120:121]
	v_pk_fma_f32 v[104:105], v[104:105], v[108:109], v[122:123]
	global_store_dwordx4 v[112:113], v[102:105], off offset:384
	global_load_dwordx4 v[102:105], v[128:129], off offset:448
	s_nop 0
	global_load_dwordx4 v[106:109], v[112:113], off offset:448
	s_waitcnt vmcnt(0)
	v_pk_fma_f32 v[94:95], v[94:95], v[102:103], v[106:107]
	v_pk_fma_f32 v[96:97], v[96:97], v[104:105], v[108:109]
	global_store_dwordx4 v[112:113], v[94:97], off offset:448
	s_nop 1
	v_or_b32_e32 v94, 16, v114
	v_cmp_lt_i32_e32 vcc, s97, v94
	v_add_u32_e32 v96, 0xffffc010, v114
	v_ashrrev_i32_e32 v95, 31, v94
	v_cndmask_b32_e64 v95, v95, 0, vcc
	v_cndmask_b32_e32 v94, v94, v96, vcc
	v_cndmask_b32_e64 v102, v115, 8, vcc
	v_cndmask_b32_e32 v97, v116, v117, vcc
	v_cndmask_b32_e32 v96, v118, v119, vcc
	v_lshlrev_b64 v[94:95], 12, v[94:95]
	v_lshl_add_u64 v[94:95], v[96:97], 0, v[94:95]
	v_mul_hi_i32_i24_e32 v97, 0x9000, v102
	v_mul_i32_i24_e32 v96, 0x9000, v102
	v_lshl_add_u64 v[96:97], s[14:15], 0, v[96:97]
	v_lshl_add_u64 v[112:113], v[96:97], 0, v[110:111]
	v_lshl_add_u64 v[94:95], v[94:95], 0, v[110:111]
	global_load_dwordx4 v[102:105], v[112:113], off
	global_load_dwordx4 v[106:109], v[94:95], off
	s_waitcnt vmcnt(0)
	v_pk_fma_f32 v[96:97], v[98:99], v[102:103], v[106:107]
	v_pk_fma_f32 v[98:99], v[100:101], v[104:105], v[108:109]
	global_store_dwordx4 v[94:95], v[96:99], off
	global_load_dwordx4 v[96:99], v[112:113], off offset:64
	s_nop 0
	global_load_dwordx4 v[100:103], v[94:95], off offset:64
	s_waitcnt vmcnt(0)
	v_pk_fma_f32 v[90:91], v[90:91], v[96:97], v[100:101]
	v_pk_fma_f32 v[92:93], v[92:93], v[98:99], v[102:103]
	global_store_dwordx4 v[94:95], v[90:93], off offset:64
	global_load_dwordx4 v[90:93], v[112:113], off offset:128
	s_nop 0
	global_load_dwordx4 v[96:99], v[94:95], off offset:128
	s_waitcnt vmcnt(0)
	v_pk_fma_f32 v[86:87], v[86:87], v[90:91], v[96:97]
	v_pk_fma_f32 v[88:89], v[88:89], v[92:93], v[98:99]
	global_store_dwordx4 v[94:95], v[86:89], off offset:128
	global_load_dwordx4 v[86:89], v[112:113], off offset:192
	s_nop 0
	global_load_dwordx4 v[90:93], v[94:95], off offset:192
	s_waitcnt vmcnt(0)
	v_pk_fma_f32 v[82:83], v[82:83], v[86:87], v[90:91]
	v_pk_fma_f32 v[84:85], v[84:85], v[88:89], v[92:93]
	global_store_dwordx4 v[94:95], v[82:85], off offset:192
	global_load_dwordx4 v[82:85], v[112:113], off offset:256
	s_nop 0
	global_load_dwordx4 v[86:89], v[94:95], off offset:256
	s_waitcnt vmcnt(0)
	v_pk_fma_f32 v[78:79], v[78:79], v[82:83], v[86:87]
	v_pk_fma_f32 v[80:81], v[80:81], v[84:85], v[88:89]
	global_store_dwordx4 v[94:95], v[78:81], off offset:256
	global_load_dwordx4 v[78:81], v[112:113], off offset:320
	s_nop 0
	global_load_dwordx4 v[82:85], v[94:95], off offset:320
	s_waitcnt vmcnt(0)
	v_pk_fma_f32 v[74:75], v[74:75], v[78:79], v[82:83]
	v_pk_fma_f32 v[76:77], v[76:77], v[80:81], v[84:85]
	global_store_dwordx4 v[94:95], v[74:77], off offset:320
	global_load_dwordx4 v[74:77], v[112:113], off offset:384
	s_nop 0
	global_load_dwordx4 v[78:81], v[94:95], off offset:384
	s_waitcnt vmcnt(0)
	v_pk_fma_f32 v[70:71], v[70:71], v[74:75], v[78:79]
	v_pk_fma_f32 v[72:73], v[72:73], v[76:77], v[80:81]
	global_store_dwordx4 v[94:95], v[70:73], off offset:384
	global_load_dwordx4 v[70:73], v[112:113], off offset:448
	s_nop 0
	global_load_dwordx4 v[74:77], v[94:95], off offset:448
	s_waitcnt vmcnt(0)
	v_pk_fma_f32 v[62:63], v[62:63], v[70:71], v[74:75]
	v_pk_fma_f32 v[64:65], v[64:65], v[72:73], v[76:77]
	global_store_dwordx4 v[94:95], v[62:65], off offset:448
	s_nop 1
	v_or_b32_e32 v62, 32, v114
	v_cmp_lt_i32_e32 vcc, s97, v62
	v_add_u32_e32 v64, 0xffffc020, v114
	v_ashrrev_i32_e32 v63, 31, v62
	v_cndmask_b32_e64 v63, v63, 0, vcc
	v_cndmask_b32_e32 v62, v62, v64, vcc
	v_cndmask_b32_e64 v70, v115, 8, vcc
	v_cndmask_b32_e32 v65, v116, v117, vcc
	v_cndmask_b32_e32 v64, v118, v119, vcc
	v_lshlrev_b64 v[62:63], 12, v[62:63]
	v_lshl_add_u64 v[62:63], v[64:65], 0, v[62:63]
	v_mul_hi_i32_i24_e32 v65, 0x9000, v70
	v_mul_i32_i24_e32 v64, 0x9000, v70
	v_lshl_add_u64 v[64:65], s[14:15], 0, v[64:65]
	v_lshl_add_u64 v[78:79], v[64:65], 0, v[110:111]
	v_lshl_add_u64 v[62:63], v[62:63], 0, v[110:111]
	global_load_dwordx4 v[70:73], v[78:79], off
	global_load_dwordx4 v[74:77], v[62:63], off
	s_waitcnt vmcnt(0)
	v_pk_fma_f32 v[64:65], v[66:67], v[70:71], v[74:75]
	v_pk_fma_f32 v[66:67], v[68:69], v[72:73], v[76:77]
	global_store_dwordx4 v[62:63], v[64:67], off
	global_load_dwordx4 v[64:67], v[78:79], off offset:64
	s_nop 0
	global_load_dwordx4 v[68:71], v[62:63], off offset:64
	s_waitcnt vmcnt(0)
	v_pk_fma_f32 v[58:59], v[58:59], v[64:65], v[68:69]
	v_pk_fma_f32 v[60:61], v[60:61], v[66:67], v[70:71]
	global_store_dwordx4 v[62:63], v[58:61], off offset:64
	global_load_dwordx4 v[58:61], v[78:79], off offset:128
	s_nop 0
	global_load_dwordx4 v[64:67], v[62:63], off offset:128
	s_waitcnt vmcnt(0)
	v_pk_fma_f32 v[54:55], v[54:55], v[58:59], v[64:65]
	v_pk_fma_f32 v[56:57], v[56:57], v[60:61], v[66:67]
	global_store_dwordx4 v[62:63], v[54:57], off offset:128
	global_load_dwordx4 v[54:57], v[78:79], off offset:192
	s_nop 0
	global_load_dwordx4 v[58:61], v[62:63], off offset:192
	s_waitcnt vmcnt(0)
	v_pk_fma_f32 v[50:51], v[50:51], v[54:55], v[58:59]
	v_pk_fma_f32 v[52:53], v[52:53], v[56:57], v[60:61]
	global_store_dwordx4 v[62:63], v[50:53], off offset:192
	global_load_dwordx4 v[50:53], v[78:79], off offset:256
	s_nop 0
	global_load_dwordx4 v[54:57], v[62:63], off offset:256
	s_waitcnt vmcnt(0)
	v_pk_fma_f32 v[46:47], v[46:47], v[50:51], v[54:55]
	v_pk_fma_f32 v[48:49], v[48:49], v[52:53], v[56:57]
	global_store_dwordx4 v[62:63], v[46:49], off offset:256
	global_load_dwordx4 v[46:49], v[78:79], off offset:320
	s_nop 0
	global_load_dwordx4 v[50:53], v[62:63], off offset:320
	s_waitcnt vmcnt(0)
	v_pk_fma_f32 v[42:43], v[42:43], v[46:47], v[50:51]
	v_pk_fma_f32 v[44:45], v[44:45], v[48:49], v[52:53]
	global_store_dwordx4 v[62:63], v[42:45], off offset:320
	global_load_dwordx4 v[42:45], v[78:79], off offset:384
	s_nop 0
	global_load_dwordx4 v[46:49], v[62:63], off offset:384
	s_waitcnt vmcnt(0)
	v_pk_fma_f32 v[38:39], v[38:39], v[42:43], v[46:47]
	v_pk_fma_f32 v[40:41], v[40:41], v[44:45], v[48:49]
	global_store_dwordx4 v[62:63], v[38:41], off offset:384
	global_load_dwordx4 v[38:41], v[78:79], off offset:448
	s_nop 0
	global_load_dwordx4 v[42:45], v[62:63], off offset:448
	s_waitcnt vmcnt(0)
	v_pk_fma_f32 v[30:31], v[30:31], v[38:39], v[42:43]
	v_pk_fma_f32 v[32:33], v[32:33], v[40:41], v[44:45]
	global_store_dwordx4 v[62:63], v[30:33], off offset:448
	s_nop 1
	v_or_b32_e32 v30, 48, v114
	v_cmp_lt_i32_e32 vcc, s97, v30
	v_add_u32_e32 v32, 0xffffc030, v114
	v_ashrrev_i32_e32 v31, 31, v30
	v_cndmask_b32_e64 v31, v31, 0, vcc
	v_cndmask_b32_e32 v30, v30, v32, vcc
	v_cndmask_b32_e64 v38, v115, 8, vcc
	v_cndmask_b32_e32 v33, v116, v117, vcc
	v_cndmask_b32_e32 v32, v118, v119, vcc
	v_lshlrev_b64 v[30:31], 12, v[30:31]
	v_lshl_add_u64 v[30:31], v[32:33], 0, v[30:31]
	v_mul_hi_i32_i24_e32 v33, 0x9000, v38
	v_mul_i32_i24_e32 v32, 0x9000, v38
	v_lshl_add_u64 v[32:33], s[14:15], 0, v[32:33]
	v_lshl_add_u64 v[46:47], v[32:33], 0, v[110:111]
	v_lshl_add_u64 v[30:31], v[30:31], 0, v[110:111]
	global_load_dwordx4 v[38:41], v[46:47], off
	global_load_dwordx4 v[42:45], v[30:31], off
	s_waitcnt vmcnt(0)
	v_pk_fma_f32 v[32:33], v[34:35], v[38:39], v[42:43]
	v_pk_fma_f32 v[34:35], v[36:37], v[40:41], v[44:45]
	global_store_dwordx4 v[30:31], v[32:35], off
	global_load_dwordx4 v[32:35], v[46:47], off offset:64
	s_nop 0
	global_load_dwordx4 v[36:39], v[30:31], off offset:64
	s_waitcnt vmcnt(0)
	v_pk_fma_f32 v[26:27], v[26:27], v[32:33], v[36:37]
	v_pk_fma_f32 v[28:29], v[28:29], v[34:35], v[38:39]
	global_store_dwordx4 v[30:31], v[26:29], off offset:64
	global_load_dwordx4 v[26:29], v[46:47], off offset:128
	s_nop 0
	global_load_dwordx4 v[32:35], v[30:31], off offset:128
	s_waitcnt vmcnt(0)
	v_pk_fma_f32 v[22:23], v[22:23], v[26:27], v[32:33]
	v_pk_fma_f32 v[24:25], v[24:25], v[28:29], v[34:35]
	global_store_dwordx4 v[30:31], v[22:25], off offset:128
	global_load_dwordx4 v[22:25], v[46:47], off offset:192
	s_nop 0
	global_load_dwordx4 v[26:29], v[30:31], off offset:192
	s_waitcnt vmcnt(0)
	v_pk_fma_f32 v[18:19], v[18:19], v[22:23], v[26:27]
	v_pk_fma_f32 v[20:21], v[20:21], v[24:25], v[28:29]
	global_store_dwordx4 v[30:31], v[18:21], off offset:192
	global_load_dwordx4 v[18:21], v[46:47], off offset:256
	s_nop 0
	global_load_dwordx4 v[22:25], v[30:31], off offset:256
	s_waitcnt vmcnt(0)
	v_pk_fma_f32 v[14:15], v[14:15], v[18:19], v[22:23]
	v_pk_fma_f32 v[16:17], v[16:17], v[20:21], v[24:25]
	global_store_dwordx4 v[30:31], v[14:17], off offset:256
	global_load_dwordx4 v[14:17], v[46:47], off offset:320
	s_nop 0
	global_load_dwordx4 v[18:21], v[30:31], off offset:320
	s_waitcnt vmcnt(0)
	v_pk_fma_f32 v[10:11], v[10:11], v[14:15], v[18:19]
	v_pk_fma_f32 v[12:13], v[12:13], v[16:17], v[20:21]
	global_store_dwordx4 v[30:31], v[10:13], off offset:320
	global_load_dwordx4 v[10:13], v[46:47], off offset:384
	s_nop 0
	global_load_dwordx4 v[14:17], v[30:31], off offset:384
	s_waitcnt vmcnt(0)
	v_pk_fma_f32 v[6:7], v[6:7], v[10:11], v[14:15]
	v_pk_fma_f32 v[8:9], v[8:9], v[12:13], v[16:17]
	global_store_dwordx4 v[30:31], v[6:9], off offset:384
	global_load_dwordx4 v[6:9], v[46:47], off offset:448
	s_nop 0
	global_load_dwordx4 v[10:13], v[30:31], off offset:448
	s_waitcnt vmcnt(0)
	v_pk_fma_f32 v[2:3], v[2:3], v[6:7], v[10:11]
	v_pk_fma_f32 v[4:5], v[4:5], v[8:9], v[12:13]
	global_store_dwordx4 v[30:31], v[2:5], off offset:448
	s_add_i32 s19, s19, s18
	s_cmpk_gt_i32 s19, 0xff
	s_cbranch_scc0 .LBB0_1307

.LBB0_1437:
	s_or_b64 exec, exec, s[12:13]
	s_mov_b64 s[6:7], s[60:61]
	s_waitcnt lgkmcnt(0)
	s_barrier
	s_load_dwordx2 s[6:7], s[6:7], 0x130
	v_readlane_b32 s2, v255, 44
	v_readlane_b32 s3, v255, 45
	s_mov_b64 s[14:15], -1
	s_waitcnt lgkmcnt(0)
	s_add_u32 s12, s6, 0x6035800
	s_addc_u32 s13, s7, 0
	s_add_u32 s44, s6, 0xb00000
	s_addc_u32 s45, s7, 0
	s_add_u32 s46, s6, 0x3200000
	s_addc_u32 s47, s7, 0
	s_and_b64 vcc, exec, s[2:3]
	s_cbranch_vccz .LBB0_1458
	v_mov_b32_e32 v2, v172
	s_mov_b32 s11, s42
	s_mov_b32 s14, s94
	s_cmpk_gt_i32 s14, 0x4ff
	s_cbranch_scc1 .LBB0_1443
	v_ashrrev_i32_e32 v204, 3, v2
	v_bfe_u32 v3, v2, 4, 2
	v_and_b32_e32 v4, 15, v2
	v_lshlrev_b32_e32 v0, 4, v2
	v_ashrrev_i32_e32 v5, 1, v2
	s_movk_i32 s2, 0xffc0
	v_lshlrev_b32_e32 v2, 1, v2
	v_and_b32_e32 v0, 0x70, v0
	v_and_or_b32 v205, v5, s2, v4
	v_and_b32_e32 v207, 0x80, v2
	s_movk_i32 s2, 0x90
	v_or_b32_e32 v2, v207, v4
	v_and_b32_e32 v100, 7, v204
	v_lshlrev_b32_e32 v100, 4, v100
	v_xor_b32_e32 v100, v100, v0
	v_lshl_add_u32 v166, v204, 7, v100
	v_lshl_add_u64 v[162:163], s[46:47], 0, v[0:1]
	v_lshl_add_u64 v[164:165], s[44:45], 0, v[0:1]
	v_and_b32_e32 v100, 7, v4
	v_xor_b32_e32 v100, v100, v3
	v_lshlrev_b32_e32 v206, 4, v100
	v_lshlrev_b32_e32 v208, 2, v3
	v_lshlrev_b32_e32 v0, 7, v205
	v_lshlrev_b32_e32 v167, 7, v2
.LBB0_1440:
	s_ashr_i32 s2, s14, 31
	s_lshr_b32 s2, s2, 26
	s_add_i32 s2, s14, s2
	s_and_b32 s3, s2, 0xffffc0
	s_sub_i32 s3, s14, s3
	s_lshl_b32 s6, s3, 8
	v_add_u32_e32 v2, s6, v204
	v_ashrrev_i32_e32 v3, 31, v2
	v_lshlrev_b64 v[2:3], 11, v[2:3]
	v_lshl_add_u64 v[168:169], v[162:163], 0, v[2:3]
	s_lshl_b32 s2, s2, 2
	v_add_co_u32_e32 v56, vcc, s34, v168
	s_and_b32 s7, s2, 0xffffff00
	s_nop 0
	v_addc_co_u32_e32 v57, vcc, 0, v169, vcc
	v_add_u32_e32 v2, s7, v204
	v_add_co_u32_e32 v58, vcc, s35, v168
	v_ashrrev_i32_e32 v3, 31, v2
	s_nop 0
	v_addc_co_u32_e32 v59, vcc, 0, v169, vcc
	v_lshlrev_b64 v[2:3], 11, v[2:3]
	v_add_co_u32_e32 v60, vcc, s36, v168
	v_lshl_add_u64 v[170:171], v[164:165], 0, v[2:3]
	s_nop 0
	v_addc_co_u32_e32 v61, vcc, 0, v169, vcc
	v_add_co_u32_e32 v62, vcc, s35, v170
	global_load_dwordx4 v[24:27], v[56:57], off
	global_load_dwordx4 v[28:31], v[58:59], off
	v_addc_co_u32_e32 v63, vcc, 0, v171, vcc
	v_add_co_u32_e32 v64, vcc, s36, v170
	global_load_dwordx4 v[32:35], v[168:169], off
	global_load_dwordx4 v[36:39], v[170:171], off
	v_addc_co_u32_e32 v65, vcc, 0, v171, vcc
	v_add_co_u32_e32 v66, vcc, s34, v170
	global_load_dwordx4 v[40:43], v[62:63], off
	global_load_dwordx4 v[44:47], v[64:65], off
	v_addc_co_u32_e32 v67, vcc, 0, v171, vcc
	global_load_dwordx4 v[48:51], v[60:61], off
	global_load_dwordx4 v[52:55], v[66:67], off
	s_barrier
	global_load_dwordx4 v[114:117], v[168:169], off offset:128
	global_load_dwordx4 v[106:109], v[56:57], off offset:128
	global_load_dwordx4 v[110:113], v[58:59], off offset:128
	global_load_dwordx4 v[126:129], v[60:61], off offset:128
	global_load_dwordx4 v[122:125], v[170:171], off offset:128
	global_load_dwordx4 v[118:121], v[66:67], off offset:128
	global_load_dwordx4 v[134:137], v[62:63], off offset:128
	global_load_dwordx4 v[130:133], v[64:65], off offset:128
	v_readfirstlane_b32 vcc_lo, v168
	v_readfirstlane_b32 vcc_hi, v169
	v_readfirstlane_b32 s100, v170
	v_readfirstlane_b32 s101, v171
	s_nop 1
	v_subrev_u32_e32 v168, vcc_lo, v168
	v_subrev_u32_e32 v170, s100, v170
	v_mov_b32_e32 v2, 0
	s_mov_b32 s4, 0
	v_mov_b32_e32 v3, v2
	v_mov_b32_e32 v4, v2
	v_mov_b32_e32 v5, v2
	v_mov_b32_e32 v6, v2
	v_mov_b32_e32 v7, v2
	v_mov_b32_e32 v8, v2
	v_mov_b32_e32 v9, v2
	v_mov_b32_e32 v10, v2
	v_mov_b32_e32 v11, v2
	v_mov_b32_e32 v12, v2
	v_mov_b32_e32 v13, v2
	v_mov_b32_e32 v14, v2
	v_mov_b32_e32 v15, v2
	v_mov_b32_e32 v16, v2
	v_mov_b32_e32 v17, v2
	v_mov_b32_e32 v18, v2
	v_mov_b32_e32 v19, v2
	v_mov_b32_e32 v20, v2
	v_mov_b32_e32 v21, v2
	v_mov_b32_e32 v22, v2
	v_mov_b32_e32 v23, v2
	v_mov_b32_e32 v56, v2
	v_mov_b32_e32 v57, v2
	v_mov_b32_e32 v58, v2
	v_mov_b32_e32 v59, v2
	v_mov_b32_e32 v60, v2
	v_mov_b32_e32 v61, v2
	v_mov_b32_e32 v62, v2
	v_mov_b32_e32 v63, v2
	v_mov_b32_e32 v64, v2
	v_mov_b32_e32 v65, v2
	v_mov_b32_e32 v66, v2
	v_mov_b32_e32 v67, v2
	v_mov_b32_e32 v68, v2
	v_mov_b32_e32 v69, v2
	v_mov_b32_e32 v70, v2
	v_mov_b32_e32 v71, v2
	v_mov_b32_e32 v72, v2
	v_mov_b32_e32 v73, v2
	v_mov_b32_e32 v74, v2
	v_mov_b32_e32 v75, v2
	v_mov_b32_e32 v76, v2
	v_mov_b32_e32 v77, v2
	v_mov_b32_e32 v78, v2
	v_mov_b32_e32 v79, v2
	v_mov_b32_e32 v80, v2
	v_mov_b32_e32 v81, v2
	v_mov_b32_e32 v82, v2
	v_mov_b32_e32 v83, v2
	v_mov_b32_e32 v84, v2
	v_mov_b32_e32 v85, v2
	s_waitcnt vmcnt(13)
	ds_write_b128 v166, v[32:35]
	s_waitcnt vmcnt(12)
	ds_write_b128 v166, v[36:39] offset:32768
	s_waitcnt vmcnt(11)
	ds_write_b128 v166, v[40:43] offset:49152
	s_waitcnt vmcnt(10)
	ds_write_b128 v166, v[44:47] offset:57344
	ds_write_b128 v166, v[24:27] offset:8192
	ds_write_b128 v166, v[28:31] offset:16384
	s_waitcnt vmcnt(9)
	ds_write_b128 v166, v[48:51] offset:24576
	s_waitcnt vmcnt(8)
	ds_write_b128 v166, v[52:55] offset:40960
	v_mov_b32_e32 v24, v2
	v_mov_b32_e32 v25, v2
	v_mov_b32_e32 v26, v2
	v_mov_b32_e32 v27, v2
	v_mov_b32_e32 v28, v2
	v_mov_b32_e32 v29, v2
	v_mov_b32_e32 v30, v2
	v_mov_b32_e32 v31, v2
	v_mov_b32_e32 v32, v2
	v_mov_b32_e32 v33, v2
	v_mov_b32_e32 v34, v2
	v_mov_b32_e32 v35, v2
	v_mov_b32_e32 v36, v2
	v_mov_b32_e32 v37, v2
	v_mov_b32_e32 v38, v2
	v_mov_b32_e32 v39, v2
	v_mov_b32_e32 v40, v2
	v_mov_b32_e32 v41, v2
	v_mov_b32_e32 v42, v2
	v_mov_b32_e32 v43, v2
	v_mov_b32_e32 v44, v2
	v_mov_b32_e32 v45, v2
	v_mov_b32_e32 v46, v2
	v_mov_b32_e32 v47, v2
	v_mov_b32_e32 v48, v2
	v_mov_b32_e32 v49, v2
	v_mov_b32_e32 v50, v2
	v_mov_b32_e32 v51, v2
	v_mov_b32_e32 v52, v2
	v_mov_b32_e32 v53, v2
	v_mov_b32_e32 v54, v2
	v_mov_b32_e32 v55, v2
	v_mov_b32_e32 v86, v2
	v_mov_b32_e32 v87, v2
	v_mov_b32_e32 v88, v2
	v_mov_b32_e32 v89, v2
	v_mov_b32_e32 v90, v2
	v_mov_b32_e32 v91, v2
	v_mov_b32_e32 v92, v2
	v_mov_b32_e32 v93, v2
	v_mov_b32_e32 v94, v2
	v_mov_b32_e32 v95, v2
	v_mov_b32_e32 v96, v2
	v_mov_b32_e32 v97, v2
	v_mov_b32_e32 v98, v2
	v_mov_b32_e32 v99, v2
	v_mov_b32_e32 v100, v2
	v_mov_b32_e32 v101, v2
	v_mov_b32_e32 v102, v2
	v_mov_b32_e32 v103, v2
	v_mov_b32_e32 v104, v2
	v_mov_b32_e32 v105, v2
	v_mov_b32_e32 v138, v2
	v_mov_b32_e32 v139, v2
	v_mov_b32_e32 v140, v2
	v_mov_b32_e32 v141, v2
	v_mov_b32_e32 v142, v2
	v_mov_b32_e32 v143, v2
	v_mov_b32_e32 v144, v2
	v_mov_b32_e32 v145, v2
	v_mov_b32_e32 v146, v2
	v_mov_b32_e32 v147, v2
	v_mov_b32_e32 v148, v2
	v_mov_b32_e32 v149, v2
	v_mov_b32_e32 v150, v2
	v_mov_b32_e32 v151, v2
	v_mov_b32_e32 v152, v2
	v_mov_b32_e32 v153, v2
	v_mov_b32_e32 v154, v2
	v_mov_b32_e32 v155, v2
	v_mov_b32_e32 v156, v2
	v_mov_b32_e32 v157, v2
	v_mov_b32_e32 v158, v2
	v_mov_b32_e32 v159, v2
	v_mov_b32_e32 v160, v2
	v_mov_b32_e32 v161, v2
	s_waitcnt lgkmcnt(0)
	s_barrier
.LBB0_1441:
	s_bitcmp1_b32 s4, 0
	s_cselect_b32 s2, 0x12000, 0
	v_or_b32_e32 v218, s2, v206
	v_add_u32_e32 v214, v218, v0
	v_add_u32_e32 v246, v218, v167
	ds_read_b128 v[184:187], v214
	ds_read_b128 v[198:201], v214 offset:2048
	ds_read_b128 v[210:213], v214 offset:4096
	ds_read_b128 v[214:217], v214 offset:6144
	ds_read_b128 v[218:221], v246 offset:32768
	ds_read_b128 v[222:225], v246 offset:34816
	ds_read_b128 v[226:229], v246 offset:36864
	ds_read_b128 v[230:233], v246 offset:38912
	ds_read_b128 v[234:237], v246 offset:40960
	ds_read_b128 v[238:241], v246 offset:43008
	ds_read_b128 v[242:245], v246 offset:45056
	ds_read_b128 v[246:249], v246 offset:47104
	s_add_i32 s10, s4, 1
	s_bitcmp1_b32 s10, 0
	s_cselect_b32 s3, 0x12000, 0
	s_waitcnt lgkmcnt(7)
	v_mfma_f32_16x16x32_bf16 v[158:161], v[218:221], v[184:187], v[158:161]
	v_mfma_f32_16x16x32_bf16 v[94:97], v[218:221], v[198:201], v[94:97]
	v_mfma_f32_16x16x32_bf16 v[62:65], v[218:221], v[210:213], v[62:65]
	v_mfma_f32_16x16x32_bf16 v[30:33], v[218:221], v[214:217], v[30:33]
	v_add_u32_e32 v218, s3, v166
	s_waitcnt vmcnt(7)
	ds_write_b128 v218, v[114:117]
	s_waitcnt lgkmcnt(7)
	v_mfma_f32_16x16x32_bf16 v[154:157], v[222:225], v[184:187], v[154:157]
	v_mfma_f32_16x16x32_bf16 v[90:93], v[222:225], v[198:201], v[90:93]
	global_load_dwordx4 v[114:117], v168, vcc offset:256
	v_mfma_f32_16x16x32_bf16 v[58:61], v[222:225], v[210:213], v[58:61]
	v_mfma_f32_16x16x32_bf16 v[26:29], v[222:225], v[214:217], v[26:29]
	s_waitcnt vmcnt(7)
	ds_write_b128 v218, v[106:109] offset:8192
	s_waitcnt lgkmcnt(7)
	v_mfma_f32_16x16x32_bf16 v[150:153], v[226:229], v[184:187], v[150:153]
	v_mfma_f32_16x16x32_bf16 v[86:89], v[226:229], v[198:201], v[86:89]
	v_add_u32_e32 v106, s34, v168
	global_load_dwordx4 v[106:109], v106, vcc offset:256
	v_mfma_f32_16x16x32_bf16 v[54:57], v[226:229], v[210:213], v[54:57]
	v_mfma_f32_16x16x32_bf16 v[22:25], v[226:229], v[214:217], v[22:25]
	s_waitcnt vmcnt(7)
	ds_write_b128 v218, v[110:113] offset:16384
	s_waitcnt lgkmcnt(7)
	v_mfma_f32_16x16x32_bf16 v[146:149], v[230:233], v[184:187], v[146:149]
	v_mfma_f32_16x16x32_bf16 v[82:85], v[230:233], v[198:201], v[82:85]
	v_add_u32_e32 v110, s35, v168
	global_load_dwordx4 v[110:113], v110, vcc offset:256
	v_mfma_f32_16x16x32_bf16 v[50:53], v[230:233], v[210:213], v[50:53]
	v_mfma_f32_16x16x32_bf16 v[18:21], v[230:233], v[214:217], v[18:21]
	s_waitcnt vmcnt(7)
	ds_write_b128 v218, v[126:129] offset:24576
	s_waitcnt lgkmcnt(7)
	v_mfma_f32_16x16x32_bf16 v[142:145], v[234:237], v[184:187], v[142:145]
	v_mfma_f32_16x16x32_bf16 v[78:81], v[234:237], v[198:201], v[78:81]
	v_add_u32_e32 v126, s36, v168
	global_load_dwordx4 v[126:129], v126, vcc offset:256
	v_mfma_f32_16x16x32_bf16 v[46:49], v[234:237], v[210:213], v[46:49]
	v_mfma_f32_16x16x32_bf16 v[14:17], v[234:237], v[214:217], v[14:17]
	s_waitcnt vmcnt(7)
	ds_write_b128 v218, v[122:125] offset:32768
	s_waitcnt lgkmcnt(7)
	v_mfma_f32_16x16x32_bf16 v[138:141], v[238:241], v[184:187], v[138:141]
	v_mfma_f32_16x16x32_bf16 v[74:77], v[238:241], v[198:201], v[74:77]
	global_load_dwordx4 v[122:125], v170, s[100:101] offset:256
	v_mfma_f32_16x16x32_bf16 v[42:45], v[238:241], v[210:213], v[42:45]
	v_mfma_f32_16x16x32_bf16 v[10:13], v[238:241], v[214:217], v[10:13]
	s_waitcnt vmcnt(7)
	ds_write_b128 v218, v[118:121] offset:40960
	s_waitcnt lgkmcnt(7)
	v_mfma_f32_16x16x32_bf16 v[102:105], v[242:245], v[184:187], v[102:105]
	v_mfma_f32_16x16x32_bf16 v[70:73], v[242:245], v[198:201], v[70:73]
	v_add_u32_e32 v118, s34, v170
	global_load_dwordx4 v[118:121], v118, s[100:101] offset:256
	v_mfma_f32_16x16x32_bf16 v[38:41], v[242:245], v[210:213], v[38:41]
	v_mfma_f32_16x16x32_bf16 v[6:9], v[242:245], v[214:217], v[6:9]
	s_waitcnt vmcnt(7)
	ds_write_b128 v218, v[134:137] offset:49152
	s_waitcnt lgkmcnt(7)
	v_mfma_f32_16x16x32_bf16 v[98:101], v[246:249], v[184:187], v[98:101]
	v_mfma_f32_16x16x32_bf16 v[66:69], v[246:249], v[198:201], v[66:69]
	v_add_u32_e32 v134, s35, v170
	global_load_dwordx4 v[134:137], v134, s[100:101] offset:256
	v_mfma_f32_16x16x32_bf16 v[34:37], v[246:249], v[210:213], v[34:37]
	v_mfma_f32_16x16x32_bf16 v[2:5], v[246:249], v[214:217], v[2:5]
	s_waitcnt vmcnt(7)
	ds_write_b128 v218, v[130:133] offset:57344
	v_add3_u32 v214, s2, v0, v206
	v_xor_b32_e32 v214, 64, v214
	v_add3_u32 v246, s2, v167, v206
	v_xor_b32_e32 v246, 64, v246
	v_add_u32_e32 v130, s36, v170
	global_load_dwordx4 v[130:133], v130, s[100:101] offset:256
	v_add_u32_e32 v168, 0x80, v168
	v_add_u32_e32 v170, 0x80, v170
	ds_read_b128 v[184:187], v214
	ds_read_b128 v[198:201], v214 offset:2048
	ds_read_b128 v[210:213], v214 offset:4096
	ds_read_b128 v[214:217], v214 offset:6144
	ds_read_b128 v[218:221], v246 offset:32768
	ds_read_b128 v[222:225], v246 offset:34816
	ds_read_b128 v[226:229], v246 offset:36864
	ds_read_b128 v[230:233], v246 offset:38912
	ds_read_b128 v[234:237], v246 offset:40960
	ds_read_b128 v[238:241], v246 offset:43008
	ds_read_b128 v[242:245], v246 offset:45056
	ds_read_b128 v[246:249], v246 offset:47104
	s_waitcnt lgkmcnt(7)
	v_mfma_f32_16x16x32_bf16 v[158:161], v[218:221], v[184:187], v[158:161]
	v_mfma_f32_16x16x32_bf16 v[94:97], v[218:221], v[198:201], v[94:97]
	v_mfma_f32_16x16x32_bf16 v[62:65], v[218:221], v[210:213], v[62:65]
	v_mfma_f32_16x16x32_bf16 v[30:33], v[218:221], v[214:217], v[30:33]
	s_waitcnt lgkmcnt(6)
	v_mfma_f32_16x16x32_bf16 v[154:157], v[222:225], v[184:187], v[154:157]
	v_mfma_f32_16x16x32_bf16 v[90:93], v[222:225], v[198:201], v[90:93]
	v_mfma_f32_16x16x32_bf16 v[58:61], v[222:225], v[210:213], v[58:61]
	v_mfma_f32_16x16x32_bf16 v[26:29], v[222:225], v[214:217], v[26:29]
	s_waitcnt lgkmcnt(5)
	v_mfma_f32_16x16x32_bf16 v[150:153], v[226:229], v[184:187], v[150:153]
	v_mfma_f32_16x16x32_bf16 v[86:89], v[226:229], v[198:201], v[86:89]
	v_mfma_f32_16x16x32_bf16 v[54:57], v[226:229], v[210:213], v[54:57]
	v_mfma_f32_16x16x32_bf16 v[22:25], v[226:229], v[214:217], v[22:25]
	s_waitcnt lgkmcnt(4)
	v_mfma_f32_16x16x32_bf16 v[146:149], v[230:233], v[184:187], v[146:149]
	v_mfma_f32_16x16x32_bf16 v[82:85], v[230:233], v[198:201], v[82:85]
	v_mfma_f32_16x16x32_bf16 v[50:53], v[230:233], v[210:213], v[50:53]
	v_mfma_f32_16x16x32_bf16 v[18:21], v[230:233], v[214:217], v[18:21]
	s_waitcnt lgkmcnt(3)
	v_mfma_f32_16x16x32_bf16 v[142:145], v[234:237], v[184:187], v[142:145]
	v_mfma_f32_16x16x32_bf16 v[78:81], v[234:237], v[198:201], v[78:81]
	v_mfma_f32_16x16x32_bf16 v[46:49], v[234:237], v[210:213], v[46:49]
	v_mfma_f32_16x16x32_bf16 v[14:17], v[234:237], v[214:217], v[14:17]
	s_waitcnt lgkmcnt(2)
	v_mfma_f32_16x16x32_bf16 v[138:141], v[238:241], v[184:187], v[138:141]
	v_mfma_f32_16x16x32_bf16 v[74:77], v[238:241], v[198:201], v[74:77]
	v_mfma_f32_16x16x32_bf16 v[42:45], v[238:241], v[210:213], v[42:45]
	v_mfma_f32_16x16x32_bf16 v[10:13], v[238:241], v[214:217], v[10:13]
	s_waitcnt lgkmcnt(1)
	v_mfma_f32_16x16x32_bf16 v[102:105], v[242:245], v[184:187], v[102:105]
	v_mfma_f32_16x16x32_bf16 v[70:73], v[242:245], v[198:201], v[70:73]
	v_mfma_f32_16x16x32_bf16 v[38:41], v[242:245], v[210:213], v[38:41]
	v_mfma_f32_16x16x32_bf16 v[6:9], v[242:245], v[214:217], v[6:9]
	s_waitcnt lgkmcnt(0)
	v_mfma_f32_16x16x32_bf16 v[98:101], v[246:249], v[184:187], v[98:101]
	v_mfma_f32_16x16x32_bf16 v[66:69], v[246:249], v[198:201], v[66:69]
	v_mfma_f32_16x16x32_bf16 v[34:37], v[246:249], v[210:213], v[34:37]
	v_mfma_f32_16x16x32_bf16 v[2:5], v[246:249], v[214:217], v[2:5]
	s_waitcnt lgkmcnt(0)
	s_barrier
	s_cmp_eq_u32 s10, 16
	s_mov_b32 s4, s10
	s_cbranch_scc0 .LBB0_1441
	s_waitcnt vmcnt(4)
	v_mul_f32_e32 v109, 0xbfb8aa3b, v158
	v_exp_f32_e32 v109, v109
	s_waitcnt vmcnt(3)
	v_mul_f32_e32 v111, 0xbfb8aa3b, v159
	v_exp_f32_e32 v111, v111
	v_mul_f32_e32 v115, 0xbfb8aa3b, v161
	v_add_f32_e32 v109, 1.0, v109
	v_rcp_f32_e32 v114, v109
	v_add_f32_e32 v109, 1.0, v111
	v_mul_f32_e32 v111, 0xbfb8aa3b, v160
	v_exp_f32_e32 v111, v111
	v_exp_f32_e32 v117, v115
	v_rcp_f32_e32 v116, v109
	s_waitcnt vmcnt(2)
	v_mov_b32_e32 v118, v158
	v_add_f32_e32 v109, 1.0, v111
	v_rcp_f32_e32 v115, v109
	v_add_f32_e32 v109, 1.0, v117
	v_rcp_f32_e32 v117, v109
	v_mov_b32_e32 v119, v160
	v_pk_mul_f32 v[114:115], v[118:119], v[114:115]
	v_mov_b32_e32 v118, v154
	v_mov_b32_e32 v119, v156
	v_mov_b32_e32 v160, v159
	v_pk_mul_f32 v[114:115], v[118:119], v[114:115]
	v_pk_mul_f32 v[116:117], v[160:161], v[116:117]
	v_mov_b32_e32 v156, v155
	v_pk_mul_f32 v[116:117], v[156:157], v[116:117]
	v_and_b32_sdwa v111, v115, v177 dst_sel:DWORD dst_unused:UNUSED_PAD src0_sel:WORD_1 src1_sel:DWORD
	v_and_b32_sdwa v118, v114, v177 dst_sel:DWORD dst_unused:UNUSED_PAD src0_sel:WORD_1 src1_sel:DWORD
	v_add3_u32 v111, v115, v111, s28
	v_and_b32_sdwa v115, v117, v177 dst_sel:DWORD dst_unused:UNUSED_PAD src0_sel:WORD_1 src1_sel:DWORD
	v_add3_u32 v114, v114, v118, s28
	v_and_b32_sdwa v118, v116, v177 dst_sel:DWORD dst_unused:UNUSED_PAD src0_sel:WORD_1 src1_sel:DWORD
	v_add3_u32 v115, v117, v115, s28
	v_or_b32_e32 v106, s7, v207
	v_add3_u32 v116, v116, v118, s28
	v_and_b32_e32 v115, 0xffff0000, v115
	v_ashrrev_i32_e32 v106, 1, v106
	v_and_b32_e32 v116, 0xffff0000, v116
	v_or_b32_sdwa v115, v115, v111 dst_sel:DWORD dst_unused:UNUSED_PAD src0_sel:DWORD src1_sel:WORD_1
	v_mul_f32_e32 v111, 0xbfb8aa3b, v150
	v_or_b32_e32 v108, v106, v208
	v_or_b32_sdwa v114, v116, v114 dst_sel:DWORD dst_unused:UNUSED_PAD src0_sel:DWORD src1_sel:WORD_1
	v_exp_f32_e32 v111, v111
	v_mul_f32_e32 v116, 0xbfb8aa3b, v151
	v_add_u32_e32 v110, s6, v205
	v_mov_b64_e32 v[106:107], s[12:13]
	v_ashrrev_i32_e32 v109, 31, v108
	v_exp_f32_e32 v116, v116
	v_mad_i64_i32 v[112:113], s[6:7], v110, s52, v[106:107]
	v_lshlrev_b64 v[108:109], 1, v[108:109]
	v_lshl_add_u64 v[112:113], v[112:113], 0, v[108:109]
	s_waitcnt vmcnt(0)
	global_store_dwordx2 v[112:113], v[114:115], off
	v_add_f32_e32 v111, 1.0, v111
	v_mul_f32_e32 v115, 0xbfb8aa3b, v152
	v_rcp_f32_e32 v114, v111
	v_add_f32_e32 v111, 1.0, v116
	v_exp_f32_e32 v115, v115
	v_mul_f32_e32 v116, 0xbfb8aa3b, v153
	v_exp_f32_e32 v117, v116
	v_rcp_f32_e32 v116, v111
	v_add_f32_e32 v111, 1.0, v115
	v_rcp_f32_e32 v115, v111
	v_add_f32_e32 v111, 1.0, v117
	v_rcp_f32_e32 v117, v111
	v_mov_b32_e32 v118, v150
	v_mov_b32_e32 v119, v152
	v_pk_mul_f32 v[114:115], v[118:119], v[114:115]
	v_mov_b32_e32 v118, v146
	v_mov_b32_e32 v119, v148
	v_mov_b32_e32 v152, v151
	v_pk_mul_f32 v[114:115], v[118:119], v[114:115]
	v_pk_mul_f32 v[116:117], v[152:153], v[116:117]
	v_mov_b32_e32 v148, v147
	v_pk_mul_f32 v[116:117], v[148:149], v[116:117]
	v_and_b32_sdwa v111, v115, v177 dst_sel:DWORD dst_unused:UNUSED_PAD src0_sel:WORD_1 src1_sel:DWORD
	v_and_b32_sdwa v118, v114, v177 dst_sel:DWORD dst_unused:UNUSED_PAD src0_sel:WORD_1 src1_sel:DWORD
	v_add3_u32 v111, v115, v111, s28
	v_and_b32_sdwa v115, v117, v177 dst_sel:DWORD dst_unused:UNUSED_PAD src0_sel:WORD_1 src1_sel:DWORD
	v_add3_u32 v114, v114, v118, s28
	v_and_b32_sdwa v118, v116, v177 dst_sel:DWORD dst_unused:UNUSED_PAD src0_sel:WORD_1 src1_sel:DWORD
	v_add3_u32 v115, v117, v115, s28
	v_add3_u32 v116, v116, v118, s28
	v_and_b32_e32 v115, 0xffff0000, v115
	v_and_b32_e32 v116, 0xffff0000, v116
	v_or_b32_sdwa v115, v115, v111 dst_sel:DWORD dst_unused:UNUSED_PAD src0_sel:DWORD src1_sel:WORD_1
	v_mul_f32_e32 v111, 0xbfb8aa3b, v142
	v_or_b32_sdwa v114, v116, v114 dst_sel:DWORD dst_unused:UNUSED_PAD src0_sel:DWORD src1_sel:WORD_1
	v_exp_f32_e32 v111, v111
	v_mul_f32_e32 v116, 0xbfb8aa3b, v143
	v_exp_f32_e32 v116, v116
	global_store_dwordx2 v[112:113], v[114:115], off offset:32
	v_add_f32_e32 v111, 1.0, v111
	v_mul_f32_e32 v115, 0xbfb8aa3b, v144
	v_rcp_f32_e32 v114, v111
	v_add_f32_e32 v111, 1.0, v116
	v_exp_f32_e32 v115, v115
	v_mul_f32_e32 v116, 0xbfb8aa3b, v145
	v_exp_f32_e32 v117, v116
	v_rcp_f32_e32 v116, v111
	v_add_f32_e32 v111, 1.0, v115
	v_rcp_f32_e32 v115, v111
	v_add_f32_e32 v111, 1.0, v117
	v_rcp_f32_e32 v117, v111
	v_mov_b32_e32 v118, v142
	v_mov_b32_e32 v119, v144
	v_pk_mul_f32 v[114:115], v[118:119], v[114:115]
	v_mov_b32_e32 v118, v138
	v_mov_b32_e32 v119, v140
	v_mov_b32_e32 v144, v143
	v_pk_mul_f32 v[114:115], v[118:119], v[114:115]
	v_pk_mul_f32 v[116:117], v[144:145], v[116:117]
	v_mov_b32_e32 v140, v139
	v_pk_mul_f32 v[116:117], v[140:141], v[116:117]
	v_and_b32_sdwa v111, v115, v177 dst_sel:DWORD dst_unused:UNUSED_PAD src0_sel:WORD_1 src1_sel:DWORD
	v_and_b32_sdwa v118, v114, v177 dst_sel:DWORD dst_unused:UNUSED_PAD src0_sel:WORD_1 src1_sel:DWORD
	v_add3_u32 v111, v115, v111, s28
	v_and_b32_sdwa v115, v117, v177 dst_sel:DWORD dst_unused:UNUSED_PAD src0_sel:WORD_1 src1_sel:DWORD
	v_add3_u32 v114, v114, v118, s28
	v_and_b32_sdwa v118, v116, v177 dst_sel:DWORD dst_unused:UNUSED_PAD src0_sel:WORD_1 src1_sel:DWORD
	v_add3_u32 v115, v117, v115, s28
	v_add3_u32 v116, v116, v118, s28
	v_and_b32_e32 v115, 0xffff0000, v115
	v_and_b32_e32 v116, 0xffff0000, v116
	v_or_b32_sdwa v115, v115, v111 dst_sel:DWORD dst_unused:UNUSED_PAD src0_sel:DWORD src1_sel:WORD_1
	v_mul_f32_e32 v111, 0xbfb8aa3b, v102
	v_or_b32_sdwa v114, v116, v114 dst_sel:DWORD dst_unused:UNUSED_PAD src0_sel:DWORD src1_sel:WORD_1
	v_exp_f32_e32 v111, v111
	v_mul_f32_e32 v116, 0xbfb8aa3b, v103
	v_exp_f32_e32 v116, v116
	global_store_dwordx2 v[112:113], v[114:115], off offset:64
	v_add_f32_e32 v111, 1.0, v111
	v_mul_f32_e32 v115, 0xbfb8aa3b, v104
	v_rcp_f32_e32 v114, v111
	v_add_f32_e32 v111, 1.0, v116
	v_exp_f32_e32 v115, v115
	v_mul_f32_e32 v116, 0xbfb8aa3b, v105
	v_exp_f32_e32 v117, v116
	v_rcp_f32_e32 v116, v111
	v_add_f32_e32 v111, 1.0, v115
	v_rcp_f32_e32 v115, v111
	v_add_f32_e32 v111, 1.0, v117
	v_rcp_f32_e32 v117, v111
	v_mov_b32_e32 v118, v102
	v_mov_b32_e32 v119, v104
	v_mov_b32_e32 v104, v103
	v_pk_mul_f32 v[114:115], v[118:119], v[114:115]
	v_mov_b32_e32 v119, v100
	v_pk_mul_f32 v[102:103], v[104:105], v[116:117]
	v_mov_b32_e32 v100, v99
	v_mov_b32_e32 v118, v98
	v_pk_mul_f32 v[98:99], v[100:101], v[102:103]
	v_pk_mul_f32 v[114:115], v[118:119], v[114:115]
	v_and_b32_sdwa v102, v99, v177 dst_sel:DWORD dst_unused:UNUSED_PAD src0_sel:WORD_1 src1_sel:DWORD
	v_and_b32_sdwa v103, v98, v177 dst_sel:DWORD dst_unused:UNUSED_PAD src0_sel:WORD_1 src1_sel:DWORD
	v_and_b32_sdwa v100, v115, v177 dst_sel:DWORD dst_unused:UNUSED_PAD src0_sel:WORD_1 src1_sel:DWORD
	v_and_b32_sdwa v101, v114, v177 dst_sel:DWORD dst_unused:UNUSED_PAD src0_sel:WORD_1 src1_sel:DWORD
	v_add3_u32 v99, v99, v102, s28
	v_add3_u32 v98, v98, v103, s28
	v_add3_u32 v101, v114, v101, s28
	v_add3_u32 v100, v115, v100, s28
	v_and_b32_e32 v99, 0xffff0000, v99
	v_and_b32_e32 v98, 0xffff0000, v98
	v_or_b32_sdwa v99, v99, v100 dst_sel:DWORD dst_unused:UNUSED_PAD src0_sel:DWORD src1_sel:WORD_1
	v_or_b32_sdwa v98, v98, v101 dst_sel:DWORD dst_unused:UNUSED_PAD src0_sel:DWORD src1_sel:WORD_1
	global_store_dwordx2 v[112:113], v[98:99], off offset:96
	v_mul_f32_e32 v99, 0xbfb8aa3b, v94
	v_exp_f32_e32 v100, v99
	v_mul_f32_e32 v99, 0xbfb8aa3b, v95
	v_mul_f32_e32 v102, 0xbfb8aa3b, v96
	v_exp_f32_e32 v101, v99
	v_exp_f32_e32 v103, v102
	v_mul_f32_e32 v102, 0xbfb8aa3b, v97
	v_exp_f32_e32 v104, v102
	v_add_f32_e32 v101, 1.0, v101
	v_add_f32_e32 v100, 1.0, v100
	v_rcp_f32_e32 v102, v101
	v_add_f32_e32 v101, 1.0, v103
	v_add_f32_e32 v103, 1.0, v104
	v_rcp_f32_e32 v100, v100
	v_rcp_f32_e32 v101, v101
	v_rcp_f32_e32 v103, v103
	v_mov_b32_e32 v104, v94
	v_mov_b32_e32 v105, v96
	v_mov_b32_e32 v96, v95
	v_pk_mul_f32 v[100:101], v[104:105], v[100:101]
	v_mov_b32_e32 v105, v92
	v_pk_mul_f32 v[94:95], v[96:97], v[102:103]
	v_mov_b32_e32 v92, v91
	v_mov_b32_e32 v104, v90
	v_pk_mul_f32 v[90:91], v[92:93], v[94:95]
	v_pk_mul_f32 v[100:101], v[104:105], v[100:101]
	v_and_b32_sdwa v94, v91, v177 dst_sel:DWORD dst_unused:UNUSED_PAD src0_sel:WORD_1 src1_sel:DWORD
	v_and_b32_sdwa v92, v101, v177 dst_sel:DWORD dst_unused:UNUSED_PAD src0_sel:WORD_1 src1_sel:DWORD
	v_and_b32_sdwa v95, v90, v177 dst_sel:DWORD dst_unused:UNUSED_PAD src0_sel:WORD_1 src1_sel:DWORD
	v_add3_u32 v91, v91, v94, s28
	v_and_b32_sdwa v93, v100, v177 dst_sel:DWORD dst_unused:UNUSED_PAD src0_sel:WORD_1 src1_sel:DWORD
	v_add3_u32 v92, v101, v92, s28
	v_add3_u32 v90, v90, v95, s28
	v_and_b32_e32 v91, 0xffff0000, v91
	v_add3_u32 v93, v100, v93, s28
	v_and_b32_e32 v90, 0xffff0000, v90
	v_or_b32_sdwa v91, v91, v92 dst_sel:DWORD dst_unused:UNUSED_PAD src0_sel:DWORD src1_sel:WORD_1
	v_mul_f32_e32 v92, 0xbfb8aa3b, v86
	v_or_b32_sdwa v90, v90, v93 dst_sel:DWORD dst_unused:UNUSED_PAD src0_sel:DWORD src1_sel:WORD_1
	v_exp_f32_e32 v92, v92
	v_mul_f32_e32 v93, 0xbfb8aa3b, v87
	v_or_b32_e32 v98, 16, v110
	v_exp_f32_e32 v93, v93
	v_mad_i64_i32 v[98:99], s[6:7], v98, s52, v[106:107]
	v_lshl_add_u64 v[98:99], v[98:99], 0, v[108:109]
	global_store_dwordx2 v[98:99], v[90:91], off
	v_add_f32_e32 v90, 1.0, v92
	v_mul_f32_e32 v92, 0xbfb8aa3b, v88
	v_add_f32_e32 v91, 1.0, v93
	v_exp_f32_e32 v93, v92
	v_mul_f32_e32 v92, 0xbfb8aa3b, v89
	v_exp_f32_e32 v94, v92
	v_rcp_f32_e32 v92, v91
	v_add_f32_e32 v91, 1.0, v93
	v_rcp_f32_e32 v90, v90
	v_add_f32_e32 v93, 1.0, v94
	v_rcp_f32_e32 v91, v91
	v_rcp_f32_e32 v93, v93
	v_mov_b32_e32 v94, v86
	v_mov_b32_e32 v95, v88
	v_mov_b32_e32 v88, v87
	v_pk_mul_f32 v[90:91], v[94:95], v[90:91]
	v_mov_b32_e32 v95, v84
	v_pk_mul_f32 v[86:87], v[88:89], v[92:93]
	v_mov_b32_e32 v84, v83
	v_mov_b32_e32 v94, v82
	v_pk_mul_f32 v[82:83], v[84:85], v[86:87]
	v_pk_mul_f32 v[90:91], v[94:95], v[90:91]
	v_and_b32_sdwa v86, v83, v177 dst_sel:DWORD dst_unused:UNUSED_PAD src0_sel:WORD_1 src1_sel:DWORD
	v_and_b32_sdwa v84, v91, v177 dst_sel:DWORD dst_unused:UNUSED_PAD src0_sel:WORD_1 src1_sel:DWORD
	v_and_b32_sdwa v87, v82, v177 dst_sel:DWORD dst_unused:UNUSED_PAD src0_sel:WORD_1 src1_sel:DWORD
	v_add3_u32 v83, v83, v86, s28
	v_and_b32_sdwa v85, v90, v177 dst_sel:DWORD dst_unused:UNUSED_PAD src0_sel:WORD_1 src1_sel:DWORD
	v_add3_u32 v84, v91, v84, s28
	v_add3_u32 v82, v82, v87, s28
	v_and_b32_e32 v83, 0xffff0000, v83
	v_add3_u32 v85, v90, v85, s28
	v_and_b32_e32 v82, 0xffff0000, v82
	v_or_b32_sdwa v83, v83, v84 dst_sel:DWORD dst_unused:UNUSED_PAD src0_sel:DWORD src1_sel:WORD_1
	v_mul_f32_e32 v84, 0xbfb8aa3b, v78
	v_or_b32_sdwa v82, v82, v85 dst_sel:DWORD dst_unused:UNUSED_PAD src0_sel:DWORD src1_sel:WORD_1
	v_exp_f32_e32 v84, v84
	v_mul_f32_e32 v85, 0xbfb8aa3b, v79
	v_exp_f32_e32 v85, v85
	global_store_dwordx2 v[98:99], v[82:83], off offset:32
	v_add_f32_e32 v82, 1.0, v84
	v_mul_f32_e32 v84, 0xbfb8aa3b, v80
	v_add_f32_e32 v83, 1.0, v85
	v_exp_f32_e32 v85, v84
	v_mul_f32_e32 v84, 0xbfb8aa3b, v81
	v_exp_f32_e32 v86, v84
	v_rcp_f32_e32 v84, v83
	v_add_f32_e32 v83, 1.0, v85
	v_rcp_f32_e32 v82, v82
	v_add_f32_e32 v85, 1.0, v86
	v_rcp_f32_e32 v83, v83
	v_rcp_f32_e32 v85, v85
	v_mov_b32_e32 v86, v78
	v_mov_b32_e32 v87, v80
	v_mov_b32_e32 v80, v79
	v_pk_mul_f32 v[82:83], v[86:87], v[82:83]
	v_mov_b32_e32 v87, v76
	v_pk_mul_f32 v[78:79], v[80:81], v[84:85]
	v_mov_b32_e32 v76, v75
	v_mov_b32_e32 v86, v74
	v_pk_mul_f32 v[74:75], v[76:77], v[78:79]
	v_pk_mul_f32 v[82:83], v[86:87], v[82:83]
	v_and_b32_sdwa v78, v75, v177 dst_sel:DWORD dst_unused:UNUSED_PAD src0_sel:WORD_1 src1_sel:DWORD
	v_and_b32_sdwa v76, v83, v177 dst_sel:DWORD dst_unused:UNUSED_PAD src0_sel:WORD_1 src1_sel:DWORD
	v_and_b32_sdwa v79, v74, v177 dst_sel:DWORD dst_unused:UNUSED_PAD src0_sel:WORD_1 src1_sel:DWORD
	v_add3_u32 v75, v75, v78, s28
	v_and_b32_sdwa v77, v82, v177 dst_sel:DWORD dst_unused:UNUSED_PAD src0_sel:WORD_1 src1_sel:DWORD
	v_add3_u32 v76, v83, v76, s28
	v_add3_u32 v74, v74, v79, s28
	v_and_b32_e32 v75, 0xffff0000, v75
	v_add3_u32 v77, v82, v77, s28
	v_and_b32_e32 v74, 0xffff0000, v74
	v_or_b32_sdwa v75, v75, v76 dst_sel:DWORD dst_unused:UNUSED_PAD src0_sel:DWORD src1_sel:WORD_1
	v_mul_f32_e32 v76, 0xbfb8aa3b, v70
	v_or_b32_sdwa v74, v74, v77 dst_sel:DWORD dst_unused:UNUSED_PAD src0_sel:DWORD src1_sel:WORD_1
	v_exp_f32_e32 v76, v76
	v_mul_f32_e32 v77, 0xbfb8aa3b, v71
	v_exp_f32_e32 v77, v77
	global_store_dwordx2 v[98:99], v[74:75], off offset:64
	v_add_f32_e32 v74, 1.0, v76
	v_mul_f32_e32 v76, 0xbfb8aa3b, v72
	v_add_f32_e32 v75, 1.0, v77
	v_exp_f32_e32 v77, v76
	v_mul_f32_e32 v76, 0xbfb8aa3b, v73
	v_exp_f32_e32 v78, v76
	v_rcp_f32_e32 v76, v75
	v_add_f32_e32 v75, 1.0, v77
	v_rcp_f32_e32 v74, v74
	v_add_f32_e32 v77, 1.0, v78
	v_rcp_f32_e32 v75, v75
	v_rcp_f32_e32 v77, v77
	v_mov_b32_e32 v78, v70
	v_mov_b32_e32 v79, v72
	v_mov_b32_e32 v72, v71
	v_pk_mul_f32 v[74:75], v[78:79], v[74:75]
	v_mov_b32_e32 v79, v68
	v_pk_mul_f32 v[70:71], v[72:73], v[76:77]
	v_mov_b32_e32 v68, v67
	v_mov_b32_e32 v78, v66
	v_pk_mul_f32 v[66:67], v[68:69], v[70:71]
	v_pk_mul_f32 v[74:75], v[78:79], v[74:75]
	v_and_b32_sdwa v70, v67, v177 dst_sel:DWORD dst_unused:UNUSED_PAD src0_sel:WORD_1 src1_sel:DWORD
	v_and_b32_sdwa v71, v66, v177 dst_sel:DWORD dst_unused:UNUSED_PAD src0_sel:WORD_1 src1_sel:DWORD
	v_and_b32_sdwa v68, v75, v177 dst_sel:DWORD dst_unused:UNUSED_PAD src0_sel:WORD_1 src1_sel:DWORD
	v_and_b32_sdwa v69, v74, v177 dst_sel:DWORD dst_unused:UNUSED_PAD src0_sel:WORD_1 src1_sel:DWORD
	v_add3_u32 v67, v67, v70, s28
	v_add3_u32 v66, v66, v71, s28
	v_add3_u32 v69, v74, v69, s28
	v_add3_u32 v68, v75, v68, s28
	v_and_b32_e32 v67, 0xffff0000, v67
	v_and_b32_e32 v66, 0xffff0000, v66
	v_or_b32_sdwa v67, v67, v68 dst_sel:DWORD dst_unused:UNUSED_PAD src0_sel:DWORD src1_sel:WORD_1
	v_or_b32_sdwa v66, v66, v69 dst_sel:DWORD dst_unused:UNUSED_PAD src0_sel:DWORD src1_sel:WORD_1
	global_store_dwordx2 v[98:99], v[66:67], off offset:96
	v_mul_f32_e32 v67, 0xbfb8aa3b, v62
	v_exp_f32_e32 v68, v67
	v_mul_f32_e32 v67, 0xbfb8aa3b, v63
	v_mul_f32_e32 v70, 0xbfb8aa3b, v64
	v_exp_f32_e32 v69, v67
	v_exp_f32_e32 v71, v70
	v_mul_f32_e32 v70, 0xbfb8aa3b, v65
	v_exp_f32_e32 v72, v70
	v_add_f32_e32 v69, 1.0, v69
	v_add_f32_e32 v68, 1.0, v68
	v_rcp_f32_e32 v70, v69
	v_add_f32_e32 v69, 1.0, v71
	v_add_f32_e32 v71, 1.0, v72
	v_rcp_f32_e32 v68, v68
	v_rcp_f32_e32 v69, v69
	v_rcp_f32_e32 v71, v71
	v_mov_b32_e32 v72, v62
	v_mov_b32_e32 v73, v64
	v_mov_b32_e32 v64, v63
	v_pk_mul_f32 v[68:69], v[72:73], v[68:69]
	v_mov_b32_e32 v73, v60
	v_pk_mul_f32 v[62:63], v[64:65], v[70:71]
	v_mov_b32_e32 v60, v59
	v_mov_b32_e32 v72, v58
	v_pk_mul_f32 v[58:59], v[60:61], v[62:63]
	v_pk_mul_f32 v[68:69], v[72:73], v[68:69]
	v_and_b32_sdwa v62, v59, v177 dst_sel:DWORD dst_unused:UNUSED_PAD src0_sel:WORD_1 src1_sel:DWORD
	v_and_b32_sdwa v60, v69, v177 dst_sel:DWORD dst_unused:UNUSED_PAD src0_sel:WORD_1 src1_sel:DWORD
	v_and_b32_sdwa v63, v58, v177 dst_sel:DWORD dst_unused:UNUSED_PAD src0_sel:WORD_1 src1_sel:DWORD
	v_add3_u32 v59, v59, v62, s28
	v_and_b32_sdwa v61, v68, v177 dst_sel:DWORD dst_unused:UNUSED_PAD src0_sel:WORD_1 src1_sel:DWORD
	v_add3_u32 v60, v69, v60, s28
	v_add3_u32 v58, v58, v63, s28
	v_and_b32_e32 v59, 0xffff0000, v59
	v_add3_u32 v61, v68, v61, s28
	v_and_b32_e32 v58, 0xffff0000, v58
	v_or_b32_sdwa v59, v59, v60 dst_sel:DWORD dst_unused:UNUSED_PAD src0_sel:DWORD src1_sel:WORD_1
	v_mul_f32_e32 v60, 0xbfb8aa3b, v54
	v_or_b32_sdwa v58, v58, v61 dst_sel:DWORD dst_unused:UNUSED_PAD src0_sel:DWORD src1_sel:WORD_1
	v_exp_f32_e32 v60, v60
	v_mul_f32_e32 v61, 0xbfb8aa3b, v55
	v_or_b32_e32 v66, 32, v110
	v_exp_f32_e32 v61, v61
	v_mad_i64_i32 v[66:67], s[6:7], v66, s52, v[106:107]
	v_lshl_add_u64 v[66:67], v[66:67], 0, v[108:109]
	global_store_dwordx2 v[66:67], v[58:59], off
	v_add_f32_e32 v58, 1.0, v60
	v_mul_f32_e32 v60, 0xbfb8aa3b, v56
	v_add_f32_e32 v59, 1.0, v61
	v_exp_f32_e32 v61, v60
	v_mul_f32_e32 v60, 0xbfb8aa3b, v57
	v_exp_f32_e32 v62, v60
	v_rcp_f32_e32 v60, v59
	v_add_f32_e32 v59, 1.0, v61
	v_rcp_f32_e32 v58, v58
	v_add_f32_e32 v61, 1.0, v62
	v_rcp_f32_e32 v59, v59
	v_rcp_f32_e32 v61, v61
	v_mov_b32_e32 v62, v54
	v_mov_b32_e32 v63, v56
	v_mov_b32_e32 v56, v55
	v_pk_mul_f32 v[58:59], v[62:63], v[58:59]
	v_mov_b32_e32 v63, v52
	v_pk_mul_f32 v[54:55], v[56:57], v[60:61]
	v_mov_b32_e32 v52, v51
	v_mov_b32_e32 v62, v50
	v_pk_mul_f32 v[50:51], v[52:53], v[54:55]
	v_pk_mul_f32 v[58:59], v[62:63], v[58:59]
	v_and_b32_sdwa v54, v51, v177 dst_sel:DWORD dst_unused:UNUSED_PAD src0_sel:WORD_1 src1_sel:DWORD
	v_and_b32_sdwa v52, v59, v177 dst_sel:DWORD dst_unused:UNUSED_PAD src0_sel:WORD_1 src1_sel:DWORD
	v_and_b32_sdwa v55, v50, v177 dst_sel:DWORD dst_unused:UNUSED_PAD src0_sel:WORD_1 src1_sel:DWORD
	v_add3_u32 v51, v51, v54, s28
	v_and_b32_sdwa v53, v58, v177 dst_sel:DWORD dst_unused:UNUSED_PAD src0_sel:WORD_1 src1_sel:DWORD
	v_add3_u32 v52, v59, v52, s28
	v_add3_u32 v50, v50, v55, s28
	v_and_b32_e32 v51, 0xffff0000, v51
	v_add3_u32 v53, v58, v53, s28
	v_and_b32_e32 v50, 0xffff0000, v50
	v_or_b32_sdwa v51, v51, v52 dst_sel:DWORD dst_unused:UNUSED_PAD src0_sel:DWORD src1_sel:WORD_1
	v_mul_f32_e32 v52, 0xbfb8aa3b, v46
	v_or_b32_sdwa v50, v50, v53 dst_sel:DWORD dst_unused:UNUSED_PAD src0_sel:DWORD src1_sel:WORD_1
	v_exp_f32_e32 v52, v52
	v_mul_f32_e32 v53, 0xbfb8aa3b, v47
	v_exp_f32_e32 v53, v53
	global_store_dwordx2 v[66:67], v[50:51], off offset:32
	v_add_f32_e32 v50, 1.0, v52
	v_mul_f32_e32 v52, 0xbfb8aa3b, v48
	v_add_f32_e32 v51, 1.0, v53
	v_exp_f32_e32 v53, v52
	v_mul_f32_e32 v52, 0xbfb8aa3b, v49
	v_exp_f32_e32 v54, v52
	v_rcp_f32_e32 v52, v51
	v_add_f32_e32 v51, 1.0, v53
	v_rcp_f32_e32 v50, v50
	v_add_f32_e32 v53, 1.0, v54
	v_rcp_f32_e32 v51, v51
	v_rcp_f32_e32 v53, v53
	v_mov_b32_e32 v54, v46
	v_mov_b32_e32 v55, v48
	v_mov_b32_e32 v48, v47
	v_pk_mul_f32 v[50:51], v[54:55], v[50:51]
	v_mov_b32_e32 v55, v44
	v_pk_mul_f32 v[46:47], v[48:49], v[52:53]
	v_mov_b32_e32 v44, v43
	v_mov_b32_e32 v54, v42
	v_pk_mul_f32 v[42:43], v[44:45], v[46:47]
	v_pk_mul_f32 v[50:51], v[54:55], v[50:51]
	v_and_b32_sdwa v46, v43, v177 dst_sel:DWORD dst_unused:UNUSED_PAD src0_sel:WORD_1 src1_sel:DWORD
	v_and_b32_sdwa v44, v51, v177 dst_sel:DWORD dst_unused:UNUSED_PAD src0_sel:WORD_1 src1_sel:DWORD
	v_and_b32_sdwa v47, v42, v177 dst_sel:DWORD dst_unused:UNUSED_PAD src0_sel:WORD_1 src1_sel:DWORD
	v_add3_u32 v43, v43, v46, s28
	v_and_b32_sdwa v45, v50, v177 dst_sel:DWORD dst_unused:UNUSED_PAD src0_sel:WORD_1 src1_sel:DWORD
	v_add3_u32 v44, v51, v44, s28
	v_add3_u32 v42, v42, v47, s28
	v_and_b32_e32 v43, 0xffff0000, v43
	v_add3_u32 v45, v50, v45, s28
	v_and_b32_e32 v42, 0xffff0000, v42
	v_or_b32_sdwa v43, v43, v44 dst_sel:DWORD dst_unused:UNUSED_PAD src0_sel:DWORD src1_sel:WORD_1
	v_mul_f32_e32 v44, 0xbfb8aa3b, v38
	v_or_b32_sdwa v42, v42, v45 dst_sel:DWORD dst_unused:UNUSED_PAD src0_sel:DWORD src1_sel:WORD_1
	v_exp_f32_e32 v44, v44
	v_mul_f32_e32 v45, 0xbfb8aa3b, v39
	v_exp_f32_e32 v45, v45
	global_store_dwordx2 v[66:67], v[42:43], off offset:64
	v_add_f32_e32 v42, 1.0, v44
	v_mul_f32_e32 v44, 0xbfb8aa3b, v40
	v_add_f32_e32 v43, 1.0, v45
	v_exp_f32_e32 v45, v44
	v_mul_f32_e32 v44, 0xbfb8aa3b, v41
	v_exp_f32_e32 v46, v44
	v_rcp_f32_e32 v44, v43
	v_add_f32_e32 v43, 1.0, v45
	v_rcp_f32_e32 v42, v42
	v_add_f32_e32 v45, 1.0, v46
	v_rcp_f32_e32 v43, v43
	v_rcp_f32_e32 v45, v45
	v_mov_b32_e32 v46, v38
	v_mov_b32_e32 v47, v40
	v_mov_b32_e32 v40, v39
	v_pk_mul_f32 v[42:43], v[46:47], v[42:43]
	v_mov_b32_e32 v47, v36
	v_pk_mul_f32 v[38:39], v[40:41], v[44:45]
	v_mov_b32_e32 v36, v35
	v_mov_b32_e32 v46, v34
	v_pk_mul_f32 v[34:35], v[36:37], v[38:39]
	v_pk_mul_f32 v[42:43], v[46:47], v[42:43]
	v_and_b32_sdwa v38, v35, v177 dst_sel:DWORD dst_unused:UNUSED_PAD src0_sel:WORD_1 src1_sel:DWORD
	v_and_b32_sdwa v39, v34, v177 dst_sel:DWORD dst_unused:UNUSED_PAD src0_sel:WORD_1 src1_sel:DWORD
	v_and_b32_sdwa v36, v43, v177 dst_sel:DWORD dst_unused:UNUSED_PAD src0_sel:WORD_1 src1_sel:DWORD
	v_and_b32_sdwa v37, v42, v177 dst_sel:DWORD dst_unused:UNUSED_PAD src0_sel:WORD_1 src1_sel:DWORD
	v_add3_u32 v35, v35, v38, s28
	v_add3_u32 v34, v34, v39, s28
	v_add3_u32 v37, v42, v37, s28
	v_add3_u32 v36, v43, v36, s28
	v_and_b32_e32 v35, 0xffff0000, v35
	v_and_b32_e32 v34, 0xffff0000, v34
	v_or_b32_sdwa v35, v35, v36 dst_sel:DWORD dst_unused:UNUSED_PAD src0_sel:DWORD src1_sel:WORD_1
	v_or_b32_sdwa v34, v34, v37 dst_sel:DWORD dst_unused:UNUSED_PAD src0_sel:DWORD src1_sel:WORD_1
	global_store_dwordx2 v[66:67], v[34:35], off offset:96
	v_mul_f32_e32 v35, 0xbfb8aa3b, v30
	v_exp_f32_e32 v36, v35
	v_mul_f32_e32 v35, 0xbfb8aa3b, v31
	v_mul_f32_e32 v38, 0xbfb8aa3b, v32
	v_exp_f32_e32 v37, v35
	v_exp_f32_e32 v39, v38
	v_mul_f32_e32 v38, 0xbfb8aa3b, v33
	v_exp_f32_e32 v40, v38
	v_add_f32_e32 v37, 1.0, v37
	v_add_f32_e32 v36, 1.0, v36
	v_rcp_f32_e32 v38, v37
	v_add_f32_e32 v37, 1.0, v39
	v_add_f32_e32 v39, 1.0, v40
	v_rcp_f32_e32 v36, v36
	v_rcp_f32_e32 v37, v37
	v_rcp_f32_e32 v39, v39
	v_mov_b32_e32 v40, v30
	v_mov_b32_e32 v41, v32
	v_mov_b32_e32 v32, v31
	v_pk_mul_f32 v[36:37], v[40:41], v[36:37]
	v_mov_b32_e32 v41, v28
	v_pk_mul_f32 v[30:31], v[32:33], v[38:39]
	v_mov_b32_e32 v28, v27
	v_mov_b32_e32 v40, v26
	v_pk_mul_f32 v[26:27], v[28:29], v[30:31]
	v_pk_mul_f32 v[36:37], v[40:41], v[36:37]
	v_and_b32_sdwa v30, v27, v177 dst_sel:DWORD dst_unused:UNUSED_PAD src0_sel:WORD_1 src1_sel:DWORD
	v_and_b32_sdwa v28, v37, v177 dst_sel:DWORD dst_unused:UNUSED_PAD src0_sel:WORD_1 src1_sel:DWORD
	v_and_b32_sdwa v31, v26, v177 dst_sel:DWORD dst_unused:UNUSED_PAD src0_sel:WORD_1 src1_sel:DWORD
	v_add3_u32 v27, v27, v30, s28
	v_and_b32_sdwa v29, v36, v177 dst_sel:DWORD dst_unused:UNUSED_PAD src0_sel:WORD_1 src1_sel:DWORD
	v_add3_u32 v28, v37, v28, s28
	v_add3_u32 v26, v26, v31, s28
	v_and_b32_e32 v27, 0xffff0000, v27
	v_add3_u32 v29, v36, v29, s28
	v_and_b32_e32 v26, 0xffff0000, v26
	v_or_b32_sdwa v27, v27, v28 dst_sel:DWORD dst_unused:UNUSED_PAD src0_sel:DWORD src1_sel:WORD_1
	v_mul_f32_e32 v28, 0xbfb8aa3b, v22
	v_or_b32_sdwa v26, v26, v29 dst_sel:DWORD dst_unused:UNUSED_PAD src0_sel:DWORD src1_sel:WORD_1
	v_exp_f32_e32 v28, v28
	v_mul_f32_e32 v29, 0xbfb8aa3b, v23
	v_or_b32_e32 v34, 48, v110
	v_exp_f32_e32 v29, v29
	v_mad_i64_i32 v[34:35], s[6:7], v34, s52, v[106:107]
	v_lshl_add_u64 v[34:35], v[34:35], 0, v[108:109]
	global_store_dwordx2 v[34:35], v[26:27], off
	v_add_f32_e32 v26, 1.0, v28
	v_mul_f32_e32 v28, 0xbfb8aa3b, v24
	v_add_f32_e32 v27, 1.0, v29
	v_exp_f32_e32 v29, v28
	v_mul_f32_e32 v28, 0xbfb8aa3b, v25
	v_exp_f32_e32 v30, v28
	v_rcp_f32_e32 v28, v27
	v_add_f32_e32 v27, 1.0, v29
	v_rcp_f32_e32 v26, v26
	v_add_f32_e32 v29, 1.0, v30
	v_rcp_f32_e32 v27, v27
	v_rcp_f32_e32 v29, v29
	v_mov_b32_e32 v30, v22
	v_mov_b32_e32 v31, v24
	v_mov_b32_e32 v24, v23
	v_pk_mul_f32 v[26:27], v[30:31], v[26:27]
	v_mov_b32_e32 v31, v20
	v_pk_mul_f32 v[22:23], v[24:25], v[28:29]
	v_mov_b32_e32 v20, v19
	v_mov_b32_e32 v30, v18
	v_pk_mul_f32 v[18:19], v[20:21], v[22:23]
	v_pk_mul_f32 v[26:27], v[30:31], v[26:27]
	v_and_b32_sdwa v22, v19, v177 dst_sel:DWORD dst_unused:UNUSED_PAD src0_sel:WORD_1 src1_sel:DWORD
	v_and_b32_sdwa v20, v27, v177 dst_sel:DWORD dst_unused:UNUSED_PAD src0_sel:WORD_1 src1_sel:DWORD
	v_and_b32_sdwa v23, v18, v177 dst_sel:DWORD dst_unused:UNUSED_PAD src0_sel:WORD_1 src1_sel:DWORD
	v_add3_u32 v19, v19, v22, s28
	v_and_b32_sdwa v21, v26, v177 dst_sel:DWORD dst_unused:UNUSED_PAD src0_sel:WORD_1 src1_sel:DWORD
	v_add3_u32 v20, v27, v20, s28
	v_add3_u32 v18, v18, v23, s28
	v_and_b32_e32 v19, 0xffff0000, v19
	v_add3_u32 v21, v26, v21, s28
	v_and_b32_e32 v18, 0xffff0000, v18
	v_or_b32_sdwa v19, v19, v20 dst_sel:DWORD dst_unused:UNUSED_PAD src0_sel:DWORD src1_sel:WORD_1
	v_mul_f32_e32 v20, 0xbfb8aa3b, v14
	v_or_b32_sdwa v18, v18, v21 dst_sel:DWORD dst_unused:UNUSED_PAD src0_sel:DWORD src1_sel:WORD_1
	v_exp_f32_e32 v20, v20
	v_mul_f32_e32 v21, 0xbfb8aa3b, v15
	v_exp_f32_e32 v21, v21
	global_store_dwordx2 v[34:35], v[18:19], off offset:32
	v_add_f32_e32 v18, 1.0, v20
	v_mul_f32_e32 v20, 0xbfb8aa3b, v16
	v_add_f32_e32 v19, 1.0, v21
	v_exp_f32_e32 v21, v20
	v_mul_f32_e32 v20, 0xbfb8aa3b, v17
	v_exp_f32_e32 v22, v20
	v_rcp_f32_e32 v20, v19
	v_add_f32_e32 v19, 1.0, v21
	v_rcp_f32_e32 v18, v18
	v_add_f32_e32 v21, 1.0, v22
	v_rcp_f32_e32 v19, v19
	v_rcp_f32_e32 v21, v21
	v_mov_b32_e32 v22, v14
	v_mov_b32_e32 v23, v16
	v_mov_b32_e32 v16, v15
	v_pk_mul_f32 v[18:19], v[22:23], v[18:19]
	v_mov_b32_e32 v23, v12
	v_pk_mul_f32 v[14:15], v[16:17], v[20:21]
	v_mov_b32_e32 v12, v11
	v_mov_b32_e32 v22, v10
	v_pk_mul_f32 v[10:11], v[12:13], v[14:15]
	v_pk_mul_f32 v[18:19], v[22:23], v[18:19]
	v_and_b32_sdwa v14, v11, v177 dst_sel:DWORD dst_unused:UNUSED_PAD src0_sel:WORD_1 src1_sel:DWORD
	v_and_b32_sdwa v12, v19, v177 dst_sel:DWORD dst_unused:UNUSED_PAD src0_sel:WORD_1 src1_sel:DWORD
	v_and_b32_sdwa v15, v10, v177 dst_sel:DWORD dst_unused:UNUSED_PAD src0_sel:WORD_1 src1_sel:DWORD
	v_add3_u32 v11, v11, v14, s28
	v_and_b32_sdwa v13, v18, v177 dst_sel:DWORD dst_unused:UNUSED_PAD src0_sel:WORD_1 src1_sel:DWORD
	v_add3_u32 v12, v19, v12, s28
	v_add3_u32 v10, v10, v15, s28
	v_and_b32_e32 v11, 0xffff0000, v11
	v_add3_u32 v13, v18, v13, s28
	v_and_b32_e32 v10, 0xffff0000, v10
	v_or_b32_sdwa v11, v11, v12 dst_sel:DWORD dst_unused:UNUSED_PAD src0_sel:DWORD src1_sel:WORD_1
	v_mul_f32_e32 v12, 0xbfb8aa3b, v6
	v_or_b32_sdwa v10, v10, v13 dst_sel:DWORD dst_unused:UNUSED_PAD src0_sel:DWORD src1_sel:WORD_1
	v_exp_f32_e32 v12, v12
	v_mul_f32_e32 v13, 0xbfb8aa3b, v7
	v_exp_f32_e32 v13, v13
	global_store_dwordx2 v[34:35], v[10:11], off offset:64
	v_add_f32_e32 v10, 1.0, v12
	v_mul_f32_e32 v12, 0xbfb8aa3b, v8
	v_add_f32_e32 v11, 1.0, v13
	v_exp_f32_e32 v13, v12
	v_mul_f32_e32 v12, 0xbfb8aa3b, v9
	v_exp_f32_e32 v14, v12
	v_rcp_f32_e32 v12, v11
	v_add_f32_e32 v11, 1.0, v13
	v_rcp_f32_e32 v10, v10
	v_add_f32_e32 v13, 1.0, v14
	v_rcp_f32_e32 v11, v11
	v_rcp_f32_e32 v13, v13
	v_mov_b32_e32 v14, v6
	v_mov_b32_e32 v15, v8
	v_mov_b32_e32 v8, v7
	v_pk_mul_f32 v[10:11], v[14:15], v[10:11]
	v_mov_b32_e32 v15, v4
	v_pk_mul_f32 v[6:7], v[8:9], v[12:13]
	v_mov_b32_e32 v4, v3
	v_mov_b32_e32 v14, v2
	v_pk_mul_f32 v[2:3], v[4:5], v[6:7]
	v_pk_mul_f32 v[10:11], v[14:15], v[10:11]
	v_and_b32_sdwa v6, v3, v177 dst_sel:DWORD dst_unused:UNUSED_PAD src0_sel:WORD_1 src1_sel:DWORD
	v_and_b32_sdwa v7, v2, v177 dst_sel:DWORD dst_unused:UNUSED_PAD src0_sel:WORD_1 src1_sel:DWORD
	v_and_b32_sdwa v4, v11, v177 dst_sel:DWORD dst_unused:UNUSED_PAD src0_sel:WORD_1 src1_sel:DWORD
	v_and_b32_sdwa v5, v10, v177 dst_sel:DWORD dst_unused:UNUSED_PAD src0_sel:WORD_1 src1_sel:DWORD
	v_add3_u32 v3, v3, v6, s28
	v_add3_u32 v2, v2, v7, s28
	v_add3_u32 v5, v10, v5, s28
	v_add3_u32 v4, v11, v4, s28
	v_and_b32_e32 v3, 0xffff0000, v3
	v_and_b32_e32 v2, 0xffff0000, v2
	s_add_i32 s14, s14, s11
	v_or_b32_sdwa v3, v3, v4 dst_sel:DWORD dst_unused:UNUSED_PAD src0_sel:DWORD src1_sel:WORD_1
	v_or_b32_sdwa v2, v2, v5 dst_sel:DWORD dst_unused:UNUSED_PAD src0_sel:DWORD src1_sel:WORD_1
	s_cmpk_gt_i32 s14, 0x4ff
	global_store_dwordx2 v[34:35], v[2:3], off offset:96
	s_cbranch_scc0 .LBB0_1440

.LBB0_1458:
	s_and_b64 vcc, exec, s[14:15]
	s_cbranch_vccz .LBB0_1472
	v_mov_b32_e32 v2, v172
	s_mov_b32 s11, s42
	s_mov_b32 s14, s94
	s_cmpk_gt_i32 s14, 0x5ff
	s_cbranch_scc1 .LBB0_1464
	v_ashrrev_i32_e32 v204, 3, v2
	v_bfe_u32 v3, v2, 4, 2
	v_and_b32_e32 v4, 15, v2
	v_lshlrev_b32_e32 v0, 4, v2
	v_ashrrev_i32_e32 v5, 1, v2
	s_movk_i32 s2, 0xffc0
	v_lshlrev_b32_e32 v2, 1, v2
	v_and_b32_e32 v0, 0x70, v0
	v_and_or_b32 v205, v5, s2, v4
	v_and_b32_e32 v207, 0x80, v2
	s_movk_i32 s2, 0x90
	v_or_b32_e32 v2, v207, v4
	v_and_b32_e32 v100, 7, v204
	v_lshlrev_b32_e32 v100, 4, v100
	v_xor_b32_e32 v100, v100, v0
	v_lshl_add_u32 v166, v204, 7, v100
	v_lshl_add_u64 v[162:163], s[46:47], 0, v[0:1]
	v_lshl_add_u64 v[164:165], s[44:45], 0, v[0:1]
	v_and_b32_e32 v100, 7, v4
	v_xor_b32_e32 v100, v100, v3
	v_lshlrev_b32_e32 v206, 4, v100
	v_lshlrev_b32_e32 v208, 2, v3
	v_lshlrev_b32_e32 v0, 7, v205
	v_lshlrev_b32_e32 v167, 7, v2
.LBB0_1461:
	s_mul_hi_i32 s2, s14, 0x38e38e39
	s_lshr_b32 s3, s2, 31
	s_ashr_i32 s2, s2, 4
	s_add_i32 s2, s2, s3
	s_mul_i32 s3, s2, 0x48
	s_sub_i32 s3, s14, s3
	s_lshl_b32 s6, s3, 8
	v_add_u32_e32 v2, s6, v204
	v_ashrrev_i32_e32 v3, 31, v2
	v_lshlrev_b64 v[2:3], 11, v[2:3]
	v_lshl_add_u64 v[168:169], v[162:163], 0, v[2:3]
	v_add_co_u32_e32 v56, vcc, s34, v168
	s_lshl_b32 s7, s2, 8
	s_nop 0
	v_addc_co_u32_e32 v57, vcc, 0, v169, vcc
	v_add_u32_e32 v2, s7, v204
	s_waitcnt vmcnt(9)
	v_add_co_u32_e32 v58, vcc, s35, v168
	v_ashrrev_i32_e32 v3, 31, v2
	s_nop 0
	v_addc_co_u32_e32 v59, vcc, 0, v169, vcc
	v_lshlrev_b64 v[2:3], 11, v[2:3]
	v_add_co_u32_e32 v60, vcc, s36, v168
	v_lshl_add_u64 v[170:171], v[164:165], 0, v[2:3]
	s_nop 0
	v_addc_co_u32_e32 v61, vcc, 0, v169, vcc
	s_waitcnt vmcnt(8)
	v_add_co_u32_e32 v62, vcc, s35, v170
	global_load_dwordx4 v[24:27], v[56:57], off
	global_load_dwordx4 v[28:31], v[58:59], off
	v_addc_co_u32_e32 v63, vcc, 0, v171, vcc
	v_add_co_u32_e32 v64, vcc, s36, v170
	global_load_dwordx4 v[32:35], v[168:169], off
	global_load_dwordx4 v[36:39], v[170:171], off
	v_addc_co_u32_e32 v65, vcc, 0, v171, vcc
	v_add_co_u32_e32 v66, vcc, s34, v170
	global_load_dwordx4 v[40:43], v[62:63], off
	global_load_dwordx4 v[44:47], v[64:65], off
	v_addc_co_u32_e32 v67, vcc, 0, v171, vcc
	global_load_dwordx4 v[48:51], v[60:61], off
	global_load_dwordx4 v[52:55], v[66:67], off
	s_waitcnt lgkmcnt(0)
	s_barrier
	global_load_dwordx4 v[114:117], v[168:169], off offset:128
	global_load_dwordx4 v[106:109], v[56:57], off offset:128
	global_load_dwordx4 v[110:113], v[58:59], off offset:128
	global_load_dwordx4 v[126:129], v[60:61], off offset:128
	global_load_dwordx4 v[122:125], v[170:171], off offset:128
	global_load_dwordx4 v[118:121], v[66:67], off offset:128
	global_load_dwordx4 v[134:137], v[62:63], off offset:128
	global_load_dwordx4 v[130:133], v[64:65], off offset:128
	v_readfirstlane_b32 vcc_lo, v168
	v_readfirstlane_b32 vcc_hi, v169
	v_readfirstlane_b32 s100, v170
	v_readfirstlane_b32 s101, v171
	s_nop 1
	v_subrev_u32_e32 v168, vcc_lo, v168
	v_subrev_u32_e32 v170, s100, v170
	v_mov_b32_e32 v2, 0
	s_mov_b32 s4, 0
	v_mov_b32_e32 v3, v2
	v_mov_b32_e32 v4, v2
	v_mov_b32_e32 v5, v2
	v_mov_b32_e32 v6, v2
	v_mov_b32_e32 v7, v2
	v_mov_b32_e32 v8, v2
	v_mov_b32_e32 v9, v2
	v_mov_b32_e32 v10, v2
	v_mov_b32_e32 v11, v2
	v_mov_b32_e32 v12, v2
	v_mov_b32_e32 v13, v2
	v_mov_b32_e32 v14, v2
	v_mov_b32_e32 v15, v2
	v_mov_b32_e32 v16, v2
	v_mov_b32_e32 v17, v2
	v_mov_b32_e32 v18, v2
	v_mov_b32_e32 v19, v2
	v_mov_b32_e32 v20, v2
	v_mov_b32_e32 v21, v2
	v_mov_b32_e32 v22, v2
	v_mov_b32_e32 v23, v2
	v_mov_b32_e32 v56, v2
	v_mov_b32_e32 v57, v2
	v_mov_b32_e32 v58, v2
	v_mov_b32_e32 v59, v2
	v_mov_b32_e32 v60, v2
	v_mov_b32_e32 v61, v2
	v_mov_b32_e32 v62, v2
	v_mov_b32_e32 v63, v2
	v_mov_b32_e32 v64, v2
	v_mov_b32_e32 v65, v2
	v_mov_b32_e32 v66, v2
	v_mov_b32_e32 v67, v2
	v_mov_b32_e32 v68, v2
	v_mov_b32_e32 v69, v2
	v_mov_b32_e32 v70, v2
	v_mov_b32_e32 v71, v2
	v_mov_b32_e32 v72, v2
	v_mov_b32_e32 v73, v2
	v_mov_b32_e32 v74, v2
	v_mov_b32_e32 v75, v2
	v_mov_b32_e32 v76, v2
	v_mov_b32_e32 v77, v2
	v_mov_b32_e32 v78, v2
	v_mov_b32_e32 v79, v2
	v_mov_b32_e32 v80, v2
	v_mov_b32_e32 v81, v2
	v_mov_b32_e32 v82, v2
	v_mov_b32_e32 v83, v2
	v_mov_b32_e32 v84, v2
	v_mov_b32_e32 v85, v2
	s_waitcnt vmcnt(11)
	ds_write_b128 v166, v[40:43] offset:49152
	s_waitcnt vmcnt(10)
	ds_write_b128 v166, v[44:47] offset:57344
	ds_write_b128 v166, v[32:35]
	ds_write_b128 v166, v[36:39] offset:32768
	ds_write_b128 v166, v[24:27] offset:8192
	ds_write_b128 v166, v[28:31] offset:16384
	s_waitcnt vmcnt(9)
	ds_write_b128 v166, v[48:51] offset:24576
	s_waitcnt vmcnt(8)
	ds_write_b128 v166, v[52:55] offset:40960
	v_mov_b32_e32 v24, v2
	v_mov_b32_e32 v25, v2
	v_mov_b32_e32 v26, v2
	v_mov_b32_e32 v27, v2
	v_mov_b32_e32 v28, v2
	v_mov_b32_e32 v29, v2
	v_mov_b32_e32 v30, v2
	v_mov_b32_e32 v31, v2
	v_mov_b32_e32 v32, v2
	v_mov_b32_e32 v33, v2
	v_mov_b32_e32 v34, v2
	v_mov_b32_e32 v35, v2
	v_mov_b32_e32 v36, v2
	v_mov_b32_e32 v37, v2
	v_mov_b32_e32 v38, v2
	v_mov_b32_e32 v39, v2
	v_mov_b32_e32 v40, v2
	v_mov_b32_e32 v41, v2
	v_mov_b32_e32 v42, v2
	v_mov_b32_e32 v43, v2
	v_mov_b32_e32 v44, v2
	v_mov_b32_e32 v45, v2
	v_mov_b32_e32 v46, v2
	v_mov_b32_e32 v47, v2
	v_mov_b32_e32 v48, v2
	v_mov_b32_e32 v49, v2
	v_mov_b32_e32 v50, v2
	v_mov_b32_e32 v51, v2
	v_mov_b32_e32 v52, v2
	v_mov_b32_e32 v53, v2
	v_mov_b32_e32 v54, v2
	v_mov_b32_e32 v55, v2
	v_mov_b32_e32 v86, v2
	v_mov_b32_e32 v87, v2
	v_mov_b32_e32 v88, v2
	v_mov_b32_e32 v89, v2
	v_mov_b32_e32 v90, v2
	v_mov_b32_e32 v91, v2
	v_mov_b32_e32 v92, v2
	v_mov_b32_e32 v93, v2
	v_mov_b32_e32 v94, v2
	v_mov_b32_e32 v95, v2
	v_mov_b32_e32 v96, v2
	v_mov_b32_e32 v97, v2
	v_mov_b32_e32 v98, v2
	v_mov_b32_e32 v99, v2
	v_mov_b32_e32 v100, v2
	v_mov_b32_e32 v101, v2
	v_mov_b32_e32 v102, v2
	v_mov_b32_e32 v103, v2
	v_mov_b32_e32 v104, v2
	v_mov_b32_e32 v105, v2
	v_mov_b32_e32 v138, v2
	v_mov_b32_e32 v139, v2
	v_mov_b32_e32 v140, v2
	v_mov_b32_e32 v141, v2
	v_mov_b32_e32 v142, v2
	v_mov_b32_e32 v143, v2
	v_mov_b32_e32 v144, v2
	v_mov_b32_e32 v145, v2
	v_mov_b32_e32 v146, v2
	v_mov_b32_e32 v147, v2
	v_mov_b32_e32 v148, v2
	v_mov_b32_e32 v149, v2
	v_mov_b32_e32 v150, v2
	v_mov_b32_e32 v151, v2
	v_mov_b32_e32 v152, v2
	v_mov_b32_e32 v153, v2
	v_mov_b32_e32 v154, v2
	v_mov_b32_e32 v155, v2
	v_mov_b32_e32 v156, v2
	v_mov_b32_e32 v157, v2
	v_mov_b32_e32 v158, v2
	v_mov_b32_e32 v159, v2
	v_mov_b32_e32 v160, v2
	v_mov_b32_e32 v161, v2
	s_waitcnt lgkmcnt(0)
	s_barrier
.LBB0_1462:
	s_bitcmp1_b32 s4, 0
	s_cselect_b32 s2, 0x12000, 0
	v_or_b32_e32 v218, s2, v206
	v_add_u32_e32 v214, v218, v0
	v_add_u32_e32 v246, v218, v167
	ds_read_b128 v[184:187], v214
	ds_read_b128 v[198:201], v214 offset:2048
	ds_read_b128 v[210:213], v214 offset:4096
	ds_read_b128 v[214:217], v214 offset:6144
	ds_read_b128 v[218:221], v246 offset:32768
	ds_read_b128 v[222:225], v246 offset:34816
	ds_read_b128 v[226:229], v246 offset:36864
	ds_read_b128 v[230:233], v246 offset:38912
	ds_read_b128 v[234:237], v246 offset:40960
	ds_read_b128 v[238:241], v246 offset:43008
	ds_read_b128 v[242:245], v246 offset:45056
	ds_read_b128 v[246:249], v246 offset:47104
	s_add_i32 s10, s4, 1
	s_bitcmp1_b32 s10, 0
	s_cselect_b32 s3, 0x12000, 0
	s_waitcnt lgkmcnt(7)
	v_mfma_f32_16x16x32_bf16 v[158:161], v[218:221], v[184:187], v[158:161]
	v_mfma_f32_16x16x32_bf16 v[94:97], v[218:221], v[198:201], v[94:97]
	v_mfma_f32_16x16x32_bf16 v[62:65], v[218:221], v[210:213], v[62:65]
	v_mfma_f32_16x16x32_bf16 v[30:33], v[218:221], v[214:217], v[30:33]
	v_add_u32_e32 v218, s3, v166
	s_waitcnt vmcnt(7)
	ds_write_b128 v218, v[114:117]
	s_waitcnt lgkmcnt(7)
	v_mfma_f32_16x16x32_bf16 v[154:157], v[222:225], v[184:187], v[154:157]
	v_mfma_f32_16x16x32_bf16 v[90:93], v[222:225], v[198:201], v[90:93]
	global_load_dwordx4 v[114:117], v168, vcc offset:256
	v_mfma_f32_16x16x32_bf16 v[58:61], v[222:225], v[210:213], v[58:61]
	v_mfma_f32_16x16x32_bf16 v[26:29], v[222:225], v[214:217], v[26:29]
	s_waitcnt vmcnt(7)
	ds_write_b128 v218, v[106:109] offset:8192
	s_waitcnt lgkmcnt(7)
	v_mfma_f32_16x16x32_bf16 v[150:153], v[226:229], v[184:187], v[150:153]
	v_mfma_f32_16x16x32_bf16 v[86:89], v[226:229], v[198:201], v[86:89]
	v_add_u32_e32 v106, s34, v168
	global_load_dwordx4 v[106:109], v106, vcc offset:256
	v_mfma_f32_16x16x32_bf16 v[54:57], v[226:229], v[210:213], v[54:57]
	v_mfma_f32_16x16x32_bf16 v[22:25], v[226:229], v[214:217], v[22:25]
	s_waitcnt vmcnt(7)
	ds_write_b128 v218, v[110:113] offset:16384
	s_waitcnt lgkmcnt(7)
	v_mfma_f32_16x16x32_bf16 v[146:149], v[230:233], v[184:187], v[146:149]
	v_mfma_f32_16x16x32_bf16 v[82:85], v[230:233], v[198:201], v[82:85]
	v_add_u32_e32 v110, s35, v168
	global_load_dwordx4 v[110:113], v110, vcc offset:256
	v_mfma_f32_16x16x32_bf16 v[50:53], v[230:233], v[210:213], v[50:53]
	v_mfma_f32_16x16x32_bf16 v[18:21], v[230:233], v[214:217], v[18:21]
	s_waitcnt vmcnt(7)
	ds_write_b128 v218, v[126:129] offset:24576
	s_waitcnt lgkmcnt(7)
	v_mfma_f32_16x16x32_bf16 v[142:145], v[234:237], v[184:187], v[142:145]
	v_mfma_f32_16x16x32_bf16 v[78:81], v[234:237], v[198:201], v[78:81]
	v_add_u32_e32 v126, s36, v168
	global_load_dwordx4 v[126:129], v126, vcc offset:256
	v_mfma_f32_16x16x32_bf16 v[46:49], v[234:237], v[210:213], v[46:49]
	v_mfma_f32_16x16x32_bf16 v[14:17], v[234:237], v[214:217], v[14:17]
	s_waitcnt vmcnt(7)
	ds_write_b128 v218, v[122:125] offset:32768
	s_waitcnt lgkmcnt(7)
	v_mfma_f32_16x16x32_bf16 v[138:141], v[238:241], v[184:187], v[138:141]
	v_mfma_f32_16x16x32_bf16 v[74:77], v[238:241], v[198:201], v[74:77]
	global_load_dwordx4 v[122:125], v170, s[100:101] offset:256
	v_mfma_f32_16x16x32_bf16 v[42:45], v[238:241], v[210:213], v[42:45]
	v_mfma_f32_16x16x32_bf16 v[10:13], v[238:241], v[214:217], v[10:13]
	s_waitcnt vmcnt(7)
	ds_write_b128 v218, v[118:121] offset:40960
	s_waitcnt lgkmcnt(7)
	v_mfma_f32_16x16x32_bf16 v[102:105], v[242:245], v[184:187], v[102:105]
	v_mfma_f32_16x16x32_bf16 v[70:73], v[242:245], v[198:201], v[70:73]
	v_add_u32_e32 v118, s34, v170
	global_load_dwordx4 v[118:121], v118, s[100:101] offset:256
	v_mfma_f32_16x16x32_bf16 v[38:41], v[242:245], v[210:213], v[38:41]
	v_mfma_f32_16x16x32_bf16 v[6:9], v[242:245], v[214:217], v[6:9]
	s_waitcnt vmcnt(7)
	ds_write_b128 v218, v[134:137] offset:49152
	s_waitcnt lgkmcnt(7)
	v_mfma_f32_16x16x32_bf16 v[98:101], v[246:249], v[184:187], v[98:101]
	v_mfma_f32_16x16x32_bf16 v[66:69], v[246:249], v[198:201], v[66:69]
	v_add_u32_e32 v134, s35, v170
	global_load_dwordx4 v[134:137], v134, s[100:101] offset:256
	v_mfma_f32_16x16x32_bf16 v[34:37], v[246:249], v[210:213], v[34:37]
	v_mfma_f32_16x16x32_bf16 v[2:5], v[246:249], v[214:217], v[2:5]
	s_waitcnt vmcnt(7)
	ds_write_b128 v218, v[130:133] offset:57344
	v_add3_u32 v214, s2, v0, v206
	v_xor_b32_e32 v214, 64, v214
	v_add3_u32 v246, s2, v167, v206
	v_xor_b32_e32 v246, 64, v246
	v_add_u32_e32 v130, s36, v170
	global_load_dwordx4 v[130:133], v130, s[100:101] offset:256
	v_add_u32_e32 v168, 0x80, v168
	v_add_u32_e32 v170, 0x80, v170
	ds_read_b128 v[184:187], v214
	ds_read_b128 v[198:201], v214 offset:2048
	ds_read_b128 v[210:213], v214 offset:4096
	ds_read_b128 v[214:217], v214 offset:6144
	ds_read_b128 v[218:221], v246 offset:32768
	ds_read_b128 v[222:225], v246 offset:34816
	ds_read_b128 v[226:229], v246 offset:36864
	ds_read_b128 v[230:233], v246 offset:38912
	ds_read_b128 v[234:237], v246 offset:40960
	ds_read_b128 v[238:241], v246 offset:43008
	ds_read_b128 v[242:245], v246 offset:45056
	ds_read_b128 v[246:249], v246 offset:47104
	s_waitcnt lgkmcnt(7)
	v_mfma_f32_16x16x32_bf16 v[158:161], v[218:221], v[184:187], v[158:161]
	v_mfma_f32_16x16x32_bf16 v[94:97], v[218:221], v[198:201], v[94:97]
	v_mfma_f32_16x16x32_bf16 v[62:65], v[218:221], v[210:213], v[62:65]
	v_mfma_f32_16x16x32_bf16 v[30:33], v[218:221], v[214:217], v[30:33]
	s_waitcnt lgkmcnt(6)
	v_mfma_f32_16x16x32_bf16 v[154:157], v[222:225], v[184:187], v[154:157]
	v_mfma_f32_16x16x32_bf16 v[90:93], v[222:225], v[198:201], v[90:93]
	v_mfma_f32_16x16x32_bf16 v[58:61], v[222:225], v[210:213], v[58:61]
	v_mfma_f32_16x16x32_bf16 v[26:29], v[222:225], v[214:217], v[26:29]
	s_waitcnt lgkmcnt(5)
	v_mfma_f32_16x16x32_bf16 v[150:153], v[226:229], v[184:187], v[150:153]
	v_mfma_f32_16x16x32_bf16 v[86:89], v[226:229], v[198:201], v[86:89]
	v_mfma_f32_16x16x32_bf16 v[54:57], v[226:229], v[210:213], v[54:57]
	v_mfma_f32_16x16x32_bf16 v[22:25], v[226:229], v[214:217], v[22:25]
	s_waitcnt lgkmcnt(4)
	v_mfma_f32_16x16x32_bf16 v[146:149], v[230:233], v[184:187], v[146:149]
	v_mfma_f32_16x16x32_bf16 v[82:85], v[230:233], v[198:201], v[82:85]
	v_mfma_f32_16x16x32_bf16 v[50:53], v[230:233], v[210:213], v[50:53]
	v_mfma_f32_16x16x32_bf16 v[18:21], v[230:233], v[214:217], v[18:21]
	s_waitcnt lgkmcnt(3)
	v_mfma_f32_16x16x32_bf16 v[142:145], v[234:237], v[184:187], v[142:145]
	v_mfma_f32_16x16x32_bf16 v[78:81], v[234:237], v[198:201], v[78:81]
	v_mfma_f32_16x16x32_bf16 v[46:49], v[234:237], v[210:213], v[46:49]
	v_mfma_f32_16x16x32_bf16 v[14:17], v[234:237], v[214:217], v[14:17]
	s_waitcnt lgkmcnt(2)
	v_mfma_f32_16x16x32_bf16 v[138:141], v[238:241], v[184:187], v[138:141]
	v_mfma_f32_16x16x32_bf16 v[74:77], v[238:241], v[198:201], v[74:77]
	v_mfma_f32_16x16x32_bf16 v[42:45], v[238:241], v[210:213], v[42:45]
	v_mfma_f32_16x16x32_bf16 v[10:13], v[238:241], v[214:217], v[10:13]
	s_waitcnt lgkmcnt(1)
	v_mfma_f32_16x16x32_bf16 v[102:105], v[242:245], v[184:187], v[102:105]
	v_mfma_f32_16x16x32_bf16 v[70:73], v[242:245], v[198:201], v[70:73]
	v_mfma_f32_16x16x32_bf16 v[38:41], v[242:245], v[210:213], v[38:41]
	v_mfma_f32_16x16x32_bf16 v[6:9], v[242:245], v[214:217], v[6:9]
	s_waitcnt lgkmcnt(0)
	v_mfma_f32_16x16x32_bf16 v[98:101], v[246:249], v[184:187], v[98:101]
	v_mfma_f32_16x16x32_bf16 v[66:69], v[246:249], v[198:201], v[66:69]
	v_mfma_f32_16x16x32_bf16 v[34:37], v[246:249], v[210:213], v[34:37]
	v_mfma_f32_16x16x32_bf16 v[2:5], v[246:249], v[214:217], v[2:5]
	s_waitcnt lgkmcnt(0)
	s_barrier
	s_cmp_eq_u32 s10, 16
	s_mov_b32 s4, s10
	s_cbranch_scc0 .LBB0_1462
	s_waitcnt vmcnt(4)
	v_mul_f32_e32 v109, 0xbfb8aa3b, v158
	v_exp_f32_e32 v109, v109
	s_waitcnt vmcnt(3)
	v_mul_f32_e32 v111, 0xbfb8aa3b, v159
	v_exp_f32_e32 v111, v111
	v_mul_f32_e32 v115, 0xbfb8aa3b, v161
	v_add_f32_e32 v109, 1.0, v109
	v_rcp_f32_e32 v114, v109
	v_add_f32_e32 v109, 1.0, v111
	v_mul_f32_e32 v111, 0xbfb8aa3b, v160
	v_exp_f32_e32 v111, v111
	v_exp_f32_e32 v117, v115
	v_rcp_f32_e32 v116, v109
	s_waitcnt vmcnt(2)
	v_mov_b32_e32 v118, v158
	v_add_f32_e32 v109, 1.0, v111
	v_rcp_f32_e32 v115, v109
	v_add_f32_e32 v109, 1.0, v117
	v_rcp_f32_e32 v117, v109
	v_mov_b32_e32 v119, v160
	v_pk_mul_f32 v[114:115], v[118:119], v[114:115]
	v_mov_b32_e32 v118, v154
	v_mov_b32_e32 v119, v156
	v_mov_b32_e32 v160, v159
	v_pk_mul_f32 v[114:115], v[118:119], v[114:115]
	v_pk_mul_f32 v[116:117], v[160:161], v[116:117]
	v_mov_b32_e32 v156, v155
	v_pk_mul_f32 v[116:117], v[156:157], v[116:117]
	v_and_b32_sdwa v111, v115, v177 dst_sel:DWORD dst_unused:UNUSED_PAD src0_sel:WORD_1 src1_sel:DWORD
	v_and_b32_sdwa v118, v114, v177 dst_sel:DWORD dst_unused:UNUSED_PAD src0_sel:WORD_1 src1_sel:DWORD
	v_add3_u32 v111, v115, v111, s28
	v_and_b32_sdwa v115, v117, v177 dst_sel:DWORD dst_unused:UNUSED_PAD src0_sel:WORD_1 src1_sel:DWORD
	v_add3_u32 v114, v114, v118, s28
	v_and_b32_sdwa v118, v116, v177 dst_sel:DWORD dst_unused:UNUSED_PAD src0_sel:WORD_1 src1_sel:DWORD
	v_add3_u32 v115, v117, v115, s28
	v_or_b32_e32 v106, s7, v207
	v_add3_u32 v116, v116, v118, s28
	v_and_b32_e32 v115, 0xffff0000, v115
	v_ashrrev_i32_e32 v106, 1, v106
	v_and_b32_e32 v116, 0xffff0000, v116
	v_or_b32_sdwa v115, v115, v111 dst_sel:DWORD dst_unused:UNUSED_PAD src0_sel:DWORD src1_sel:WORD_1
	v_mul_f32_e32 v111, 0xbfb8aa3b, v150
	v_or_b32_e32 v108, v106, v208
	v_or_b32_sdwa v114, v116, v114 dst_sel:DWORD dst_unused:UNUSED_PAD src0_sel:DWORD src1_sel:WORD_1
	v_exp_f32_e32 v111, v111
	v_mul_f32_e32 v116, 0xbfb8aa3b, v151
	v_add_u32_e32 v110, s6, v205
	v_mov_b64_e32 v[106:107], s[12:13]
	v_ashrrev_i32_e32 v109, 31, v108
	v_exp_f32_e32 v116, v116
	v_mad_i64_i32 v[112:113], s[6:7], v110, s52, v[106:107]
	v_lshlrev_b64 v[108:109], 1, v[108:109]
	v_lshl_add_u64 v[112:113], v[112:113], 0, v[108:109]
	s_waitcnt vmcnt(0)
	global_store_dwordx2 v[112:113], v[114:115], off
	v_add_f32_e32 v111, 1.0, v111
	v_mul_f32_e32 v115, 0xbfb8aa3b, v152
	v_rcp_f32_e32 v114, v111
	v_add_f32_e32 v111, 1.0, v116
	v_exp_f32_e32 v115, v115
	v_mul_f32_e32 v116, 0xbfb8aa3b, v153
	v_exp_f32_e32 v117, v116
	v_rcp_f32_e32 v116, v111
	v_add_f32_e32 v111, 1.0, v115
	v_rcp_f32_e32 v115, v111
	v_add_f32_e32 v111, 1.0, v117
	v_rcp_f32_e32 v117, v111
	v_mov_b32_e32 v118, v150
	v_mov_b32_e32 v119, v152
	v_pk_mul_f32 v[114:115], v[118:119], v[114:115]
	v_mov_b32_e32 v118, v146
	v_mov_b32_e32 v119, v148
	v_mov_b32_e32 v152, v151
	v_pk_mul_f32 v[114:115], v[118:119], v[114:115]
	v_pk_mul_f32 v[116:117], v[152:153], v[116:117]
	v_mov_b32_e32 v148, v147
	v_pk_mul_f32 v[116:117], v[148:149], v[116:117]
	v_and_b32_sdwa v111, v115, v177 dst_sel:DWORD dst_unused:UNUSED_PAD src0_sel:WORD_1 src1_sel:DWORD
	v_and_b32_sdwa v118, v114, v177 dst_sel:DWORD dst_unused:UNUSED_PAD src0_sel:WORD_1 src1_sel:DWORD
	v_add3_u32 v111, v115, v111, s28
	v_and_b32_sdwa v115, v117, v177 dst_sel:DWORD dst_unused:UNUSED_PAD src0_sel:WORD_1 src1_sel:DWORD
	v_add3_u32 v114, v114, v118, s28
	v_and_b32_sdwa v118, v116, v177 dst_sel:DWORD dst_unused:UNUSED_PAD src0_sel:WORD_1 src1_sel:DWORD
	v_add3_u32 v115, v117, v115, s28
	v_add3_u32 v116, v116, v118, s28
	v_and_b32_e32 v115, 0xffff0000, v115
	v_and_b32_e32 v116, 0xffff0000, v116
	v_or_b32_sdwa v115, v115, v111 dst_sel:DWORD dst_unused:UNUSED_PAD src0_sel:DWORD src1_sel:WORD_1
	v_mul_f32_e32 v111, 0xbfb8aa3b, v142
	v_or_b32_sdwa v114, v116, v114 dst_sel:DWORD dst_unused:UNUSED_PAD src0_sel:DWORD src1_sel:WORD_1
	v_exp_f32_e32 v111, v111
	v_mul_f32_e32 v116, 0xbfb8aa3b, v143
	v_exp_f32_e32 v116, v116
	global_store_dwordx2 v[112:113], v[114:115], off offset:32
	v_add_f32_e32 v111, 1.0, v111
	v_mul_f32_e32 v115, 0xbfb8aa3b, v144
	v_rcp_f32_e32 v114, v111
	v_add_f32_e32 v111, 1.0, v116
	v_exp_f32_e32 v115, v115
	v_mul_f32_e32 v116, 0xbfb8aa3b, v145
	v_exp_f32_e32 v117, v116
	v_rcp_f32_e32 v116, v111
	v_add_f32_e32 v111, 1.0, v115
	v_rcp_f32_e32 v115, v111
	v_add_f32_e32 v111, 1.0, v117
	v_rcp_f32_e32 v117, v111
	v_mov_b32_e32 v118, v142
	v_mov_b32_e32 v119, v144
	v_pk_mul_f32 v[114:115], v[118:119], v[114:115]
	v_mov_b32_e32 v118, v138
	v_mov_b32_e32 v119, v140
	v_mov_b32_e32 v144, v143
	v_pk_mul_f32 v[114:115], v[118:119], v[114:115]
	v_pk_mul_f32 v[116:117], v[144:145], v[116:117]
	v_mov_b32_e32 v140, v139
	v_pk_mul_f32 v[116:117], v[140:141], v[116:117]
	v_and_b32_sdwa v111, v115, v177 dst_sel:DWORD dst_unused:UNUSED_PAD src0_sel:WORD_1 src1_sel:DWORD
	v_and_b32_sdwa v118, v114, v177 dst_sel:DWORD dst_unused:UNUSED_PAD src0_sel:WORD_1 src1_sel:DWORD
	v_add3_u32 v111, v115, v111, s28
	v_and_b32_sdwa v115, v117, v177 dst_sel:DWORD dst_unused:UNUSED_PAD src0_sel:WORD_1 src1_sel:DWORD
	v_add3_u32 v114, v114, v118, s28
	v_and_b32_sdwa v118, v116, v177 dst_sel:DWORD dst_unused:UNUSED_PAD src0_sel:WORD_1 src1_sel:DWORD
	v_add3_u32 v115, v117, v115, s28
	v_add3_u32 v116, v116, v118, s28
	v_and_b32_e32 v115, 0xffff0000, v115
	v_and_b32_e32 v116, 0xffff0000, v116
	v_or_b32_sdwa v115, v115, v111 dst_sel:DWORD dst_unused:UNUSED_PAD src0_sel:DWORD src1_sel:WORD_1
	v_mul_f32_e32 v111, 0xbfb8aa3b, v102
	v_or_b32_sdwa v114, v116, v114 dst_sel:DWORD dst_unused:UNUSED_PAD src0_sel:DWORD src1_sel:WORD_1
	v_exp_f32_e32 v111, v111
	v_mul_f32_e32 v116, 0xbfb8aa3b, v103
	v_exp_f32_e32 v116, v116
	global_store_dwordx2 v[112:113], v[114:115], off offset:64
	v_add_f32_e32 v111, 1.0, v111
	v_mul_f32_e32 v115, 0xbfb8aa3b, v104
	v_rcp_f32_e32 v114, v111
	v_add_f32_e32 v111, 1.0, v116
	v_exp_f32_e32 v115, v115
	v_mul_f32_e32 v116, 0xbfb8aa3b, v105
	v_exp_f32_e32 v117, v116
	v_rcp_f32_e32 v116, v111
	v_add_f32_e32 v111, 1.0, v115
	v_rcp_f32_e32 v115, v111
	v_add_f32_e32 v111, 1.0, v117
	v_rcp_f32_e32 v117, v111
	v_mov_b32_e32 v118, v102
	v_mov_b32_e32 v119, v104
	v_mov_b32_e32 v104, v103
	v_pk_mul_f32 v[114:115], v[118:119], v[114:115]
	v_mov_b32_e32 v119, v100
	v_pk_mul_f32 v[102:103], v[104:105], v[116:117]
	v_mov_b32_e32 v100, v99
	v_mov_b32_e32 v118, v98
	v_pk_mul_f32 v[98:99], v[100:101], v[102:103]
	v_pk_mul_f32 v[114:115], v[118:119], v[114:115]
	v_and_b32_sdwa v102, v99, v177 dst_sel:DWORD dst_unused:UNUSED_PAD src0_sel:WORD_1 src1_sel:DWORD
	v_and_b32_sdwa v103, v98, v177 dst_sel:DWORD dst_unused:UNUSED_PAD src0_sel:WORD_1 src1_sel:DWORD
	v_and_b32_sdwa v100, v115, v177 dst_sel:DWORD dst_unused:UNUSED_PAD src0_sel:WORD_1 src1_sel:DWORD
	v_and_b32_sdwa v101, v114, v177 dst_sel:DWORD dst_unused:UNUSED_PAD src0_sel:WORD_1 src1_sel:DWORD
	v_add3_u32 v99, v99, v102, s28
	v_add3_u32 v98, v98, v103, s28
	v_add3_u32 v101, v114, v101, s28
	v_add3_u32 v100, v115, v100, s28
	v_and_b32_e32 v99, 0xffff0000, v99
	v_and_b32_e32 v98, 0xffff0000, v98
	v_or_b32_sdwa v99, v99, v100 dst_sel:DWORD dst_unused:UNUSED_PAD src0_sel:DWORD src1_sel:WORD_1
	v_or_b32_sdwa v98, v98, v101 dst_sel:DWORD dst_unused:UNUSED_PAD src0_sel:DWORD src1_sel:WORD_1
	global_store_dwordx2 v[112:113], v[98:99], off offset:96
	v_mul_f32_e32 v99, 0xbfb8aa3b, v94
	v_exp_f32_e32 v100, v99
	v_mul_f32_e32 v99, 0xbfb8aa3b, v95
	v_mul_f32_e32 v102, 0xbfb8aa3b, v96
	v_exp_f32_e32 v101, v99
	v_exp_f32_e32 v103, v102
	v_mul_f32_e32 v102, 0xbfb8aa3b, v97
	v_exp_f32_e32 v104, v102
	v_add_f32_e32 v101, 1.0, v101
	v_add_f32_e32 v100, 1.0, v100
	v_rcp_f32_e32 v102, v101
	v_add_f32_e32 v101, 1.0, v103
	v_add_f32_e32 v103, 1.0, v104
	v_rcp_f32_e32 v100, v100
	v_rcp_f32_e32 v101, v101
	v_rcp_f32_e32 v103, v103
	v_mov_b32_e32 v104, v94
	v_mov_b32_e32 v105, v96
	v_mov_b32_e32 v96, v95
	v_pk_mul_f32 v[100:101], v[104:105], v[100:101]
	v_mov_b32_e32 v105, v92
	v_pk_mul_f32 v[94:95], v[96:97], v[102:103]
	v_mov_b32_e32 v92, v91
	v_mov_b32_e32 v104, v90
	v_pk_mul_f32 v[90:91], v[92:93], v[94:95]
	v_pk_mul_f32 v[100:101], v[104:105], v[100:101]
	v_and_b32_sdwa v94, v91, v177 dst_sel:DWORD dst_unused:UNUSED_PAD src0_sel:WORD_1 src1_sel:DWORD
	v_and_b32_sdwa v92, v101, v177 dst_sel:DWORD dst_unused:UNUSED_PAD src0_sel:WORD_1 src1_sel:DWORD
	v_and_b32_sdwa v95, v90, v177 dst_sel:DWORD dst_unused:UNUSED_PAD src0_sel:WORD_1 src1_sel:DWORD
	v_add3_u32 v91, v91, v94, s28
	v_and_b32_sdwa v93, v100, v177 dst_sel:DWORD dst_unused:UNUSED_PAD src0_sel:WORD_1 src1_sel:DWORD
	v_add3_u32 v92, v101, v92, s28
	v_add3_u32 v90, v90, v95, s28
	v_and_b32_e32 v91, 0xffff0000, v91
	v_add3_u32 v93, v100, v93, s28
	v_and_b32_e32 v90, 0xffff0000, v90
	v_or_b32_sdwa v91, v91, v92 dst_sel:DWORD dst_unused:UNUSED_PAD src0_sel:DWORD src1_sel:WORD_1
	v_mul_f32_e32 v92, 0xbfb8aa3b, v86
	v_or_b32_sdwa v90, v90, v93 dst_sel:DWORD dst_unused:UNUSED_PAD src0_sel:DWORD src1_sel:WORD_1
	v_exp_f32_e32 v92, v92
	v_mul_f32_e32 v93, 0xbfb8aa3b, v87
	v_or_b32_e32 v98, 16, v110
	v_exp_f32_e32 v93, v93
	v_mad_i64_i32 v[98:99], s[6:7], v98, s52, v[106:107]
	v_lshl_add_u64 v[98:99], v[98:99], 0, v[108:109]
	global_store_dwordx2 v[98:99], v[90:91], off
	v_add_f32_e32 v90, 1.0, v92
	v_mul_f32_e32 v92, 0xbfb8aa3b, v88
	v_add_f32_e32 v91, 1.0, v93
	v_exp_f32_e32 v93, v92
	v_mul_f32_e32 v92, 0xbfb8aa3b, v89
	v_exp_f32_e32 v94, v92
	v_rcp_f32_e32 v92, v91
	v_add_f32_e32 v91, 1.0, v93
	v_rcp_f32_e32 v90, v90
	v_add_f32_e32 v93, 1.0, v94
	v_rcp_f32_e32 v91, v91
	v_rcp_f32_e32 v93, v93
	v_mov_b32_e32 v94, v86
	v_mov_b32_e32 v95, v88
	v_mov_b32_e32 v88, v87
	v_pk_mul_f32 v[90:91], v[94:95], v[90:91]
	v_mov_b32_e32 v95, v84
	v_pk_mul_f32 v[86:87], v[88:89], v[92:93]
	v_mov_b32_e32 v84, v83
	v_mov_b32_e32 v94, v82
	v_pk_mul_f32 v[82:83], v[84:85], v[86:87]
	v_pk_mul_f32 v[90:91], v[94:95], v[90:91]
	v_and_b32_sdwa v86, v83, v177 dst_sel:DWORD dst_unused:UNUSED_PAD src0_sel:WORD_1 src1_sel:DWORD
	v_and_b32_sdwa v84, v91, v177 dst_sel:DWORD dst_unused:UNUSED_PAD src0_sel:WORD_1 src1_sel:DWORD
	v_and_b32_sdwa v87, v82, v177 dst_sel:DWORD dst_unused:UNUSED_PAD src0_sel:WORD_1 src1_sel:DWORD
	v_add3_u32 v83, v83, v86, s28
	v_and_b32_sdwa v85, v90, v177 dst_sel:DWORD dst_unused:UNUSED_PAD src0_sel:WORD_1 src1_sel:DWORD
	v_add3_u32 v84, v91, v84, s28
	v_add3_u32 v82, v82, v87, s28
	v_and_b32_e32 v83, 0xffff0000, v83
	v_add3_u32 v85, v90, v85, s28
	v_and_b32_e32 v82, 0xffff0000, v82
	v_or_b32_sdwa v83, v83, v84 dst_sel:DWORD dst_unused:UNUSED_PAD src0_sel:DWORD src1_sel:WORD_1
	v_mul_f32_e32 v84, 0xbfb8aa3b, v78
	v_or_b32_sdwa v82, v82, v85 dst_sel:DWORD dst_unused:UNUSED_PAD src0_sel:DWORD src1_sel:WORD_1
	v_exp_f32_e32 v84, v84
	v_mul_f32_e32 v85, 0xbfb8aa3b, v79
	v_exp_f32_e32 v85, v85
	global_store_dwordx2 v[98:99], v[82:83], off offset:32
	v_add_f32_e32 v82, 1.0, v84
	v_mul_f32_e32 v84, 0xbfb8aa3b, v80
	v_add_f32_e32 v83, 1.0, v85
	v_exp_f32_e32 v85, v84
	v_mul_f32_e32 v84, 0xbfb8aa3b, v81
	v_exp_f32_e32 v86, v84
	v_rcp_f32_e32 v84, v83
	v_add_f32_e32 v83, 1.0, v85
	v_rcp_f32_e32 v82, v82
	v_add_f32_e32 v85, 1.0, v86
	v_rcp_f32_e32 v83, v83
	v_rcp_f32_e32 v85, v85
	v_mov_b32_e32 v86, v78
	v_mov_b32_e32 v87, v80
	v_mov_b32_e32 v80, v79
	v_pk_mul_f32 v[82:83], v[86:87], v[82:83]
	v_mov_b32_e32 v87, v76
	v_pk_mul_f32 v[78:79], v[80:81], v[84:85]
	v_mov_b32_e32 v76, v75
	v_mov_b32_e32 v86, v74
	v_pk_mul_f32 v[74:75], v[76:77], v[78:79]
	v_pk_mul_f32 v[82:83], v[86:87], v[82:83]
	v_and_b32_sdwa v78, v75, v177 dst_sel:DWORD dst_unused:UNUSED_PAD src0_sel:WORD_1 src1_sel:DWORD
	v_and_b32_sdwa v76, v83, v177 dst_sel:DWORD dst_unused:UNUSED_PAD src0_sel:WORD_1 src1_sel:DWORD
	v_and_b32_sdwa v79, v74, v177 dst_sel:DWORD dst_unused:UNUSED_PAD src0_sel:WORD_1 src1_sel:DWORD
	v_add3_u32 v75, v75, v78, s28
	v_and_b32_sdwa v77, v82, v177 dst_sel:DWORD dst_unused:UNUSED_PAD src0_sel:WORD_1 src1_sel:DWORD
	v_add3_u32 v76, v83, v76, s28
	v_add3_u32 v74, v74, v79, s28
	v_and_b32_e32 v75, 0xffff0000, v75
	v_add3_u32 v77, v82, v77, s28
	v_and_b32_e32 v74, 0xffff0000, v74
	v_or_b32_sdwa v75, v75, v76 dst_sel:DWORD dst_unused:UNUSED_PAD src0_sel:DWORD src1_sel:WORD_1
	v_mul_f32_e32 v76, 0xbfb8aa3b, v70
	v_or_b32_sdwa v74, v74, v77 dst_sel:DWORD dst_unused:UNUSED_PAD src0_sel:DWORD src1_sel:WORD_1
	v_exp_f32_e32 v76, v76
	v_mul_f32_e32 v77, 0xbfb8aa3b, v71
	v_exp_f32_e32 v77, v77
	global_store_dwordx2 v[98:99], v[74:75], off offset:64
	v_add_f32_e32 v74, 1.0, v76
	v_mul_f32_e32 v76, 0xbfb8aa3b, v72
	v_add_f32_e32 v75, 1.0, v77
	v_exp_f32_e32 v77, v76
	v_mul_f32_e32 v76, 0xbfb8aa3b, v73
	v_exp_f32_e32 v78, v76
	v_rcp_f32_e32 v76, v75
	v_add_f32_e32 v75, 1.0, v77
	v_rcp_f32_e32 v74, v74
	v_add_f32_e32 v77, 1.0, v78
	v_rcp_f32_e32 v75, v75
	v_rcp_f32_e32 v77, v77
	v_mov_b32_e32 v78, v70
	v_mov_b32_e32 v79, v72
	v_mov_b32_e32 v72, v71
	v_pk_mul_f32 v[74:75], v[78:79], v[74:75]
	v_mov_b32_e32 v79, v68
	v_pk_mul_f32 v[70:71], v[72:73], v[76:77]
	v_mov_b32_e32 v68, v67
	v_mov_b32_e32 v78, v66
	v_pk_mul_f32 v[66:67], v[68:69], v[70:71]
	v_pk_mul_f32 v[74:75], v[78:79], v[74:75]
	v_and_b32_sdwa v70, v67, v177 dst_sel:DWORD dst_unused:UNUSED_PAD src0_sel:WORD_1 src1_sel:DWORD
	v_and_b32_sdwa v71, v66, v177 dst_sel:DWORD dst_unused:UNUSED_PAD src0_sel:WORD_1 src1_sel:DWORD
	v_and_b32_sdwa v68, v75, v177 dst_sel:DWORD dst_unused:UNUSED_PAD src0_sel:WORD_1 src1_sel:DWORD
	v_and_b32_sdwa v69, v74, v177 dst_sel:DWORD dst_unused:UNUSED_PAD src0_sel:WORD_1 src1_sel:DWORD
	v_add3_u32 v67, v67, v70, s28
	v_add3_u32 v66, v66, v71, s28
	v_add3_u32 v69, v74, v69, s28
	v_add3_u32 v68, v75, v68, s28
	v_and_b32_e32 v67, 0xffff0000, v67
	v_and_b32_e32 v66, 0xffff0000, v66
	v_or_b32_sdwa v67, v67, v68 dst_sel:DWORD dst_unused:UNUSED_PAD src0_sel:DWORD src1_sel:WORD_1
	v_or_b32_sdwa v66, v66, v69 dst_sel:DWORD dst_unused:UNUSED_PAD src0_sel:DWORD src1_sel:WORD_1
	global_store_dwordx2 v[98:99], v[66:67], off offset:96
	v_mul_f32_e32 v67, 0xbfb8aa3b, v62
	v_exp_f32_e32 v68, v67
	v_mul_f32_e32 v67, 0xbfb8aa3b, v63
	v_mul_f32_e32 v70, 0xbfb8aa3b, v64
	v_exp_f32_e32 v69, v67
	v_exp_f32_e32 v71, v70
	v_mul_f32_e32 v70, 0xbfb8aa3b, v65
	v_exp_f32_e32 v72, v70
	v_add_f32_e32 v69, 1.0, v69
	v_add_f32_e32 v68, 1.0, v68
	v_rcp_f32_e32 v70, v69
	v_add_f32_e32 v69, 1.0, v71
	v_add_f32_e32 v71, 1.0, v72
	v_rcp_f32_e32 v68, v68
	v_rcp_f32_e32 v69, v69
	v_rcp_f32_e32 v71, v71
	v_mov_b32_e32 v72, v62
	v_mov_b32_e32 v73, v64
	v_mov_b32_e32 v64, v63
	v_pk_mul_f32 v[68:69], v[72:73], v[68:69]
	v_mov_b32_e32 v73, v60
	v_pk_mul_f32 v[62:63], v[64:65], v[70:71]
	v_mov_b32_e32 v60, v59
	v_mov_b32_e32 v72, v58
	v_pk_mul_f32 v[58:59], v[60:61], v[62:63]
	v_pk_mul_f32 v[68:69], v[72:73], v[68:69]
	v_and_b32_sdwa v62, v59, v177 dst_sel:DWORD dst_unused:UNUSED_PAD src0_sel:WORD_1 src1_sel:DWORD
	v_and_b32_sdwa v60, v69, v177 dst_sel:DWORD dst_unused:UNUSED_PAD src0_sel:WORD_1 src1_sel:DWORD
	v_and_b32_sdwa v63, v58, v177 dst_sel:DWORD dst_unused:UNUSED_PAD src0_sel:WORD_1 src1_sel:DWORD
	v_add3_u32 v59, v59, v62, s28
	v_and_b32_sdwa v61, v68, v177 dst_sel:DWORD dst_unused:UNUSED_PAD src0_sel:WORD_1 src1_sel:DWORD
	v_add3_u32 v60, v69, v60, s28
	v_add3_u32 v58, v58, v63, s28
	v_and_b32_e32 v59, 0xffff0000, v59
	v_add3_u32 v61, v68, v61, s28
	v_and_b32_e32 v58, 0xffff0000, v58
	v_or_b32_sdwa v59, v59, v60 dst_sel:DWORD dst_unused:UNUSED_PAD src0_sel:DWORD src1_sel:WORD_1
	v_mul_f32_e32 v60, 0xbfb8aa3b, v54
	v_or_b32_sdwa v58, v58, v61 dst_sel:DWORD dst_unused:UNUSED_PAD src0_sel:DWORD src1_sel:WORD_1
	v_exp_f32_e32 v60, v60
	v_mul_f32_e32 v61, 0xbfb8aa3b, v55
	v_or_b32_e32 v66, 32, v110
	v_exp_f32_e32 v61, v61
	v_mad_i64_i32 v[66:67], s[6:7], v66, s52, v[106:107]
	v_lshl_add_u64 v[66:67], v[66:67], 0, v[108:109]
	global_store_dwordx2 v[66:67], v[58:59], off
	v_add_f32_e32 v58, 1.0, v60
	v_mul_f32_e32 v60, 0xbfb8aa3b, v56
	v_add_f32_e32 v59, 1.0, v61
	v_exp_f32_e32 v61, v60
	v_mul_f32_e32 v60, 0xbfb8aa3b, v57
	v_exp_f32_e32 v62, v60
	v_rcp_f32_e32 v60, v59
	v_add_f32_e32 v59, 1.0, v61
	v_rcp_f32_e32 v58, v58
	v_add_f32_e32 v61, 1.0, v62
	v_rcp_f32_e32 v59, v59
	v_rcp_f32_e32 v61, v61
	v_mov_b32_e32 v62, v54
	v_mov_b32_e32 v63, v56
	v_mov_b32_e32 v56, v55
	v_pk_mul_f32 v[58:59], v[62:63], v[58:59]
	v_mov_b32_e32 v63, v52
	v_pk_mul_f32 v[54:55], v[56:57], v[60:61]
	v_mov_b32_e32 v52, v51
	v_mov_b32_e32 v62, v50
	v_pk_mul_f32 v[50:51], v[52:53], v[54:55]
	v_pk_mul_f32 v[58:59], v[62:63], v[58:59]
	v_and_b32_sdwa v54, v51, v177 dst_sel:DWORD dst_unused:UNUSED_PAD src0_sel:WORD_1 src1_sel:DWORD
	v_and_b32_sdwa v52, v59, v177 dst_sel:DWORD dst_unused:UNUSED_PAD src0_sel:WORD_1 src1_sel:DWORD
	v_and_b32_sdwa v55, v50, v177 dst_sel:DWORD dst_unused:UNUSED_PAD src0_sel:WORD_1 src1_sel:DWORD
	v_add3_u32 v51, v51, v54, s28
	v_and_b32_sdwa v53, v58, v177 dst_sel:DWORD dst_unused:UNUSED_PAD src0_sel:WORD_1 src1_sel:DWORD
	v_add3_u32 v52, v59, v52, s28
	v_add3_u32 v50, v50, v55, s28
	v_and_b32_e32 v51, 0xffff0000, v51
	v_add3_u32 v53, v58, v53, s28
	v_and_b32_e32 v50, 0xffff0000, v50
	v_or_b32_sdwa v51, v51, v52 dst_sel:DWORD dst_unused:UNUSED_PAD src0_sel:DWORD src1_sel:WORD_1
	v_mul_f32_e32 v52, 0xbfb8aa3b, v46
	v_or_b32_sdwa v50, v50, v53 dst_sel:DWORD dst_unused:UNUSED_PAD src0_sel:DWORD src1_sel:WORD_1
	v_exp_f32_e32 v52, v52
	v_mul_f32_e32 v53, 0xbfb8aa3b, v47
	v_exp_f32_e32 v53, v53
	global_store_dwordx2 v[66:67], v[50:51], off offset:32
	v_add_f32_e32 v50, 1.0, v52
	v_mul_f32_e32 v52, 0xbfb8aa3b, v48
	v_add_f32_e32 v51, 1.0, v53
	v_exp_f32_e32 v53, v52
	v_mul_f32_e32 v52, 0xbfb8aa3b, v49
	v_exp_f32_e32 v54, v52
	v_rcp_f32_e32 v52, v51
	v_add_f32_e32 v51, 1.0, v53
	v_rcp_f32_e32 v50, v50
	v_add_f32_e32 v53, 1.0, v54
	v_rcp_f32_e32 v51, v51
	v_rcp_f32_e32 v53, v53
	v_mov_b32_e32 v54, v46
	v_mov_b32_e32 v55, v48
	v_mov_b32_e32 v48, v47
	v_pk_mul_f32 v[50:51], v[54:55], v[50:51]
	v_mov_b32_e32 v55, v44
	v_pk_mul_f32 v[46:47], v[48:49], v[52:53]
	v_mov_b32_e32 v44, v43
	v_mov_b32_e32 v54, v42
	v_pk_mul_f32 v[42:43], v[44:45], v[46:47]
	v_pk_mul_f32 v[50:51], v[54:55], v[50:51]
	v_and_b32_sdwa v46, v43, v177 dst_sel:DWORD dst_unused:UNUSED_PAD src0_sel:WORD_1 src1_sel:DWORD
	v_and_b32_sdwa v44, v51, v177 dst_sel:DWORD dst_unused:UNUSED_PAD src0_sel:WORD_1 src1_sel:DWORD
	v_and_b32_sdwa v47, v42, v177 dst_sel:DWORD dst_unused:UNUSED_PAD src0_sel:WORD_1 src1_sel:DWORD
	v_add3_u32 v43, v43, v46, s28
	v_and_b32_sdwa v45, v50, v177 dst_sel:DWORD dst_unused:UNUSED_PAD src0_sel:WORD_1 src1_sel:DWORD
	v_add3_u32 v44, v51, v44, s28
	v_add3_u32 v42, v42, v47, s28
	v_and_b32_e32 v43, 0xffff0000, v43
	v_add3_u32 v45, v50, v45, s28
	v_and_b32_e32 v42, 0xffff0000, v42
	v_or_b32_sdwa v43, v43, v44 dst_sel:DWORD dst_unused:UNUSED_PAD src0_sel:DWORD src1_sel:WORD_1
	v_mul_f32_e32 v44, 0xbfb8aa3b, v38
	v_or_b32_sdwa v42, v42, v45 dst_sel:DWORD dst_unused:UNUSED_PAD src0_sel:DWORD src1_sel:WORD_1
	v_exp_f32_e32 v44, v44
	v_mul_f32_e32 v45, 0xbfb8aa3b, v39
	v_exp_f32_e32 v45, v45
	global_store_dwordx2 v[66:67], v[42:43], off offset:64
	v_add_f32_e32 v42, 1.0, v44
	v_mul_f32_e32 v44, 0xbfb8aa3b, v40
	v_add_f32_e32 v43, 1.0, v45
	v_exp_f32_e32 v45, v44
	v_mul_f32_e32 v44, 0xbfb8aa3b, v41
	v_exp_f32_e32 v46, v44
	v_rcp_f32_e32 v44, v43
	v_add_f32_e32 v43, 1.0, v45
	v_rcp_f32_e32 v42, v42
	v_add_f32_e32 v45, 1.0, v46
	v_rcp_f32_e32 v43, v43
	v_rcp_f32_e32 v45, v45
	v_mov_b32_e32 v46, v38
	v_mov_b32_e32 v47, v40
	v_mov_b32_e32 v40, v39
	v_pk_mul_f32 v[42:43], v[46:47], v[42:43]
	v_mov_b32_e32 v47, v36
	v_pk_mul_f32 v[38:39], v[40:41], v[44:45]
	v_mov_b32_e32 v36, v35
	v_mov_b32_e32 v46, v34
	v_pk_mul_f32 v[34:35], v[36:37], v[38:39]
	v_pk_mul_f32 v[42:43], v[46:47], v[42:43]
	v_and_b32_sdwa v38, v35, v177 dst_sel:DWORD dst_unused:UNUSED_PAD src0_sel:WORD_1 src1_sel:DWORD
	v_and_b32_sdwa v39, v34, v177 dst_sel:DWORD dst_unused:UNUSED_PAD src0_sel:WORD_1 src1_sel:DWORD
	v_and_b32_sdwa v36, v43, v177 dst_sel:DWORD dst_unused:UNUSED_PAD src0_sel:WORD_1 src1_sel:DWORD
	v_and_b32_sdwa v37, v42, v177 dst_sel:DWORD dst_unused:UNUSED_PAD src0_sel:WORD_1 src1_sel:DWORD
	v_add3_u32 v35, v35, v38, s28
	v_add3_u32 v34, v34, v39, s28
	v_add3_u32 v37, v42, v37, s28
	v_add3_u32 v36, v43, v36, s28
	v_and_b32_e32 v35, 0xffff0000, v35
	v_and_b32_e32 v34, 0xffff0000, v34
	v_or_b32_sdwa v35, v35, v36 dst_sel:DWORD dst_unused:UNUSED_PAD src0_sel:DWORD src1_sel:WORD_1
	v_or_b32_sdwa v34, v34, v37 dst_sel:DWORD dst_unused:UNUSED_PAD src0_sel:DWORD src1_sel:WORD_1
	global_store_dwordx2 v[66:67], v[34:35], off offset:96
	v_mul_f32_e32 v35, 0xbfb8aa3b, v30
	v_exp_f32_e32 v36, v35
	v_mul_f32_e32 v35, 0xbfb8aa3b, v31
	v_mul_f32_e32 v38, 0xbfb8aa3b, v32
	v_exp_f32_e32 v37, v35
	v_exp_f32_e32 v39, v38
	v_mul_f32_e32 v38, 0xbfb8aa3b, v33
	v_exp_f32_e32 v40, v38
	v_add_f32_e32 v37, 1.0, v37
	v_add_f32_e32 v36, 1.0, v36
	v_rcp_f32_e32 v38, v37
	v_add_f32_e32 v37, 1.0, v39
	v_add_f32_e32 v39, 1.0, v40
	v_rcp_f32_e32 v36, v36
	v_rcp_f32_e32 v37, v37
	v_rcp_f32_e32 v39, v39
	v_mov_b32_e32 v40, v30
	v_mov_b32_e32 v41, v32
	v_mov_b32_e32 v32, v31
	v_pk_mul_f32 v[36:37], v[40:41], v[36:37]
	v_mov_b32_e32 v41, v28
	v_pk_mul_f32 v[30:31], v[32:33], v[38:39]
	v_mov_b32_e32 v28, v27
	v_mov_b32_e32 v40, v26
	v_pk_mul_f32 v[26:27], v[28:29], v[30:31]
	v_pk_mul_f32 v[36:37], v[40:41], v[36:37]
	v_and_b32_sdwa v30, v27, v177 dst_sel:DWORD dst_unused:UNUSED_PAD src0_sel:WORD_1 src1_sel:DWORD
	v_and_b32_sdwa v28, v37, v177 dst_sel:DWORD dst_unused:UNUSED_PAD src0_sel:WORD_1 src1_sel:DWORD
	v_and_b32_sdwa v31, v26, v177 dst_sel:DWORD dst_unused:UNUSED_PAD src0_sel:WORD_1 src1_sel:DWORD
	v_add3_u32 v27, v27, v30, s28
	v_and_b32_sdwa v29, v36, v177 dst_sel:DWORD dst_unused:UNUSED_PAD src0_sel:WORD_1 src1_sel:DWORD
	v_add3_u32 v28, v37, v28, s28
	v_add3_u32 v26, v26, v31, s28
	v_and_b32_e32 v27, 0xffff0000, v27
	v_add3_u32 v29, v36, v29, s28
	v_and_b32_e32 v26, 0xffff0000, v26
	v_or_b32_sdwa v27, v27, v28 dst_sel:DWORD dst_unused:UNUSED_PAD src0_sel:DWORD src1_sel:WORD_1
	v_mul_f32_e32 v28, 0xbfb8aa3b, v22
	v_or_b32_sdwa v26, v26, v29 dst_sel:DWORD dst_unused:UNUSED_PAD src0_sel:DWORD src1_sel:WORD_1
	v_exp_f32_e32 v28, v28
	v_mul_f32_e32 v29, 0xbfb8aa3b, v23
	v_or_b32_e32 v34, 48, v110
	v_exp_f32_e32 v29, v29
	v_mad_i64_i32 v[34:35], s[6:7], v34, s52, v[106:107]
	v_lshl_add_u64 v[34:35], v[34:35], 0, v[108:109]
	global_store_dwordx2 v[34:35], v[26:27], off
	v_add_f32_e32 v26, 1.0, v28
	v_mul_f32_e32 v28, 0xbfb8aa3b, v24
	v_add_f32_e32 v27, 1.0, v29
	v_exp_f32_e32 v29, v28
	v_mul_f32_e32 v28, 0xbfb8aa3b, v25
	v_exp_f32_e32 v30, v28
	v_rcp_f32_e32 v28, v27
	v_add_f32_e32 v27, 1.0, v29
	v_rcp_f32_e32 v26, v26
	v_add_f32_e32 v29, 1.0, v30
	v_rcp_f32_e32 v27, v27
	v_rcp_f32_e32 v29, v29
	v_mov_b32_e32 v30, v22
	v_mov_b32_e32 v31, v24
	v_mov_b32_e32 v24, v23
	v_pk_mul_f32 v[26:27], v[30:31], v[26:27]
	v_mov_b32_e32 v31, v20
	v_pk_mul_f32 v[22:23], v[24:25], v[28:29]
	v_mov_b32_e32 v20, v19
	v_mov_b32_e32 v30, v18
	v_pk_mul_f32 v[18:19], v[20:21], v[22:23]
	v_pk_mul_f32 v[26:27], v[30:31], v[26:27]
	v_and_b32_sdwa v22, v19, v177 dst_sel:DWORD dst_unused:UNUSED_PAD src0_sel:WORD_1 src1_sel:DWORD
	v_and_b32_sdwa v20, v27, v177 dst_sel:DWORD dst_unused:UNUSED_PAD src0_sel:WORD_1 src1_sel:DWORD
	v_and_b32_sdwa v23, v18, v177 dst_sel:DWORD dst_unused:UNUSED_PAD src0_sel:WORD_1 src1_sel:DWORD
	v_add3_u32 v19, v19, v22, s28
	v_and_b32_sdwa v21, v26, v177 dst_sel:DWORD dst_unused:UNUSED_PAD src0_sel:WORD_1 src1_sel:DWORD
	v_add3_u32 v20, v27, v20, s28
	v_add3_u32 v18, v18, v23, s28
	v_and_b32_e32 v19, 0xffff0000, v19
	v_add3_u32 v21, v26, v21, s28
	v_and_b32_e32 v18, 0xffff0000, v18
	v_or_b32_sdwa v19, v19, v20 dst_sel:DWORD dst_unused:UNUSED_PAD src0_sel:DWORD src1_sel:WORD_1
	v_mul_f32_e32 v20, 0xbfb8aa3b, v14
	v_or_b32_sdwa v18, v18, v21 dst_sel:DWORD dst_unused:UNUSED_PAD src0_sel:DWORD src1_sel:WORD_1
	v_exp_f32_e32 v20, v20
	v_mul_f32_e32 v21, 0xbfb8aa3b, v15
	v_exp_f32_e32 v21, v21
	global_store_dwordx2 v[34:35], v[18:19], off offset:32
	v_add_f32_e32 v18, 1.0, v20
	v_mul_f32_e32 v20, 0xbfb8aa3b, v16
	v_add_f32_e32 v19, 1.0, v21
	v_exp_f32_e32 v21, v20
	v_mul_f32_e32 v20, 0xbfb8aa3b, v17
	v_exp_f32_e32 v22, v20
	v_rcp_f32_e32 v20, v19
	v_add_f32_e32 v19, 1.0, v21
	v_rcp_f32_e32 v18, v18
	v_add_f32_e32 v21, 1.0, v22
	v_rcp_f32_e32 v19, v19
	v_rcp_f32_e32 v21, v21
	v_mov_b32_e32 v22, v14
	v_mov_b32_e32 v23, v16
	v_mov_b32_e32 v16, v15
	v_pk_mul_f32 v[18:19], v[22:23], v[18:19]
	v_mov_b32_e32 v23, v12
	v_pk_mul_f32 v[14:15], v[16:17], v[20:21]
	v_mov_b32_e32 v12, v11
	v_mov_b32_e32 v22, v10
	v_pk_mul_f32 v[10:11], v[12:13], v[14:15]
	v_pk_mul_f32 v[18:19], v[22:23], v[18:19]
	v_and_b32_sdwa v14, v11, v177 dst_sel:DWORD dst_unused:UNUSED_PAD src0_sel:WORD_1 src1_sel:DWORD
	v_and_b32_sdwa v12, v19, v177 dst_sel:DWORD dst_unused:UNUSED_PAD src0_sel:WORD_1 src1_sel:DWORD
	v_and_b32_sdwa v15, v10, v177 dst_sel:DWORD dst_unused:UNUSED_PAD src0_sel:WORD_1 src1_sel:DWORD
	v_add3_u32 v11, v11, v14, s28
	v_and_b32_sdwa v13, v18, v177 dst_sel:DWORD dst_unused:UNUSED_PAD src0_sel:WORD_1 src1_sel:DWORD
	v_add3_u32 v12, v19, v12, s28
	v_add3_u32 v10, v10, v15, s28
	v_and_b32_e32 v11, 0xffff0000, v11
	v_add3_u32 v13, v18, v13, s28
	v_and_b32_e32 v10, 0xffff0000, v10
	v_or_b32_sdwa v11, v11, v12 dst_sel:DWORD dst_unused:UNUSED_PAD src0_sel:DWORD src1_sel:WORD_1
	v_mul_f32_e32 v12, 0xbfb8aa3b, v6
	v_or_b32_sdwa v10, v10, v13 dst_sel:DWORD dst_unused:UNUSED_PAD src0_sel:DWORD src1_sel:WORD_1
	v_exp_f32_e32 v12, v12
	v_mul_f32_e32 v13, 0xbfb8aa3b, v7
	v_exp_f32_e32 v13, v13
	global_store_dwordx2 v[34:35], v[10:11], off offset:64
	v_add_f32_e32 v10, 1.0, v12
	v_mul_f32_e32 v12, 0xbfb8aa3b, v8
	v_add_f32_e32 v11, 1.0, v13
	v_exp_f32_e32 v13, v12
	v_mul_f32_e32 v12, 0xbfb8aa3b, v9
	v_exp_f32_e32 v14, v12
	v_rcp_f32_e32 v12, v11
	v_add_f32_e32 v11, 1.0, v13
	v_rcp_f32_e32 v10, v10
	v_add_f32_e32 v13, 1.0, v14
	v_rcp_f32_e32 v11, v11
	v_rcp_f32_e32 v13, v13
	v_mov_b32_e32 v14, v6
	v_mov_b32_e32 v15, v8
	v_mov_b32_e32 v8, v7
	v_pk_mul_f32 v[10:11], v[14:15], v[10:11]
	v_mov_b32_e32 v15, v4
	v_pk_mul_f32 v[6:7], v[8:9], v[12:13]
	v_mov_b32_e32 v4, v3
	v_mov_b32_e32 v14, v2
	v_pk_mul_f32 v[2:3], v[4:5], v[6:7]
	v_pk_mul_f32 v[10:11], v[14:15], v[10:11]
	v_and_b32_sdwa v6, v3, v177 dst_sel:DWORD dst_unused:UNUSED_PAD src0_sel:WORD_1 src1_sel:DWORD
	v_and_b32_sdwa v7, v2, v177 dst_sel:DWORD dst_unused:UNUSED_PAD src0_sel:WORD_1 src1_sel:DWORD
	v_and_b32_sdwa v4, v11, v177 dst_sel:DWORD dst_unused:UNUSED_PAD src0_sel:WORD_1 src1_sel:DWORD
	v_and_b32_sdwa v5, v10, v177 dst_sel:DWORD dst_unused:UNUSED_PAD src0_sel:WORD_1 src1_sel:DWORD
	v_add3_u32 v3, v3, v6, s28
	v_add3_u32 v2, v2, v7, s28
	v_add3_u32 v5, v10, v5, s28
	v_add3_u32 v4, v11, v4, s28
	v_and_b32_e32 v3, 0xffff0000, v3
	v_and_b32_e32 v2, 0xffff0000, v2
	s_add_i32 s14, s14, s11
	v_or_b32_sdwa v3, v3, v4 dst_sel:DWORD dst_unused:UNUSED_PAD src0_sel:DWORD src1_sel:WORD_1
	v_or_b32_sdwa v2, v2, v5 dst_sel:DWORD dst_unused:UNUSED_PAD src0_sel:DWORD src1_sel:WORD_1
	s_cmpk_gt_i32 s14, 0x5ff
	global_store_dwordx2 v[34:35], v[2:3], off offset:96
	s_cbranch_scc0 .LBB0_1461

.LBB0_1525:
	s_or_b64 exec, exec, s[12:13]
	s_mov_b64 s[6:7], s[60:61]
	s_waitcnt lgkmcnt(0)
	s_barrier
	s_load_dwordx4 s[44:47], s[6:7], 0x128
	v_readlane_b32 s2, v255, 48
	v_readlane_b32 s3, v255, 49
	v_mov_b32_e32 v2, v172
	s_mov_b32 s11, s42
	s_waitcnt lgkmcnt(0)
	s_add_u32 s12, s46, 0x2a00000
	s_addc_u32 s13, s47, 0
	s_add_u32 s2, s46, s2
	s_addc_u32 s3, s47, s3
	s_add_u32 s14, s2, 0x5608000
	s_addc_u32 s15, s3, 0
	s_add_u32 s16, s46, 0x6035800
	s_addc_u32 s17, s47, 0
	s_add_u32 s48, s46, 0x1b80000
	s_addc_u32 s49, s47, 0
	s_mov_b32 s18, s94
	s_cmpk_gt_i32 s18, 0xff
	s_cbranch_scc1 .LBB0_1530
	v_ashrrev_i32_e32 v204, 3, v2
	v_and_b32_e32 v205, 15, v2
	v_bfe_u32 v3, v2, 4, 2
	v_lshlrev_b32_e32 v0, 4, v2
	v_ashrrev_i32_e32 v4, 1, v2
	v_lshlrev_b32_e32 v2, 1, v2
	v_and_b32_e32 v0, 0x70, v0
	v_and_b32_e32 v206, 0xffffffc0, v4
	v_and_b32_e32 v2, 0x80, v2
	s_movk_i32 s2, 0x90
	v_or_b32_e32 v4, v206, v205
	v_or_b32_e32 v5, v2, v205
	v_and_b32_e32 v100, 7, v204
	v_lshlrev_b32_e32 v100, 4, v100
	v_xor_b32_e32 v100, v100, v0
	v_lshl_add_u32 v166, v204, 7, v100
	v_lshl_add_u64 v[162:163], s[16:17], 0, v[0:1]
	v_lshl_add_u64 v[164:165], s[48:49], 0, v[0:1]
	v_and_b32_e32 v100, 7, v205
	v_xor_b32_e32 v100, v100, v3
	v_lshlrev_b32_e32 v207, 4, v100
	v_lshl_or_b32 v208, v3, 2, v2
	v_lshlrev_b32_e32 v0, 7, v4
	v_lshlrev_b32_e32 v167, 7, v5
.LBB0_1527:
	s_ashr_i32 s2, s18, 31
	s_lshr_b32 s2, s2, 26
	s_add_i32 s2, s18, s2
	s_and_b32 s3, s2, 0xffffc0
	s_sub_i32 s3, s18, s3
	s_lshl_b32 s7, s3, 8
	v_add_u32_e32 v2, s7, v204
	v_mad_i64_i32 v[168:169], s[20:21], v2, s52, v[162:163]
	v_add_co_u32_e32 v56, vcc, 0x58000, v168
	s_lshl_b32 s2, s2, 2
	s_nop 0
	v_addc_co_u32_e32 v57, vcc, 0, v169, vcc
	s_waitcnt vmcnt(9)
	v_add_co_u32_e32 v58, vcc, 0xb0000, v168
	s_and_b32 s6, s2, 0xffffff00
	s_nop 0
	v_addc_co_u32_e32 v59, vcc, 0, v169, vcc
	v_add_u32_e32 v2, s6, v204
	v_add_co_u32_e32 v60, vcc, 0x108000, v168
	v_mad_i64_i32 v[170:171], s[20:21], v2, s52, v[164:165]
	s_nop 0
	v_addc_co_u32_e32 v61, vcc, 0, v169, vcc
	s_waitcnt vmcnt(8)
	v_add_co_u32_e32 v62, vcc, s92, v170
	s_mov_b32 s19, 0x108000
	s_nop 0
	v_addc_co_u32_e32 v63, vcc, 0, v171, vcc
	v_add_co_u32_e32 v64, vcc, s53, v170
	global_load_dwordx4 v[24:27], v[56:57], off
	global_load_dwordx4 v[28:31], v[58:59], off
	v_addc_co_u32_e32 v65, vcc, 0, v171, vcc
	v_add_co_u32_e32 v66, vcc, s19, v170
	global_load_dwordx4 v[32:35], v[168:169], off
	global_load_dwordx4 v[36:39], v[170:171], off
	global_load_dwordx4 v[40:43], v[60:61], off
	global_load_dwordx4 v[44:47], v[62:63], off
	v_addc_co_u32_e32 v67, vcc, 0, v171, vcc
	global_load_dwordx4 v[48:51], v[64:65], off
	global_load_dwordx4 v[52:55], v[66:67], off
	s_barrier
	global_load_dwordx4 v[118:121], v[168:169], off offset:128
	global_load_dwordx4 v[110:113], v[56:57], off offset:128
	global_load_dwordx4 v[114:117], v[58:59], off offset:128
	global_load_dwordx4 v[130:133], v[60:61], off offset:128
	global_load_dwordx4 v[126:129], v[170:171], off offset:128
	global_load_dwordx4 v[122:125], v[62:63], off offset:128
	global_load_dwordx4 v[142:145], v[64:65], off offset:128
	global_load_dwordx4 v[138:141], v[66:67], off offset:128
	v_readfirstlane_b32 vcc_lo, v168
	v_readfirstlane_b32 vcc_hi, v169
	v_readfirstlane_b32 s100, v170
	v_readfirstlane_b32 s101, v171
	s_nop 1
	v_subrev_u32_e32 v168, vcc_lo, v168
	v_subrev_u32_e32 v170, s100, v170
	v_mov_b32_e32 v2, 0
	s_mov_b32 s4, 0
	v_mov_b32_e32 v3, v2
	v_mov_b32_e32 v4, v2
	v_mov_b32_e32 v5, v2
	v_mov_b32_e32 v6, v2
	v_mov_b32_e32 v7, v2
	v_mov_b32_e32 v8, v2
	v_mov_b32_e32 v9, v2
	v_mov_b32_e32 v10, v2
	v_mov_b32_e32 v11, v2
	v_mov_b32_e32 v12, v2
	v_mov_b32_e32 v13, v2
	v_mov_b32_e32 v14, v2
	v_mov_b32_e32 v15, v2
	v_mov_b32_e32 v16, v2
	v_mov_b32_e32 v17, v2
	v_mov_b32_e32 v18, v2
	v_mov_b32_e32 v19, v2
	v_mov_b32_e32 v20, v2
	v_mov_b32_e32 v21, v2
	v_mov_b32_e32 v22, v2
	v_mov_b32_e32 v23, v2
	v_mov_b32_e32 v56, v2
	v_mov_b32_e32 v57, v2
	v_mov_b32_e32 v58, v2
	v_mov_b32_e32 v59, v2
	v_mov_b32_e32 v60, v2
	v_mov_b32_e32 v61, v2
	v_mov_b32_e32 v62, v2
	v_mov_b32_e32 v63, v2
	v_mov_b32_e32 v64, v2
	v_mov_b32_e32 v65, v2
	v_mov_b32_e32 v66, v2
	v_mov_b32_e32 v67, v2
	v_mov_b32_e32 v68, v2
	v_mov_b32_e32 v69, v2
	v_mov_b32_e32 v70, v2
	v_mov_b32_e32 v71, v2
	v_mov_b32_e32 v72, v2
	v_mov_b32_e32 v73, v2
	v_mov_b32_e32 v74, v2
	v_mov_b32_e32 v75, v2
	v_mov_b32_e32 v76, v2
	v_mov_b32_e32 v77, v2
	v_mov_b32_e32 v78, v2
	v_mov_b32_e32 v79, v2
	v_mov_b32_e32 v80, v2
	v_mov_b32_e32 v81, v2
	v_mov_b32_e32 v82, v2
	v_mov_b32_e32 v83, v2
	v_mov_b32_e32 v84, v2
	s_waitcnt vmcnt(13)
	ds_write_b128 v166, v[32:35]
	s_waitcnt vmcnt(12)
	ds_write_b128 v166, v[36:39] offset:32768
	ds_write_b128 v166, v[24:27] offset:8192
	ds_write_b128 v166, v[28:31] offset:16384
	s_waitcnt vmcnt(11)
	ds_write_b128 v166, v[40:43] offset:24576
	s_waitcnt vmcnt(10)
	ds_write_b128 v166, v[44:47] offset:40960
	s_waitcnt vmcnt(9)
	ds_write_b128 v166, v[48:51] offset:49152
	s_waitcnt vmcnt(8)
	ds_write_b128 v166, v[52:55] offset:57344
	v_mov_b32_e32 v24, v2
	v_mov_b32_e32 v25, v2
	v_mov_b32_e32 v26, v2
	v_mov_b32_e32 v27, v2
	v_mov_b32_e32 v28, v2
	v_mov_b32_e32 v29, v2
	v_mov_b32_e32 v30, v2
	v_mov_b32_e32 v31, v2
	v_mov_b32_e32 v32, v2
	v_mov_b32_e32 v33, v2
	v_mov_b32_e32 v34, v2
	v_mov_b32_e32 v35, v2
	v_mov_b32_e32 v36, v2
	v_mov_b32_e32 v37, v2
	v_mov_b32_e32 v38, v2
	v_mov_b32_e32 v39, v2
	v_mov_b32_e32 v40, v2
	v_mov_b32_e32 v41, v2
	v_mov_b32_e32 v42, v2
	v_mov_b32_e32 v43, v2
	v_mov_b32_e32 v44, v2
	v_mov_b32_e32 v45, v2
	v_mov_b32_e32 v46, v2
	v_mov_b32_e32 v47, v2
	v_mov_b32_e32 v48, v2
	v_mov_b32_e32 v49, v2
	v_mov_b32_e32 v50, v2
	v_mov_b32_e32 v51, v2
	v_mov_b32_e32 v52, v2
	v_mov_b32_e32 v53, v2
	v_mov_b32_e32 v54, v2
	v_mov_b32_e32 v55, v2
	v_mov_b32_e32 v85, v2
	v_mov_b32_e32 v86, v2
	v_mov_b32_e32 v87, v2
	v_mov_b32_e32 v88, v2
	v_mov_b32_e32 v89, v2
	v_mov_b32_e32 v90, v2
	v_mov_b32_e32 v91, v2
	v_mov_b32_e32 v92, v2
	v_mov_b32_e32 v93, v2
	v_mov_b32_e32 v94, v2
	v_mov_b32_e32 v95, v2
	v_mov_b32_e32 v96, v2
	v_mov_b32_e32 v97, v2
	v_mov_b32_e32 v98, v2
	v_mov_b32_e32 v99, v2
	v_mov_b32_e32 v100, v2
	v_mov_b32_e32 v101, v2
	v_mov_b32_e32 v102, v2
	v_mov_b32_e32 v103, v2
	v_mov_b32_e32 v104, v2
	v_mov_b32_e32 v105, v2
	v_mov_b32_e32 v106, v2
	v_mov_b32_e32 v107, v2
	v_mov_b32_e32 v108, v2
	v_mov_b32_e32 v109, v2
	v_mov_b32_e32 v134, v2
	v_mov_b32_e32 v135, v2
	v_mov_b32_e32 v136, v2
	v_mov_b32_e32 v137, v2
	v_mov_b32_e32 v146, v2
	v_mov_b32_e32 v147, v2
	v_mov_b32_e32 v148, v2
	v_mov_b32_e32 v149, v2
	v_mov_b32_e32 v150, v2
	v_mov_b32_e32 v151, v2
	v_mov_b32_e32 v152, v2
	v_mov_b32_e32 v153, v2
	v_mov_b32_e32 v154, v2
	v_mov_b32_e32 v155, v2
	v_mov_b32_e32 v156, v2
	v_mov_b32_e32 v157, v2
	v_mov_b32_e32 v158, v2
	v_mov_b32_e32 v159, v2
	v_mov_b32_e32 v160, v2
	v_mov_b32_e32 v161, v2
	s_waitcnt lgkmcnt(0)
	s_barrier
.LBB0_1528:
	s_bitcmp1_b32 s4, 0
	s_cselect_b32 s2, 0x12000, 0
	v_or_b32_e32 v218, s2, v207
	v_add_u32_e32 v214, v218, v0
	v_add_u32_e32 v246, v218, v167
	ds_read_b128 v[184:187], v214
	ds_read_b128 v[198:201], v214 offset:2048
	ds_read_b128 v[210:213], v214 offset:4096
	ds_read_b128 v[214:217], v214 offset:6144
	ds_read_b128 v[218:221], v246 offset:32768
	ds_read_b128 v[222:225], v246 offset:34816
	ds_read_b128 v[226:229], v246 offset:36864
	ds_read_b128 v[230:233], v246 offset:38912
	ds_read_b128 v[234:237], v246 offset:40960
	ds_read_b128 v[238:241], v246 offset:43008
	ds_read_b128 v[242:245], v246 offset:45056
	ds_read_b128 v[246:249], v246 offset:47104
	s_add_i32 s10, s4, 1
	s_bitcmp1_b32 s10, 0
	s_cselect_b32 s3, 0x12000, 0
	s_waitcnt lgkmcnt(7)
	v_mfma_f32_16x16x32_bf16 v[158:161], v[218:221], v[184:187], v[158:161]
	v_mfma_f32_16x16x32_bf16 v[94:97], v[218:221], v[198:201], v[94:97]
	v_mfma_f32_16x16x32_bf16 v[62:65], v[218:221], v[210:213], v[62:65]
	v_mfma_f32_16x16x32_bf16 v[30:33], v[218:221], v[214:217], v[30:33]
	v_add_u32_e32 v218, s3, v166
	s_waitcnt vmcnt(7)
	ds_write_b128 v218, v[118:121]
	s_waitcnt lgkmcnt(7)
	v_mfma_f32_16x16x32_bf16 v[154:157], v[222:225], v[184:187], v[154:157]
	v_mfma_f32_16x16x32_bf16 v[90:93], v[222:225], v[198:201], v[90:93]
	global_load_dwordx4 v[118:121], v168, vcc offset:256
	v_mfma_f32_16x16x32_bf16 v[58:61], v[222:225], v[210:213], v[58:61]
	v_mfma_f32_16x16x32_bf16 v[26:29], v[222:225], v[214:217], v[26:29]
	s_waitcnt vmcnt(7)
	ds_write_b128 v218, v[110:113] offset:8192
	s_waitcnt lgkmcnt(7)
	v_mfma_f32_16x16x32_bf16 v[150:153], v[226:229], v[184:187], v[150:153]
	v_mfma_f32_16x16x32_bf16 v[86:89], v[226:229], v[198:201], v[86:89]
	v_add_u32_e32 v110, 0x58000, v168
	global_load_dwordx4 v[110:113], v110, vcc offset:256
	v_mfma_f32_16x16x32_bf16 v[54:57], v[226:229], v[210:213], v[54:57]
	v_mfma_f32_16x16x32_bf16 v[22:25], v[226:229], v[214:217], v[22:25]
	s_waitcnt vmcnt(7)
	ds_write_b128 v218, v[114:117] offset:16384
	s_waitcnt lgkmcnt(7)
	v_mfma_f32_16x16x32_bf16 v[146:149], v[230:233], v[184:187], v[146:149]
	v_mfma_f32_16x16x32_bf16 v[82:85], v[230:233], v[198:201], v[82:85]
	v_add_u32_e32 v114, 0xb0000, v168
	global_load_dwordx4 v[114:117], v114, vcc offset:256
	v_mfma_f32_16x16x32_bf16 v[50:53], v[230:233], v[210:213], v[50:53]
	v_mfma_f32_16x16x32_bf16 v[18:21], v[230:233], v[214:217], v[18:21]
	s_waitcnt vmcnt(7)
	ds_write_b128 v218, v[130:133] offset:24576
	s_waitcnt lgkmcnt(7)
	v_mfma_f32_16x16x32_bf16 v[134:137], v[234:237], v[184:187], v[134:137]
	v_mfma_f32_16x16x32_bf16 v[78:81], v[234:237], v[198:201], v[78:81]
	v_add_u32_e32 v130, 0x108000, v168
	global_load_dwordx4 v[130:133], v130, vcc offset:256
	v_mfma_f32_16x16x32_bf16 v[46:49], v[234:237], v[210:213], v[46:49]
	v_mfma_f32_16x16x32_bf16 v[14:17], v[234:237], v[214:217], v[14:17]
	s_waitcnt vmcnt(7)
	ds_write_b128 v218, v[126:129] offset:32768
	s_waitcnt lgkmcnt(7)
	v_mfma_f32_16x16x32_bf16 v[106:109], v[238:241], v[184:187], v[106:109]
	v_mfma_f32_16x16x32_bf16 v[74:77], v[238:241], v[198:201], v[74:77]
	global_load_dwordx4 v[126:129], v170, s[100:101] offset:256
	v_mfma_f32_16x16x32_bf16 v[42:45], v[238:241], v[210:213], v[42:45]
	v_mfma_f32_16x16x32_bf16 v[10:13], v[238:241], v[214:217], v[10:13]
	s_waitcnt vmcnt(7)
	ds_write_b128 v218, v[122:125] offset:40960
	s_waitcnt lgkmcnt(7)
	v_mfma_f32_16x16x32_bf16 v[102:105], v[242:245], v[184:187], v[102:105]
	v_mfma_f32_16x16x32_bf16 v[70:73], v[242:245], v[198:201], v[70:73]
	v_add_u32_e32 v122, 0x58000, v170
	global_load_dwordx4 v[122:125], v122, s[100:101] offset:256
	v_mfma_f32_16x16x32_bf16 v[38:41], v[242:245], v[210:213], v[38:41]
	v_mfma_f32_16x16x32_bf16 v[6:9], v[242:245], v[214:217], v[6:9]
	s_waitcnt vmcnt(7)
	ds_write_b128 v218, v[142:145] offset:49152
	s_waitcnt lgkmcnt(7)
	v_mfma_f32_16x16x32_bf16 v[98:101], v[246:249], v[184:187], v[98:101]
	v_mfma_f32_16x16x32_bf16 v[66:69], v[246:249], v[198:201], v[66:69]
	v_add_u32_e32 v142, 0xb0000, v170
	global_load_dwordx4 v[142:145], v142, s[100:101] offset:256
	v_mfma_f32_16x16x32_bf16 v[34:37], v[246:249], v[210:213], v[34:37]
	v_mfma_f32_16x16x32_bf16 v[2:5], v[246:249], v[214:217], v[2:5]
	s_waitcnt vmcnt(7)
	ds_write_b128 v218, v[138:141] offset:57344
	v_add3_u32 v214, s2, v0, v207
	v_xor_b32_e32 v214, 64, v214
	v_add3_u32 v246, s2, v167, v207
	v_xor_b32_e32 v246, 64, v246
	v_add_u32_e32 v138, 0x108000, v170
	global_load_dwordx4 v[138:141], v138, s[100:101] offset:256
	v_add_u32_e32 v168, 0x80, v168
	v_add_u32_e32 v170, 0x80, v170
	ds_read_b128 v[184:187], v214
	ds_read_b128 v[198:201], v214 offset:2048
	ds_read_b128 v[210:213], v214 offset:4096
	ds_read_b128 v[214:217], v214 offset:6144
	ds_read_b128 v[218:221], v246 offset:32768
	ds_read_b128 v[222:225], v246 offset:34816
	ds_read_b128 v[226:229], v246 offset:36864
	ds_read_b128 v[230:233], v246 offset:38912
	ds_read_b128 v[234:237], v246 offset:40960
	ds_read_b128 v[238:241], v246 offset:43008
	ds_read_b128 v[242:245], v246 offset:45056
	ds_read_b128 v[246:249], v246 offset:47104
	s_waitcnt lgkmcnt(7)
	v_mfma_f32_16x16x32_bf16 v[158:161], v[218:221], v[184:187], v[158:161]
	v_mfma_f32_16x16x32_bf16 v[94:97], v[218:221], v[198:201], v[94:97]
	v_mfma_f32_16x16x32_bf16 v[62:65], v[218:221], v[210:213], v[62:65]
	v_mfma_f32_16x16x32_bf16 v[30:33], v[218:221], v[214:217], v[30:33]
	s_waitcnt lgkmcnt(6)
	v_mfma_f32_16x16x32_bf16 v[154:157], v[222:225], v[184:187], v[154:157]
	v_mfma_f32_16x16x32_bf16 v[90:93], v[222:225], v[198:201], v[90:93]
	v_mfma_f32_16x16x32_bf16 v[58:61], v[222:225], v[210:213], v[58:61]
	v_mfma_f32_16x16x32_bf16 v[26:29], v[222:225], v[214:217], v[26:29]
	s_waitcnt lgkmcnt(5)
	v_mfma_f32_16x16x32_bf16 v[150:153], v[226:229], v[184:187], v[150:153]
	v_mfma_f32_16x16x32_bf16 v[86:89], v[226:229], v[198:201], v[86:89]
	v_mfma_f32_16x16x32_bf16 v[54:57], v[226:229], v[210:213], v[54:57]
	v_mfma_f32_16x16x32_bf16 v[22:25], v[226:229], v[214:217], v[22:25]
	s_waitcnt lgkmcnt(4)
	v_mfma_f32_16x16x32_bf16 v[146:149], v[230:233], v[184:187], v[146:149]
	v_mfma_f32_16x16x32_bf16 v[82:85], v[230:233], v[198:201], v[82:85]
	v_mfma_f32_16x16x32_bf16 v[50:53], v[230:233], v[210:213], v[50:53]
	v_mfma_f32_16x16x32_bf16 v[18:21], v[230:233], v[214:217], v[18:21]
	s_waitcnt lgkmcnt(3)
	v_mfma_f32_16x16x32_bf16 v[134:137], v[234:237], v[184:187], v[134:137]
	v_mfma_f32_16x16x32_bf16 v[78:81], v[234:237], v[198:201], v[78:81]
	v_mfma_f32_16x16x32_bf16 v[46:49], v[234:237], v[210:213], v[46:49]
	v_mfma_f32_16x16x32_bf16 v[14:17], v[234:237], v[214:217], v[14:17]
	s_waitcnt lgkmcnt(2)
	v_mfma_f32_16x16x32_bf16 v[106:109], v[238:241], v[184:187], v[106:109]
	v_mfma_f32_16x16x32_bf16 v[74:77], v[238:241], v[198:201], v[74:77]
	v_mfma_f32_16x16x32_bf16 v[42:45], v[238:241], v[210:213], v[42:45]
	v_mfma_f32_16x16x32_bf16 v[10:13], v[238:241], v[214:217], v[10:13]
	s_waitcnt lgkmcnt(1)
	v_mfma_f32_16x16x32_bf16 v[102:105], v[242:245], v[184:187], v[102:105]
	v_mfma_f32_16x16x32_bf16 v[70:73], v[242:245], v[198:201], v[70:73]
	v_mfma_f32_16x16x32_bf16 v[38:41], v[242:245], v[210:213], v[38:41]
	v_mfma_f32_16x16x32_bf16 v[6:9], v[242:245], v[214:217], v[6:9]
	s_waitcnt lgkmcnt(0)
	v_mfma_f32_16x16x32_bf16 v[98:101], v[246:249], v[184:187], v[98:101]
	v_mfma_f32_16x16x32_bf16 v[66:69], v[246:249], v[198:201], v[66:69]
	v_mfma_f32_16x16x32_bf16 v[34:37], v[246:249], v[210:213], v[34:37]
	v_mfma_f32_16x16x32_bf16 v[2:5], v[246:249], v[214:217], v[2:5]
	s_waitcnt lgkmcnt(0)
	s_barrier
	s_cmp_eq_u32 s10, 44
	s_mov_b32 s4, s10
	s_cbranch_scc0 .LBB0_1528
	s_waitcnt vmcnt(4)
	v_add_u32_e32 v110, s7, v206
	s_waitcnt vmcnt(3)
	v_or_b32_e32 v114, v110, v205
	v_cmp_lt_i32_e32 vcc, s97, v114
	v_ashrrev_i32_e32 v112, 31, v114
	v_add_u32_e32 v116, 0xffffc000, v114
	v_ashrrev_i32_e32 v115, 11, v110
	v_cndmask_b32_e64 v113, v112, 0, vcc
	v_cndmask_b32_e32 v112, v114, v116, vcc
	v_mov_b32_e32 v116, s45
	v_mov_b32_e32 v117, s13
	v_mov_b32_e32 v118, s44
	v_mov_b32_e32 v119, s12
	v_or_b32_e32 v110, s6, v208
	s_waitcnt vmcnt(2)
	v_cndmask_b32_e64 v122, v115, 8, vcc
	v_cndmask_b32_e32 v121, v116, v117, vcc
	v_cndmask_b32_e32 v120, v118, v119, vcc
	v_lshlrev_b64 v[112:113], 12, v[112:113]
	v_ashrrev_i32_e32 v111, 31, v110
	v_lshl_add_u64 v[112:113], v[120:121], 0, v[112:113]
	v_mul_hi_i32_i24_e32 v121, 0x9000, v122
	v_mul_i32_i24_e32 v120, 0x9000, v122
	v_lshl_add_u64 v[120:121], s[14:15], 0, v[120:121]
	v_lshlrev_b64 v[110:111], 2, v[110:111]
	s_waitcnt vmcnt(0)
	v_lshl_add_u64 v[128:129], v[120:121], 0, v[110:111]
	global_load_dwordx4 v[120:123], v[128:129], off
	v_lshl_add_u64 v[112:113], v[112:113], 0, v[110:111]
	global_load_dwordx4 v[124:127], v[112:113], off
	s_waitcnt vmcnt(1)
	v_pk_mul_f32 v[120:121], v[120:121], 0.5 op_sel_hi:[1,0]
	v_pk_mul_f32 v[122:123], v[122:123], 0.5 op_sel_hi:[1,0]
	s_waitcnt vmcnt(0)
	v_pk_fma_f32 v[120:121], v[158:159], v[120:121], v[124:125]
	v_pk_fma_f32 v[122:123], v[160:161], v[122:123], v[126:127]
	global_store_dwordx4 v[112:113], v[120:123], off
	global_load_dwordx4 v[120:123], v[128:129], off offset:64
	s_nop 0
	global_load_dwordx4 v[124:127], v[112:113], off offset:64
	s_waitcnt vmcnt(1)
	v_pk_mul_f32 v[120:121], v[120:121], 0.5 op_sel_hi:[1,0]
	v_pk_mul_f32 v[122:123], v[122:123], 0.5 op_sel_hi:[1,0]
	s_waitcnt vmcnt(0)
	v_pk_fma_f32 v[120:121], v[154:155], v[120:121], v[124:125]
	v_pk_fma_f32 v[122:123], v[156:157], v[122:123], v[126:127]
	global_store_dwordx4 v[112:113], v[120:123], off offset:64
	global_load_dwordx4 v[120:123], v[128:129], off offset:128
	s_nop 0
	global_load_dwordx4 v[124:127], v[112:113], off offset:128
	s_waitcnt vmcnt(1)
	v_pk_mul_f32 v[120:121], v[120:121], 0.5 op_sel_hi:[1,0]
	v_pk_mul_f32 v[122:123], v[122:123], 0.5 op_sel_hi:[1,0]
	s_waitcnt vmcnt(0)
	v_pk_fma_f32 v[120:121], v[150:151], v[120:121], v[124:125]
	v_pk_fma_f32 v[122:123], v[152:153], v[122:123], v[126:127]
	global_store_dwordx4 v[112:113], v[120:123], off offset:128
	global_load_dwordx4 v[120:123], v[128:129], off offset:192
	s_nop 0
	global_load_dwordx4 v[124:127], v[112:113], off offset:192
	s_waitcnt vmcnt(1)
	v_pk_mul_f32 v[120:121], v[120:121], 0.5 op_sel_hi:[1,0]
	v_pk_mul_f32 v[122:123], v[122:123], 0.5 op_sel_hi:[1,0]
	s_waitcnt vmcnt(0)
	v_pk_fma_f32 v[120:121], v[146:147], v[120:121], v[124:125]
	v_pk_fma_f32 v[122:123], v[148:149], v[122:123], v[126:127]
	global_store_dwordx4 v[112:113], v[120:123], off offset:192
	global_load_dwordx4 v[120:123], v[128:129], off offset:256
	s_nop 0
	global_load_dwordx4 v[124:127], v[112:113], off offset:256
	s_waitcnt vmcnt(1)
	v_pk_mul_f32 v[120:121], v[120:121], 0.5 op_sel_hi:[1,0]
	v_pk_mul_f32 v[122:123], v[122:123], 0.5 op_sel_hi:[1,0]
	s_waitcnt vmcnt(0)
	v_pk_fma_f32 v[120:121], v[134:135], v[120:121], v[124:125]
	v_pk_fma_f32 v[122:123], v[136:137], v[122:123], v[126:127]
	global_store_dwordx4 v[112:113], v[120:123], off offset:256
	global_load_dwordx4 v[120:123], v[128:129], off offset:320
	s_nop 0
	global_load_dwordx4 v[124:127], v[112:113], off offset:320
	s_waitcnt vmcnt(1)
	v_pk_mul_f32 v[120:121], v[120:121], 0.5 op_sel_hi:[1,0]
	v_pk_mul_f32 v[122:123], v[122:123], 0.5 op_sel_hi:[1,0]
	s_waitcnt vmcnt(0)
	v_pk_fma_f32 v[106:107], v[106:107], v[120:121], v[124:125]
	v_pk_fma_f32 v[108:109], v[108:109], v[122:123], v[126:127]
	global_store_dwordx4 v[112:113], v[106:109], off offset:320
	global_load_dwordx4 v[106:109], v[128:129], off offset:384
	s_nop 0
	global_load_dwordx4 v[120:123], v[112:113], off offset:384
	s_waitcnt vmcnt(1)
	v_pk_mul_f32 v[106:107], v[106:107], 0.5 op_sel_hi:[1,0]
	v_pk_mul_f32 v[108:109], v[108:109], 0.5 op_sel_hi:[1,0]
	s_waitcnt vmcnt(0)
	v_pk_fma_f32 v[102:103], v[102:103], v[106:107], v[120:121]
	v_pk_fma_f32 v[104:105], v[104:105], v[108:109], v[122:123]
	global_store_dwordx4 v[112:113], v[102:105], off offset:384
	global_load_dwordx4 v[102:105], v[128:129], off offset:448
	s_nop 0
	global_load_dwordx4 v[106:109], v[112:113], off offset:448
	s_waitcnt vmcnt(1)
	v_pk_mul_f32 v[102:103], v[102:103], 0.5 op_sel_hi:[1,0]
	v_pk_mul_f32 v[104:105], v[104:105], 0.5 op_sel_hi:[1,0]
	s_waitcnt vmcnt(0)
	v_pk_fma_f32 v[98:99], v[98:99], v[102:103], v[106:107]
	v_pk_fma_f32 v[100:101], v[100:101], v[104:105], v[108:109]
	global_store_dwordx4 v[112:113], v[98:101], off offset:448
	s_nop 1
	v_or_b32_e32 v98, 16, v114
	v_cmp_lt_i32_e32 vcc, s97, v98
	v_add_u32_e32 v100, 0xffffc010, v114
	v_ashrrev_i32_e32 v99, 31, v98
	v_cndmask_b32_e64 v99, v99, 0, vcc
	v_cndmask_b32_e32 v98, v98, v100, vcc
	v_cndmask_b32_e64 v102, v115, 8, vcc
	v_cndmask_b32_e32 v101, v116, v117, vcc
	v_cndmask_b32_e32 v100, v118, v119, vcc
	v_lshlrev_b64 v[98:99], 12, v[98:99]
	v_lshl_add_u64 v[98:99], v[100:101], 0, v[98:99]
	v_mul_hi_i32_i24_e32 v101, 0x9000, v102
	v_mul_i32_i24_e32 v100, 0x9000, v102
	v_lshl_add_u64 v[100:101], s[14:15], 0, v[100:101]
	v_lshl_add_u64 v[108:109], v[100:101], 0, v[110:111]
	global_load_dwordx4 v[100:103], v[108:109], off
	v_lshl_add_u64 v[98:99], v[98:99], 0, v[110:111]
	global_load_dwordx4 v[104:107], v[98:99], off
	s_waitcnt vmcnt(1)
	v_pk_mul_f32 v[100:101], v[100:101], 0.5 op_sel_hi:[1,0]
	v_pk_mul_f32 v[102:103], v[102:103], 0.5 op_sel_hi:[1,0]
	s_waitcnt vmcnt(0)
	v_pk_fma_f32 v[94:95], v[94:95], v[100:101], v[104:105]
	v_pk_fma_f32 v[96:97], v[96:97], v[102:103], v[106:107]
	global_store_dwordx4 v[98:99], v[94:97], off
	global_load_dwordx4 v[94:97], v[108:109], off offset:64
	s_nop 0
	global_load_dwordx4 v[100:103], v[98:99], off offset:64
	s_waitcnt vmcnt(1)
	v_pk_mul_f32 v[94:95], v[94:95], 0.5 op_sel_hi:[1,0]
	v_pk_mul_f32 v[96:97], v[96:97], 0.5 op_sel_hi:[1,0]
	s_waitcnt vmcnt(0)
	v_pk_fma_f32 v[90:91], v[90:91], v[94:95], v[100:101]
	v_pk_fma_f32 v[92:93], v[92:93], v[96:97], v[102:103]
	global_store_dwordx4 v[98:99], v[90:93], off offset:64
	global_load_dwordx4 v[90:93], v[108:109], off offset:128
	s_nop 0
	global_load_dwordx4 v[94:97], v[98:99], off offset:128
	s_waitcnt vmcnt(1)
	v_pk_mul_f32 v[90:91], v[90:91], 0.5 op_sel_hi:[1,0]
	v_pk_mul_f32 v[92:93], v[92:93], 0.5 op_sel_hi:[1,0]
	s_waitcnt vmcnt(0)
	v_pk_fma_f32 v[86:87], v[86:87], v[90:91], v[94:95]
	v_pk_fma_f32 v[88:89], v[88:89], v[92:93], v[96:97]
	global_store_dwordx4 v[98:99], v[86:89], off offset:128
	global_load_dwordx4 v[86:89], v[108:109], off offset:192
	s_nop 0
	global_load_dwordx4 v[90:93], v[98:99], off offset:192
	s_waitcnt vmcnt(1)
	v_pk_mul_f32 v[86:87], v[86:87], 0.5 op_sel_hi:[1,0]
	v_pk_mul_f32 v[88:89], v[88:89], 0.5 op_sel_hi:[1,0]
	s_waitcnt vmcnt(0)
	v_pk_fma_f32 v[82:83], v[82:83], v[86:87], v[90:91]
	v_pk_fma_f32 v[84:85], v[84:85], v[88:89], v[92:93]
	global_store_dwordx4 v[98:99], v[82:85], off offset:192
	global_load_dwordx4 v[82:85], v[108:109], off offset:256
	s_nop 0
	global_load_dwordx4 v[86:89], v[98:99], off offset:256
	s_waitcnt vmcnt(1)
	v_pk_mul_f32 v[82:83], v[82:83], 0.5 op_sel_hi:[1,0]
	v_pk_mul_f32 v[84:85], v[84:85], 0.5 op_sel_hi:[1,0]
	s_waitcnt vmcnt(0)
	v_pk_fma_f32 v[78:79], v[78:79], v[82:83], v[86:87]
	v_pk_fma_f32 v[80:81], v[80:81], v[84:85], v[88:89]
	global_store_dwordx4 v[98:99], v[78:81], off offset:256
	global_load_dwordx4 v[78:81], v[108:109], off offset:320
	s_nop 0
	global_load_dwordx4 v[82:85], v[98:99], off offset:320
	s_waitcnt vmcnt(1)
	v_pk_mul_f32 v[78:79], v[78:79], 0.5 op_sel_hi:[1,0]
	v_pk_mul_f32 v[80:81], v[80:81], 0.5 op_sel_hi:[1,0]
	s_waitcnt vmcnt(0)
	v_pk_fma_f32 v[74:75], v[74:75], v[78:79], v[82:83]
	v_pk_fma_f32 v[76:77], v[76:77], v[80:81], v[84:85]
	global_store_dwordx4 v[98:99], v[74:77], off offset:320
	global_load_dwordx4 v[74:77], v[108:109], off offset:384
	s_nop 0
	global_load_dwordx4 v[78:81], v[98:99], off offset:384
	s_waitcnt vmcnt(1)
	v_pk_mul_f32 v[74:75], v[74:75], 0.5 op_sel_hi:[1,0]
	v_pk_mul_f32 v[76:77], v[76:77], 0.5 op_sel_hi:[1,0]
	s_waitcnt vmcnt(0)
	v_pk_fma_f32 v[70:71], v[70:71], v[74:75], v[78:79]
	v_pk_fma_f32 v[72:73], v[72:73], v[76:77], v[80:81]
	global_store_dwordx4 v[98:99], v[70:73], off offset:384
	global_load_dwordx4 v[70:73], v[108:109], off offset:448
	s_nop 0
	global_load_dwordx4 v[74:77], v[98:99], off offset:448
	s_waitcnt vmcnt(1)
	v_pk_mul_f32 v[70:71], v[70:71], 0.5 op_sel_hi:[1,0]
	v_pk_mul_f32 v[72:73], v[72:73], 0.5 op_sel_hi:[1,0]
	s_waitcnt vmcnt(0)
	v_pk_fma_f32 v[66:67], v[66:67], v[70:71], v[74:75]
	v_pk_fma_f32 v[68:69], v[68:69], v[72:73], v[76:77]
	global_store_dwordx4 v[98:99], v[66:69], off offset:448
	s_nop 1
	v_or_b32_e32 v66, 32, v114
	v_cmp_lt_i32_e32 vcc, s97, v66
	v_add_u32_e32 v68, 0xffffc020, v114
	v_ashrrev_i32_e32 v67, 31, v66
	v_cndmask_b32_e64 v67, v67, 0, vcc
	v_cndmask_b32_e32 v66, v66, v68, vcc
	v_cndmask_b32_e64 v70, v115, 8, vcc
	v_cndmask_b32_e32 v69, v116, v117, vcc
	v_cndmask_b32_e32 v68, v118, v119, vcc
	v_lshlrev_b64 v[66:67], 12, v[66:67]
	v_lshl_add_u64 v[66:67], v[68:69], 0, v[66:67]
	v_mul_hi_i32_i24_e32 v69, 0x9000, v70
	v_mul_i32_i24_e32 v68, 0x9000, v70
	v_lshl_add_u64 v[68:69], s[14:15], 0, v[68:69]
	v_lshl_add_u64 v[76:77], v[68:69], 0, v[110:111]
	global_load_dwordx4 v[68:71], v[76:77], off
	v_lshl_add_u64 v[66:67], v[66:67], 0, v[110:111]
	global_load_dwordx4 v[72:75], v[66:67], off
	s_waitcnt vmcnt(1)
	v_pk_mul_f32 v[68:69], v[68:69], 0.5 op_sel_hi:[1,0]
	v_pk_mul_f32 v[70:71], v[70:71], 0.5 op_sel_hi:[1,0]
	s_waitcnt vmcnt(0)
	v_pk_fma_f32 v[62:63], v[62:63], v[68:69], v[72:73]
	v_pk_fma_f32 v[64:65], v[64:65], v[70:71], v[74:75]
	global_store_dwordx4 v[66:67], v[62:65], off
	global_load_dwordx4 v[62:65], v[76:77], off offset:64
	s_nop 0
	global_load_dwordx4 v[68:71], v[66:67], off offset:64
	s_waitcnt vmcnt(1)
	v_pk_mul_f32 v[62:63], v[62:63], 0.5 op_sel_hi:[1,0]
	v_pk_mul_f32 v[64:65], v[64:65], 0.5 op_sel_hi:[1,0]
	s_waitcnt vmcnt(0)
	v_pk_fma_f32 v[58:59], v[58:59], v[62:63], v[68:69]
	v_pk_fma_f32 v[60:61], v[60:61], v[64:65], v[70:71]
	global_store_dwordx4 v[66:67], v[58:61], off offset:64
	global_load_dwordx4 v[58:61], v[76:77], off offset:128
	s_nop 0
	global_load_dwordx4 v[62:65], v[66:67], off offset:128
	s_waitcnt vmcnt(1)
	v_pk_mul_f32 v[58:59], v[58:59], 0.5 op_sel_hi:[1,0]
	v_pk_mul_f32 v[60:61], v[60:61], 0.5 op_sel_hi:[1,0]
	s_waitcnt vmcnt(0)
	v_pk_fma_f32 v[54:55], v[54:55], v[58:59], v[62:63]
	v_pk_fma_f32 v[56:57], v[56:57], v[60:61], v[64:65]
	global_store_dwordx4 v[66:67], v[54:57], off offset:128
	global_load_dwordx4 v[54:57], v[76:77], off offset:192
	s_nop 0
	global_load_dwordx4 v[58:61], v[66:67], off offset:192
	s_waitcnt vmcnt(1)
	v_pk_mul_f32 v[54:55], v[54:55], 0.5 op_sel_hi:[1,0]
	v_pk_mul_f32 v[56:57], v[56:57], 0.5 op_sel_hi:[1,0]
	s_waitcnt vmcnt(0)
	v_pk_fma_f32 v[50:51], v[50:51], v[54:55], v[58:59]
	v_pk_fma_f32 v[52:53], v[52:53], v[56:57], v[60:61]
	global_store_dwordx4 v[66:67], v[50:53], off offset:192
	global_load_dwordx4 v[50:53], v[76:77], off offset:256
	s_nop 0
	global_load_dwordx4 v[54:57], v[66:67], off offset:256
	s_waitcnt vmcnt(1)
	v_pk_mul_f32 v[50:51], v[50:51], 0.5 op_sel_hi:[1,0]
	v_pk_mul_f32 v[52:53], v[52:53], 0.5 op_sel_hi:[1,0]
	s_waitcnt vmcnt(0)
	v_pk_fma_f32 v[46:47], v[46:47], v[50:51], v[54:55]
	v_pk_fma_f32 v[48:49], v[48:49], v[52:53], v[56:57]
	global_store_dwordx4 v[66:67], v[46:49], off offset:256
	global_load_dwordx4 v[46:49], v[76:77], off offset:320
	s_nop 0
	global_load_dwordx4 v[50:53], v[66:67], off offset:320
	s_waitcnt vmcnt(1)
	v_pk_mul_f32 v[46:47], v[46:47], 0.5 op_sel_hi:[1,0]
	v_pk_mul_f32 v[48:49], v[48:49], 0.5 op_sel_hi:[1,0]
	s_waitcnt vmcnt(0)
	v_pk_fma_f32 v[42:43], v[42:43], v[46:47], v[50:51]
	v_pk_fma_f32 v[44:45], v[44:45], v[48:49], v[52:53]
	global_store_dwordx4 v[66:67], v[42:45], off offset:320
	global_load_dwordx4 v[42:45], v[76:77], off offset:384
	s_nop 0
	global_load_dwordx4 v[46:49], v[66:67], off offset:384
	s_waitcnt vmcnt(1)
	v_pk_mul_f32 v[42:43], v[42:43], 0.5 op_sel_hi:[1,0]
	v_pk_mul_f32 v[44:45], v[44:45], 0.5 op_sel_hi:[1,0]
	s_waitcnt vmcnt(0)
	v_pk_fma_f32 v[38:39], v[38:39], v[42:43], v[46:47]
	v_pk_fma_f32 v[40:41], v[40:41], v[44:45], v[48:49]
	global_store_dwordx4 v[66:67], v[38:41], off offset:384
	global_load_dwordx4 v[38:41], v[76:77], off offset:448
	s_nop 0
	global_load_dwordx4 v[42:45], v[66:67], off offset:448
	s_waitcnt vmcnt(1)
	v_pk_mul_f32 v[38:39], v[38:39], 0.5 op_sel_hi:[1,0]
	v_pk_mul_f32 v[40:41], v[40:41], 0.5 op_sel_hi:[1,0]
	s_waitcnt vmcnt(0)
	v_pk_fma_f32 v[34:35], v[34:35], v[38:39], v[42:43]
	v_pk_fma_f32 v[36:37], v[36:37], v[40:41], v[44:45]
	global_store_dwordx4 v[66:67], v[34:37], off offset:448
	s_nop 1
	v_or_b32_e32 v34, 48, v114
	v_cmp_lt_i32_e32 vcc, s97, v34
	v_add_u32_e32 v36, 0xffffc030, v114
	v_ashrrev_i32_e32 v35, 31, v34
	v_cndmask_b32_e64 v35, v35, 0, vcc
	v_cndmask_b32_e32 v34, v34, v36, vcc
	v_cndmask_b32_e64 v38, v115, 8, vcc
	v_cndmask_b32_e32 v37, v116, v117, vcc
	v_cndmask_b32_e32 v36, v118, v119, vcc
	v_lshlrev_b64 v[34:35], 12, v[34:35]
	v_lshl_add_u64 v[34:35], v[36:37], 0, v[34:35]
	v_mul_hi_i32_i24_e32 v37, 0x9000, v38
	v_mul_i32_i24_e32 v36, 0x9000, v38
	v_lshl_add_u64 v[36:37], s[14:15], 0, v[36:37]
	v_lshl_add_u64 v[44:45], v[36:37], 0, v[110:111]
	global_load_dwordx4 v[36:39], v[44:45], off
	v_lshl_add_u64 v[34:35], v[34:35], 0, v[110:111]
	global_load_dwordx4 v[40:43], v[34:35], off
	s_waitcnt vmcnt(1)
	v_pk_mul_f32 v[36:37], v[36:37], 0.5 op_sel_hi:[1,0]
	v_pk_mul_f32 v[38:39], v[38:39], 0.5 op_sel_hi:[1,0]
	s_waitcnt vmcnt(0)
	v_pk_fma_f32 v[30:31], v[30:31], v[36:37], v[40:41]
	v_pk_fma_f32 v[32:33], v[32:33], v[38:39], v[42:43]
	global_store_dwordx4 v[34:35], v[30:33], off
	global_load_dwordx4 v[30:33], v[44:45], off offset:64
	s_nop 0
	global_load_dwordx4 v[36:39], v[34:35], off offset:64
	s_waitcnt vmcnt(1)
	v_pk_mul_f32 v[30:31], v[30:31], 0.5 op_sel_hi:[1,0]
	v_pk_mul_f32 v[32:33], v[32:33], 0.5 op_sel_hi:[1,0]
	s_waitcnt vmcnt(0)
	v_pk_fma_f32 v[26:27], v[26:27], v[30:31], v[36:37]
	v_pk_fma_f32 v[28:29], v[28:29], v[32:33], v[38:39]
	global_store_dwordx4 v[34:35], v[26:29], off offset:64
	global_load_dwordx4 v[26:29], v[44:45], off offset:128
	s_nop 0
	global_load_dwordx4 v[30:33], v[34:35], off offset:128
	s_waitcnt vmcnt(1)
	v_pk_mul_f32 v[26:27], v[26:27], 0.5 op_sel_hi:[1,0]
	v_pk_mul_f32 v[28:29], v[28:29], 0.5 op_sel_hi:[1,0]
	s_waitcnt vmcnt(0)
	v_pk_fma_f32 v[22:23], v[22:23], v[26:27], v[30:31]
	v_pk_fma_f32 v[24:25], v[24:25], v[28:29], v[32:33]
	global_store_dwordx4 v[34:35], v[22:25], off offset:128
	global_load_dwordx4 v[22:25], v[44:45], off offset:192
	s_nop 0
	global_load_dwordx4 v[26:29], v[34:35], off offset:192
	s_waitcnt vmcnt(1)
	v_pk_mul_f32 v[22:23], v[22:23], 0.5 op_sel_hi:[1,0]
	v_pk_mul_f32 v[24:25], v[24:25], 0.5 op_sel_hi:[1,0]
	s_waitcnt vmcnt(0)
	v_pk_fma_f32 v[18:19], v[18:19], v[22:23], v[26:27]
	v_pk_fma_f32 v[20:21], v[20:21], v[24:25], v[28:29]
	global_store_dwordx4 v[34:35], v[18:21], off offset:192
	global_load_dwordx4 v[18:21], v[44:45], off offset:256
	s_nop 0
	global_load_dwordx4 v[22:25], v[34:35], off offset:256
	s_waitcnt vmcnt(1)
	v_pk_mul_f32 v[18:19], v[18:19], 0.5 op_sel_hi:[1,0]
	v_pk_mul_f32 v[20:21], v[20:21], 0.5 op_sel_hi:[1,0]
	s_waitcnt vmcnt(0)
	v_pk_fma_f32 v[14:15], v[14:15], v[18:19], v[22:23]
	v_pk_fma_f32 v[16:17], v[16:17], v[20:21], v[24:25]
	global_store_dwordx4 v[34:35], v[14:17], off offset:256
	global_load_dwordx4 v[14:17], v[44:45], off offset:320
	s_nop 0
	global_load_dwordx4 v[18:21], v[34:35], off offset:320
	s_waitcnt vmcnt(1)
	v_pk_mul_f32 v[14:15], v[14:15], 0.5 op_sel_hi:[1,0]
	v_pk_mul_f32 v[16:17], v[16:17], 0.5 op_sel_hi:[1,0]
	s_waitcnt vmcnt(0)
	v_pk_fma_f32 v[10:11], v[10:11], v[14:15], v[18:19]
	v_pk_fma_f32 v[12:13], v[12:13], v[16:17], v[20:21]
	global_store_dwordx4 v[34:35], v[10:13], off offset:320
	global_load_dwordx4 v[10:13], v[44:45], off offset:384
	s_nop 0
	global_load_dwordx4 v[14:17], v[34:35], off offset:384
	s_waitcnt vmcnt(1)
	v_pk_mul_f32 v[10:11], v[10:11], 0.5 op_sel_hi:[1,0]
	v_pk_mul_f32 v[12:13], v[12:13], 0.5 op_sel_hi:[1,0]
	s_waitcnt vmcnt(0)
	v_pk_fma_f32 v[6:7], v[6:7], v[10:11], v[14:15]
	v_pk_fma_f32 v[8:9], v[8:9], v[12:13], v[16:17]
	global_store_dwordx4 v[34:35], v[6:9], off offset:384
	global_load_dwordx4 v[6:9], v[44:45], off offset:448
	s_nop 0
	global_load_dwordx4 v[10:13], v[34:35], off offset:448
	s_waitcnt vmcnt(1)
	v_pk_mul_f32 v[6:7], v[6:7], 0.5 op_sel_hi:[1,0]
	v_pk_mul_f32 v[8:9], v[8:9], 0.5 op_sel_hi:[1,0]
	s_waitcnt vmcnt(0)
	v_pk_fma_f32 v[2:3], v[2:3], v[6:7], v[10:11]
	v_pk_fma_f32 v[4:5], v[4:5], v[8:9], v[12:13]
	global_store_dwordx4 v[34:35], v[2:5], off offset:448
	s_add_i32 s18, s18, s11
	s_cmpk_gt_i32 s18, 0xff
	s_cbranch_scc0 .LBB0_1527
